# GEMM K-loops: the wave about to compute raises its priority before the pre-MMA barrier (so it resumes at priority 1) instead of after it
# speedup vs baseline: 1.0071x; 1.0005x over previous
.Lpk354_peel:
	ds_read_b128 v[166:169], v139
	ds_read_b128 v[170:173], v139 offset:1024
	ds_read_b128 v[178:181], v139 offset:2048
	ds_read_b128 v[182:185], v139 offset:3072
	ds_read_b128 v[186:189], v164
	ds_read_b128 v[190:193], v164 offset:1024
	ds_read_b128 v[194:197], v164 offset:2048
	ds_read_b128 v[198:201], v164 offset:3072
	s_add_u32 s2, s26, 0xfffc0080
	s_addc_u32 s3, s27, -1
	s_cmp_eq_u32 s52, 12
	s_cselect_b32 s3, s11, s3
	s_cselect_b32 s2, s13, s2
	s_cselect_b32 s29, s44, s47
	s_cselect_b32 s28, s45, s46
	v_lshl_add_u64 v[148:149], s[26:27], 0, v[142:143]
	s_add_i32 m0, s34, 0xc000
	ds_read_b128 v[202:205], v165
	ds_read_b128 v[206:209], v165 offset:1024
	ds_read_b128 v[210:213], v165 offset:2048
	ds_read_b128 v[214:217], v165 offset:3072
	ds_read_b128 v[218:221], v165 offset:4096
	ds_read_b128 v[222:225], v165 offset:5120
	ds_read_b128 v[226:229], v165 offset:6144
	ds_read_b128 v[230:233], v165 offset:7168
	global_load_lds_dwordx4 v[148:149], off
	v_lshl_add_u64 v[148:149], s[26:27], 0, v[144:145]
	s_add_i32 m0, s34, 0xe000
	s_nop 0
	global_load_lds_dwordx4 v[148:149], off
	s_waitcnt vmcnt(8)
	s_waitcnt lgkmcnt(0)
	s_setprio 1
	s_barrier
	s_waitcnt lgkmcnt(0)
	v_mfma_f32_16x16x32_bf16 v[126:129], v[166:169], v[202:205], 0
	v_mfma_f32_16x16x32_bf16 v[122:125], v[178:181], v[202:205], 0
	v_mfma_f32_16x16x32_bf16 v[110:113], v[166:169], v[210:213], 0
	v_mfma_f32_16x16x32_bf16 v[106:109], v[178:181], v[210:213], 0
	v_mfma_f32_16x16x32_bf16 v[94:97], v[166:169], v[218:221], 0
	v_mfma_f32_16x16x32_bf16 v[90:93], v[178:181], v[218:221], 0
	v_mfma_f32_16x16x32_bf16 v[78:81], v[166:169], v[226:229], 0
	v_mfma_f32_16x16x32_bf16 v[74:77], v[178:181], v[226:229], 0
	v_mfma_f32_16x16x32_bf16 v[126:129], v[170:173], v[206:209], v[126:129]
	v_mfma_f32_16x16x32_bf16 v[122:125], v[182:185], v[206:209], v[122:125]
	v_mfma_f32_16x16x32_bf16 v[110:113], v[170:173], v[214:217], v[110:113]
	v_mfma_f32_16x16x32_bf16 v[106:109], v[182:185], v[214:217], v[106:109]
	v_mfma_f32_16x16x32_bf16 v[94:97], v[170:173], v[222:225], v[94:97]
	v_mfma_f32_16x16x32_bf16 v[90:93], v[182:185], v[222:225], v[90:93]
	v_mfma_f32_16x16x32_bf16 v[78:81], v[170:173], v[230:233], v[78:81]
	v_mfma_f32_16x16x32_bf16 v[74:77], v[182:185], v[230:233], v[74:77]
	s_setprio 0
	s_setprio 1
	v_mfma_f32_16x16x32_bf16 v[118:121], v[186:189], v[202:205], 0
	v_mfma_f32_16x16x32_bf16 v[114:117], v[194:197], v[202:205], 0
	v_mfma_f32_16x16x32_bf16 v[102:105], v[186:189], v[210:213], 0
	v_mfma_f32_16x16x32_bf16 v[98:101], v[194:197], v[210:213], 0
	v_mfma_f32_16x16x32_bf16 v[86:89], v[186:189], v[218:221], 0
	v_mfma_f32_16x16x32_bf16 v[82:85], v[194:197], v[218:221], 0
	v_mfma_f32_16x16x32_bf16 v[70:73], v[186:189], v[226:229], 0
	v_mfma_f32_16x16x32_bf16 v[66:69], v[194:197], v[226:229], 0
	v_mfma_f32_16x16x32_bf16 v[118:121], v[190:193], v[206:209], v[118:121]
	v_mfma_f32_16x16x32_bf16 v[114:117], v[198:201], v[206:209], v[114:117]
	v_mfma_f32_16x16x32_bf16 v[102:105], v[190:193], v[214:217], v[102:105]
	v_mfma_f32_16x16x32_bf16 v[98:101], v[198:201], v[214:217], v[98:101]
	v_mfma_f32_16x16x32_bf16 v[86:89], v[190:193], v[222:225], v[86:89]
	v_mfma_f32_16x16x32_bf16 v[82:85], v[198:201], v[222:225], v[82:85]
	v_mfma_f32_16x16x32_bf16 v[70:73], v[190:193], v[230:233], v[70:73]
	v_mfma_f32_16x16x32_bf16 v[66:69], v[198:201], v[230:233], v[66:69]
	s_setprio 0
	s_barrier
	s_add_i32 s53, s41, s30
	v_lshl_add_u64 v[148:149], s[28:29], 0, v[132:133]
	s_mov_b32 m0, s53
	ds_read_b128 v[202:205], v165 offset:16384
	ds_read_b128 v[206:209], v165 offset:17408
	ds_read_b128 v[210:213], v165 offset:18432
	ds_read_b128 v[214:217], v165 offset:19456
	ds_read_b128 v[218:221], v165 offset:20480
	ds_read_b128 v[222:225], v165 offset:21504
	ds_read_b128 v[226:229], v165 offset:22528
	ds_read_b128 v[230:233], v165 offset:23552
	global_load_lds_dwordx4 v[148:149], off
	s_add_i32 m0, s53, 0x2000
	s_add_u32 s54, s28, 0x40000
	v_lshl_add_u64 v[174:175], s[28:29], 0, v[136:137]
	s_addc_u32 s55, s29, 0
	s_add_i32 s53, s42, s30
	global_load_lds_dwordx4 v[174:175], off
	v_lshl_add_u64 v[234:235], s[54:55], 0, v[132:133]
	s_mov_b32 m0, s53
	v_lshl_add_u64 v[236:237], s[2:3], 0, v[134:135]
	global_load_lds_dwordx4 v[234:235], off
	v_lshl_add_u64 v[234:235], s[54:55], 0, v[136:137]
	s_add_i32 m0, s53, 0x2000
	s_nop 0
	global_load_lds_dwordx4 v[234:235], off
	v_lshl_add_u64 v[234:235], s[2:3], 0, v[130:131]
	s_mov_b32 m0, s34
	s_nop 0
	global_load_lds_dwordx4 v[234:235], off
	s_mov_b32 m0, s25
	s_nop 0
	global_load_lds_dwordx4 v[236:237], off
	s_waitcnt vmcnt(8)
	s_waitcnt lgkmcnt(0)
	s_setprio 1
	s_barrier
	s_waitcnt lgkmcnt(0)
	v_mfma_f32_16x16x32_bf16 v[62:65], v[166:169], v[202:205], 0
	v_mfma_f32_16x16x32_bf16 v[58:61], v[178:181], v[202:205], 0
	v_mfma_f32_16x16x32_bf16 v[46:49], v[166:169], v[210:213], 0
	v_mfma_f32_16x16x32_bf16 v[42:45], v[178:181], v[210:213], 0
	v_mfma_f32_16x16x32_bf16 v[30:33], v[166:169], v[218:221], 0
	v_mfma_f32_16x16x32_bf16 v[26:29], v[178:181], v[218:221], 0
	v_mfma_f32_16x16x32_bf16 v[14:17], v[166:169], v[226:229], 0
	v_mfma_f32_16x16x32_bf16 v[10:13], v[178:181], v[226:229], 0
	v_mfma_f32_16x16x32_bf16 v[62:65], v[170:173], v[206:209], v[62:65]
	v_mfma_f32_16x16x32_bf16 v[58:61], v[182:185], v[206:209], v[58:61]
	v_mfma_f32_16x16x32_bf16 v[46:49], v[170:173], v[214:217], v[46:49]
	v_mfma_f32_16x16x32_bf16 v[42:45], v[182:185], v[214:217], v[42:45]
	v_mfma_f32_16x16x32_bf16 v[30:33], v[170:173], v[222:225], v[30:33]
	v_mfma_f32_16x16x32_bf16 v[26:29], v[182:185], v[222:225], v[26:29]
	v_mfma_f32_16x16x32_bf16 v[14:17], v[170:173], v[230:233], v[14:17]
	v_mfma_f32_16x16x32_bf16 v[10:13], v[182:185], v[230:233], v[10:13]
	s_setprio 0
	s_setprio 1
	v_mfma_f32_16x16x32_bf16 v[54:57], v[186:189], v[202:205], 0
	v_mfma_f32_16x16x32_bf16 v[50:53], v[194:197], v[202:205], 0
	v_mfma_f32_16x16x32_bf16 v[38:41], v[186:189], v[210:213], 0
	v_mfma_f32_16x16x32_bf16 v[34:37], v[194:197], v[210:213], 0
	v_mfma_f32_16x16x32_bf16 v[22:25], v[186:189], v[218:221], 0
	v_mfma_f32_16x16x32_bf16 v[18:21], v[194:197], v[218:221], 0
	v_mfma_f32_16x16x32_bf16 v[6:9], v[186:189], v[226:229], 0
	v_mfma_f32_16x16x32_bf16 v[2:5], v[194:197], v[226:229], 0
	v_mfma_f32_16x16x32_bf16 v[54:57], v[190:193], v[206:209], v[54:57]
	v_mfma_f32_16x16x32_bf16 v[50:53], v[198:201], v[206:209], v[50:53]
	v_mfma_f32_16x16x32_bf16 v[38:41], v[190:193], v[214:217], v[38:41]
	v_mfma_f32_16x16x32_bf16 v[34:37], v[198:201], v[214:217], v[34:37]
	v_mfma_f32_16x16x32_bf16 v[22:25], v[190:193], v[222:225], v[22:25]
	v_mfma_f32_16x16x32_bf16 v[18:21], v[198:201], v[222:225], v[18:21]
	v_mfma_f32_16x16x32_bf16 v[6:9], v[190:193], v[230:233], v[6:9]
	v_mfma_f32_16x16x32_bf16 v[2:5], v[198:201], v[230:233], v[2:5]
	s_setprio 0
	s_barrier
	s_add_i32 s53, 0, 0x18000
	v_add_u32_e32 v176, s53, v163
	s_add_i32 s54, 0, 0x1c000
	ds_read_b128 v[166:169], v176
	ds_read_b128 v[170:173], v176 offset:1024
	ds_read_b128 v[178:181], v176 offset:2048
	ds_read_b128 v[182:185], v176 offset:3072
	v_add_u32_e32 v176, s54, v163
	ds_read_b128 v[186:189], v176
	ds_read_b128 v[190:193], v176 offset:1024
	ds_read_b128 v[194:197], v176 offset:2048
	ds_read_b128 v[198:201], v176 offset:3072
	s_add_u32 s2, s2, 0x40000
	s_addc_u32 s3, s3, 0
	s_mov_b32 m0, s35
	v_lshl_add_u64 v[238:239], s[2:3], 0, v[130:131]
	ds_read_b128 v[202:205], v165 offset:32768
	ds_read_b128 v[206:209], v165 offset:33792
	ds_read_b128 v[210:213], v165 offset:34816
	ds_read_b128 v[214:217], v165 offset:35840
	ds_read_b128 v[218:221], v165 offset:36864
	ds_read_b128 v[222:225], v165 offset:37888
	ds_read_b128 v[226:229], v165 offset:38912
	ds_read_b128 v[230:233], v165 offset:39936
	global_load_lds_dwordx4 v[238:239], off
	v_lshl_add_u64 v[238:239], s[2:3], 0, v[134:135]
	s_mov_b32 m0, s36
	s_nop 0
	global_load_lds_dwordx4 v[238:239], off
	s_waitcnt vmcnt(8)
	s_waitcnt lgkmcnt(0)
	s_setprio 1
	s_barrier
	s_waitcnt lgkmcnt(0)
	v_mfma_f32_16x16x32_bf16 v[126:129], v[166:169], v[202:205], v[126:129]
	v_mfma_f32_16x16x32_bf16 v[122:125], v[178:181], v[202:205], v[122:125]
	v_mfma_f32_16x16x32_bf16 v[110:113], v[166:169], v[210:213], v[110:113]
	v_mfma_f32_16x16x32_bf16 v[106:109], v[178:181], v[210:213], v[106:109]
	v_mfma_f32_16x16x32_bf16 v[94:97], v[166:169], v[218:221], v[94:97]
	v_mfma_f32_16x16x32_bf16 v[90:93], v[178:181], v[218:221], v[90:93]
	v_mfma_f32_16x16x32_bf16 v[78:81], v[166:169], v[226:229], v[78:81]
	v_mfma_f32_16x16x32_bf16 v[74:77], v[178:181], v[226:229], v[74:77]
	v_mfma_f32_16x16x32_bf16 v[126:129], v[170:173], v[206:209], v[126:129]
	v_mfma_f32_16x16x32_bf16 v[122:125], v[182:185], v[206:209], v[122:125]
	v_mfma_f32_16x16x32_bf16 v[110:113], v[170:173], v[214:217], v[110:113]
	v_mfma_f32_16x16x32_bf16 v[106:109], v[182:185], v[214:217], v[106:109]
	v_mfma_f32_16x16x32_bf16 v[94:97], v[170:173], v[222:225], v[94:97]
	v_mfma_f32_16x16x32_bf16 v[90:93], v[182:185], v[222:225], v[90:93]
	v_mfma_f32_16x16x32_bf16 v[78:81], v[170:173], v[230:233], v[78:81]
	v_mfma_f32_16x16x32_bf16 v[74:77], v[182:185], v[230:233], v[74:77]
	s_setprio 0
	s_setprio 1
	v_mfma_f32_16x16x32_bf16 v[118:121], v[186:189], v[202:205], v[118:121]
	v_mfma_f32_16x16x32_bf16 v[114:117], v[194:197], v[202:205], v[114:117]
	v_mfma_f32_16x16x32_bf16 v[102:105], v[186:189], v[210:213], v[102:105]
	v_mfma_f32_16x16x32_bf16 v[98:101], v[194:197], v[210:213], v[98:101]
	v_mfma_f32_16x16x32_bf16 v[86:89], v[186:189], v[218:221], v[86:89]
	v_mfma_f32_16x16x32_bf16 v[82:85], v[194:197], v[218:221], v[82:85]
	v_mfma_f32_16x16x32_bf16 v[70:73], v[186:189], v[226:229], v[70:73]
	v_mfma_f32_16x16x32_bf16 v[66:69], v[194:197], v[226:229], v[66:69]
	v_mfma_f32_16x16x32_bf16 v[118:121], v[190:193], v[206:209], v[118:121]
	v_mfma_f32_16x16x32_bf16 v[114:117], v[198:201], v[206:209], v[114:117]
	v_mfma_f32_16x16x32_bf16 v[102:105], v[190:193], v[214:217], v[102:105]
	v_mfma_f32_16x16x32_bf16 v[98:101], v[198:201], v[214:217], v[98:101]
	v_mfma_f32_16x16x32_bf16 v[86:89], v[190:193], v[222:225], v[86:89]
	v_mfma_f32_16x16x32_bf16 v[82:85], v[198:201], v[222:225], v[82:85]
	v_mfma_f32_16x16x32_bf16 v[70:73], v[190:193], v[230:233], v[70:73]
	v_mfma_f32_16x16x32_bf16 v[66:69], v[198:201], v[230:233], v[66:69]
	s_setprio 0
	s_barrier
	s_add_i32 s2, s53, s30
	v_lshl_add_u64 v[148:149], v[148:149], 0, s[6:7]
	s_mov_b32 m0, s2
	ds_read_b128 v[202:205], v165 offset:49152
	ds_read_b128 v[206:209], v165 offset:50176
	ds_read_b128 v[210:213], v165 offset:51200
	ds_read_b128 v[214:217], v165 offset:52224
	ds_read_b128 v[218:221], v165 offset:53248
	ds_read_b128 v[222:225], v165 offset:54272
	ds_read_b128 v[226:229], v165 offset:55296
	ds_read_b128 v[230:233], v165 offset:56320
	global_load_lds_dwordx4 v[148:149], off
	s_add_i32 m0, s2, 0x2000
	s_add_u32 s2, s28, 0x40080
	v_lshl_add_u64 v[148:149], v[174:175], 0, s[6:7]
	s_addc_u32 s3, s29, 0
	s_add_i32 s28, s54, s30
	global_load_lds_dwordx4 v[148:149], off
	v_lshl_add_u64 v[148:149], s[2:3], 0, v[132:133]
	s_mov_b32 m0, s28
	s_nop 0
	global_load_lds_dwordx4 v[148:149], off
	v_lshl_add_u64 v[148:149], s[2:3], 0, v[136:137]
	s_add_i32 m0, s28, 0x2000
	s_nop 0
	global_load_lds_dwordx4 v[148:149], off
	v_lshl_add_u64 v[148:149], v[234:235], 0, s[6:7]
	s_mov_b32 m0, s38
	s_nop 0
	global_load_lds_dwordx4 v[148:149], off
	v_lshl_add_u64 v[148:149], v[236:237], 0, s[6:7]
	s_mov_b32 m0, s39
	s_nop 0
	global_load_lds_dwordx4 v[148:149], off
	s_waitcnt vmcnt(8)
	s_waitcnt lgkmcnt(0)
	s_setprio 1
	s_barrier
	s_waitcnt lgkmcnt(0)
	v_mfma_f32_16x16x32_bf16 v[62:65], v[166:169], v[202:205], v[62:65]
	v_mfma_f32_16x16x32_bf16 v[58:61], v[178:181], v[202:205], v[58:61]
	v_mfma_f32_16x16x32_bf16 v[46:49], v[166:169], v[210:213], v[46:49]
	v_mfma_f32_16x16x32_bf16 v[42:45], v[178:181], v[210:213], v[42:45]
	v_mfma_f32_16x16x32_bf16 v[30:33], v[166:169], v[218:221], v[30:33]
	v_mfma_f32_16x16x32_bf16 v[26:29], v[178:181], v[218:221], v[26:29]
	v_mfma_f32_16x16x32_bf16 v[14:17], v[166:169], v[226:229], v[14:17]
	v_mfma_f32_16x16x32_bf16 v[10:13], v[178:181], v[226:229], v[10:13]
	v_mfma_f32_16x16x32_bf16 v[62:65], v[170:173], v[206:209], v[62:65]
	v_mfma_f32_16x16x32_bf16 v[58:61], v[182:185], v[206:209], v[58:61]
	v_mfma_f32_16x16x32_bf16 v[46:49], v[170:173], v[214:217], v[46:49]
	v_mfma_f32_16x16x32_bf16 v[42:45], v[182:185], v[214:217], v[42:45]
	v_mfma_f32_16x16x32_bf16 v[30:33], v[170:173], v[222:225], v[30:33]
	v_mfma_f32_16x16x32_bf16 v[26:29], v[182:185], v[222:225], v[26:29]
	v_mfma_f32_16x16x32_bf16 v[14:17], v[170:173], v[230:233], v[14:17]
	v_mfma_f32_16x16x32_bf16 v[10:13], v[182:185], v[230:233], v[10:13]
	s_setprio 0
	s_setprio 1
	v_mfma_f32_16x16x32_bf16 v[54:57], v[186:189], v[202:205], v[54:57]
	v_mfma_f32_16x16x32_bf16 v[50:53], v[194:197], v[202:205], v[50:53]
	v_mfma_f32_16x16x32_bf16 v[38:41], v[186:189], v[210:213], v[38:41]
	v_mfma_f32_16x16x32_bf16 v[34:37], v[194:197], v[210:213], v[34:37]
	v_mfma_f32_16x16x32_bf16 v[22:25], v[186:189], v[218:221], v[22:25]
	v_mfma_f32_16x16x32_bf16 v[18:21], v[194:197], v[218:221], v[18:21]
	v_mfma_f32_16x16x32_bf16 v[6:9], v[186:189], v[226:229], v[6:9]
	v_mfma_f32_16x16x32_bf16 v[2:5], v[194:197], v[226:229], v[2:5]
	v_mfma_f32_16x16x32_bf16 v[54:57], v[190:193], v[206:209], v[54:57]
	v_mfma_f32_16x16x32_bf16 v[50:53], v[198:201], v[206:209], v[50:53]
	v_mfma_f32_16x16x32_bf16 v[38:41], v[190:193], v[214:217], v[38:41]
	v_mfma_f32_16x16x32_bf16 v[34:37], v[198:201], v[214:217], v[34:37]
	v_mfma_f32_16x16x32_bf16 v[22:25], v[190:193], v[222:225], v[22:25]
	v_mfma_f32_16x16x32_bf16 v[18:21], v[198:201], v[222:225], v[18:21]
	v_mfma_f32_16x16x32_bf16 v[6:9], v[190:193], v[230:233], v[6:9]
	v_mfma_f32_16x16x32_bf16 v[2:5], v[198:201], v[230:233], v[2:5]
	s_setprio 0
	s_barrier
	s_add_i32 s52, s52, 2
	s_add_u32 s26, s26, 0x100
	s_addc_u32 s27, s27, 0
	s_add_u32 s46, s46, 0x100
	s_addc_u32 s47, s47, 0
	s_cmp_gt_u32 s52, 13
	s_cbranch_scc0 .LBB0_354
	s_branch .Lpk354_exit
.LBB0_354:
	ds_read_b128 v[166:169], v139
	ds_read_b128 v[170:173], v139 offset:1024
	ds_read_b128 v[178:181], v139 offset:2048
	ds_read_b128 v[182:185], v139 offset:3072
	ds_read_b128 v[186:189], v164
	ds_read_b128 v[190:193], v164 offset:1024
	ds_read_b128 v[194:197], v164 offset:2048
	ds_read_b128 v[198:201], v164 offset:3072
	s_add_u32 s2, s26, 0xfffc0080
	s_addc_u32 s3, s27, -1
	s_cmp_eq_u32 s52, 12
	s_cselect_b32 s3, s11, s3
	s_cselect_b32 s2, s13, s2
	s_cselect_b32 s29, s44, s47
	s_cselect_b32 s28, s45, s46
	v_lshl_add_u64 v[148:149], s[26:27], 0, v[142:143]
	s_add_i32 m0, s34, 0xc000
	ds_read_b128 v[202:205], v165
	ds_read_b128 v[206:209], v165 offset:1024
	ds_read_b128 v[210:213], v165 offset:2048
	ds_read_b128 v[214:217], v165 offset:3072
	ds_read_b128 v[218:221], v165 offset:4096
	ds_read_b128 v[222:225], v165 offset:5120
	ds_read_b128 v[226:229], v165 offset:6144
	ds_read_b128 v[230:233], v165 offset:7168
	global_load_lds_dwordx4 v[148:149], off
	v_lshl_add_u64 v[148:149], s[26:27], 0, v[144:145]
	s_add_i32 m0, s34, 0xe000
	s_nop 0
	global_load_lds_dwordx4 v[148:149], off
	s_waitcnt vmcnt(8)
	s_waitcnt lgkmcnt(0)
	s_setprio 1
	s_barrier
	s_waitcnt lgkmcnt(0)
	v_mfma_f32_16x16x32_bf16 v[126:129], v[166:169], v[202:205], v[126:129]
	v_mfma_f32_16x16x32_bf16 v[122:125], v[178:181], v[202:205], v[122:125]
	v_mfma_f32_16x16x32_bf16 v[110:113], v[166:169], v[210:213], v[110:113]
	v_mfma_f32_16x16x32_bf16 v[106:109], v[178:181], v[210:213], v[106:109]
	v_mfma_f32_16x16x32_bf16 v[94:97], v[166:169], v[218:221], v[94:97]
	v_mfma_f32_16x16x32_bf16 v[90:93], v[178:181], v[218:221], v[90:93]
	v_mfma_f32_16x16x32_bf16 v[78:81], v[166:169], v[226:229], v[78:81]
	v_mfma_f32_16x16x32_bf16 v[74:77], v[178:181], v[226:229], v[74:77]
	v_mfma_f32_16x16x32_bf16 v[126:129], v[170:173], v[206:209], v[126:129]
	v_mfma_f32_16x16x32_bf16 v[122:125], v[182:185], v[206:209], v[122:125]
	v_mfma_f32_16x16x32_bf16 v[110:113], v[170:173], v[214:217], v[110:113]
	v_mfma_f32_16x16x32_bf16 v[106:109], v[182:185], v[214:217], v[106:109]
	v_mfma_f32_16x16x32_bf16 v[94:97], v[170:173], v[222:225], v[94:97]
	v_mfma_f32_16x16x32_bf16 v[90:93], v[182:185], v[222:225], v[90:93]
	v_mfma_f32_16x16x32_bf16 v[78:81], v[170:173], v[230:233], v[78:81]
	v_mfma_f32_16x16x32_bf16 v[74:77], v[182:185], v[230:233], v[74:77]
	s_setprio 0
	s_setprio 1
	v_mfma_f32_16x16x32_bf16 v[118:121], v[186:189], v[202:205], v[118:121]
	v_mfma_f32_16x16x32_bf16 v[114:117], v[194:197], v[202:205], v[114:117]
	v_mfma_f32_16x16x32_bf16 v[102:105], v[186:189], v[210:213], v[102:105]
	v_mfma_f32_16x16x32_bf16 v[98:101], v[194:197], v[210:213], v[98:101]
	v_mfma_f32_16x16x32_bf16 v[86:89], v[186:189], v[218:221], v[86:89]
	v_mfma_f32_16x16x32_bf16 v[82:85], v[194:197], v[218:221], v[82:85]
	v_mfma_f32_16x16x32_bf16 v[70:73], v[186:189], v[226:229], v[70:73]
	v_mfma_f32_16x16x32_bf16 v[66:69], v[194:197], v[226:229], v[66:69]
	v_mfma_f32_16x16x32_bf16 v[118:121], v[190:193], v[206:209], v[118:121]
	v_mfma_f32_16x16x32_bf16 v[114:117], v[198:201], v[206:209], v[114:117]
	v_mfma_f32_16x16x32_bf16 v[102:105], v[190:193], v[214:217], v[102:105]
	v_mfma_f32_16x16x32_bf16 v[98:101], v[198:201], v[214:217], v[98:101]
	v_mfma_f32_16x16x32_bf16 v[86:89], v[190:193], v[222:225], v[86:89]
	v_mfma_f32_16x16x32_bf16 v[82:85], v[198:201], v[222:225], v[82:85]
	v_mfma_f32_16x16x32_bf16 v[70:73], v[190:193], v[230:233], v[70:73]
	v_mfma_f32_16x16x32_bf16 v[66:69], v[198:201], v[230:233], v[66:69]
	s_setprio 0
	s_barrier
	s_add_i32 s53, s41, s30
	v_lshl_add_u64 v[148:149], s[28:29], 0, v[132:133]
	s_mov_b32 m0, s53
	ds_read_b128 v[202:205], v165 offset:16384
	ds_read_b128 v[206:209], v165 offset:17408
	ds_read_b128 v[210:213], v165 offset:18432
	ds_read_b128 v[214:217], v165 offset:19456
	ds_read_b128 v[218:221], v165 offset:20480
	ds_read_b128 v[222:225], v165 offset:21504
	ds_read_b128 v[226:229], v165 offset:22528
	ds_read_b128 v[230:233], v165 offset:23552
	global_load_lds_dwordx4 v[148:149], off
	s_add_i32 m0, s53, 0x2000
	s_add_u32 s54, s28, 0x40000
	v_lshl_add_u64 v[174:175], s[28:29], 0, v[136:137]
	s_addc_u32 s55, s29, 0
	s_add_i32 s53, s42, s30
	global_load_lds_dwordx4 v[174:175], off
	v_lshl_add_u64 v[234:235], s[54:55], 0, v[132:133]
	s_mov_b32 m0, s53
	v_lshl_add_u64 v[236:237], s[2:3], 0, v[134:135]
	global_load_lds_dwordx4 v[234:235], off
	v_lshl_add_u64 v[234:235], s[54:55], 0, v[136:137]
	s_add_i32 m0, s53, 0x2000
	s_nop 0
	global_load_lds_dwordx4 v[234:235], off
	v_lshl_add_u64 v[234:235], s[2:3], 0, v[130:131]
	s_mov_b32 m0, s34
	s_nop 0
	global_load_lds_dwordx4 v[234:235], off
	s_mov_b32 m0, s25
	s_nop 0
	global_load_lds_dwordx4 v[236:237], off
	s_waitcnt vmcnt(8)
	s_waitcnt lgkmcnt(0)
	s_setprio 1
	s_barrier
	s_waitcnt lgkmcnt(0)
	v_mfma_f32_16x16x32_bf16 v[62:65], v[166:169], v[202:205], v[62:65]
	v_mfma_f32_16x16x32_bf16 v[58:61], v[178:181], v[202:205], v[58:61]
	v_mfma_f32_16x16x32_bf16 v[46:49], v[166:169], v[210:213], v[46:49]
	v_mfma_f32_16x16x32_bf16 v[42:45], v[178:181], v[210:213], v[42:45]
	v_mfma_f32_16x16x32_bf16 v[30:33], v[166:169], v[218:221], v[30:33]
	v_mfma_f32_16x16x32_bf16 v[26:29], v[178:181], v[218:221], v[26:29]
	v_mfma_f32_16x16x32_bf16 v[14:17], v[166:169], v[226:229], v[14:17]
	v_mfma_f32_16x16x32_bf16 v[10:13], v[178:181], v[226:229], v[10:13]
	v_mfma_f32_16x16x32_bf16 v[62:65], v[170:173], v[206:209], v[62:65]
	v_mfma_f32_16x16x32_bf16 v[58:61], v[182:185], v[206:209], v[58:61]
	v_mfma_f32_16x16x32_bf16 v[46:49], v[170:173], v[214:217], v[46:49]
	v_mfma_f32_16x16x32_bf16 v[42:45], v[182:185], v[214:217], v[42:45]
	v_mfma_f32_16x16x32_bf16 v[30:33], v[170:173], v[222:225], v[30:33]
	v_mfma_f32_16x16x32_bf16 v[26:29], v[182:185], v[222:225], v[26:29]
	v_mfma_f32_16x16x32_bf16 v[14:17], v[170:173], v[230:233], v[14:17]
	v_mfma_f32_16x16x32_bf16 v[10:13], v[182:185], v[230:233], v[10:13]
	s_setprio 0
	s_setprio 1
	v_mfma_f32_16x16x32_bf16 v[54:57], v[186:189], v[202:205], v[54:57]
	v_mfma_f32_16x16x32_bf16 v[50:53], v[194:197], v[202:205], v[50:53]
	v_mfma_f32_16x16x32_bf16 v[38:41], v[186:189], v[210:213], v[38:41]
	v_mfma_f32_16x16x32_bf16 v[34:37], v[194:197], v[210:213], v[34:37]
	v_mfma_f32_16x16x32_bf16 v[22:25], v[186:189], v[218:221], v[22:25]
	v_mfma_f32_16x16x32_bf16 v[18:21], v[194:197], v[218:221], v[18:21]
	v_mfma_f32_16x16x32_bf16 v[6:9], v[186:189], v[226:229], v[6:9]
	v_mfma_f32_16x16x32_bf16 v[2:5], v[194:197], v[226:229], v[2:5]
	v_mfma_f32_16x16x32_bf16 v[54:57], v[190:193], v[206:209], v[54:57]
	v_mfma_f32_16x16x32_bf16 v[50:53], v[198:201], v[206:209], v[50:53]
	v_mfma_f32_16x16x32_bf16 v[38:41], v[190:193], v[214:217], v[38:41]
	v_mfma_f32_16x16x32_bf16 v[34:37], v[198:201], v[214:217], v[34:37]
	v_mfma_f32_16x16x32_bf16 v[22:25], v[190:193], v[222:225], v[22:25]
	v_mfma_f32_16x16x32_bf16 v[18:21], v[198:201], v[222:225], v[18:21]
	v_mfma_f32_16x16x32_bf16 v[6:9], v[190:193], v[230:233], v[6:9]
	v_mfma_f32_16x16x32_bf16 v[2:5], v[198:201], v[230:233], v[2:5]
	s_setprio 0
	s_barrier
	s_add_i32 s53, 0, 0x18000
	v_add_u32_e32 v176, s53, v163
	s_add_i32 s54, 0, 0x1c000
	ds_read_b128 v[166:169], v176
	ds_read_b128 v[170:173], v176 offset:1024
	ds_read_b128 v[178:181], v176 offset:2048
	ds_read_b128 v[182:185], v176 offset:3072
	v_add_u32_e32 v176, s54, v163
	ds_read_b128 v[186:189], v176
	ds_read_b128 v[190:193], v176 offset:1024
	ds_read_b128 v[194:197], v176 offset:2048
	ds_read_b128 v[198:201], v176 offset:3072
	s_add_u32 s2, s2, 0x40000
	s_addc_u32 s3, s3, 0
	s_mov_b32 m0, s35
	v_lshl_add_u64 v[238:239], s[2:3], 0, v[130:131]
	ds_read_b128 v[202:205], v165 offset:32768
	ds_read_b128 v[206:209], v165 offset:33792
	ds_read_b128 v[210:213], v165 offset:34816
	ds_read_b128 v[214:217], v165 offset:35840
	ds_read_b128 v[218:221], v165 offset:36864
	ds_read_b128 v[222:225], v165 offset:37888
	ds_read_b128 v[226:229], v165 offset:38912
	ds_read_b128 v[230:233], v165 offset:39936
	global_load_lds_dwordx4 v[238:239], off
	v_lshl_add_u64 v[238:239], s[2:3], 0, v[134:135]
	s_mov_b32 m0, s36
	s_nop 0
	global_load_lds_dwordx4 v[238:239], off
	s_waitcnt vmcnt(8)
	s_waitcnt lgkmcnt(0)
	s_setprio 1
	s_barrier
	s_waitcnt lgkmcnt(0)
	v_mfma_f32_16x16x32_bf16 v[126:129], v[166:169], v[202:205], v[126:129]
	v_mfma_f32_16x16x32_bf16 v[122:125], v[178:181], v[202:205], v[122:125]
	v_mfma_f32_16x16x32_bf16 v[110:113], v[166:169], v[210:213], v[110:113]
	v_mfma_f32_16x16x32_bf16 v[106:109], v[178:181], v[210:213], v[106:109]
	v_mfma_f32_16x16x32_bf16 v[94:97], v[166:169], v[218:221], v[94:97]
	v_mfma_f32_16x16x32_bf16 v[90:93], v[178:181], v[218:221], v[90:93]
	v_mfma_f32_16x16x32_bf16 v[78:81], v[166:169], v[226:229], v[78:81]
	v_mfma_f32_16x16x32_bf16 v[74:77], v[178:181], v[226:229], v[74:77]
	v_mfma_f32_16x16x32_bf16 v[126:129], v[170:173], v[206:209], v[126:129]
	v_mfma_f32_16x16x32_bf16 v[122:125], v[182:185], v[206:209], v[122:125]
	v_mfma_f32_16x16x32_bf16 v[110:113], v[170:173], v[214:217], v[110:113]
	v_mfma_f32_16x16x32_bf16 v[106:109], v[182:185], v[214:217], v[106:109]
	v_mfma_f32_16x16x32_bf16 v[94:97], v[170:173], v[222:225], v[94:97]
	v_mfma_f32_16x16x32_bf16 v[90:93], v[182:185], v[222:225], v[90:93]
	v_mfma_f32_16x16x32_bf16 v[78:81], v[170:173], v[230:233], v[78:81]
	v_mfma_f32_16x16x32_bf16 v[74:77], v[182:185], v[230:233], v[74:77]
	s_setprio 0
	s_setprio 1
	v_mfma_f32_16x16x32_bf16 v[118:121], v[186:189], v[202:205], v[118:121]
	v_mfma_f32_16x16x32_bf16 v[114:117], v[194:197], v[202:205], v[114:117]
	v_mfma_f32_16x16x32_bf16 v[102:105], v[186:189], v[210:213], v[102:105]
	v_mfma_f32_16x16x32_bf16 v[98:101], v[194:197], v[210:213], v[98:101]
	v_mfma_f32_16x16x32_bf16 v[86:89], v[186:189], v[218:221], v[86:89]
	v_mfma_f32_16x16x32_bf16 v[82:85], v[194:197], v[218:221], v[82:85]
	v_mfma_f32_16x16x32_bf16 v[70:73], v[186:189], v[226:229], v[70:73]
	v_mfma_f32_16x16x32_bf16 v[66:69], v[194:197], v[226:229], v[66:69]
	v_mfma_f32_16x16x32_bf16 v[118:121], v[190:193], v[206:209], v[118:121]
	v_mfma_f32_16x16x32_bf16 v[114:117], v[198:201], v[206:209], v[114:117]
	v_mfma_f32_16x16x32_bf16 v[102:105], v[190:193], v[214:217], v[102:105]
	v_mfma_f32_16x16x32_bf16 v[98:101], v[198:201], v[214:217], v[98:101]
	v_mfma_f32_16x16x32_bf16 v[86:89], v[190:193], v[222:225], v[86:89]
	v_mfma_f32_16x16x32_bf16 v[82:85], v[198:201], v[222:225], v[82:85]
	v_mfma_f32_16x16x32_bf16 v[70:73], v[190:193], v[230:233], v[70:73]
	v_mfma_f32_16x16x32_bf16 v[66:69], v[198:201], v[230:233], v[66:69]
	s_setprio 0
	s_barrier
	s_add_i32 s2, s53, s30
	v_lshl_add_u64 v[148:149], v[148:149], 0, s[6:7]
	s_mov_b32 m0, s2
	ds_read_b128 v[202:205], v165 offset:49152
	ds_read_b128 v[206:209], v165 offset:50176
	ds_read_b128 v[210:213], v165 offset:51200
	ds_read_b128 v[214:217], v165 offset:52224
	ds_read_b128 v[218:221], v165 offset:53248
	ds_read_b128 v[222:225], v165 offset:54272
	ds_read_b128 v[226:229], v165 offset:55296
	ds_read_b128 v[230:233], v165 offset:56320
	global_load_lds_dwordx4 v[148:149], off
	s_add_i32 m0, s2, 0x2000
	s_add_u32 s2, s28, 0x40080
	v_lshl_add_u64 v[148:149], v[174:175], 0, s[6:7]
	s_addc_u32 s3, s29, 0
	s_add_i32 s28, s54, s30
	global_load_lds_dwordx4 v[148:149], off
	v_lshl_add_u64 v[148:149], s[2:3], 0, v[132:133]
	s_mov_b32 m0, s28
	s_nop 0
	global_load_lds_dwordx4 v[148:149], off
	v_lshl_add_u64 v[148:149], s[2:3], 0, v[136:137]
	s_add_i32 m0, s28, 0x2000
	s_nop 0
	global_load_lds_dwordx4 v[148:149], off
	v_lshl_add_u64 v[148:149], v[234:235], 0, s[6:7]
	s_mov_b32 m0, s38
	s_nop 0
	global_load_lds_dwordx4 v[148:149], off
	v_lshl_add_u64 v[148:149], v[236:237], 0, s[6:7]
	s_mov_b32 m0, s39
	s_nop 0
	global_load_lds_dwordx4 v[148:149], off
	s_waitcnt vmcnt(8)
	s_waitcnt lgkmcnt(0)
	s_setprio 1
	s_barrier
	s_waitcnt lgkmcnt(0)
	v_mfma_f32_16x16x32_bf16 v[62:65], v[166:169], v[202:205], v[62:65]
	v_mfma_f32_16x16x32_bf16 v[58:61], v[178:181], v[202:205], v[58:61]
	v_mfma_f32_16x16x32_bf16 v[46:49], v[166:169], v[210:213], v[46:49]
	v_mfma_f32_16x16x32_bf16 v[42:45], v[178:181], v[210:213], v[42:45]
	v_mfma_f32_16x16x32_bf16 v[30:33], v[166:169], v[218:221], v[30:33]
	v_mfma_f32_16x16x32_bf16 v[26:29], v[178:181], v[218:221], v[26:29]
	v_mfma_f32_16x16x32_bf16 v[14:17], v[166:169], v[226:229], v[14:17]
	v_mfma_f32_16x16x32_bf16 v[10:13], v[178:181], v[226:229], v[10:13]
	v_mfma_f32_16x16x32_bf16 v[62:65], v[170:173], v[206:209], v[62:65]
	v_mfma_f32_16x16x32_bf16 v[58:61], v[182:185], v[206:209], v[58:61]
	v_mfma_f32_16x16x32_bf16 v[46:49], v[170:173], v[214:217], v[46:49]
	v_mfma_f32_16x16x32_bf16 v[42:45], v[182:185], v[214:217], v[42:45]
	v_mfma_f32_16x16x32_bf16 v[30:33], v[170:173], v[222:225], v[30:33]
	v_mfma_f32_16x16x32_bf16 v[26:29], v[182:185], v[222:225], v[26:29]
	v_mfma_f32_16x16x32_bf16 v[14:17], v[170:173], v[230:233], v[14:17]
	v_mfma_f32_16x16x32_bf16 v[10:13], v[182:185], v[230:233], v[10:13]
	s_setprio 0
	s_setprio 1
	v_mfma_f32_16x16x32_bf16 v[54:57], v[186:189], v[202:205], v[54:57]
	v_mfma_f32_16x16x32_bf16 v[50:53], v[194:197], v[202:205], v[50:53]
	v_mfma_f32_16x16x32_bf16 v[38:41], v[186:189], v[210:213], v[38:41]
	v_mfma_f32_16x16x32_bf16 v[34:37], v[194:197], v[210:213], v[34:37]
	v_mfma_f32_16x16x32_bf16 v[22:25], v[186:189], v[218:221], v[22:25]
	v_mfma_f32_16x16x32_bf16 v[18:21], v[194:197], v[218:221], v[18:21]
	v_mfma_f32_16x16x32_bf16 v[6:9], v[186:189], v[226:229], v[6:9]
	v_mfma_f32_16x16x32_bf16 v[2:5], v[194:197], v[226:229], v[2:5]
	v_mfma_f32_16x16x32_bf16 v[54:57], v[190:193], v[206:209], v[54:57]
	v_mfma_f32_16x16x32_bf16 v[50:53], v[198:201], v[206:209], v[50:53]
	v_mfma_f32_16x16x32_bf16 v[38:41], v[190:193], v[214:217], v[38:41]
	v_mfma_f32_16x16x32_bf16 v[34:37], v[198:201], v[214:217], v[34:37]
	v_mfma_f32_16x16x32_bf16 v[22:25], v[190:193], v[222:225], v[22:25]
	v_mfma_f32_16x16x32_bf16 v[18:21], v[198:201], v[222:225], v[18:21]
	v_mfma_f32_16x16x32_bf16 v[6:9], v[190:193], v[230:233], v[6:9]
	v_mfma_f32_16x16x32_bf16 v[2:5], v[198:201], v[230:233], v[2:5]
	s_setprio 0
	s_barrier
	s_add_i32 s52, s52, 2
	s_add_u32 s26, s26, 0x100
	s_addc_u32 s27, s27, 0
	s_add_u32 s46, s46, 0x100
	s_addc_u32 s47, s47, 0
	s_cmp_gt_u32 s52, 13
	s_cbranch_scc0 .LBB0_354

.LBB0_437:
	ds_read_b128 v[160:163], v133
	ds_read_b128 v[164:167], v133 offset:1024
	ds_read_b128 v[168:171], v133 offset:2048
	ds_read_b128 v[172:175], v133 offset:3072
	ds_read_b128 v[178:181], v135
	ds_read_b128 v[182:185], v135 offset:1024
	ds_read_b128 v[186:189], v135 offset:2048
	ds_read_b128 v[190:193], v135 offset:3072
	s_cmp_lg_u32 s8, 0x160000
	s_cselect_b32 s13, s8, 0
	s_cselect_b32 s12, s9, 0
	s_add_u32 s2, s6, s13
	s_addc_u32 s3, s7, s12
	s_add_u32 s14, s0, s13
	s_addc_u32 s15, s1, s12
	s_add_u32 s12, s2, 0x8000
	s_addc_u32 s13, s3, 0
	v_lshl_add_u64 v[226:227], v[148:149], 0, s[8:9]
	s_mov_b32 m0, s27
	v_lshl_add_u64 v[226:227], v[226:227], 0, s[10:11]
	ds_read_b128 v[194:197], v137
	ds_read_b128 v[198:201], v137 offset:1024
	ds_read_b128 v[202:205], v137 offset:2048
	ds_read_b128 v[206:209], v137 offset:3072
	ds_read_b128 v[210:213], v137 offset:4096
	ds_read_b128 v[214:217], v137 offset:5120
	ds_read_b128 v[218:221], v137 offset:6144
	ds_read_b128 v[222:225], v137 offset:7168
	global_load_lds_dwordx4 v[226:227], off
	v_lshl_add_u64 v[226:227], v[150:151], 0, s[8:9]
	v_lshl_add_u64 v[226:227], v[226:227], 0, s[10:11]
	s_mov_b32 m0, s28
	s_nop 0
	global_load_lds_dwordx4 v[226:227], off
	s_waitcnt vmcnt(8)
	s_waitcnt lgkmcnt(0)
	s_setprio 1
	s_barrier
	s_waitcnt lgkmcnt(0)
	v_mfma_f32_16x16x32_bf16 v[126:129], v[160:163], v[194:197], v[126:129]
	v_mfma_f32_16x16x32_bf16 v[122:125], v[168:171], v[194:197], v[122:125]
	v_mfma_f32_16x16x32_bf16 v[114:117], v[160:163], v[202:205], v[114:117]
	v_mfma_f32_16x16x32_bf16 v[106:109], v[168:171], v[202:205], v[106:109]
	v_mfma_f32_16x16x32_bf16 v[98:101], v[160:163], v[210:213], v[98:101]
	v_mfma_f32_16x16x32_bf16 v[90:93], v[168:171], v[210:213], v[90:93]
	v_mfma_f32_16x16x32_bf16 v[82:85], v[160:163], v[218:221], v[82:85]
	v_mfma_f32_16x16x32_bf16 v[74:77], v[168:171], v[218:221], v[74:77]
	v_mfma_f32_16x16x32_bf16 v[126:129], v[164:167], v[198:201], v[126:129]
	v_mfma_f32_16x16x32_bf16 v[122:125], v[172:175], v[198:201], v[122:125]
	v_mfma_f32_16x16x32_bf16 v[114:117], v[164:167], v[206:209], v[114:117]
	v_mfma_f32_16x16x32_bf16 v[106:109], v[172:175], v[206:209], v[106:109]
	v_mfma_f32_16x16x32_bf16 v[98:101], v[164:167], v[214:217], v[98:101]
	v_mfma_f32_16x16x32_bf16 v[90:93], v[172:175], v[214:217], v[90:93]
	v_mfma_f32_16x16x32_bf16 v[82:85], v[164:167], v[222:225], v[82:85]
	v_mfma_f32_16x16x32_bf16 v[74:77], v[172:175], v[222:225], v[74:77]
	s_setprio 0
	s_setprio 1
	v_mfma_f32_16x16x32_bf16 v[118:121], v[178:181], v[194:197], v[118:121]
	v_mfma_f32_16x16x32_bf16 v[110:113], v[186:189], v[194:197], v[110:113]
	v_mfma_f32_16x16x32_bf16 v[102:105], v[178:181], v[202:205], v[102:105]
	v_mfma_f32_16x16x32_bf16 v[94:97], v[186:189], v[202:205], v[94:97]
	v_mfma_f32_16x16x32_bf16 v[86:89], v[178:181], v[210:213], v[86:89]
	v_mfma_f32_16x16x32_bf16 v[78:81], v[186:189], v[210:213], v[78:81]
	v_mfma_f32_16x16x32_bf16 v[70:73], v[178:181], v[218:221], v[70:73]
	v_mfma_f32_16x16x32_bf16 v[66:69], v[186:189], v[218:221], v[66:69]
	v_mfma_f32_16x16x32_bf16 v[118:121], v[182:185], v[198:201], v[118:121]
	v_mfma_f32_16x16x32_bf16 v[110:113], v[190:193], v[198:201], v[110:113]
	v_mfma_f32_16x16x32_bf16 v[102:105], v[182:185], v[206:209], v[102:105]
	v_mfma_f32_16x16x32_bf16 v[94:97], v[190:193], v[206:209], v[94:97]
	v_mfma_f32_16x16x32_bf16 v[86:89], v[182:185], v[214:217], v[86:89]
	v_mfma_f32_16x16x32_bf16 v[78:81], v[190:193], v[214:217], v[78:81]
	v_mfma_f32_16x16x32_bf16 v[70:73], v[182:185], v[222:225], v[70:73]
	v_mfma_f32_16x16x32_bf16 v[66:69], v[190:193], v[222:225], v[66:69]
	s_setprio 0
	s_barrier
	s_mov_b32 m0, s29
	v_lshl_add_u64 v[226:227], s[14:15], 0, v[142:143]
	s_add_u32 s40, s14, 0x4000
	ds_read_b128 v[194:197], v137 offset:16384
	ds_read_b128 v[198:201], v137 offset:17408
	ds_read_b128 v[202:205], v137 offset:18432
	ds_read_b128 v[206:209], v137 offset:19456
	ds_read_b128 v[210:213], v137 offset:20480
	ds_read_b128 v[214:217], v137 offset:21504
	ds_read_b128 v[218:221], v137 offset:22528
	ds_read_b128 v[222:225], v137 offset:23552
	global_load_lds_dwordx4 v[226:227], off
	v_lshl_add_u64 v[226:227], s[14:15], 0, v[146:147]
	s_mov_b32 m0, s30
	s_addc_u32 s41, s15, 0
	global_load_lds_dwordx4 v[226:227], off
	v_lshl_add_u64 v[226:227], s[40:41], 0, v[142:143]
	s_mov_b32 m0, s31
	s_nop 0
	global_load_lds_dwordx4 v[226:227], off
	v_lshl_add_u64 v[226:227], s[40:41], 0, v[146:147]
	s_mov_b32 m0, s34
	s_nop 0
	global_load_lds_dwordx4 v[226:227], off
	v_lshl_add_u64 v[226:227], s[2:3], 0, v[140:141]
	s_mov_b32 m0, s19
	s_nop 0
	global_load_lds_dwordx4 v[226:227], off
	v_lshl_add_u64 v[226:227], s[2:3], 0, v[144:145]
	s_mov_b32 m0, s20
	s_nop 0
	global_load_lds_dwordx4 v[226:227], off
	s_waitcnt vmcnt(8)
	s_waitcnt lgkmcnt(0)
	s_setprio 1
	s_barrier
	s_waitcnt lgkmcnt(0)
	v_mfma_f32_16x16x32_bf16 v[62:65], v[160:163], v[194:197], v[62:65]
	v_mfma_f32_16x16x32_bf16 v[58:61], v[168:171], v[194:197], v[58:61]
	v_mfma_f32_16x16x32_bf16 v[50:53], v[160:163], v[202:205], v[50:53]
	v_mfma_f32_16x16x32_bf16 v[42:45], v[168:171], v[202:205], v[42:45]
	v_mfma_f32_16x16x32_bf16 v[34:37], v[160:163], v[210:213], v[34:37]
	v_mfma_f32_16x16x32_bf16 v[26:29], v[168:171], v[210:213], v[26:29]
	v_mfma_f32_16x16x32_bf16 v[18:21], v[160:163], v[218:221], v[18:21]
	v_mfma_f32_16x16x32_bf16 v[10:13], v[168:171], v[218:221], v[10:13]
	v_mfma_f32_16x16x32_bf16 v[62:65], v[164:167], v[198:201], v[62:65]
	v_mfma_f32_16x16x32_bf16 v[58:61], v[172:175], v[198:201], v[58:61]
	v_mfma_f32_16x16x32_bf16 v[50:53], v[164:167], v[206:209], v[50:53]
	v_mfma_f32_16x16x32_bf16 v[42:45], v[172:175], v[206:209], v[42:45]
	v_mfma_f32_16x16x32_bf16 v[34:37], v[164:167], v[214:217], v[34:37]
	v_mfma_f32_16x16x32_bf16 v[26:29], v[172:175], v[214:217], v[26:29]
	v_mfma_f32_16x16x32_bf16 v[18:21], v[164:167], v[222:225], v[18:21]
	v_mfma_f32_16x16x32_bf16 v[10:13], v[172:175], v[222:225], v[10:13]
	s_setprio 0
	s_setprio 1
	v_mfma_f32_16x16x32_bf16 v[54:57], v[178:181], v[194:197], v[54:57]
	v_mfma_f32_16x16x32_bf16 v[46:49], v[186:189], v[194:197], v[46:49]
	v_mfma_f32_16x16x32_bf16 v[38:41], v[178:181], v[202:205], v[38:41]
	v_mfma_f32_16x16x32_bf16 v[30:33], v[186:189], v[202:205], v[30:33]
	v_mfma_f32_16x16x32_bf16 v[22:25], v[178:181], v[210:213], v[22:25]
	v_mfma_f32_16x16x32_bf16 v[14:17], v[186:189], v[210:213], v[14:17]
	v_mfma_f32_16x16x32_bf16 v[6:9], v[178:181], v[218:221], v[6:9]
	v_mfma_f32_16x16x32_bf16 v[2:5], v[186:189], v[218:221], v[2:5]
	v_mfma_f32_16x16x32_bf16 v[54:57], v[182:185], v[198:201], v[54:57]
	v_mfma_f32_16x16x32_bf16 v[46:49], v[190:193], v[198:201], v[46:49]
	v_mfma_f32_16x16x32_bf16 v[38:41], v[182:185], v[206:209], v[38:41]
	v_mfma_f32_16x16x32_bf16 v[30:33], v[190:193], v[206:209], v[30:33]
	v_mfma_f32_16x16x32_bf16 v[22:25], v[182:185], v[214:217], v[22:25]
	v_mfma_f32_16x16x32_bf16 v[14:17], v[190:193], v[214:217], v[14:17]
	v_mfma_f32_16x16x32_bf16 v[6:9], v[182:185], v[222:225], v[6:9]
	v_mfma_f32_16x16x32_bf16 v[2:5], v[190:193], v[222:225], v[2:5]
	s_setprio 0
	s_barrier
	ds_read_b128 v[160:163], v139
	ds_read_b128 v[164:167], v139 offset:1024
	ds_read_b128 v[168:171], v139 offset:2048
	ds_read_b128 v[172:175], v139 offset:3072
	ds_read_b128 v[178:181], v159
	ds_read_b128 v[182:185], v159 offset:1024
	ds_read_b128 v[186:189], v159 offset:2048
	ds_read_b128 v[190:193], v159 offset:3072
	s_add_u32 s2, s2, 0x4000
	s_addc_u32 s3, s3, 0
	s_mov_b32 m0, s21
	v_lshl_add_u64 v[226:227], s[2:3], 0, v[140:141]
	ds_read_b128 v[194:197], v137 offset:32768
	ds_read_b128 v[198:201], v137 offset:33792
	ds_read_b128 v[202:205], v137 offset:34816
	ds_read_b128 v[206:209], v137 offset:35840
	ds_read_b128 v[210:213], v137 offset:36864
	ds_read_b128 v[214:217], v137 offset:37888
	ds_read_b128 v[218:221], v137 offset:38912
	ds_read_b128 v[222:225], v137 offset:39936
	global_load_lds_dwordx4 v[226:227], off
	v_lshl_add_u64 v[226:227], s[2:3], 0, v[144:145]
	s_mov_b32 m0, s22
	s_nop 0
	global_load_lds_dwordx4 v[226:227], off
	s_waitcnt vmcnt(8)
	s_waitcnt lgkmcnt(0)
	s_setprio 1
	s_barrier
	s_waitcnt lgkmcnt(0)
	v_mfma_f32_16x16x32_bf16 v[126:129], v[160:163], v[194:197], v[126:129]
	v_mfma_f32_16x16x32_bf16 v[122:125], v[168:171], v[194:197], v[122:125]
	v_mfma_f32_16x16x32_bf16 v[114:117], v[160:163], v[202:205], v[114:117]
	v_mfma_f32_16x16x32_bf16 v[106:109], v[168:171], v[202:205], v[106:109]
	v_mfma_f32_16x16x32_bf16 v[98:101], v[160:163], v[210:213], v[98:101]
	v_mfma_f32_16x16x32_bf16 v[90:93], v[168:171], v[210:213], v[90:93]
	v_mfma_f32_16x16x32_bf16 v[82:85], v[160:163], v[218:221], v[82:85]
	v_mfma_f32_16x16x32_bf16 v[74:77], v[168:171], v[218:221], v[74:77]
	v_mfma_f32_16x16x32_bf16 v[126:129], v[164:167], v[198:201], v[126:129]
	v_mfma_f32_16x16x32_bf16 v[122:125], v[172:175], v[198:201], v[122:125]
	v_mfma_f32_16x16x32_bf16 v[114:117], v[164:167], v[206:209], v[114:117]
	v_mfma_f32_16x16x32_bf16 v[106:109], v[172:175], v[206:209], v[106:109]
	v_mfma_f32_16x16x32_bf16 v[98:101], v[164:167], v[214:217], v[98:101]
	v_mfma_f32_16x16x32_bf16 v[90:93], v[172:175], v[214:217], v[90:93]
	v_mfma_f32_16x16x32_bf16 v[82:85], v[164:167], v[222:225], v[82:85]
	v_mfma_f32_16x16x32_bf16 v[74:77], v[172:175], v[222:225], v[74:77]
	s_setprio 0
	s_setprio 1
	v_mfma_f32_16x16x32_bf16 v[118:121], v[178:181], v[194:197], v[118:121]
	v_mfma_f32_16x16x32_bf16 v[110:113], v[186:189], v[194:197], v[110:113]
	v_mfma_f32_16x16x32_bf16 v[102:105], v[178:181], v[202:205], v[102:105]
	v_mfma_f32_16x16x32_bf16 v[94:97], v[186:189], v[202:205], v[94:97]
	v_mfma_f32_16x16x32_bf16 v[86:89], v[178:181], v[210:213], v[86:89]
	v_mfma_f32_16x16x32_bf16 v[78:81], v[186:189], v[210:213], v[78:81]
	v_mfma_f32_16x16x32_bf16 v[70:73], v[178:181], v[218:221], v[70:73]
	v_mfma_f32_16x16x32_bf16 v[66:69], v[186:189], v[218:221], v[66:69]
	v_mfma_f32_16x16x32_bf16 v[118:121], v[182:185], v[198:201], v[118:121]
	v_mfma_f32_16x16x32_bf16 v[110:113], v[190:193], v[198:201], v[110:113]
	v_mfma_f32_16x16x32_bf16 v[102:105], v[182:185], v[206:209], v[102:105]
	v_mfma_f32_16x16x32_bf16 v[94:97], v[190:193], v[206:209], v[94:97]
	v_mfma_f32_16x16x32_bf16 v[86:89], v[182:185], v[214:217], v[86:89]
	v_mfma_f32_16x16x32_bf16 v[78:81], v[190:193], v[214:217], v[78:81]
	v_mfma_f32_16x16x32_bf16 v[70:73], v[182:185], v[222:225], v[70:73]
	v_mfma_f32_16x16x32_bf16 v[66:69], v[190:193], v[222:225], v[66:69]
	s_setprio 0
	s_barrier
	s_add_u32 s2, s14, 0x8000
	s_addc_u32 s3, s15, 0
	s_mov_b32 m0, s35
	v_lshl_add_u64 v[226:227], s[2:3], 0, v[142:143]
	ds_read_b128 v[194:197], v137 offset:49152
	ds_read_b128 v[198:201], v137 offset:50176
	ds_read_b128 v[202:205], v137 offset:51200
	ds_read_b128 v[206:209], v137 offset:52224
	ds_read_b128 v[210:213], v137 offset:53248
	ds_read_b128 v[214:217], v137 offset:54272
	ds_read_b128 v[218:221], v137 offset:55296
	ds_read_b128 v[222:225], v137 offset:56320
	global_load_lds_dwordx4 v[226:227], off
	v_lshl_add_u64 v[226:227], s[2:3], 0, v[146:147]
	s_add_u32 s2, s14, 0xc000
	s_mov_b32 m0, s36
	s_addc_u32 s3, s15, 0
	global_load_lds_dwordx4 v[226:227], off
	v_lshl_add_u64 v[226:227], s[2:3], 0, v[142:143]
	s_mov_b32 m0, s37
	s_nop 0
	global_load_lds_dwordx4 v[226:227], off
	v_lshl_add_u64 v[226:227], s[2:3], 0, v[146:147]
	s_mov_b32 m0, s38
	s_nop 0
	global_load_lds_dwordx4 v[226:227], off
	v_lshl_add_u64 v[226:227], s[12:13], 0, v[140:141]
	s_mov_b32 m0, s24
	s_nop 0
	global_load_lds_dwordx4 v[226:227], off
	v_lshl_add_u64 v[226:227], s[12:13], 0, v[144:145]
	s_mov_b32 m0, s25
	s_nop 0
	global_load_lds_dwordx4 v[226:227], off
	s_waitcnt vmcnt(8)
	s_waitcnt lgkmcnt(0)
	s_setprio 1
	s_barrier
	s_waitcnt lgkmcnt(0)
	v_mfma_f32_16x16x32_bf16 v[62:65], v[160:163], v[194:197], v[62:65]
	v_mfma_f32_16x16x32_bf16 v[58:61], v[168:171], v[194:197], v[58:61]
	v_mfma_f32_16x16x32_bf16 v[50:53], v[160:163], v[202:205], v[50:53]
	v_mfma_f32_16x16x32_bf16 v[42:45], v[168:171], v[202:205], v[42:45]
	v_mfma_f32_16x16x32_bf16 v[34:37], v[160:163], v[210:213], v[34:37]
	v_mfma_f32_16x16x32_bf16 v[26:29], v[168:171], v[210:213], v[26:29]
	v_mfma_f32_16x16x32_bf16 v[18:21], v[160:163], v[218:221], v[18:21]
	v_mfma_f32_16x16x32_bf16 v[10:13], v[168:171], v[218:221], v[10:13]
	v_mfma_f32_16x16x32_bf16 v[62:65], v[164:167], v[198:201], v[62:65]
	v_mfma_f32_16x16x32_bf16 v[58:61], v[172:175], v[198:201], v[58:61]
	v_mfma_f32_16x16x32_bf16 v[50:53], v[164:167], v[206:209], v[50:53]
	v_mfma_f32_16x16x32_bf16 v[42:45], v[172:175], v[206:209], v[42:45]
	v_mfma_f32_16x16x32_bf16 v[34:37], v[164:167], v[214:217], v[34:37]
	v_mfma_f32_16x16x32_bf16 v[26:29], v[172:175], v[214:217], v[26:29]
	v_mfma_f32_16x16x32_bf16 v[18:21], v[164:167], v[222:225], v[18:21]
	v_mfma_f32_16x16x32_bf16 v[10:13], v[172:175], v[222:225], v[10:13]
	s_setprio 0
	s_setprio 1
	v_mfma_f32_16x16x32_bf16 v[54:57], v[178:181], v[194:197], v[54:57]
	v_mfma_f32_16x16x32_bf16 v[46:49], v[186:189], v[194:197], v[46:49]
	v_mfma_f32_16x16x32_bf16 v[38:41], v[178:181], v[202:205], v[38:41]
	v_mfma_f32_16x16x32_bf16 v[30:33], v[186:189], v[202:205], v[30:33]
	v_mfma_f32_16x16x32_bf16 v[22:25], v[178:181], v[210:213], v[22:25]
	v_mfma_f32_16x16x32_bf16 v[14:17], v[186:189], v[210:213], v[14:17]
	v_mfma_f32_16x16x32_bf16 v[6:9], v[178:181], v[218:221], v[6:9]
	v_mfma_f32_16x16x32_bf16 v[2:5], v[186:189], v[218:221], v[2:5]
	v_mfma_f32_16x16x32_bf16 v[54:57], v[182:185], v[198:201], v[54:57]
	v_mfma_f32_16x16x32_bf16 v[46:49], v[190:193], v[198:201], v[46:49]
	v_mfma_f32_16x16x32_bf16 v[38:41], v[182:185], v[206:209], v[38:41]
	v_mfma_f32_16x16x32_bf16 v[30:33], v[190:193], v[206:209], v[30:33]
	v_mfma_f32_16x16x32_bf16 v[22:25], v[182:185], v[214:217], v[22:25]
	v_mfma_f32_16x16x32_bf16 v[14:17], v[190:193], v[214:217], v[14:17]
	v_mfma_f32_16x16x32_bf16 v[6:9], v[182:185], v[222:225], v[6:9]
	v_mfma_f32_16x16x32_bf16 v[2:5], v[190:193], v[222:225], v[2:5]
	s_setprio 0
	s_barrier
	s_add_i32 s26, s26, 2
	s_add_u32 s8, s8, 0x10000
	s_addc_u32 s9, s9, 0
	s_cmp_gt_u32 s26, 41
	s_cbranch_scc0 .LBB0_437
	s_cmpk_lt_u32 s16, 0x100
	s_cbranch_scc0 .LBB0_440
	s_barrier

.Lpk451_peel:
	ds_read_b128 v[152:155], v149
	ds_read_b128 v[156:159], v149 offset:1024
	ds_read_b128 v[160:163], v149 offset:2048
	ds_read_b128 v[164:167], v149 offset:3072
	ds_read_b128 v[168:171], v150
	ds_read_b128 v[172:175], v150 offset:1024
	ds_read_b128 v[178:181], v150 offset:2048
	ds_read_b128 v[182:185], v150 offset:3072
	s_add_u32 s2, s28, 0xfffc0080
	s_addc_u32 s3, s29, -1
	s_cmp_eq_u32 s52, 12
	s_cselect_b32 s3, s11, s3
	s_cselect_b32 s2, s13, s2
	s_cselect_b32 s31, s44, s47
	s_cselect_b32 s30, s45, s46
	v_lshl_add_u64 v[146:147], s[28:29], 0, v[140:141]
	s_add_i32 m0, s25, 0xc000
	ds_read_b128 v[186:189], v151
	ds_read_b128 v[190:193], v151 offset:1024
	ds_read_b128 v[194:197], v151 offset:2048
	ds_read_b128 v[198:201], v151 offset:3072
	ds_read_b128 v[202:205], v151 offset:4096
	ds_read_b128 v[206:209], v151 offset:5120
	ds_read_b128 v[210:213], v151 offset:6144
	ds_read_b128 v[214:217], v151 offset:7168
	global_load_lds_dwordx4 v[146:147], off
	v_lshl_add_u64 v[146:147], s[28:29], 0, v[142:143]
	s_add_i32 m0, s25, 0xe000
	s_nop 0
	global_load_lds_dwordx4 v[146:147], off
	s_waitcnt vmcnt(8)
	s_waitcnt lgkmcnt(0)
	s_setprio 1
	s_barrier
	s_waitcnt lgkmcnt(0)
	v_mfma_f32_16x16x32_bf16 v[126:129], v[152:155], v[186:189], 0
	v_mfma_f32_16x16x32_bf16 v[122:125], v[160:163], v[186:189], 0
	v_mfma_f32_16x16x32_bf16 v[110:113], v[152:155], v[194:197], 0
	v_mfma_f32_16x16x32_bf16 v[106:109], v[160:163], v[194:197], 0
	v_mfma_f32_16x16x32_bf16 v[94:97], v[152:155], v[202:205], 0
	v_mfma_f32_16x16x32_bf16 v[90:93], v[160:163], v[202:205], 0
	v_mfma_f32_16x16x32_bf16 v[78:81], v[152:155], v[210:213], 0
	v_mfma_f32_16x16x32_bf16 v[74:77], v[160:163], v[210:213], 0
	v_mfma_f32_16x16x32_bf16 v[126:129], v[156:159], v[190:193], v[126:129]
	v_mfma_f32_16x16x32_bf16 v[122:125], v[164:167], v[190:193], v[122:125]
	v_mfma_f32_16x16x32_bf16 v[110:113], v[156:159], v[198:201], v[110:113]
	v_mfma_f32_16x16x32_bf16 v[106:109], v[164:167], v[198:201], v[106:109]
	v_mfma_f32_16x16x32_bf16 v[94:97], v[156:159], v[206:209], v[94:97]
	v_mfma_f32_16x16x32_bf16 v[90:93], v[164:167], v[206:209], v[90:93]
	v_mfma_f32_16x16x32_bf16 v[78:81], v[156:159], v[214:217], v[78:81]
	v_mfma_f32_16x16x32_bf16 v[74:77], v[164:167], v[214:217], v[74:77]
	s_setprio 0
	s_setprio 1
	v_mfma_f32_16x16x32_bf16 v[118:121], v[168:171], v[186:189], 0
	v_mfma_f32_16x16x32_bf16 v[114:117], v[178:181], v[186:189], 0
	v_mfma_f32_16x16x32_bf16 v[102:105], v[168:171], v[194:197], 0
	v_mfma_f32_16x16x32_bf16 v[98:101], v[178:181], v[194:197], 0
	v_mfma_f32_16x16x32_bf16 v[86:89], v[168:171], v[202:205], 0
	v_mfma_f32_16x16x32_bf16 v[82:85], v[178:181], v[202:205], 0
	v_mfma_f32_16x16x32_bf16 v[70:73], v[168:171], v[210:213], 0
	v_mfma_f32_16x16x32_bf16 v[66:69], v[178:181], v[210:213], 0
	v_mfma_f32_16x16x32_bf16 v[118:121], v[172:175], v[190:193], v[118:121]
	v_mfma_f32_16x16x32_bf16 v[114:117], v[182:185], v[190:193], v[114:117]
	v_mfma_f32_16x16x32_bf16 v[102:105], v[172:175], v[198:201], v[102:105]
	v_mfma_f32_16x16x32_bf16 v[98:101], v[182:185], v[198:201], v[98:101]
	v_mfma_f32_16x16x32_bf16 v[86:89], v[172:175], v[206:209], v[86:89]
	v_mfma_f32_16x16x32_bf16 v[82:85], v[182:185], v[206:209], v[82:85]
	v_mfma_f32_16x16x32_bf16 v[70:73], v[172:175], v[214:217], v[70:73]
	v_mfma_f32_16x16x32_bf16 v[66:69], v[182:185], v[214:217], v[66:69]
	s_setprio 0
	s_barrier
	s_add_i32 s53, s42, s34
	v_lshl_add_u64 v[146:147], s[30:31], 0, v[132:133]
	s_mov_b32 m0, s53
	ds_read_b128 v[186:189], v151 offset:16384
	ds_read_b128 v[190:193], v151 offset:17408
	ds_read_b128 v[194:197], v151 offset:18432
	ds_read_b128 v[198:201], v151 offset:19456
	ds_read_b128 v[202:205], v151 offset:20480
	ds_read_b128 v[206:209], v151 offset:21504
	ds_read_b128 v[210:213], v151 offset:22528
	ds_read_b128 v[214:217], v151 offset:23552
	global_load_lds_dwordx4 v[146:147], off
	s_add_i32 m0, s53, 0x2000
	s_add_u32 s54, s30, 0x40000
	v_lshl_add_u64 v[218:219], s[30:31], 0, v[136:137]
	s_addc_u32 s55, s31, 0
	s_add_i32 s53, s43, s34
	global_load_lds_dwordx4 v[218:219], off
	v_lshl_add_u64 v[220:221], s[54:55], 0, v[132:133]
	s_mov_b32 m0, s53
	v_lshl_add_u64 v[222:223], s[2:3], 0, v[134:135]
	global_load_lds_dwordx4 v[220:221], off
	v_lshl_add_u64 v[220:221], s[54:55], 0, v[136:137]
	s_add_i32 m0, s53, 0x2000
	s_nop 0
	global_load_lds_dwordx4 v[220:221], off
	v_lshl_add_u64 v[220:221], s[2:3], 0, v[130:131]
	s_mov_b32 m0, s25
	s_nop 0
	global_load_lds_dwordx4 v[220:221], off
	s_mov_b32 m0, s27
	s_nop 0
	global_load_lds_dwordx4 v[222:223], off
	s_waitcnt vmcnt(8)
	s_waitcnt lgkmcnt(0)
	s_setprio 1
	s_barrier
	s_waitcnt lgkmcnt(0)
	v_mfma_f32_16x16x32_bf16 v[62:65], v[152:155], v[186:189], 0
	v_mfma_f32_16x16x32_bf16 v[58:61], v[160:163], v[186:189], 0
	v_mfma_f32_16x16x32_bf16 v[46:49], v[152:155], v[194:197], 0
	v_mfma_f32_16x16x32_bf16 v[42:45], v[160:163], v[194:197], 0
	v_mfma_f32_16x16x32_bf16 v[30:33], v[152:155], v[202:205], 0
	v_mfma_f32_16x16x32_bf16 v[26:29], v[160:163], v[202:205], 0
	v_mfma_f32_16x16x32_bf16 v[14:17], v[152:155], v[210:213], 0
	v_mfma_f32_16x16x32_bf16 v[10:13], v[160:163], v[210:213], 0
	v_mfma_f32_16x16x32_bf16 v[62:65], v[156:159], v[190:193], v[62:65]
	v_mfma_f32_16x16x32_bf16 v[58:61], v[164:167], v[190:193], v[58:61]
	v_mfma_f32_16x16x32_bf16 v[46:49], v[156:159], v[198:201], v[46:49]
	v_mfma_f32_16x16x32_bf16 v[42:45], v[164:167], v[198:201], v[42:45]
	v_mfma_f32_16x16x32_bf16 v[30:33], v[156:159], v[206:209], v[30:33]
	v_mfma_f32_16x16x32_bf16 v[26:29], v[164:167], v[206:209], v[26:29]
	v_mfma_f32_16x16x32_bf16 v[14:17], v[156:159], v[214:217], v[14:17]
	v_mfma_f32_16x16x32_bf16 v[10:13], v[164:167], v[214:217], v[10:13]
	s_setprio 0
	s_setprio 1
	v_mfma_f32_16x16x32_bf16 v[54:57], v[168:171], v[186:189], 0
	v_mfma_f32_16x16x32_bf16 v[50:53], v[178:181], v[186:189], 0
	v_mfma_f32_16x16x32_bf16 v[38:41], v[168:171], v[194:197], 0
	v_mfma_f32_16x16x32_bf16 v[34:37], v[178:181], v[194:197], 0
	v_mfma_f32_16x16x32_bf16 v[22:25], v[168:171], v[202:205], 0
	v_mfma_f32_16x16x32_bf16 v[18:21], v[178:181], v[202:205], 0
	v_mfma_f32_16x16x32_bf16 v[6:9], v[168:171], v[210:213], 0
	v_mfma_f32_16x16x32_bf16 v[2:5], v[178:181], v[210:213], 0
	v_mfma_f32_16x16x32_bf16 v[54:57], v[172:175], v[190:193], v[54:57]
	v_mfma_f32_16x16x32_bf16 v[50:53], v[182:185], v[190:193], v[50:53]
	v_mfma_f32_16x16x32_bf16 v[38:41], v[172:175], v[198:201], v[38:41]
	v_mfma_f32_16x16x32_bf16 v[34:37], v[182:185], v[198:201], v[34:37]
	v_mfma_f32_16x16x32_bf16 v[22:25], v[172:175], v[206:209], v[22:25]
	v_mfma_f32_16x16x32_bf16 v[18:21], v[182:185], v[206:209], v[18:21]
	v_mfma_f32_16x16x32_bf16 v[6:9], v[172:175], v[214:217], v[6:9]
	v_mfma_f32_16x16x32_bf16 v[2:5], v[182:185], v[214:217], v[2:5]
	s_setprio 0
	s_barrier
	s_add_i32 s53, 0, 0x18000
	s_add_i32 s54, 0, 0x1c000
	v_add_u32_e32 v164, s53, v148
	v_add_u32_e32 v176, s54, v148
	ds_read_b128 v[152:155], v164
	ds_read_b128 v[156:159], v164 offset:1024
	ds_read_b128 v[160:163], v164 offset:2048
	ds_read_b128 v[164:167], v164 offset:3072
	ds_read_b128 v[168:171], v176
	ds_read_b128 v[172:175], v176 offset:1024
	ds_read_b128 v[178:181], v176 offset:2048
	ds_read_b128 v[182:185], v176 offset:3072
	s_add_u32 s2, s2, 0x40000
	s_addc_u32 s3, s3, 0
	s_mov_b32 m0, s36
	v_lshl_add_u64 v[224:225], s[2:3], 0, v[130:131]
	ds_read_b128 v[186:189], v151 offset:32768
	ds_read_b128 v[190:193], v151 offset:33792
	ds_read_b128 v[194:197], v151 offset:34816
	ds_read_b128 v[198:201], v151 offset:35840
	ds_read_b128 v[202:205], v151 offset:36864
	ds_read_b128 v[206:209], v151 offset:37888
	ds_read_b128 v[210:213], v151 offset:38912
	ds_read_b128 v[214:217], v151 offset:39936
	global_load_lds_dwordx4 v[224:225], off
	v_lshl_add_u64 v[224:225], s[2:3], 0, v[134:135]
	s_mov_b32 m0, s37
	s_nop 0
	global_load_lds_dwordx4 v[224:225], off
	s_waitcnt vmcnt(8)
	s_waitcnt lgkmcnt(0)
	s_setprio 1
	s_barrier
	s_waitcnt lgkmcnt(0)
	v_mfma_f32_16x16x32_bf16 v[126:129], v[152:155], v[186:189], v[126:129]
	v_mfma_f32_16x16x32_bf16 v[122:125], v[160:163], v[186:189], v[122:125]
	v_mfma_f32_16x16x32_bf16 v[110:113], v[152:155], v[194:197], v[110:113]
	v_mfma_f32_16x16x32_bf16 v[106:109], v[160:163], v[194:197], v[106:109]
	v_mfma_f32_16x16x32_bf16 v[94:97], v[152:155], v[202:205], v[94:97]
	v_mfma_f32_16x16x32_bf16 v[90:93], v[160:163], v[202:205], v[90:93]
	v_mfma_f32_16x16x32_bf16 v[78:81], v[152:155], v[210:213], v[78:81]
	v_mfma_f32_16x16x32_bf16 v[74:77], v[160:163], v[210:213], v[74:77]
	v_mfma_f32_16x16x32_bf16 v[126:129], v[156:159], v[190:193], v[126:129]
	v_mfma_f32_16x16x32_bf16 v[122:125], v[164:167], v[190:193], v[122:125]
	v_mfma_f32_16x16x32_bf16 v[110:113], v[156:159], v[198:201], v[110:113]
	v_mfma_f32_16x16x32_bf16 v[106:109], v[164:167], v[198:201], v[106:109]
	v_mfma_f32_16x16x32_bf16 v[94:97], v[156:159], v[206:209], v[94:97]
	v_mfma_f32_16x16x32_bf16 v[90:93], v[164:167], v[206:209], v[90:93]
	v_mfma_f32_16x16x32_bf16 v[78:81], v[156:159], v[214:217], v[78:81]
	v_mfma_f32_16x16x32_bf16 v[74:77], v[164:167], v[214:217], v[74:77]
	s_setprio 0
	s_setprio 1
	v_mfma_f32_16x16x32_bf16 v[118:121], v[168:171], v[186:189], v[118:121]
	v_mfma_f32_16x16x32_bf16 v[114:117], v[178:181], v[186:189], v[114:117]
	v_mfma_f32_16x16x32_bf16 v[102:105], v[168:171], v[194:197], v[102:105]
	v_mfma_f32_16x16x32_bf16 v[98:101], v[178:181], v[194:197], v[98:101]
	v_mfma_f32_16x16x32_bf16 v[86:89], v[168:171], v[202:205], v[86:89]
	v_mfma_f32_16x16x32_bf16 v[82:85], v[178:181], v[202:205], v[82:85]
	v_mfma_f32_16x16x32_bf16 v[70:73], v[168:171], v[210:213], v[70:73]
	v_mfma_f32_16x16x32_bf16 v[66:69], v[178:181], v[210:213], v[66:69]
	v_mfma_f32_16x16x32_bf16 v[118:121], v[172:175], v[190:193], v[118:121]
	v_mfma_f32_16x16x32_bf16 v[114:117], v[182:185], v[190:193], v[114:117]
	v_mfma_f32_16x16x32_bf16 v[102:105], v[172:175], v[198:201], v[102:105]
	v_mfma_f32_16x16x32_bf16 v[98:101], v[182:185], v[198:201], v[98:101]
	v_mfma_f32_16x16x32_bf16 v[86:89], v[172:175], v[206:209], v[86:89]
	v_mfma_f32_16x16x32_bf16 v[82:85], v[182:185], v[206:209], v[82:85]
	v_mfma_f32_16x16x32_bf16 v[70:73], v[172:175], v[214:217], v[70:73]
	v_mfma_f32_16x16x32_bf16 v[66:69], v[182:185], v[214:217], v[66:69]
	s_setprio 0
	s_barrier
	s_add_i32 s2, s53, s34
	v_lshl_add_u64 v[146:147], v[146:147], 0, s[6:7]
	s_mov_b32 m0, s2
	ds_read_b128 v[186:189], v151 offset:49152
	ds_read_b128 v[190:193], v151 offset:50176
	ds_read_b128 v[194:197], v151 offset:51200
	ds_read_b128 v[198:201], v151 offset:52224
	ds_read_b128 v[202:205], v151 offset:53248
	ds_read_b128 v[206:209], v151 offset:54272
	ds_read_b128 v[210:213], v151 offset:55296
	ds_read_b128 v[214:217], v151 offset:56320
	global_load_lds_dwordx4 v[146:147], off
	s_add_i32 m0, s2, 0x2000
	s_add_u32 s2, s30, 0x40080
	v_lshl_add_u64 v[146:147], v[218:219], 0, s[6:7]
	s_addc_u32 s3, s31, 0
	s_add_i32 s30, s54, s34
	global_load_lds_dwordx4 v[146:147], off
	v_lshl_add_u64 v[146:147], s[2:3], 0, v[132:133]
	s_mov_b32 m0, s30
	s_nop 0
	global_load_lds_dwordx4 v[146:147], off
	v_lshl_add_u64 v[146:147], s[2:3], 0, v[136:137]
	s_add_i32 m0, s30, 0x2000
	s_nop 0
	global_load_lds_dwordx4 v[146:147], off
	v_lshl_add_u64 v[146:147], v[220:221], 0, s[6:7]
	s_mov_b32 m0, s39
	s_nop 0
	global_load_lds_dwordx4 v[146:147], off
	v_lshl_add_u64 v[146:147], v[222:223], 0, s[6:7]
	s_mov_b32 m0, s40
	s_nop 0
	global_load_lds_dwordx4 v[146:147], off
	s_waitcnt vmcnt(8)
	s_waitcnt lgkmcnt(0)
	s_setprio 1
	s_barrier
	s_waitcnt lgkmcnt(0)
	v_mfma_f32_16x16x32_bf16 v[62:65], v[152:155], v[186:189], v[62:65]
	v_mfma_f32_16x16x32_bf16 v[58:61], v[160:163], v[186:189], v[58:61]
	v_mfma_f32_16x16x32_bf16 v[46:49], v[152:155], v[194:197], v[46:49]
	v_mfma_f32_16x16x32_bf16 v[42:45], v[160:163], v[194:197], v[42:45]
	v_mfma_f32_16x16x32_bf16 v[30:33], v[152:155], v[202:205], v[30:33]
	v_mfma_f32_16x16x32_bf16 v[26:29], v[160:163], v[202:205], v[26:29]
	v_mfma_f32_16x16x32_bf16 v[14:17], v[152:155], v[210:213], v[14:17]
	v_mfma_f32_16x16x32_bf16 v[10:13], v[160:163], v[210:213], v[10:13]
	v_mfma_f32_16x16x32_bf16 v[62:65], v[156:159], v[190:193], v[62:65]
	v_mfma_f32_16x16x32_bf16 v[58:61], v[164:167], v[190:193], v[58:61]
	v_mfma_f32_16x16x32_bf16 v[46:49], v[156:159], v[198:201], v[46:49]
	v_mfma_f32_16x16x32_bf16 v[42:45], v[164:167], v[198:201], v[42:45]
	v_mfma_f32_16x16x32_bf16 v[30:33], v[156:159], v[206:209], v[30:33]
	v_mfma_f32_16x16x32_bf16 v[26:29], v[164:167], v[206:209], v[26:29]
	v_mfma_f32_16x16x32_bf16 v[14:17], v[156:159], v[214:217], v[14:17]
	v_mfma_f32_16x16x32_bf16 v[10:13], v[164:167], v[214:217], v[10:13]
	s_setprio 0
	s_setprio 1
	v_mfma_f32_16x16x32_bf16 v[54:57], v[168:171], v[186:189], v[54:57]
	v_mfma_f32_16x16x32_bf16 v[50:53], v[178:181], v[186:189], v[50:53]
	v_mfma_f32_16x16x32_bf16 v[38:41], v[168:171], v[194:197], v[38:41]
	v_mfma_f32_16x16x32_bf16 v[34:37], v[178:181], v[194:197], v[34:37]
	v_mfma_f32_16x16x32_bf16 v[22:25], v[168:171], v[202:205], v[22:25]
	v_mfma_f32_16x16x32_bf16 v[18:21], v[178:181], v[202:205], v[18:21]
	v_mfma_f32_16x16x32_bf16 v[6:9], v[168:171], v[210:213], v[6:9]
	v_mfma_f32_16x16x32_bf16 v[2:5], v[178:181], v[210:213], v[2:5]
	v_mfma_f32_16x16x32_bf16 v[54:57], v[172:175], v[190:193], v[54:57]
	v_mfma_f32_16x16x32_bf16 v[50:53], v[182:185], v[190:193], v[50:53]
	v_mfma_f32_16x16x32_bf16 v[38:41], v[172:175], v[198:201], v[38:41]
	v_mfma_f32_16x16x32_bf16 v[34:37], v[182:185], v[198:201], v[34:37]
	v_mfma_f32_16x16x32_bf16 v[22:25], v[172:175], v[206:209], v[22:25]
	v_mfma_f32_16x16x32_bf16 v[18:21], v[182:185], v[206:209], v[18:21]
	v_mfma_f32_16x16x32_bf16 v[6:9], v[172:175], v[214:217], v[6:9]
	v_mfma_f32_16x16x32_bf16 v[2:5], v[182:185], v[214:217], v[2:5]
	s_setprio 0
	s_barrier
	s_add_i32 s52, s52, 2
	s_add_u32 s28, s28, 0x100
	s_addc_u32 s29, s29, 0
	s_add_u32 s46, s46, 0x100
	s_addc_u32 s47, s47, 0
	s_cmp_gt_u32 s52, 13
	s_cbranch_scc0 .LBB0_451
	s_branch .Lpk451_exit
.LBB0_451:
	ds_read_b128 v[152:155], v149
	ds_read_b128 v[156:159], v149 offset:1024
	ds_read_b128 v[160:163], v149 offset:2048
	ds_read_b128 v[164:167], v149 offset:3072
	ds_read_b128 v[168:171], v150
	ds_read_b128 v[172:175], v150 offset:1024
	ds_read_b128 v[178:181], v150 offset:2048
	ds_read_b128 v[182:185], v150 offset:3072
	s_add_u32 s2, s28, 0xfffc0080
	s_addc_u32 s3, s29, -1
	s_cmp_eq_u32 s52, 12
	s_cselect_b32 s3, s11, s3
	s_cselect_b32 s2, s13, s2
	s_cselect_b32 s31, s44, s47
	s_cselect_b32 s30, s45, s46
	v_lshl_add_u64 v[146:147], s[28:29], 0, v[140:141]
	s_add_i32 m0, s25, 0xc000
	ds_read_b128 v[186:189], v151
	ds_read_b128 v[190:193], v151 offset:1024
	ds_read_b128 v[194:197], v151 offset:2048
	ds_read_b128 v[198:201], v151 offset:3072
	ds_read_b128 v[202:205], v151 offset:4096
	ds_read_b128 v[206:209], v151 offset:5120
	ds_read_b128 v[210:213], v151 offset:6144
	ds_read_b128 v[214:217], v151 offset:7168
	global_load_lds_dwordx4 v[146:147], off
	v_lshl_add_u64 v[146:147], s[28:29], 0, v[142:143]
	s_add_i32 m0, s25, 0xe000
	s_nop 0
	global_load_lds_dwordx4 v[146:147], off
	s_waitcnt vmcnt(8)
	s_waitcnt lgkmcnt(0)
	s_setprio 1
	s_barrier
	s_waitcnt lgkmcnt(0)
	v_mfma_f32_16x16x32_bf16 v[126:129], v[152:155], v[186:189], v[126:129]
	v_mfma_f32_16x16x32_bf16 v[122:125], v[160:163], v[186:189], v[122:125]
	v_mfma_f32_16x16x32_bf16 v[110:113], v[152:155], v[194:197], v[110:113]
	v_mfma_f32_16x16x32_bf16 v[106:109], v[160:163], v[194:197], v[106:109]
	v_mfma_f32_16x16x32_bf16 v[94:97], v[152:155], v[202:205], v[94:97]
	v_mfma_f32_16x16x32_bf16 v[90:93], v[160:163], v[202:205], v[90:93]
	v_mfma_f32_16x16x32_bf16 v[78:81], v[152:155], v[210:213], v[78:81]
	v_mfma_f32_16x16x32_bf16 v[74:77], v[160:163], v[210:213], v[74:77]
	v_mfma_f32_16x16x32_bf16 v[126:129], v[156:159], v[190:193], v[126:129]
	v_mfma_f32_16x16x32_bf16 v[122:125], v[164:167], v[190:193], v[122:125]
	v_mfma_f32_16x16x32_bf16 v[110:113], v[156:159], v[198:201], v[110:113]
	v_mfma_f32_16x16x32_bf16 v[106:109], v[164:167], v[198:201], v[106:109]
	v_mfma_f32_16x16x32_bf16 v[94:97], v[156:159], v[206:209], v[94:97]
	v_mfma_f32_16x16x32_bf16 v[90:93], v[164:167], v[206:209], v[90:93]
	v_mfma_f32_16x16x32_bf16 v[78:81], v[156:159], v[214:217], v[78:81]
	v_mfma_f32_16x16x32_bf16 v[74:77], v[164:167], v[214:217], v[74:77]
	s_setprio 0
	s_setprio 1
	v_mfma_f32_16x16x32_bf16 v[118:121], v[168:171], v[186:189], v[118:121]
	v_mfma_f32_16x16x32_bf16 v[114:117], v[178:181], v[186:189], v[114:117]
	v_mfma_f32_16x16x32_bf16 v[102:105], v[168:171], v[194:197], v[102:105]
	v_mfma_f32_16x16x32_bf16 v[98:101], v[178:181], v[194:197], v[98:101]
	v_mfma_f32_16x16x32_bf16 v[86:89], v[168:171], v[202:205], v[86:89]
	v_mfma_f32_16x16x32_bf16 v[82:85], v[178:181], v[202:205], v[82:85]
	v_mfma_f32_16x16x32_bf16 v[70:73], v[168:171], v[210:213], v[70:73]
	v_mfma_f32_16x16x32_bf16 v[66:69], v[178:181], v[210:213], v[66:69]
	v_mfma_f32_16x16x32_bf16 v[118:121], v[172:175], v[190:193], v[118:121]
	v_mfma_f32_16x16x32_bf16 v[114:117], v[182:185], v[190:193], v[114:117]
	v_mfma_f32_16x16x32_bf16 v[102:105], v[172:175], v[198:201], v[102:105]
	v_mfma_f32_16x16x32_bf16 v[98:101], v[182:185], v[198:201], v[98:101]
	v_mfma_f32_16x16x32_bf16 v[86:89], v[172:175], v[206:209], v[86:89]
	v_mfma_f32_16x16x32_bf16 v[82:85], v[182:185], v[206:209], v[82:85]
	v_mfma_f32_16x16x32_bf16 v[70:73], v[172:175], v[214:217], v[70:73]
	v_mfma_f32_16x16x32_bf16 v[66:69], v[182:185], v[214:217], v[66:69]
	s_setprio 0
	s_barrier
	s_add_i32 s53, s42, s34
	v_lshl_add_u64 v[146:147], s[30:31], 0, v[132:133]
	s_mov_b32 m0, s53
	ds_read_b128 v[186:189], v151 offset:16384
	ds_read_b128 v[190:193], v151 offset:17408
	ds_read_b128 v[194:197], v151 offset:18432
	ds_read_b128 v[198:201], v151 offset:19456
	ds_read_b128 v[202:205], v151 offset:20480
	ds_read_b128 v[206:209], v151 offset:21504
	ds_read_b128 v[210:213], v151 offset:22528
	ds_read_b128 v[214:217], v151 offset:23552
	global_load_lds_dwordx4 v[146:147], off
	s_add_i32 m0, s53, 0x2000
	s_add_u32 s54, s30, 0x40000
	v_lshl_add_u64 v[218:219], s[30:31], 0, v[136:137]
	s_addc_u32 s55, s31, 0
	s_add_i32 s53, s43, s34
	global_load_lds_dwordx4 v[218:219], off
	v_lshl_add_u64 v[220:221], s[54:55], 0, v[132:133]
	s_mov_b32 m0, s53
	v_lshl_add_u64 v[222:223], s[2:3], 0, v[134:135]
	global_load_lds_dwordx4 v[220:221], off
	v_lshl_add_u64 v[220:221], s[54:55], 0, v[136:137]
	s_add_i32 m0, s53, 0x2000
	s_nop 0
	global_load_lds_dwordx4 v[220:221], off
	v_lshl_add_u64 v[220:221], s[2:3], 0, v[130:131]
	s_mov_b32 m0, s25
	s_nop 0
	global_load_lds_dwordx4 v[220:221], off
	s_mov_b32 m0, s27
	s_nop 0
	global_load_lds_dwordx4 v[222:223], off
	s_waitcnt vmcnt(8)
	s_waitcnt lgkmcnt(0)
	s_setprio 1
	s_barrier
	s_waitcnt lgkmcnt(0)
	v_mfma_f32_16x16x32_bf16 v[62:65], v[152:155], v[186:189], v[62:65]
	v_mfma_f32_16x16x32_bf16 v[58:61], v[160:163], v[186:189], v[58:61]
	v_mfma_f32_16x16x32_bf16 v[46:49], v[152:155], v[194:197], v[46:49]
	v_mfma_f32_16x16x32_bf16 v[42:45], v[160:163], v[194:197], v[42:45]
	v_mfma_f32_16x16x32_bf16 v[30:33], v[152:155], v[202:205], v[30:33]
	v_mfma_f32_16x16x32_bf16 v[26:29], v[160:163], v[202:205], v[26:29]
	v_mfma_f32_16x16x32_bf16 v[14:17], v[152:155], v[210:213], v[14:17]
	v_mfma_f32_16x16x32_bf16 v[10:13], v[160:163], v[210:213], v[10:13]
	v_mfma_f32_16x16x32_bf16 v[62:65], v[156:159], v[190:193], v[62:65]
	v_mfma_f32_16x16x32_bf16 v[58:61], v[164:167], v[190:193], v[58:61]
	v_mfma_f32_16x16x32_bf16 v[46:49], v[156:159], v[198:201], v[46:49]
	v_mfma_f32_16x16x32_bf16 v[42:45], v[164:167], v[198:201], v[42:45]
	v_mfma_f32_16x16x32_bf16 v[30:33], v[156:159], v[206:209], v[30:33]
	v_mfma_f32_16x16x32_bf16 v[26:29], v[164:167], v[206:209], v[26:29]
	v_mfma_f32_16x16x32_bf16 v[14:17], v[156:159], v[214:217], v[14:17]
	v_mfma_f32_16x16x32_bf16 v[10:13], v[164:167], v[214:217], v[10:13]
	s_setprio 0
	s_setprio 1
	v_mfma_f32_16x16x32_bf16 v[54:57], v[168:171], v[186:189], v[54:57]
	v_mfma_f32_16x16x32_bf16 v[50:53], v[178:181], v[186:189], v[50:53]
	v_mfma_f32_16x16x32_bf16 v[38:41], v[168:171], v[194:197], v[38:41]
	v_mfma_f32_16x16x32_bf16 v[34:37], v[178:181], v[194:197], v[34:37]
	v_mfma_f32_16x16x32_bf16 v[22:25], v[168:171], v[202:205], v[22:25]
	v_mfma_f32_16x16x32_bf16 v[18:21], v[178:181], v[202:205], v[18:21]
	v_mfma_f32_16x16x32_bf16 v[6:9], v[168:171], v[210:213], v[6:9]
	v_mfma_f32_16x16x32_bf16 v[2:5], v[178:181], v[210:213], v[2:5]
	v_mfma_f32_16x16x32_bf16 v[54:57], v[172:175], v[190:193], v[54:57]
	v_mfma_f32_16x16x32_bf16 v[50:53], v[182:185], v[190:193], v[50:53]
	v_mfma_f32_16x16x32_bf16 v[38:41], v[172:175], v[198:201], v[38:41]
	v_mfma_f32_16x16x32_bf16 v[34:37], v[182:185], v[198:201], v[34:37]
	v_mfma_f32_16x16x32_bf16 v[22:25], v[172:175], v[206:209], v[22:25]
	v_mfma_f32_16x16x32_bf16 v[18:21], v[182:185], v[206:209], v[18:21]
	v_mfma_f32_16x16x32_bf16 v[6:9], v[172:175], v[214:217], v[6:9]
	v_mfma_f32_16x16x32_bf16 v[2:5], v[182:185], v[214:217], v[2:5]
	s_setprio 0
	s_barrier
	s_add_i32 s53, 0, 0x18000
	s_add_i32 s54, 0, 0x1c000
	v_add_u32_e32 v164, s53, v148
	v_add_u32_e32 v176, s54, v148
	ds_read_b128 v[152:155], v164
	ds_read_b128 v[156:159], v164 offset:1024
	ds_read_b128 v[160:163], v164 offset:2048
	ds_read_b128 v[164:167], v164 offset:3072
	ds_read_b128 v[168:171], v176
	ds_read_b128 v[172:175], v176 offset:1024
	ds_read_b128 v[178:181], v176 offset:2048
	ds_read_b128 v[182:185], v176 offset:3072
	s_add_u32 s2, s2, 0x40000
	s_addc_u32 s3, s3, 0
	s_mov_b32 m0, s36
	v_lshl_add_u64 v[224:225], s[2:3], 0, v[130:131]
	ds_read_b128 v[186:189], v151 offset:32768
	ds_read_b128 v[190:193], v151 offset:33792
	ds_read_b128 v[194:197], v151 offset:34816
	ds_read_b128 v[198:201], v151 offset:35840
	ds_read_b128 v[202:205], v151 offset:36864
	ds_read_b128 v[206:209], v151 offset:37888
	ds_read_b128 v[210:213], v151 offset:38912
	ds_read_b128 v[214:217], v151 offset:39936
	global_load_lds_dwordx4 v[224:225], off
	v_lshl_add_u64 v[224:225], s[2:3], 0, v[134:135]
	s_mov_b32 m0, s37
	s_nop 0
	global_load_lds_dwordx4 v[224:225], off
	s_waitcnt vmcnt(8)
	s_waitcnt lgkmcnt(0)
	s_setprio 1
	s_barrier
	s_waitcnt lgkmcnt(0)
	v_mfma_f32_16x16x32_bf16 v[126:129], v[152:155], v[186:189], v[126:129]
	v_mfma_f32_16x16x32_bf16 v[122:125], v[160:163], v[186:189], v[122:125]
	v_mfma_f32_16x16x32_bf16 v[110:113], v[152:155], v[194:197], v[110:113]
	v_mfma_f32_16x16x32_bf16 v[106:109], v[160:163], v[194:197], v[106:109]
	v_mfma_f32_16x16x32_bf16 v[94:97], v[152:155], v[202:205], v[94:97]
	v_mfma_f32_16x16x32_bf16 v[90:93], v[160:163], v[202:205], v[90:93]
	v_mfma_f32_16x16x32_bf16 v[78:81], v[152:155], v[210:213], v[78:81]
	v_mfma_f32_16x16x32_bf16 v[74:77], v[160:163], v[210:213], v[74:77]
	v_mfma_f32_16x16x32_bf16 v[126:129], v[156:159], v[190:193], v[126:129]
	v_mfma_f32_16x16x32_bf16 v[122:125], v[164:167], v[190:193], v[122:125]
	v_mfma_f32_16x16x32_bf16 v[110:113], v[156:159], v[198:201], v[110:113]
	v_mfma_f32_16x16x32_bf16 v[106:109], v[164:167], v[198:201], v[106:109]
	v_mfma_f32_16x16x32_bf16 v[94:97], v[156:159], v[206:209], v[94:97]
	v_mfma_f32_16x16x32_bf16 v[90:93], v[164:167], v[206:209], v[90:93]
	v_mfma_f32_16x16x32_bf16 v[78:81], v[156:159], v[214:217], v[78:81]
	v_mfma_f32_16x16x32_bf16 v[74:77], v[164:167], v[214:217], v[74:77]
	s_setprio 0
	s_setprio 1
	v_mfma_f32_16x16x32_bf16 v[118:121], v[168:171], v[186:189], v[118:121]
	v_mfma_f32_16x16x32_bf16 v[114:117], v[178:181], v[186:189], v[114:117]
	v_mfma_f32_16x16x32_bf16 v[102:105], v[168:171], v[194:197], v[102:105]
	v_mfma_f32_16x16x32_bf16 v[98:101], v[178:181], v[194:197], v[98:101]
	v_mfma_f32_16x16x32_bf16 v[86:89], v[168:171], v[202:205], v[86:89]
	v_mfma_f32_16x16x32_bf16 v[82:85], v[178:181], v[202:205], v[82:85]
	v_mfma_f32_16x16x32_bf16 v[70:73], v[168:171], v[210:213], v[70:73]
	v_mfma_f32_16x16x32_bf16 v[66:69], v[178:181], v[210:213], v[66:69]
	v_mfma_f32_16x16x32_bf16 v[118:121], v[172:175], v[190:193], v[118:121]
	v_mfma_f32_16x16x32_bf16 v[114:117], v[182:185], v[190:193], v[114:117]
	v_mfma_f32_16x16x32_bf16 v[102:105], v[172:175], v[198:201], v[102:105]
	v_mfma_f32_16x16x32_bf16 v[98:101], v[182:185], v[198:201], v[98:101]
	v_mfma_f32_16x16x32_bf16 v[86:89], v[172:175], v[206:209], v[86:89]
	v_mfma_f32_16x16x32_bf16 v[82:85], v[182:185], v[206:209], v[82:85]
	v_mfma_f32_16x16x32_bf16 v[70:73], v[172:175], v[214:217], v[70:73]
	v_mfma_f32_16x16x32_bf16 v[66:69], v[182:185], v[214:217], v[66:69]
	s_setprio 0
	s_barrier
	s_add_i32 s2, s53, s34
	v_lshl_add_u64 v[146:147], v[146:147], 0, s[6:7]
	s_mov_b32 m0, s2
	ds_read_b128 v[186:189], v151 offset:49152
	ds_read_b128 v[190:193], v151 offset:50176
	ds_read_b128 v[194:197], v151 offset:51200
	ds_read_b128 v[198:201], v151 offset:52224
	ds_read_b128 v[202:205], v151 offset:53248
	ds_read_b128 v[206:209], v151 offset:54272
	ds_read_b128 v[210:213], v151 offset:55296
	ds_read_b128 v[214:217], v151 offset:56320
	global_load_lds_dwordx4 v[146:147], off
	s_add_i32 m0, s2, 0x2000
	s_add_u32 s2, s30, 0x40080
	v_lshl_add_u64 v[146:147], v[218:219], 0, s[6:7]
	s_addc_u32 s3, s31, 0
	s_add_i32 s30, s54, s34
	global_load_lds_dwordx4 v[146:147], off
	v_lshl_add_u64 v[146:147], s[2:3], 0, v[132:133]
	s_mov_b32 m0, s30
	s_nop 0
	global_load_lds_dwordx4 v[146:147], off
	v_lshl_add_u64 v[146:147], s[2:3], 0, v[136:137]
	s_add_i32 m0, s30, 0x2000
	s_nop 0
	global_load_lds_dwordx4 v[146:147], off
	v_lshl_add_u64 v[146:147], v[220:221], 0, s[6:7]
	s_mov_b32 m0, s39
	s_nop 0
	global_load_lds_dwordx4 v[146:147], off
	v_lshl_add_u64 v[146:147], v[222:223], 0, s[6:7]
	s_mov_b32 m0, s40
	s_nop 0
	global_load_lds_dwordx4 v[146:147], off
	s_waitcnt vmcnt(8)
	s_waitcnt lgkmcnt(0)
	s_setprio 1
	s_barrier
	s_waitcnt lgkmcnt(0)
	v_mfma_f32_16x16x32_bf16 v[62:65], v[152:155], v[186:189], v[62:65]
	v_mfma_f32_16x16x32_bf16 v[58:61], v[160:163], v[186:189], v[58:61]
	v_mfma_f32_16x16x32_bf16 v[46:49], v[152:155], v[194:197], v[46:49]
	v_mfma_f32_16x16x32_bf16 v[42:45], v[160:163], v[194:197], v[42:45]
	v_mfma_f32_16x16x32_bf16 v[30:33], v[152:155], v[202:205], v[30:33]
	v_mfma_f32_16x16x32_bf16 v[26:29], v[160:163], v[202:205], v[26:29]
	v_mfma_f32_16x16x32_bf16 v[14:17], v[152:155], v[210:213], v[14:17]
	v_mfma_f32_16x16x32_bf16 v[10:13], v[160:163], v[210:213], v[10:13]
	v_mfma_f32_16x16x32_bf16 v[62:65], v[156:159], v[190:193], v[62:65]
	v_mfma_f32_16x16x32_bf16 v[58:61], v[164:167], v[190:193], v[58:61]
	v_mfma_f32_16x16x32_bf16 v[46:49], v[156:159], v[198:201], v[46:49]
	v_mfma_f32_16x16x32_bf16 v[42:45], v[164:167], v[198:201], v[42:45]
	v_mfma_f32_16x16x32_bf16 v[30:33], v[156:159], v[206:209], v[30:33]
	v_mfma_f32_16x16x32_bf16 v[26:29], v[164:167], v[206:209], v[26:29]
	v_mfma_f32_16x16x32_bf16 v[14:17], v[156:159], v[214:217], v[14:17]
	v_mfma_f32_16x16x32_bf16 v[10:13], v[164:167], v[214:217], v[10:13]
	s_setprio 0
	s_setprio 1
	v_mfma_f32_16x16x32_bf16 v[54:57], v[168:171], v[186:189], v[54:57]
	v_mfma_f32_16x16x32_bf16 v[50:53], v[178:181], v[186:189], v[50:53]
	v_mfma_f32_16x16x32_bf16 v[38:41], v[168:171], v[194:197], v[38:41]
	v_mfma_f32_16x16x32_bf16 v[34:37], v[178:181], v[194:197], v[34:37]
	v_mfma_f32_16x16x32_bf16 v[22:25], v[168:171], v[202:205], v[22:25]
	v_mfma_f32_16x16x32_bf16 v[18:21], v[178:181], v[202:205], v[18:21]
	v_mfma_f32_16x16x32_bf16 v[6:9], v[168:171], v[210:213], v[6:9]
	v_mfma_f32_16x16x32_bf16 v[2:5], v[178:181], v[210:213], v[2:5]
	v_mfma_f32_16x16x32_bf16 v[54:57], v[172:175], v[190:193], v[54:57]
	v_mfma_f32_16x16x32_bf16 v[50:53], v[182:185], v[190:193], v[50:53]
	v_mfma_f32_16x16x32_bf16 v[38:41], v[172:175], v[198:201], v[38:41]
	v_mfma_f32_16x16x32_bf16 v[34:37], v[182:185], v[198:201], v[34:37]
	v_mfma_f32_16x16x32_bf16 v[22:25], v[172:175], v[206:209], v[22:25]
	v_mfma_f32_16x16x32_bf16 v[18:21], v[182:185], v[206:209], v[18:21]
	v_mfma_f32_16x16x32_bf16 v[6:9], v[172:175], v[214:217], v[6:9]
	v_mfma_f32_16x16x32_bf16 v[2:5], v[182:185], v[214:217], v[2:5]
	s_setprio 0
	s_barrier
	s_add_i32 s52, s52, 2
	s_add_u32 s28, s28, 0x100
	s_addc_u32 s29, s29, 0
	s_add_u32 s46, s46, 0x100
	s_addc_u32 s47, s47, 0
	s_cmp_gt_u32 s52, 13
	s_cbranch_scc0 .LBB0_451

.Lpk495_peel:
	ds_read_b128 v[152:155], v149
	ds_read_b128 v[156:159], v149 offset:1024
	ds_read_b128 v[160:163], v149 offset:2048
	ds_read_b128 v[164:167], v149 offset:3072
	ds_read_b128 v[168:171], v150
	ds_read_b128 v[172:175], v150 offset:1024
	ds_read_b128 v[178:181], v150 offset:2048
	ds_read_b128 v[182:185], v150 offset:3072
	s_add_u32 s2, s18, 0x4000
	s_addc_u32 s3, s19, 0
	s_cmp_eq_u32 s50, 40
	s_cselect_b32 s2, s45, s2
	s_cselect_b32 s3, s44, s3
	s_cselect_b32 s23, s46, s49
	s_cselect_b32 s22, s47, s48
	s_add_u32 s20, s2, 0x8000
	s_addc_u32 s21, s3, 0
	v_lshl_add_u64 v[144:145], s[18:19], 0, v[138:139]
	s_add_i32 m0, s29, 0xc000
	ds_read_b128 v[186:189], v151
	ds_read_b128 v[190:193], v151 offset:1024
	ds_read_b128 v[194:197], v151 offset:2048
	ds_read_b128 v[198:201], v151 offset:3072
	ds_read_b128 v[202:205], v151 offset:4096
	ds_read_b128 v[206:209], v151 offset:5120
	ds_read_b128 v[210:213], v151 offset:6144
	ds_read_b128 v[214:217], v151 offset:7168
	global_load_lds_dwordx4 v[144:145], off
	v_lshl_add_u64 v[144:145], s[18:19], 0, v[140:141]
	s_add_i32 m0, s29, 0xe000
	s_nop 0
	global_load_lds_dwordx4 v[144:145], off
	s_waitcnt vmcnt(8)
	s_waitcnt lgkmcnt(0)
	s_setprio 1
	s_barrier
	s_waitcnt lgkmcnt(0)
	v_mfma_f32_16x16x32_bf16 v[126:129], v[152:155], v[186:189], 0
	v_mfma_f32_16x16x32_bf16 v[122:125], v[160:163], v[186:189], 0
	v_mfma_f32_16x16x32_bf16 v[114:117], v[152:155], v[194:197], 0
	v_mfma_f32_16x16x32_bf16 v[106:109], v[160:163], v[194:197], 0
	v_mfma_f32_16x16x32_bf16 v[98:101], v[152:155], v[202:205], 0
	v_mfma_f32_16x16x32_bf16 v[90:93], v[160:163], v[202:205], 0
	v_mfma_f32_16x16x32_bf16 v[82:85], v[152:155], v[210:213], 0
	v_mfma_f32_16x16x32_bf16 v[74:77], v[160:163], v[210:213], 0
	v_mfma_f32_16x16x32_bf16 v[126:129], v[156:159], v[190:193], v[126:129]
	v_mfma_f32_16x16x32_bf16 v[122:125], v[164:167], v[190:193], v[122:125]
	v_mfma_f32_16x16x32_bf16 v[114:117], v[156:159], v[198:201], v[114:117]
	v_mfma_f32_16x16x32_bf16 v[106:109], v[164:167], v[198:201], v[106:109]
	v_mfma_f32_16x16x32_bf16 v[98:101], v[156:159], v[206:209], v[98:101]
	v_mfma_f32_16x16x32_bf16 v[90:93], v[164:167], v[206:209], v[90:93]
	v_mfma_f32_16x16x32_bf16 v[82:85], v[156:159], v[214:217], v[82:85]
	v_mfma_f32_16x16x32_bf16 v[74:77], v[164:167], v[214:217], v[74:77]
	s_setprio 0
	s_setprio 1
	v_mfma_f32_16x16x32_bf16 v[118:121], v[168:171], v[186:189], 0
	v_mfma_f32_16x16x32_bf16 v[110:113], v[178:181], v[186:189], 0
	v_mfma_f32_16x16x32_bf16 v[102:105], v[168:171], v[194:197], 0
	v_mfma_f32_16x16x32_bf16 v[94:97], v[178:181], v[194:197], 0
	v_mfma_f32_16x16x32_bf16 v[86:89], v[168:171], v[202:205], 0
	v_mfma_f32_16x16x32_bf16 v[78:81], v[178:181], v[202:205], 0
	v_mfma_f32_16x16x32_bf16 v[70:73], v[168:171], v[210:213], 0
	v_mfma_f32_16x16x32_bf16 v[66:69], v[178:181], v[210:213], 0
	v_mfma_f32_16x16x32_bf16 v[118:121], v[172:175], v[190:193], v[118:121]
	v_mfma_f32_16x16x32_bf16 v[110:113], v[182:185], v[190:193], v[110:113]
	v_mfma_f32_16x16x32_bf16 v[102:105], v[172:175], v[198:201], v[102:105]
	v_mfma_f32_16x16x32_bf16 v[94:97], v[182:185], v[198:201], v[94:97]
	v_mfma_f32_16x16x32_bf16 v[86:89], v[172:175], v[206:209], v[86:89]
	v_mfma_f32_16x16x32_bf16 v[78:81], v[182:185], v[206:209], v[78:81]
	v_mfma_f32_16x16x32_bf16 v[70:73], v[172:175], v[214:217], v[70:73]
	v_mfma_f32_16x16x32_bf16 v[66:69], v[182:185], v[214:217], v[66:69]
	s_setprio 0
	s_barrier
	s_add_i32 s51, s38, s28
	v_lshl_add_u64 v[144:145], s[22:23], 0, v[132:133]
	s_mov_b32 m0, s51
	ds_read_b128 v[186:189], v151 offset:16384
	ds_read_b128 v[190:193], v151 offset:17408
	ds_read_b128 v[194:197], v151 offset:18432
	ds_read_b128 v[198:201], v151 offset:19456
	ds_read_b128 v[202:205], v151 offset:20480
	ds_read_b128 v[206:209], v151 offset:21504
	ds_read_b128 v[210:213], v151 offset:22528
	ds_read_b128 v[214:217], v151 offset:23552
	global_load_lds_dwordx4 v[144:145], off
	s_add_i32 m0, s51, 0x2000
	s_add_u32 s52, s22, 0x4000
	v_lshl_add_u64 v[144:145], s[22:23], 0, v[136:137]
	s_addc_u32 s53, s23, 0
	s_add_i32 s51, s39, s28
	global_load_lds_dwordx4 v[144:145], off
	v_lshl_add_u64 v[144:145], s[52:53], 0, v[132:133]
	s_mov_b32 m0, s51
	s_nop 0
	global_load_lds_dwordx4 v[144:145], off
	v_lshl_add_u64 v[144:145], s[52:53], 0, v[136:137]
	s_add_i32 m0, s51, 0x2000
	s_nop 0
	global_load_lds_dwordx4 v[144:145], off
	v_lshl_add_u64 v[144:145], s[2:3], 0, v[130:131]
	s_mov_b32 m0, s29
	s_nop 0
	global_load_lds_dwordx4 v[144:145], off
	v_lshl_add_u64 v[144:145], s[2:3], 0, v[134:135]
	s_mov_b32 m0, s30
	s_nop 0
	global_load_lds_dwordx4 v[144:145], off
	s_waitcnt vmcnt(8)
	s_waitcnt lgkmcnt(0)
	s_setprio 1
	s_barrier
	s_waitcnt lgkmcnt(0)
	v_mfma_f32_16x16x32_bf16 v[62:65], v[152:155], v[186:189], 0
	v_mfma_f32_16x16x32_bf16 v[58:61], v[160:163], v[186:189], 0
	v_mfma_f32_16x16x32_bf16 v[50:53], v[152:155], v[194:197], 0
	v_mfma_f32_16x16x32_bf16 v[42:45], v[160:163], v[194:197], 0
	v_mfma_f32_16x16x32_bf16 v[34:37], v[152:155], v[202:205], 0
	v_mfma_f32_16x16x32_bf16 v[26:29], v[160:163], v[202:205], 0
	v_mfma_f32_16x16x32_bf16 v[18:21], v[152:155], v[210:213], 0
	v_mfma_f32_16x16x32_bf16 v[10:13], v[160:163], v[210:213], 0
	v_mfma_f32_16x16x32_bf16 v[62:65], v[156:159], v[190:193], v[62:65]
	v_mfma_f32_16x16x32_bf16 v[58:61], v[164:167], v[190:193], v[58:61]
	v_mfma_f32_16x16x32_bf16 v[50:53], v[156:159], v[198:201], v[50:53]
	v_mfma_f32_16x16x32_bf16 v[42:45], v[164:167], v[198:201], v[42:45]
	v_mfma_f32_16x16x32_bf16 v[34:37], v[156:159], v[206:209], v[34:37]
	v_mfma_f32_16x16x32_bf16 v[26:29], v[164:167], v[206:209], v[26:29]
	v_mfma_f32_16x16x32_bf16 v[18:21], v[156:159], v[214:217], v[18:21]
	v_mfma_f32_16x16x32_bf16 v[10:13], v[164:167], v[214:217], v[10:13]
	s_setprio 0
	s_setprio 1
	v_mfma_f32_16x16x32_bf16 v[54:57], v[168:171], v[186:189], 0
	v_mfma_f32_16x16x32_bf16 v[46:49], v[178:181], v[186:189], 0
	v_mfma_f32_16x16x32_bf16 v[38:41], v[168:171], v[194:197], 0
	v_mfma_f32_16x16x32_bf16 v[30:33], v[178:181], v[194:197], 0
	v_mfma_f32_16x16x32_bf16 v[22:25], v[168:171], v[202:205], 0
	v_mfma_f32_16x16x32_bf16 v[14:17], v[178:181], v[202:205], 0
	v_mfma_f32_16x16x32_bf16 v[6:9], v[168:171], v[210:213], 0
	v_mfma_f32_16x16x32_bf16 v[2:5], v[178:181], v[210:213], 0
	v_mfma_f32_16x16x32_bf16 v[54:57], v[172:175], v[190:193], v[54:57]
	v_mfma_f32_16x16x32_bf16 v[46:49], v[182:185], v[190:193], v[46:49]
	v_mfma_f32_16x16x32_bf16 v[38:41], v[172:175], v[198:201], v[38:41]
	v_mfma_f32_16x16x32_bf16 v[30:33], v[182:185], v[198:201], v[30:33]
	v_mfma_f32_16x16x32_bf16 v[22:25], v[172:175], v[206:209], v[22:25]
	v_mfma_f32_16x16x32_bf16 v[14:17], v[182:185], v[206:209], v[14:17]
	v_mfma_f32_16x16x32_bf16 v[6:9], v[172:175], v[214:217], v[6:9]
	v_mfma_f32_16x16x32_bf16 v[2:5], v[182:185], v[214:217], v[2:5]
	s_setprio 0
	s_barrier
	s_add_i32 s51, 0, 0x18000
	v_add_u32_e32 v144, s51, v147
	s_add_i32 s52, 0, 0x1c000
	ds_read_b128 v[152:155], v144
	ds_read_b128 v[156:159], v144 offset:1024
	ds_read_b128 v[160:163], v144 offset:2048
	ds_read_b128 v[164:167], v144 offset:3072
	v_add_u32_e32 v144, s52, v147
	ds_read_b128 v[168:171], v144
	ds_read_b128 v[172:175], v144 offset:1024
	ds_read_b128 v[178:181], v144 offset:2048
	ds_read_b128 v[182:185], v144 offset:3072
	s_add_u32 s2, s2, 0x4000
	s_addc_u32 s3, s3, 0
	s_mov_b32 m0, s31
	v_lshl_add_u64 v[144:145], s[2:3], 0, v[130:131]
	ds_read_b128 v[186:189], v151 offset:32768
	ds_read_b128 v[190:193], v151 offset:33792
	ds_read_b128 v[194:197], v151 offset:34816
	ds_read_b128 v[198:201], v151 offset:35840
	ds_read_b128 v[202:205], v151 offset:36864
	ds_read_b128 v[206:209], v151 offset:37888
	ds_read_b128 v[210:213], v151 offset:38912
	ds_read_b128 v[214:217], v151 offset:39936
	global_load_lds_dwordx4 v[144:145], off
	v_lshl_add_u64 v[144:145], s[2:3], 0, v[134:135]
	s_mov_b32 m0, s34
	s_nop 0
	global_load_lds_dwordx4 v[144:145], off
	s_waitcnt vmcnt(8)
	s_waitcnt lgkmcnt(0)
	s_setprio 1
	s_barrier
	s_waitcnt lgkmcnt(0)
	v_mfma_f32_16x16x32_bf16 v[126:129], v[152:155], v[186:189], v[126:129]
	v_mfma_f32_16x16x32_bf16 v[122:125], v[160:163], v[186:189], v[122:125]
	v_mfma_f32_16x16x32_bf16 v[114:117], v[152:155], v[194:197], v[114:117]
	v_mfma_f32_16x16x32_bf16 v[106:109], v[160:163], v[194:197], v[106:109]
	v_mfma_f32_16x16x32_bf16 v[98:101], v[152:155], v[202:205], v[98:101]
	v_mfma_f32_16x16x32_bf16 v[90:93], v[160:163], v[202:205], v[90:93]
	v_mfma_f32_16x16x32_bf16 v[82:85], v[152:155], v[210:213], v[82:85]
	v_mfma_f32_16x16x32_bf16 v[74:77], v[160:163], v[210:213], v[74:77]
	v_mfma_f32_16x16x32_bf16 v[126:129], v[156:159], v[190:193], v[126:129]
	v_mfma_f32_16x16x32_bf16 v[122:125], v[164:167], v[190:193], v[122:125]
	v_mfma_f32_16x16x32_bf16 v[114:117], v[156:159], v[198:201], v[114:117]
	v_mfma_f32_16x16x32_bf16 v[106:109], v[164:167], v[198:201], v[106:109]
	v_mfma_f32_16x16x32_bf16 v[98:101], v[156:159], v[206:209], v[98:101]
	v_mfma_f32_16x16x32_bf16 v[90:93], v[164:167], v[206:209], v[90:93]
	v_mfma_f32_16x16x32_bf16 v[82:85], v[156:159], v[214:217], v[82:85]
	v_mfma_f32_16x16x32_bf16 v[74:77], v[164:167], v[214:217], v[74:77]
	s_setprio 0
	s_setprio 1
	v_mfma_f32_16x16x32_bf16 v[118:121], v[168:171], v[186:189], v[118:121]
	v_mfma_f32_16x16x32_bf16 v[110:113], v[178:181], v[186:189], v[110:113]
	v_mfma_f32_16x16x32_bf16 v[102:105], v[168:171], v[194:197], v[102:105]
	v_mfma_f32_16x16x32_bf16 v[94:97], v[178:181], v[194:197], v[94:97]
	v_mfma_f32_16x16x32_bf16 v[86:89], v[168:171], v[202:205], v[86:89]
	v_mfma_f32_16x16x32_bf16 v[78:81], v[178:181], v[202:205], v[78:81]
	v_mfma_f32_16x16x32_bf16 v[70:73], v[168:171], v[210:213], v[70:73]
	v_mfma_f32_16x16x32_bf16 v[66:69], v[178:181], v[210:213], v[66:69]
	v_mfma_f32_16x16x32_bf16 v[118:121], v[172:175], v[190:193], v[118:121]
	v_mfma_f32_16x16x32_bf16 v[110:113], v[182:185], v[190:193], v[110:113]
	v_mfma_f32_16x16x32_bf16 v[102:105], v[172:175], v[198:201], v[102:105]
	v_mfma_f32_16x16x32_bf16 v[94:97], v[182:185], v[198:201], v[94:97]
	v_mfma_f32_16x16x32_bf16 v[86:89], v[172:175], v[206:209], v[86:89]
	v_mfma_f32_16x16x32_bf16 v[78:81], v[182:185], v[206:209], v[78:81]
	v_mfma_f32_16x16x32_bf16 v[70:73], v[172:175], v[214:217], v[70:73]
	v_mfma_f32_16x16x32_bf16 v[66:69], v[182:185], v[214:217], v[66:69]
	s_setprio 0
	s_barrier
	s_add_u32 s2, s22, 0x8000
	s_addc_u32 s3, s23, 0
	s_add_i32 s51, s51, s28
	v_lshl_add_u64 v[144:145], s[2:3], 0, v[132:133]
	s_mov_b32 m0, s51
	ds_read_b128 v[186:189], v151 offset:49152
	ds_read_b128 v[190:193], v151 offset:50176
	ds_read_b128 v[194:197], v151 offset:51200
	ds_read_b128 v[198:201], v151 offset:52224
	ds_read_b128 v[202:205], v151 offset:53248
	ds_read_b128 v[206:209], v151 offset:54272
	ds_read_b128 v[210:213], v151 offset:55296
	ds_read_b128 v[214:217], v151 offset:56320
	global_load_lds_dwordx4 v[144:145], off
	s_add_i32 m0, s51, 0x2000
	v_lshl_add_u64 v[144:145], s[2:3], 0, v[136:137]
	s_add_u32 s2, s22, 0xc000
	s_addc_u32 s3, s23, 0
	s_add_i32 s22, s52, s28
	global_load_lds_dwordx4 v[144:145], off
	v_lshl_add_u64 v[144:145], s[2:3], 0, v[132:133]
	s_mov_b32 m0, s22
	s_nop 0
	global_load_lds_dwordx4 v[144:145], off
	v_lshl_add_u64 v[144:145], s[2:3], 0, v[136:137]
	s_add_i32 m0, s22, 0x2000
	s_nop 0
	global_load_lds_dwordx4 v[144:145], off
	v_lshl_add_u64 v[144:145], s[20:21], 0, v[130:131]
	s_mov_b32 m0, s36
	s_nop 0
	global_load_lds_dwordx4 v[144:145], off
	v_lshl_add_u64 v[144:145], s[20:21], 0, v[134:135]
	s_mov_b32 m0, s37
	s_nop 0
	global_load_lds_dwordx4 v[144:145], off
	s_waitcnt vmcnt(8)
	s_waitcnt lgkmcnt(0)
	s_setprio 1
	s_barrier
	s_waitcnt lgkmcnt(0)
	v_mfma_f32_16x16x32_bf16 v[62:65], v[152:155], v[186:189], v[62:65]
	v_mfma_f32_16x16x32_bf16 v[58:61], v[160:163], v[186:189], v[58:61]
	v_mfma_f32_16x16x32_bf16 v[50:53], v[152:155], v[194:197], v[50:53]
	v_mfma_f32_16x16x32_bf16 v[42:45], v[160:163], v[194:197], v[42:45]
	v_mfma_f32_16x16x32_bf16 v[34:37], v[152:155], v[202:205], v[34:37]
	v_mfma_f32_16x16x32_bf16 v[26:29], v[160:163], v[202:205], v[26:29]
	v_mfma_f32_16x16x32_bf16 v[18:21], v[152:155], v[210:213], v[18:21]
	v_mfma_f32_16x16x32_bf16 v[10:13], v[160:163], v[210:213], v[10:13]
	v_mfma_f32_16x16x32_bf16 v[62:65], v[156:159], v[190:193], v[62:65]
	v_mfma_f32_16x16x32_bf16 v[58:61], v[164:167], v[190:193], v[58:61]
	v_mfma_f32_16x16x32_bf16 v[50:53], v[156:159], v[198:201], v[50:53]
	v_mfma_f32_16x16x32_bf16 v[42:45], v[164:167], v[198:201], v[42:45]
	v_mfma_f32_16x16x32_bf16 v[34:37], v[156:159], v[206:209], v[34:37]
	v_mfma_f32_16x16x32_bf16 v[26:29], v[164:167], v[206:209], v[26:29]
	v_mfma_f32_16x16x32_bf16 v[18:21], v[156:159], v[214:217], v[18:21]
	v_mfma_f32_16x16x32_bf16 v[10:13], v[164:167], v[214:217], v[10:13]
	s_setprio 0
	s_setprio 1
	v_mfma_f32_16x16x32_bf16 v[54:57], v[168:171], v[186:189], v[54:57]
	v_mfma_f32_16x16x32_bf16 v[46:49], v[178:181], v[186:189], v[46:49]
	v_mfma_f32_16x16x32_bf16 v[38:41], v[168:171], v[194:197], v[38:41]
	v_mfma_f32_16x16x32_bf16 v[30:33], v[178:181], v[194:197], v[30:33]
	v_mfma_f32_16x16x32_bf16 v[22:25], v[168:171], v[202:205], v[22:25]
	v_mfma_f32_16x16x32_bf16 v[14:17], v[178:181], v[202:205], v[14:17]
	v_mfma_f32_16x16x32_bf16 v[6:9], v[168:171], v[210:213], v[6:9]
	v_mfma_f32_16x16x32_bf16 v[2:5], v[178:181], v[210:213], v[2:5]
	v_mfma_f32_16x16x32_bf16 v[54:57], v[172:175], v[190:193], v[54:57]
	v_mfma_f32_16x16x32_bf16 v[46:49], v[182:185], v[190:193], v[46:49]
	v_mfma_f32_16x16x32_bf16 v[38:41], v[172:175], v[198:201], v[38:41]
	v_mfma_f32_16x16x32_bf16 v[30:33], v[182:185], v[198:201], v[30:33]
	v_mfma_f32_16x16x32_bf16 v[22:25], v[172:175], v[206:209], v[22:25]
	v_mfma_f32_16x16x32_bf16 v[14:17], v[182:185], v[206:209], v[14:17]
	v_mfma_f32_16x16x32_bf16 v[6:9], v[172:175], v[214:217], v[6:9]
	v_mfma_f32_16x16x32_bf16 v[2:5], v[182:185], v[214:217], v[2:5]
	s_setprio 0
	s_barrier
	s_add_i32 s50, s50, 2
	s_add_u32 s18, s18, 0x10000
	s_addc_u32 s19, s19, 0
	s_add_u32 s48, s48, 0x10000
	s_addc_u32 s49, s49, 0
	s_cmp_gt_u32 s50, 41
	s_cbranch_scc0 .LBB0_495
	s_branch .Lpk495_exit
.LBB0_495:
	ds_read_b128 v[152:155], v149
	ds_read_b128 v[156:159], v149 offset:1024
	ds_read_b128 v[160:163], v149 offset:2048
	ds_read_b128 v[164:167], v149 offset:3072
	ds_read_b128 v[168:171], v150
	ds_read_b128 v[172:175], v150 offset:1024
	ds_read_b128 v[178:181], v150 offset:2048
	ds_read_b128 v[182:185], v150 offset:3072
	s_add_u32 s2, s18, 0x4000
	s_addc_u32 s3, s19, 0
	s_cmp_eq_u32 s50, 40
	s_cselect_b32 s2, s45, s2
	s_cselect_b32 s3, s44, s3
	s_cselect_b32 s23, s46, s49
	s_cselect_b32 s22, s47, s48
	s_add_u32 s20, s2, 0x8000
	s_addc_u32 s21, s3, 0
	v_lshl_add_u64 v[144:145], s[18:19], 0, v[138:139]
	s_add_i32 m0, s29, 0xc000
	ds_read_b128 v[186:189], v151
	ds_read_b128 v[190:193], v151 offset:1024
	ds_read_b128 v[194:197], v151 offset:2048
	ds_read_b128 v[198:201], v151 offset:3072
	ds_read_b128 v[202:205], v151 offset:4096
	ds_read_b128 v[206:209], v151 offset:5120
	ds_read_b128 v[210:213], v151 offset:6144
	ds_read_b128 v[214:217], v151 offset:7168
	global_load_lds_dwordx4 v[144:145], off
	v_lshl_add_u64 v[144:145], s[18:19], 0, v[140:141]
	s_add_i32 m0, s29, 0xe000
	s_nop 0
	global_load_lds_dwordx4 v[144:145], off
	s_waitcnt vmcnt(8)
	s_waitcnt lgkmcnt(0)
	s_setprio 1
	s_barrier
	s_waitcnt lgkmcnt(0)
	v_mfma_f32_16x16x32_bf16 v[126:129], v[152:155], v[186:189], v[126:129]
	v_mfma_f32_16x16x32_bf16 v[122:125], v[160:163], v[186:189], v[122:125]
	v_mfma_f32_16x16x32_bf16 v[114:117], v[152:155], v[194:197], v[114:117]
	v_mfma_f32_16x16x32_bf16 v[106:109], v[160:163], v[194:197], v[106:109]
	v_mfma_f32_16x16x32_bf16 v[98:101], v[152:155], v[202:205], v[98:101]
	v_mfma_f32_16x16x32_bf16 v[90:93], v[160:163], v[202:205], v[90:93]
	v_mfma_f32_16x16x32_bf16 v[82:85], v[152:155], v[210:213], v[82:85]
	v_mfma_f32_16x16x32_bf16 v[74:77], v[160:163], v[210:213], v[74:77]
	v_mfma_f32_16x16x32_bf16 v[126:129], v[156:159], v[190:193], v[126:129]
	v_mfma_f32_16x16x32_bf16 v[122:125], v[164:167], v[190:193], v[122:125]
	v_mfma_f32_16x16x32_bf16 v[114:117], v[156:159], v[198:201], v[114:117]
	v_mfma_f32_16x16x32_bf16 v[106:109], v[164:167], v[198:201], v[106:109]
	v_mfma_f32_16x16x32_bf16 v[98:101], v[156:159], v[206:209], v[98:101]
	v_mfma_f32_16x16x32_bf16 v[90:93], v[164:167], v[206:209], v[90:93]
	v_mfma_f32_16x16x32_bf16 v[82:85], v[156:159], v[214:217], v[82:85]
	v_mfma_f32_16x16x32_bf16 v[74:77], v[164:167], v[214:217], v[74:77]
	s_setprio 0
	s_setprio 1
	v_mfma_f32_16x16x32_bf16 v[118:121], v[168:171], v[186:189], v[118:121]
	v_mfma_f32_16x16x32_bf16 v[110:113], v[178:181], v[186:189], v[110:113]
	v_mfma_f32_16x16x32_bf16 v[102:105], v[168:171], v[194:197], v[102:105]
	v_mfma_f32_16x16x32_bf16 v[94:97], v[178:181], v[194:197], v[94:97]
	v_mfma_f32_16x16x32_bf16 v[86:89], v[168:171], v[202:205], v[86:89]
	v_mfma_f32_16x16x32_bf16 v[78:81], v[178:181], v[202:205], v[78:81]
	v_mfma_f32_16x16x32_bf16 v[70:73], v[168:171], v[210:213], v[70:73]
	v_mfma_f32_16x16x32_bf16 v[66:69], v[178:181], v[210:213], v[66:69]
	v_mfma_f32_16x16x32_bf16 v[118:121], v[172:175], v[190:193], v[118:121]
	v_mfma_f32_16x16x32_bf16 v[110:113], v[182:185], v[190:193], v[110:113]
	v_mfma_f32_16x16x32_bf16 v[102:105], v[172:175], v[198:201], v[102:105]
	v_mfma_f32_16x16x32_bf16 v[94:97], v[182:185], v[198:201], v[94:97]
	v_mfma_f32_16x16x32_bf16 v[86:89], v[172:175], v[206:209], v[86:89]
	v_mfma_f32_16x16x32_bf16 v[78:81], v[182:185], v[206:209], v[78:81]
	v_mfma_f32_16x16x32_bf16 v[70:73], v[172:175], v[214:217], v[70:73]
	v_mfma_f32_16x16x32_bf16 v[66:69], v[182:185], v[214:217], v[66:69]
	s_setprio 0
	s_barrier
	s_add_i32 s51, s38, s28
	v_lshl_add_u64 v[144:145], s[22:23], 0, v[132:133]
	s_mov_b32 m0, s51
	ds_read_b128 v[186:189], v151 offset:16384
	ds_read_b128 v[190:193], v151 offset:17408
	ds_read_b128 v[194:197], v151 offset:18432
	ds_read_b128 v[198:201], v151 offset:19456
	ds_read_b128 v[202:205], v151 offset:20480
	ds_read_b128 v[206:209], v151 offset:21504
	ds_read_b128 v[210:213], v151 offset:22528
	ds_read_b128 v[214:217], v151 offset:23552
	global_load_lds_dwordx4 v[144:145], off
	s_add_i32 m0, s51, 0x2000
	s_add_u32 s52, s22, 0x4000
	v_lshl_add_u64 v[144:145], s[22:23], 0, v[136:137]
	s_addc_u32 s53, s23, 0
	s_add_i32 s51, s39, s28
	global_load_lds_dwordx4 v[144:145], off
	v_lshl_add_u64 v[144:145], s[52:53], 0, v[132:133]
	s_mov_b32 m0, s51
	s_nop 0
	global_load_lds_dwordx4 v[144:145], off
	v_lshl_add_u64 v[144:145], s[52:53], 0, v[136:137]
	s_add_i32 m0, s51, 0x2000
	s_nop 0
	global_load_lds_dwordx4 v[144:145], off
	v_lshl_add_u64 v[144:145], s[2:3], 0, v[130:131]
	s_mov_b32 m0, s29
	s_nop 0
	global_load_lds_dwordx4 v[144:145], off
	v_lshl_add_u64 v[144:145], s[2:3], 0, v[134:135]
	s_mov_b32 m0, s30
	s_nop 0
	global_load_lds_dwordx4 v[144:145], off
	s_waitcnt vmcnt(8)
	s_waitcnt lgkmcnt(0)
	s_setprio 1
	s_barrier
	s_waitcnt lgkmcnt(0)
	v_mfma_f32_16x16x32_bf16 v[62:65], v[152:155], v[186:189], v[62:65]
	v_mfma_f32_16x16x32_bf16 v[58:61], v[160:163], v[186:189], v[58:61]
	v_mfma_f32_16x16x32_bf16 v[50:53], v[152:155], v[194:197], v[50:53]
	v_mfma_f32_16x16x32_bf16 v[42:45], v[160:163], v[194:197], v[42:45]
	v_mfma_f32_16x16x32_bf16 v[34:37], v[152:155], v[202:205], v[34:37]
	v_mfma_f32_16x16x32_bf16 v[26:29], v[160:163], v[202:205], v[26:29]
	v_mfma_f32_16x16x32_bf16 v[18:21], v[152:155], v[210:213], v[18:21]
	v_mfma_f32_16x16x32_bf16 v[10:13], v[160:163], v[210:213], v[10:13]
	v_mfma_f32_16x16x32_bf16 v[62:65], v[156:159], v[190:193], v[62:65]
	v_mfma_f32_16x16x32_bf16 v[58:61], v[164:167], v[190:193], v[58:61]
	v_mfma_f32_16x16x32_bf16 v[50:53], v[156:159], v[198:201], v[50:53]
	v_mfma_f32_16x16x32_bf16 v[42:45], v[164:167], v[198:201], v[42:45]
	v_mfma_f32_16x16x32_bf16 v[34:37], v[156:159], v[206:209], v[34:37]
	v_mfma_f32_16x16x32_bf16 v[26:29], v[164:167], v[206:209], v[26:29]
	v_mfma_f32_16x16x32_bf16 v[18:21], v[156:159], v[214:217], v[18:21]
	v_mfma_f32_16x16x32_bf16 v[10:13], v[164:167], v[214:217], v[10:13]
	s_setprio 0
	s_setprio 1
	v_mfma_f32_16x16x32_bf16 v[54:57], v[168:171], v[186:189], v[54:57]
	v_mfma_f32_16x16x32_bf16 v[46:49], v[178:181], v[186:189], v[46:49]
	v_mfma_f32_16x16x32_bf16 v[38:41], v[168:171], v[194:197], v[38:41]
	v_mfma_f32_16x16x32_bf16 v[30:33], v[178:181], v[194:197], v[30:33]
	v_mfma_f32_16x16x32_bf16 v[22:25], v[168:171], v[202:205], v[22:25]
	v_mfma_f32_16x16x32_bf16 v[14:17], v[178:181], v[202:205], v[14:17]
	v_mfma_f32_16x16x32_bf16 v[6:9], v[168:171], v[210:213], v[6:9]
	v_mfma_f32_16x16x32_bf16 v[2:5], v[178:181], v[210:213], v[2:5]
	v_mfma_f32_16x16x32_bf16 v[54:57], v[172:175], v[190:193], v[54:57]
	v_mfma_f32_16x16x32_bf16 v[46:49], v[182:185], v[190:193], v[46:49]
	v_mfma_f32_16x16x32_bf16 v[38:41], v[172:175], v[198:201], v[38:41]
	v_mfma_f32_16x16x32_bf16 v[30:33], v[182:185], v[198:201], v[30:33]
	v_mfma_f32_16x16x32_bf16 v[22:25], v[172:175], v[206:209], v[22:25]
	v_mfma_f32_16x16x32_bf16 v[14:17], v[182:185], v[206:209], v[14:17]
	v_mfma_f32_16x16x32_bf16 v[6:9], v[172:175], v[214:217], v[6:9]
	v_mfma_f32_16x16x32_bf16 v[2:5], v[182:185], v[214:217], v[2:5]
	s_setprio 0
	s_barrier
	s_add_i32 s51, 0, 0x18000
	v_add_u32_e32 v144, s51, v147
	s_add_i32 s52, 0, 0x1c000
	ds_read_b128 v[152:155], v144
	ds_read_b128 v[156:159], v144 offset:1024
	ds_read_b128 v[160:163], v144 offset:2048
	ds_read_b128 v[164:167], v144 offset:3072
	v_add_u32_e32 v144, s52, v147
	ds_read_b128 v[168:171], v144
	ds_read_b128 v[172:175], v144 offset:1024
	ds_read_b128 v[178:181], v144 offset:2048
	ds_read_b128 v[182:185], v144 offset:3072
	s_add_u32 s2, s2, 0x4000
	s_addc_u32 s3, s3, 0
	s_mov_b32 m0, s31
	v_lshl_add_u64 v[144:145], s[2:3], 0, v[130:131]
	ds_read_b128 v[186:189], v151 offset:32768
	ds_read_b128 v[190:193], v151 offset:33792
	ds_read_b128 v[194:197], v151 offset:34816
	ds_read_b128 v[198:201], v151 offset:35840
	ds_read_b128 v[202:205], v151 offset:36864
	ds_read_b128 v[206:209], v151 offset:37888
	ds_read_b128 v[210:213], v151 offset:38912
	ds_read_b128 v[214:217], v151 offset:39936
	global_load_lds_dwordx4 v[144:145], off
	v_lshl_add_u64 v[144:145], s[2:3], 0, v[134:135]
	s_mov_b32 m0, s34
	s_nop 0
	global_load_lds_dwordx4 v[144:145], off
	s_waitcnt vmcnt(8)
	s_waitcnt lgkmcnt(0)
	s_setprio 1
	s_barrier
	s_waitcnt lgkmcnt(0)
	v_mfma_f32_16x16x32_bf16 v[126:129], v[152:155], v[186:189], v[126:129]
	v_mfma_f32_16x16x32_bf16 v[122:125], v[160:163], v[186:189], v[122:125]
	v_mfma_f32_16x16x32_bf16 v[114:117], v[152:155], v[194:197], v[114:117]
	v_mfma_f32_16x16x32_bf16 v[106:109], v[160:163], v[194:197], v[106:109]
	v_mfma_f32_16x16x32_bf16 v[98:101], v[152:155], v[202:205], v[98:101]
	v_mfma_f32_16x16x32_bf16 v[90:93], v[160:163], v[202:205], v[90:93]
	v_mfma_f32_16x16x32_bf16 v[82:85], v[152:155], v[210:213], v[82:85]
	v_mfma_f32_16x16x32_bf16 v[74:77], v[160:163], v[210:213], v[74:77]
	v_mfma_f32_16x16x32_bf16 v[126:129], v[156:159], v[190:193], v[126:129]
	v_mfma_f32_16x16x32_bf16 v[122:125], v[164:167], v[190:193], v[122:125]
	v_mfma_f32_16x16x32_bf16 v[114:117], v[156:159], v[198:201], v[114:117]
	v_mfma_f32_16x16x32_bf16 v[106:109], v[164:167], v[198:201], v[106:109]
	v_mfma_f32_16x16x32_bf16 v[98:101], v[156:159], v[206:209], v[98:101]
	v_mfma_f32_16x16x32_bf16 v[90:93], v[164:167], v[206:209], v[90:93]
	v_mfma_f32_16x16x32_bf16 v[82:85], v[156:159], v[214:217], v[82:85]
	v_mfma_f32_16x16x32_bf16 v[74:77], v[164:167], v[214:217], v[74:77]
	s_setprio 0
	s_setprio 1
	v_mfma_f32_16x16x32_bf16 v[118:121], v[168:171], v[186:189], v[118:121]
	v_mfma_f32_16x16x32_bf16 v[110:113], v[178:181], v[186:189], v[110:113]
	v_mfma_f32_16x16x32_bf16 v[102:105], v[168:171], v[194:197], v[102:105]
	v_mfma_f32_16x16x32_bf16 v[94:97], v[178:181], v[194:197], v[94:97]
	v_mfma_f32_16x16x32_bf16 v[86:89], v[168:171], v[202:205], v[86:89]
	v_mfma_f32_16x16x32_bf16 v[78:81], v[178:181], v[202:205], v[78:81]
	v_mfma_f32_16x16x32_bf16 v[70:73], v[168:171], v[210:213], v[70:73]
	v_mfma_f32_16x16x32_bf16 v[66:69], v[178:181], v[210:213], v[66:69]
	v_mfma_f32_16x16x32_bf16 v[118:121], v[172:175], v[190:193], v[118:121]
	v_mfma_f32_16x16x32_bf16 v[110:113], v[182:185], v[190:193], v[110:113]
	v_mfma_f32_16x16x32_bf16 v[102:105], v[172:175], v[198:201], v[102:105]
	v_mfma_f32_16x16x32_bf16 v[94:97], v[182:185], v[198:201], v[94:97]
	v_mfma_f32_16x16x32_bf16 v[86:89], v[172:175], v[206:209], v[86:89]
	v_mfma_f32_16x16x32_bf16 v[78:81], v[182:185], v[206:209], v[78:81]
	v_mfma_f32_16x16x32_bf16 v[70:73], v[172:175], v[214:217], v[70:73]
	v_mfma_f32_16x16x32_bf16 v[66:69], v[182:185], v[214:217], v[66:69]
	s_setprio 0
	s_barrier
	s_add_u32 s2, s22, 0x8000
	s_addc_u32 s3, s23, 0
	s_add_i32 s51, s51, s28
	v_lshl_add_u64 v[144:145], s[2:3], 0, v[132:133]
	s_mov_b32 m0, s51
	ds_read_b128 v[186:189], v151 offset:49152
	ds_read_b128 v[190:193], v151 offset:50176
	ds_read_b128 v[194:197], v151 offset:51200
	ds_read_b128 v[198:201], v151 offset:52224
	ds_read_b128 v[202:205], v151 offset:53248
	ds_read_b128 v[206:209], v151 offset:54272
	ds_read_b128 v[210:213], v151 offset:55296
	ds_read_b128 v[214:217], v151 offset:56320
	global_load_lds_dwordx4 v[144:145], off
	s_add_i32 m0, s51, 0x2000
	v_lshl_add_u64 v[144:145], s[2:3], 0, v[136:137]
	s_add_u32 s2, s22, 0xc000
	s_addc_u32 s3, s23, 0
	s_add_i32 s22, s52, s28
	global_load_lds_dwordx4 v[144:145], off
	v_lshl_add_u64 v[144:145], s[2:3], 0, v[132:133]
	s_mov_b32 m0, s22
	s_nop 0
	global_load_lds_dwordx4 v[144:145], off
	v_lshl_add_u64 v[144:145], s[2:3], 0, v[136:137]
	s_add_i32 m0, s22, 0x2000
	s_nop 0
	global_load_lds_dwordx4 v[144:145], off
	v_lshl_add_u64 v[144:145], s[20:21], 0, v[130:131]
	s_mov_b32 m0, s36
	s_nop 0
	global_load_lds_dwordx4 v[144:145], off
	v_lshl_add_u64 v[144:145], s[20:21], 0, v[134:135]
	s_mov_b32 m0, s37
	s_nop 0
	global_load_lds_dwordx4 v[144:145], off
	s_waitcnt vmcnt(8)
	s_waitcnt lgkmcnt(0)
	s_setprio 1
	s_barrier
	s_waitcnt lgkmcnt(0)
	v_mfma_f32_16x16x32_bf16 v[62:65], v[152:155], v[186:189], v[62:65]
	v_mfma_f32_16x16x32_bf16 v[58:61], v[160:163], v[186:189], v[58:61]
	v_mfma_f32_16x16x32_bf16 v[50:53], v[152:155], v[194:197], v[50:53]
	v_mfma_f32_16x16x32_bf16 v[42:45], v[160:163], v[194:197], v[42:45]
	v_mfma_f32_16x16x32_bf16 v[34:37], v[152:155], v[202:205], v[34:37]
	v_mfma_f32_16x16x32_bf16 v[26:29], v[160:163], v[202:205], v[26:29]
	v_mfma_f32_16x16x32_bf16 v[18:21], v[152:155], v[210:213], v[18:21]
	v_mfma_f32_16x16x32_bf16 v[10:13], v[160:163], v[210:213], v[10:13]
	v_mfma_f32_16x16x32_bf16 v[62:65], v[156:159], v[190:193], v[62:65]
	v_mfma_f32_16x16x32_bf16 v[58:61], v[164:167], v[190:193], v[58:61]
	v_mfma_f32_16x16x32_bf16 v[50:53], v[156:159], v[198:201], v[50:53]
	v_mfma_f32_16x16x32_bf16 v[42:45], v[164:167], v[198:201], v[42:45]
	v_mfma_f32_16x16x32_bf16 v[34:37], v[156:159], v[206:209], v[34:37]
	v_mfma_f32_16x16x32_bf16 v[26:29], v[164:167], v[206:209], v[26:29]
	v_mfma_f32_16x16x32_bf16 v[18:21], v[156:159], v[214:217], v[18:21]
	v_mfma_f32_16x16x32_bf16 v[10:13], v[164:167], v[214:217], v[10:13]
	s_setprio 0
	s_setprio 1
	v_mfma_f32_16x16x32_bf16 v[54:57], v[168:171], v[186:189], v[54:57]
	v_mfma_f32_16x16x32_bf16 v[46:49], v[178:181], v[186:189], v[46:49]
	v_mfma_f32_16x16x32_bf16 v[38:41], v[168:171], v[194:197], v[38:41]
	v_mfma_f32_16x16x32_bf16 v[30:33], v[178:181], v[194:197], v[30:33]
	v_mfma_f32_16x16x32_bf16 v[22:25], v[168:171], v[202:205], v[22:25]
	v_mfma_f32_16x16x32_bf16 v[14:17], v[178:181], v[202:205], v[14:17]
	v_mfma_f32_16x16x32_bf16 v[6:9], v[168:171], v[210:213], v[6:9]
	v_mfma_f32_16x16x32_bf16 v[2:5], v[178:181], v[210:213], v[2:5]
	v_mfma_f32_16x16x32_bf16 v[54:57], v[172:175], v[190:193], v[54:57]
	v_mfma_f32_16x16x32_bf16 v[46:49], v[182:185], v[190:193], v[46:49]
	v_mfma_f32_16x16x32_bf16 v[38:41], v[172:175], v[198:201], v[38:41]
	v_mfma_f32_16x16x32_bf16 v[30:33], v[182:185], v[198:201], v[30:33]
	v_mfma_f32_16x16x32_bf16 v[22:25], v[172:175], v[206:209], v[22:25]
	v_mfma_f32_16x16x32_bf16 v[14:17], v[182:185], v[206:209], v[14:17]
	v_mfma_f32_16x16x32_bf16 v[6:9], v[172:175], v[214:217], v[6:9]
	v_mfma_f32_16x16x32_bf16 v[2:5], v[182:185], v[214:217], v[2:5]
	s_setprio 0
	s_barrier
	s_add_i32 s50, s50, 2
	s_add_u32 s18, s18, 0x10000
	s_addc_u32 s19, s19, 0
	s_add_u32 s48, s48, 0x10000
	s_addc_u32 s49, s49, 0
	s_cmp_gt_u32 s50, 41
	s_cbranch_scc0 .LBB0_495

.Lpk555_peel:
	ds_read_b128 v[154:157], v151
	ds_read_b128 v[158:161], v151 offset:1024
	ds_read_b128 v[162:165], v151 offset:2048
	ds_read_b128 v[166:169], v151 offset:3072
	ds_read_b128 v[170:173], v152
	ds_read_b128 v[178:181], v152 offset:1024
	ds_read_b128 v[182:185], v152 offset:2048
	ds_read_b128 v[186:189], v152 offset:3072
	s_add_u32 s2, s26, 0xfffc0080
	s_addc_u32 s3, s27, -1
	s_cmp_eq_u32 s52, 12
	s_cselect_b32 s3, s11, s3
	s_cselect_b32 s2, s13, s2
	s_cselect_b32 s29, s48, s51
	s_cselect_b32 s28, s49, s50
	v_lshl_add_u64 v[144:145], s[26:27], 0, v[138:139]
	s_add_i32 m0, s37, 0xc000
	ds_read_b128 v[190:193], v153
	ds_read_b128 v[194:197], v153 offset:1024
	ds_read_b128 v[198:201], v153 offset:2048
	ds_read_b128 v[202:205], v153 offset:3072
	ds_read_b128 v[206:209], v153 offset:4096
	ds_read_b128 v[210:213], v153 offset:5120
	ds_read_b128 v[214:217], v153 offset:6144
	ds_read_b128 v[218:221], v153 offset:7168
	global_load_lds_dwordx4 v[144:145], off
	v_lshl_add_u64 v[144:145], s[26:27], 0, v[140:141]
	s_add_i32 m0, s37, 0xe000
	s_nop 0
	global_load_lds_dwordx4 v[144:145], off
	s_waitcnt vmcnt(8)
	s_waitcnt lgkmcnt(0)
	s_setprio 1
	s_barrier
	s_waitcnt lgkmcnt(0)
	v_mfma_f32_16x16x32_bf16 v[126:129], v[154:157], v[190:193], 0
	v_mfma_f32_16x16x32_bf16 v[122:125], v[162:165], v[190:193], 0
	v_mfma_f32_16x16x32_bf16 v[114:117], v[154:157], v[198:201], 0
	v_mfma_f32_16x16x32_bf16 v[106:109], v[162:165], v[198:201], 0
	v_mfma_f32_16x16x32_bf16 v[98:101], v[154:157], v[206:209], 0
	v_mfma_f32_16x16x32_bf16 v[90:93], v[162:165], v[206:209], 0
	v_mfma_f32_16x16x32_bf16 v[82:85], v[154:157], v[214:217], 0
	v_mfma_f32_16x16x32_bf16 v[74:77], v[162:165], v[214:217], 0
	v_mfma_f32_16x16x32_bf16 v[126:129], v[158:161], v[194:197], v[126:129]
	v_mfma_f32_16x16x32_bf16 v[122:125], v[166:169], v[194:197], v[122:125]
	v_mfma_f32_16x16x32_bf16 v[114:117], v[158:161], v[202:205], v[114:117]
	v_mfma_f32_16x16x32_bf16 v[106:109], v[166:169], v[202:205], v[106:109]
	v_mfma_f32_16x16x32_bf16 v[98:101], v[158:161], v[210:213], v[98:101]
	v_mfma_f32_16x16x32_bf16 v[90:93], v[166:169], v[210:213], v[90:93]
	v_mfma_f32_16x16x32_bf16 v[82:85], v[158:161], v[218:221], v[82:85]
	v_mfma_f32_16x16x32_bf16 v[74:77], v[166:169], v[218:221], v[74:77]
	s_setprio 0
	s_setprio 1
	v_mfma_f32_16x16x32_bf16 v[118:121], v[170:173], v[190:193], 0
	v_mfma_f32_16x16x32_bf16 v[110:113], v[182:185], v[190:193], 0
	v_mfma_f32_16x16x32_bf16 v[102:105], v[170:173], v[198:201], 0
	v_mfma_f32_16x16x32_bf16 v[94:97], v[182:185], v[198:201], 0
	v_mfma_f32_16x16x32_bf16 v[86:89], v[170:173], v[206:209], 0
	v_mfma_f32_16x16x32_bf16 v[78:81], v[182:185], v[206:209], 0
	v_mfma_f32_16x16x32_bf16 v[70:73], v[170:173], v[214:217], 0
	v_mfma_f32_16x16x32_bf16 v[66:69], v[182:185], v[214:217], 0
	v_mfma_f32_16x16x32_bf16 v[118:121], v[178:181], v[194:197], v[118:121]
	v_mfma_f32_16x16x32_bf16 v[110:113], v[186:189], v[194:197], v[110:113]
	v_mfma_f32_16x16x32_bf16 v[102:105], v[178:181], v[202:205], v[102:105]
	v_mfma_f32_16x16x32_bf16 v[94:97], v[186:189], v[202:205], v[94:97]
	v_mfma_f32_16x16x32_bf16 v[86:89], v[178:181], v[210:213], v[86:89]
	v_mfma_f32_16x16x32_bf16 v[78:81], v[186:189], v[210:213], v[78:81]
	v_mfma_f32_16x16x32_bf16 v[70:73], v[178:181], v[218:221], v[70:73]
	v_mfma_f32_16x16x32_bf16 v[66:69], v[186:189], v[218:221], v[66:69]
	s_setprio 0
	s_barrier
	s_add_i32 s53, s44, s34
	v_lshl_add_u64 v[144:145], s[28:29], 0, v[134:135]
	s_mov_b32 m0, s53
	ds_read_b128 v[190:193], v153 offset:16384
	ds_read_b128 v[194:197], v153 offset:17408
	ds_read_b128 v[198:201], v153 offset:18432
	ds_read_b128 v[202:205], v153 offset:19456
	ds_read_b128 v[206:209], v153 offset:20480
	ds_read_b128 v[210:213], v153 offset:21504
	ds_read_b128 v[214:217], v153 offset:22528
	ds_read_b128 v[218:221], v153 offset:23552
	global_load_lds_dwordx4 v[144:145], off
	s_add_i32 m0, s53, 0x2000
	s_add_u32 s54, s28, 0x40000
	v_lshl_add_u64 v[174:175], s[28:29], 0, v[130:131]
	s_addc_u32 s55, s29, 0
	s_add_i32 s53, s45, s34
	global_load_lds_dwordx4 v[174:175], off
	v_lshl_add_u64 v[222:223], s[54:55], 0, v[134:135]
	s_mov_b32 m0, s53
	v_lshl_add_u64 v[224:225], s[2:3], 0, v[132:133]
	global_load_lds_dwordx4 v[222:223], off
	v_lshl_add_u64 v[222:223], s[54:55], 0, v[130:131]
	s_add_i32 m0, s53, 0x2000
	s_nop 0
	global_load_lds_dwordx4 v[222:223], off
	v_lshl_add_u64 v[222:223], s[2:3], 0, v[136:137]
	s_mov_b32 m0, s37
	s_nop 0
	global_load_lds_dwordx4 v[222:223], off
	s_mov_b32 m0, s25
	s_nop 0
	global_load_lds_dwordx4 v[224:225], off
	s_waitcnt vmcnt(8)
	s_waitcnt lgkmcnt(0)
	s_setprio 1
	s_barrier
	s_waitcnt lgkmcnt(0)
	v_mfma_f32_16x16x32_bf16 v[62:65], v[154:157], v[190:193], 0
	v_mfma_f32_16x16x32_bf16 v[58:61], v[162:165], v[190:193], 0
	v_mfma_f32_16x16x32_bf16 v[50:53], v[154:157], v[198:201], 0
	v_mfma_f32_16x16x32_bf16 v[42:45], v[162:165], v[198:201], 0
	v_mfma_f32_16x16x32_bf16 v[34:37], v[154:157], v[206:209], 0
	v_mfma_f32_16x16x32_bf16 v[26:29], v[162:165], v[206:209], 0
	v_mfma_f32_16x16x32_bf16 v[18:21], v[154:157], v[214:217], 0
	v_mfma_f32_16x16x32_bf16 v[10:13], v[162:165], v[214:217], 0
	v_mfma_f32_16x16x32_bf16 v[62:65], v[158:161], v[194:197], v[62:65]
	v_mfma_f32_16x16x32_bf16 v[58:61], v[166:169], v[194:197], v[58:61]
	v_mfma_f32_16x16x32_bf16 v[50:53], v[158:161], v[202:205], v[50:53]
	v_mfma_f32_16x16x32_bf16 v[42:45], v[166:169], v[202:205], v[42:45]
	v_mfma_f32_16x16x32_bf16 v[34:37], v[158:161], v[210:213], v[34:37]
	v_mfma_f32_16x16x32_bf16 v[26:29], v[166:169], v[210:213], v[26:29]
	v_mfma_f32_16x16x32_bf16 v[18:21], v[158:161], v[218:221], v[18:21]
	v_mfma_f32_16x16x32_bf16 v[10:13], v[166:169], v[218:221], v[10:13]
	s_setprio 0
	s_setprio 1
	v_mfma_f32_16x16x32_bf16 v[54:57], v[170:173], v[190:193], 0
	v_mfma_f32_16x16x32_bf16 v[46:49], v[182:185], v[190:193], 0
	v_mfma_f32_16x16x32_bf16 v[38:41], v[170:173], v[198:201], 0
	v_mfma_f32_16x16x32_bf16 v[30:33], v[182:185], v[198:201], 0
	v_mfma_f32_16x16x32_bf16 v[22:25], v[170:173], v[206:209], 0
	v_mfma_f32_16x16x32_bf16 v[14:17], v[182:185], v[206:209], 0
	v_mfma_f32_16x16x32_bf16 v[6:9], v[170:173], v[214:217], 0
	v_mfma_f32_16x16x32_bf16 v[2:5], v[182:185], v[214:217], 0
	v_mfma_f32_16x16x32_bf16 v[54:57], v[178:181], v[194:197], v[54:57]
	v_mfma_f32_16x16x32_bf16 v[46:49], v[186:189], v[194:197], v[46:49]
	v_mfma_f32_16x16x32_bf16 v[38:41], v[178:181], v[202:205], v[38:41]
	v_mfma_f32_16x16x32_bf16 v[30:33], v[186:189], v[202:205], v[30:33]
	v_mfma_f32_16x16x32_bf16 v[22:25], v[178:181], v[210:213], v[22:25]
	v_mfma_f32_16x16x32_bf16 v[14:17], v[186:189], v[210:213], v[14:17]
	v_mfma_f32_16x16x32_bf16 v[6:9], v[178:181], v[218:221], v[6:9]
	v_mfma_f32_16x16x32_bf16 v[2:5], v[186:189], v[218:221], v[2:5]
	s_setprio 0
	s_barrier
	s_add_i32 s53, 0, 0x18000
	s_add_i32 s54, 0, 0x1c000
	v_add_u32_e32 v166, s53, v149
	v_add_u32_e32 v176, s54, v149
	ds_read_b128 v[154:157], v166
	ds_read_b128 v[158:161], v166 offset:1024
	ds_read_b128 v[162:165], v166 offset:2048
	ds_read_b128 v[166:169], v166 offset:3072
	ds_read_b128 v[170:173], v176
	ds_read_b128 v[178:181], v176 offset:1024
	ds_read_b128 v[182:185], v176 offset:2048
	ds_read_b128 v[186:189], v176 offset:3072
	s_add_u32 s2, s2, 0x40000
	s_addc_u32 s3, s3, 0
	s_mov_b32 m0, s38
	v_lshl_add_u64 v[226:227], s[2:3], 0, v[136:137]
	ds_read_b128 v[190:193], v153 offset:32768
	ds_read_b128 v[194:197], v153 offset:33792
	ds_read_b128 v[198:201], v153 offset:34816
	ds_read_b128 v[202:205], v153 offset:35840
	ds_read_b128 v[206:209], v153 offset:36864
	ds_read_b128 v[210:213], v153 offset:37888
	ds_read_b128 v[214:217], v153 offset:38912
	ds_read_b128 v[218:221], v153 offset:39936
	global_load_lds_dwordx4 v[226:227], off
	v_lshl_add_u64 v[226:227], s[2:3], 0, v[132:133]
	s_mov_b32 m0, s39
	s_nop 0
	global_load_lds_dwordx4 v[226:227], off
	s_waitcnt vmcnt(8)
	s_waitcnt lgkmcnt(0)
	s_setprio 1
	s_barrier
	s_waitcnt lgkmcnt(0)
	v_mfma_f32_16x16x32_bf16 v[126:129], v[154:157], v[190:193], v[126:129]
	v_mfma_f32_16x16x32_bf16 v[122:125], v[162:165], v[190:193], v[122:125]
	v_mfma_f32_16x16x32_bf16 v[114:117], v[154:157], v[198:201], v[114:117]
	v_mfma_f32_16x16x32_bf16 v[106:109], v[162:165], v[198:201], v[106:109]
	v_mfma_f32_16x16x32_bf16 v[98:101], v[154:157], v[206:209], v[98:101]
	v_mfma_f32_16x16x32_bf16 v[90:93], v[162:165], v[206:209], v[90:93]
	v_mfma_f32_16x16x32_bf16 v[82:85], v[154:157], v[214:217], v[82:85]
	v_mfma_f32_16x16x32_bf16 v[74:77], v[162:165], v[214:217], v[74:77]
	v_mfma_f32_16x16x32_bf16 v[126:129], v[158:161], v[194:197], v[126:129]
	v_mfma_f32_16x16x32_bf16 v[122:125], v[166:169], v[194:197], v[122:125]
	v_mfma_f32_16x16x32_bf16 v[114:117], v[158:161], v[202:205], v[114:117]
	v_mfma_f32_16x16x32_bf16 v[106:109], v[166:169], v[202:205], v[106:109]
	v_mfma_f32_16x16x32_bf16 v[98:101], v[158:161], v[210:213], v[98:101]
	v_mfma_f32_16x16x32_bf16 v[90:93], v[166:169], v[210:213], v[90:93]
	v_mfma_f32_16x16x32_bf16 v[82:85], v[158:161], v[218:221], v[82:85]
	v_mfma_f32_16x16x32_bf16 v[74:77], v[166:169], v[218:221], v[74:77]
	s_setprio 0
	s_setprio 1
	v_mfma_f32_16x16x32_bf16 v[118:121], v[170:173], v[190:193], v[118:121]
	v_mfma_f32_16x16x32_bf16 v[110:113], v[182:185], v[190:193], v[110:113]
	v_mfma_f32_16x16x32_bf16 v[102:105], v[170:173], v[198:201], v[102:105]
	v_mfma_f32_16x16x32_bf16 v[94:97], v[182:185], v[198:201], v[94:97]
	v_mfma_f32_16x16x32_bf16 v[86:89], v[170:173], v[206:209], v[86:89]
	v_mfma_f32_16x16x32_bf16 v[78:81], v[182:185], v[206:209], v[78:81]
	v_mfma_f32_16x16x32_bf16 v[70:73], v[170:173], v[214:217], v[70:73]
	v_mfma_f32_16x16x32_bf16 v[66:69], v[182:185], v[214:217], v[66:69]
	v_mfma_f32_16x16x32_bf16 v[118:121], v[178:181], v[194:197], v[118:121]
	v_mfma_f32_16x16x32_bf16 v[110:113], v[186:189], v[194:197], v[110:113]
	v_mfma_f32_16x16x32_bf16 v[102:105], v[178:181], v[202:205], v[102:105]
	v_mfma_f32_16x16x32_bf16 v[94:97], v[186:189], v[202:205], v[94:97]
	v_mfma_f32_16x16x32_bf16 v[86:89], v[178:181], v[210:213], v[86:89]
	v_mfma_f32_16x16x32_bf16 v[78:81], v[186:189], v[210:213], v[78:81]
	v_mfma_f32_16x16x32_bf16 v[70:73], v[178:181], v[218:221], v[70:73]
	v_mfma_f32_16x16x32_bf16 v[66:69], v[186:189], v[218:221], v[66:69]
	s_setprio 0
	s_barrier
	s_add_i32 s2, s53, s34
	v_lshl_add_u64 v[144:145], v[144:145], 0, s[6:7]
	s_mov_b32 m0, s2
	ds_read_b128 v[190:193], v153 offset:49152
	ds_read_b128 v[194:197], v153 offset:50176
	ds_read_b128 v[198:201], v153 offset:51200
	ds_read_b128 v[202:205], v153 offset:52224
	ds_read_b128 v[206:209], v153 offset:53248
	ds_read_b128 v[210:213], v153 offset:54272
	ds_read_b128 v[214:217], v153 offset:55296
	ds_read_b128 v[218:221], v153 offset:56320
	global_load_lds_dwordx4 v[144:145], off
	s_add_i32 m0, s2, 0x2000
	s_add_u32 s2, s28, 0x40080
	v_lshl_add_u64 v[144:145], v[174:175], 0, s[6:7]
	s_addc_u32 s3, s29, 0
	s_add_i32 s28, s54, s34
	global_load_lds_dwordx4 v[144:145], off
	v_lshl_add_u64 v[144:145], s[2:3], 0, v[134:135]
	s_mov_b32 m0, s28
	s_nop 0
	global_load_lds_dwordx4 v[144:145], off
	v_lshl_add_u64 v[144:145], s[2:3], 0, v[130:131]
	s_add_i32 m0, s28, 0x2000
	s_nop 0
	global_load_lds_dwordx4 v[144:145], off
	v_lshl_add_u64 v[144:145], v[222:223], 0, s[6:7]
	s_mov_b32 m0, s41
	s_nop 0
	global_load_lds_dwordx4 v[144:145], off
	v_lshl_add_u64 v[144:145], v[224:225], 0, s[6:7]
	s_mov_b32 m0, s42
	s_nop 0
	global_load_lds_dwordx4 v[144:145], off
	s_waitcnt vmcnt(8)
	s_waitcnt lgkmcnt(0)
	s_setprio 1
	s_barrier
	s_waitcnt lgkmcnt(0)
	v_mfma_f32_16x16x32_bf16 v[62:65], v[154:157], v[190:193], v[62:65]
	v_mfma_f32_16x16x32_bf16 v[58:61], v[162:165], v[190:193], v[58:61]
	v_mfma_f32_16x16x32_bf16 v[50:53], v[154:157], v[198:201], v[50:53]
	v_mfma_f32_16x16x32_bf16 v[42:45], v[162:165], v[198:201], v[42:45]
	v_mfma_f32_16x16x32_bf16 v[34:37], v[154:157], v[206:209], v[34:37]
	v_mfma_f32_16x16x32_bf16 v[26:29], v[162:165], v[206:209], v[26:29]
	v_mfma_f32_16x16x32_bf16 v[18:21], v[154:157], v[214:217], v[18:21]
	v_mfma_f32_16x16x32_bf16 v[10:13], v[162:165], v[214:217], v[10:13]
	v_mfma_f32_16x16x32_bf16 v[62:65], v[158:161], v[194:197], v[62:65]
	v_mfma_f32_16x16x32_bf16 v[58:61], v[166:169], v[194:197], v[58:61]
	v_mfma_f32_16x16x32_bf16 v[50:53], v[158:161], v[202:205], v[50:53]
	v_mfma_f32_16x16x32_bf16 v[42:45], v[166:169], v[202:205], v[42:45]
	v_mfma_f32_16x16x32_bf16 v[34:37], v[158:161], v[210:213], v[34:37]
	v_mfma_f32_16x16x32_bf16 v[26:29], v[166:169], v[210:213], v[26:29]
	v_mfma_f32_16x16x32_bf16 v[18:21], v[158:161], v[218:221], v[18:21]
	v_mfma_f32_16x16x32_bf16 v[10:13], v[166:169], v[218:221], v[10:13]
	s_setprio 0
	s_setprio 1
	v_mfma_f32_16x16x32_bf16 v[54:57], v[170:173], v[190:193], v[54:57]
	v_mfma_f32_16x16x32_bf16 v[46:49], v[182:185], v[190:193], v[46:49]
	v_mfma_f32_16x16x32_bf16 v[38:41], v[170:173], v[198:201], v[38:41]
	v_mfma_f32_16x16x32_bf16 v[30:33], v[182:185], v[198:201], v[30:33]
	v_mfma_f32_16x16x32_bf16 v[22:25], v[170:173], v[206:209], v[22:25]
	v_mfma_f32_16x16x32_bf16 v[14:17], v[182:185], v[206:209], v[14:17]
	v_mfma_f32_16x16x32_bf16 v[6:9], v[170:173], v[214:217], v[6:9]
	v_mfma_f32_16x16x32_bf16 v[2:5], v[182:185], v[214:217], v[2:5]
	v_mfma_f32_16x16x32_bf16 v[54:57], v[178:181], v[194:197], v[54:57]
	v_mfma_f32_16x16x32_bf16 v[46:49], v[186:189], v[194:197], v[46:49]
	v_mfma_f32_16x16x32_bf16 v[38:41], v[178:181], v[202:205], v[38:41]
	v_mfma_f32_16x16x32_bf16 v[30:33], v[186:189], v[202:205], v[30:33]
	v_mfma_f32_16x16x32_bf16 v[22:25], v[178:181], v[210:213], v[22:25]
	v_mfma_f32_16x16x32_bf16 v[14:17], v[186:189], v[210:213], v[14:17]
	v_mfma_f32_16x16x32_bf16 v[6:9], v[178:181], v[218:221], v[6:9]
	v_mfma_f32_16x16x32_bf16 v[2:5], v[186:189], v[218:221], v[2:5]
	s_setprio 0
	s_barrier
	s_add_i32 s52, s52, 2
	s_add_u32 s26, s26, 0x100
	s_addc_u32 s27, s27, 0
	s_add_u32 s50, s50, 0x100
	s_addc_u32 s51, s51, 0
	s_cmp_gt_u32 s52, 13
	s_cbranch_scc0 .LBB0_555
	s_branch .Lpk555_exit
.LBB0_555:
	ds_read_b128 v[154:157], v151
	ds_read_b128 v[158:161], v151 offset:1024
	ds_read_b128 v[162:165], v151 offset:2048
	ds_read_b128 v[166:169], v151 offset:3072
	ds_read_b128 v[170:173], v152
	ds_read_b128 v[178:181], v152 offset:1024
	ds_read_b128 v[182:185], v152 offset:2048
	ds_read_b128 v[186:189], v152 offset:3072
	s_add_u32 s2, s26, 0xfffc0080
	s_addc_u32 s3, s27, -1
	s_cmp_eq_u32 s52, 12
	s_cselect_b32 s3, s11, s3
	s_cselect_b32 s2, s13, s2
	s_cselect_b32 s29, s48, s51
	s_cselect_b32 s28, s49, s50
	v_lshl_add_u64 v[144:145], s[26:27], 0, v[138:139]
	s_add_i32 m0, s37, 0xc000
	ds_read_b128 v[190:193], v153
	ds_read_b128 v[194:197], v153 offset:1024
	ds_read_b128 v[198:201], v153 offset:2048
	ds_read_b128 v[202:205], v153 offset:3072
	ds_read_b128 v[206:209], v153 offset:4096
	ds_read_b128 v[210:213], v153 offset:5120
	ds_read_b128 v[214:217], v153 offset:6144
	ds_read_b128 v[218:221], v153 offset:7168
	global_load_lds_dwordx4 v[144:145], off
	v_lshl_add_u64 v[144:145], s[26:27], 0, v[140:141]
	s_add_i32 m0, s37, 0xe000
	s_nop 0
	global_load_lds_dwordx4 v[144:145], off
	s_waitcnt vmcnt(8)
	s_waitcnt lgkmcnt(0)
	s_setprio 1
	s_barrier
	s_waitcnt lgkmcnt(0)
	v_mfma_f32_16x16x32_bf16 v[126:129], v[154:157], v[190:193], v[126:129]
	v_mfma_f32_16x16x32_bf16 v[122:125], v[162:165], v[190:193], v[122:125]
	v_mfma_f32_16x16x32_bf16 v[114:117], v[154:157], v[198:201], v[114:117]
	v_mfma_f32_16x16x32_bf16 v[106:109], v[162:165], v[198:201], v[106:109]
	v_mfma_f32_16x16x32_bf16 v[98:101], v[154:157], v[206:209], v[98:101]
	v_mfma_f32_16x16x32_bf16 v[90:93], v[162:165], v[206:209], v[90:93]
	v_mfma_f32_16x16x32_bf16 v[82:85], v[154:157], v[214:217], v[82:85]
	v_mfma_f32_16x16x32_bf16 v[74:77], v[162:165], v[214:217], v[74:77]
	v_mfma_f32_16x16x32_bf16 v[126:129], v[158:161], v[194:197], v[126:129]
	v_mfma_f32_16x16x32_bf16 v[122:125], v[166:169], v[194:197], v[122:125]
	v_mfma_f32_16x16x32_bf16 v[114:117], v[158:161], v[202:205], v[114:117]
	v_mfma_f32_16x16x32_bf16 v[106:109], v[166:169], v[202:205], v[106:109]
	v_mfma_f32_16x16x32_bf16 v[98:101], v[158:161], v[210:213], v[98:101]
	v_mfma_f32_16x16x32_bf16 v[90:93], v[166:169], v[210:213], v[90:93]
	v_mfma_f32_16x16x32_bf16 v[82:85], v[158:161], v[218:221], v[82:85]
	v_mfma_f32_16x16x32_bf16 v[74:77], v[166:169], v[218:221], v[74:77]
	s_setprio 0
	s_setprio 1
	v_mfma_f32_16x16x32_bf16 v[118:121], v[170:173], v[190:193], v[118:121]
	v_mfma_f32_16x16x32_bf16 v[110:113], v[182:185], v[190:193], v[110:113]
	v_mfma_f32_16x16x32_bf16 v[102:105], v[170:173], v[198:201], v[102:105]
	v_mfma_f32_16x16x32_bf16 v[94:97], v[182:185], v[198:201], v[94:97]
	v_mfma_f32_16x16x32_bf16 v[86:89], v[170:173], v[206:209], v[86:89]
	v_mfma_f32_16x16x32_bf16 v[78:81], v[182:185], v[206:209], v[78:81]
	v_mfma_f32_16x16x32_bf16 v[70:73], v[170:173], v[214:217], v[70:73]
	v_mfma_f32_16x16x32_bf16 v[66:69], v[182:185], v[214:217], v[66:69]
	v_mfma_f32_16x16x32_bf16 v[118:121], v[178:181], v[194:197], v[118:121]
	v_mfma_f32_16x16x32_bf16 v[110:113], v[186:189], v[194:197], v[110:113]
	v_mfma_f32_16x16x32_bf16 v[102:105], v[178:181], v[202:205], v[102:105]
	v_mfma_f32_16x16x32_bf16 v[94:97], v[186:189], v[202:205], v[94:97]
	v_mfma_f32_16x16x32_bf16 v[86:89], v[178:181], v[210:213], v[86:89]
	v_mfma_f32_16x16x32_bf16 v[78:81], v[186:189], v[210:213], v[78:81]
	v_mfma_f32_16x16x32_bf16 v[70:73], v[178:181], v[218:221], v[70:73]
	v_mfma_f32_16x16x32_bf16 v[66:69], v[186:189], v[218:221], v[66:69]
	s_setprio 0
	s_barrier
	s_add_i32 s53, s44, s34
	v_lshl_add_u64 v[144:145], s[28:29], 0, v[134:135]
	s_mov_b32 m0, s53
	ds_read_b128 v[190:193], v153 offset:16384
	ds_read_b128 v[194:197], v153 offset:17408
	ds_read_b128 v[198:201], v153 offset:18432
	ds_read_b128 v[202:205], v153 offset:19456
	ds_read_b128 v[206:209], v153 offset:20480
	ds_read_b128 v[210:213], v153 offset:21504
	ds_read_b128 v[214:217], v153 offset:22528
	ds_read_b128 v[218:221], v153 offset:23552
	global_load_lds_dwordx4 v[144:145], off
	s_add_i32 m0, s53, 0x2000
	s_add_u32 s54, s28, 0x40000
	v_lshl_add_u64 v[174:175], s[28:29], 0, v[130:131]
	s_addc_u32 s55, s29, 0
	s_add_i32 s53, s45, s34
	global_load_lds_dwordx4 v[174:175], off
	v_lshl_add_u64 v[222:223], s[54:55], 0, v[134:135]
	s_mov_b32 m0, s53
	v_lshl_add_u64 v[224:225], s[2:3], 0, v[132:133]
	global_load_lds_dwordx4 v[222:223], off
	v_lshl_add_u64 v[222:223], s[54:55], 0, v[130:131]
	s_add_i32 m0, s53, 0x2000
	s_nop 0
	global_load_lds_dwordx4 v[222:223], off
	v_lshl_add_u64 v[222:223], s[2:3], 0, v[136:137]
	s_mov_b32 m0, s37
	s_nop 0
	global_load_lds_dwordx4 v[222:223], off
	s_mov_b32 m0, s25
	s_nop 0
	global_load_lds_dwordx4 v[224:225], off
	s_waitcnt vmcnt(8)
	s_waitcnt lgkmcnt(0)
	s_setprio 1
	s_barrier
	s_waitcnt lgkmcnt(0)
	v_mfma_f32_16x16x32_bf16 v[62:65], v[154:157], v[190:193], v[62:65]
	v_mfma_f32_16x16x32_bf16 v[58:61], v[162:165], v[190:193], v[58:61]
	v_mfma_f32_16x16x32_bf16 v[50:53], v[154:157], v[198:201], v[50:53]
	v_mfma_f32_16x16x32_bf16 v[42:45], v[162:165], v[198:201], v[42:45]
	v_mfma_f32_16x16x32_bf16 v[34:37], v[154:157], v[206:209], v[34:37]
	v_mfma_f32_16x16x32_bf16 v[26:29], v[162:165], v[206:209], v[26:29]
	v_mfma_f32_16x16x32_bf16 v[18:21], v[154:157], v[214:217], v[18:21]
	v_mfma_f32_16x16x32_bf16 v[10:13], v[162:165], v[214:217], v[10:13]
	v_mfma_f32_16x16x32_bf16 v[62:65], v[158:161], v[194:197], v[62:65]
	v_mfma_f32_16x16x32_bf16 v[58:61], v[166:169], v[194:197], v[58:61]
	v_mfma_f32_16x16x32_bf16 v[50:53], v[158:161], v[202:205], v[50:53]
	v_mfma_f32_16x16x32_bf16 v[42:45], v[166:169], v[202:205], v[42:45]
	v_mfma_f32_16x16x32_bf16 v[34:37], v[158:161], v[210:213], v[34:37]
	v_mfma_f32_16x16x32_bf16 v[26:29], v[166:169], v[210:213], v[26:29]
	v_mfma_f32_16x16x32_bf16 v[18:21], v[158:161], v[218:221], v[18:21]
	v_mfma_f32_16x16x32_bf16 v[10:13], v[166:169], v[218:221], v[10:13]
	s_setprio 0
	s_setprio 1
	v_mfma_f32_16x16x32_bf16 v[54:57], v[170:173], v[190:193], v[54:57]
	v_mfma_f32_16x16x32_bf16 v[46:49], v[182:185], v[190:193], v[46:49]
	v_mfma_f32_16x16x32_bf16 v[38:41], v[170:173], v[198:201], v[38:41]
	v_mfma_f32_16x16x32_bf16 v[30:33], v[182:185], v[198:201], v[30:33]
	v_mfma_f32_16x16x32_bf16 v[22:25], v[170:173], v[206:209], v[22:25]
	v_mfma_f32_16x16x32_bf16 v[14:17], v[182:185], v[206:209], v[14:17]
	v_mfma_f32_16x16x32_bf16 v[6:9], v[170:173], v[214:217], v[6:9]
	v_mfma_f32_16x16x32_bf16 v[2:5], v[182:185], v[214:217], v[2:5]
	v_mfma_f32_16x16x32_bf16 v[54:57], v[178:181], v[194:197], v[54:57]
	v_mfma_f32_16x16x32_bf16 v[46:49], v[186:189], v[194:197], v[46:49]
	v_mfma_f32_16x16x32_bf16 v[38:41], v[178:181], v[202:205], v[38:41]
	v_mfma_f32_16x16x32_bf16 v[30:33], v[186:189], v[202:205], v[30:33]
	v_mfma_f32_16x16x32_bf16 v[22:25], v[178:181], v[210:213], v[22:25]
	v_mfma_f32_16x16x32_bf16 v[14:17], v[186:189], v[210:213], v[14:17]
	v_mfma_f32_16x16x32_bf16 v[6:9], v[178:181], v[218:221], v[6:9]
	v_mfma_f32_16x16x32_bf16 v[2:5], v[186:189], v[218:221], v[2:5]
	s_setprio 0
	s_barrier
	s_add_i32 s53, 0, 0x18000
	s_add_i32 s54, 0, 0x1c000
	v_add_u32_e32 v166, s53, v149
	v_add_u32_e32 v176, s54, v149
	ds_read_b128 v[154:157], v166
	ds_read_b128 v[158:161], v166 offset:1024
	ds_read_b128 v[162:165], v166 offset:2048
	ds_read_b128 v[166:169], v166 offset:3072
	ds_read_b128 v[170:173], v176
	ds_read_b128 v[178:181], v176 offset:1024
	ds_read_b128 v[182:185], v176 offset:2048
	ds_read_b128 v[186:189], v176 offset:3072
	s_add_u32 s2, s2, 0x40000
	s_addc_u32 s3, s3, 0
	s_mov_b32 m0, s38
	v_lshl_add_u64 v[226:227], s[2:3], 0, v[136:137]
	ds_read_b128 v[190:193], v153 offset:32768
	ds_read_b128 v[194:197], v153 offset:33792
	ds_read_b128 v[198:201], v153 offset:34816
	ds_read_b128 v[202:205], v153 offset:35840
	ds_read_b128 v[206:209], v153 offset:36864
	ds_read_b128 v[210:213], v153 offset:37888
	ds_read_b128 v[214:217], v153 offset:38912
	ds_read_b128 v[218:221], v153 offset:39936
	global_load_lds_dwordx4 v[226:227], off
	v_lshl_add_u64 v[226:227], s[2:3], 0, v[132:133]
	s_mov_b32 m0, s39
	s_nop 0
	global_load_lds_dwordx4 v[226:227], off
	s_waitcnt vmcnt(8)
	s_waitcnt lgkmcnt(0)
	s_setprio 1
	s_barrier
	s_waitcnt lgkmcnt(0)
	v_mfma_f32_16x16x32_bf16 v[126:129], v[154:157], v[190:193], v[126:129]
	v_mfma_f32_16x16x32_bf16 v[122:125], v[162:165], v[190:193], v[122:125]
	v_mfma_f32_16x16x32_bf16 v[114:117], v[154:157], v[198:201], v[114:117]
	v_mfma_f32_16x16x32_bf16 v[106:109], v[162:165], v[198:201], v[106:109]
	v_mfma_f32_16x16x32_bf16 v[98:101], v[154:157], v[206:209], v[98:101]
	v_mfma_f32_16x16x32_bf16 v[90:93], v[162:165], v[206:209], v[90:93]
	v_mfma_f32_16x16x32_bf16 v[82:85], v[154:157], v[214:217], v[82:85]
	v_mfma_f32_16x16x32_bf16 v[74:77], v[162:165], v[214:217], v[74:77]
	v_mfma_f32_16x16x32_bf16 v[126:129], v[158:161], v[194:197], v[126:129]
	v_mfma_f32_16x16x32_bf16 v[122:125], v[166:169], v[194:197], v[122:125]
	v_mfma_f32_16x16x32_bf16 v[114:117], v[158:161], v[202:205], v[114:117]
	v_mfma_f32_16x16x32_bf16 v[106:109], v[166:169], v[202:205], v[106:109]
	v_mfma_f32_16x16x32_bf16 v[98:101], v[158:161], v[210:213], v[98:101]
	v_mfma_f32_16x16x32_bf16 v[90:93], v[166:169], v[210:213], v[90:93]
	v_mfma_f32_16x16x32_bf16 v[82:85], v[158:161], v[218:221], v[82:85]
	v_mfma_f32_16x16x32_bf16 v[74:77], v[166:169], v[218:221], v[74:77]
	s_setprio 0
	s_setprio 1
	v_mfma_f32_16x16x32_bf16 v[118:121], v[170:173], v[190:193], v[118:121]
	v_mfma_f32_16x16x32_bf16 v[110:113], v[182:185], v[190:193], v[110:113]
	v_mfma_f32_16x16x32_bf16 v[102:105], v[170:173], v[198:201], v[102:105]
	v_mfma_f32_16x16x32_bf16 v[94:97], v[182:185], v[198:201], v[94:97]
	v_mfma_f32_16x16x32_bf16 v[86:89], v[170:173], v[206:209], v[86:89]
	v_mfma_f32_16x16x32_bf16 v[78:81], v[182:185], v[206:209], v[78:81]
	v_mfma_f32_16x16x32_bf16 v[70:73], v[170:173], v[214:217], v[70:73]
	v_mfma_f32_16x16x32_bf16 v[66:69], v[182:185], v[214:217], v[66:69]
	v_mfma_f32_16x16x32_bf16 v[118:121], v[178:181], v[194:197], v[118:121]
	v_mfma_f32_16x16x32_bf16 v[110:113], v[186:189], v[194:197], v[110:113]
	v_mfma_f32_16x16x32_bf16 v[102:105], v[178:181], v[202:205], v[102:105]
	v_mfma_f32_16x16x32_bf16 v[94:97], v[186:189], v[202:205], v[94:97]
	v_mfma_f32_16x16x32_bf16 v[86:89], v[178:181], v[210:213], v[86:89]
	v_mfma_f32_16x16x32_bf16 v[78:81], v[186:189], v[210:213], v[78:81]
	v_mfma_f32_16x16x32_bf16 v[70:73], v[178:181], v[218:221], v[70:73]
	v_mfma_f32_16x16x32_bf16 v[66:69], v[186:189], v[218:221], v[66:69]
	s_setprio 0
	s_barrier
	s_add_i32 s2, s53, s34
	v_lshl_add_u64 v[144:145], v[144:145], 0, s[6:7]
	s_mov_b32 m0, s2
	ds_read_b128 v[190:193], v153 offset:49152
	ds_read_b128 v[194:197], v153 offset:50176
	ds_read_b128 v[198:201], v153 offset:51200
	ds_read_b128 v[202:205], v153 offset:52224
	ds_read_b128 v[206:209], v153 offset:53248
	ds_read_b128 v[210:213], v153 offset:54272
	ds_read_b128 v[214:217], v153 offset:55296
	ds_read_b128 v[218:221], v153 offset:56320
	global_load_lds_dwordx4 v[144:145], off
	s_add_i32 m0, s2, 0x2000
	s_add_u32 s2, s28, 0x40080
	v_lshl_add_u64 v[144:145], v[174:175], 0, s[6:7]
	s_addc_u32 s3, s29, 0
	s_add_i32 s28, s54, s34
	global_load_lds_dwordx4 v[144:145], off
	v_lshl_add_u64 v[144:145], s[2:3], 0, v[134:135]
	s_mov_b32 m0, s28
	s_nop 0
	global_load_lds_dwordx4 v[144:145], off
	v_lshl_add_u64 v[144:145], s[2:3], 0, v[130:131]
	s_add_i32 m0, s28, 0x2000
	s_nop 0
	global_load_lds_dwordx4 v[144:145], off
	v_lshl_add_u64 v[144:145], v[222:223], 0, s[6:7]
	s_mov_b32 m0, s41
	s_nop 0
	global_load_lds_dwordx4 v[144:145], off
	v_lshl_add_u64 v[144:145], v[224:225], 0, s[6:7]
	s_mov_b32 m0, s42
	s_nop 0
	global_load_lds_dwordx4 v[144:145], off
	s_waitcnt vmcnt(8)
	s_waitcnt lgkmcnt(0)
	s_setprio 1
	s_barrier
	s_waitcnt lgkmcnt(0)
	v_mfma_f32_16x16x32_bf16 v[62:65], v[154:157], v[190:193], v[62:65]
	v_mfma_f32_16x16x32_bf16 v[58:61], v[162:165], v[190:193], v[58:61]
	v_mfma_f32_16x16x32_bf16 v[50:53], v[154:157], v[198:201], v[50:53]
	v_mfma_f32_16x16x32_bf16 v[42:45], v[162:165], v[198:201], v[42:45]
	v_mfma_f32_16x16x32_bf16 v[34:37], v[154:157], v[206:209], v[34:37]
	v_mfma_f32_16x16x32_bf16 v[26:29], v[162:165], v[206:209], v[26:29]
	v_mfma_f32_16x16x32_bf16 v[18:21], v[154:157], v[214:217], v[18:21]
	v_mfma_f32_16x16x32_bf16 v[10:13], v[162:165], v[214:217], v[10:13]
	v_mfma_f32_16x16x32_bf16 v[62:65], v[158:161], v[194:197], v[62:65]
	v_mfma_f32_16x16x32_bf16 v[58:61], v[166:169], v[194:197], v[58:61]
	v_mfma_f32_16x16x32_bf16 v[50:53], v[158:161], v[202:205], v[50:53]
	v_mfma_f32_16x16x32_bf16 v[42:45], v[166:169], v[202:205], v[42:45]
	v_mfma_f32_16x16x32_bf16 v[34:37], v[158:161], v[210:213], v[34:37]
	v_mfma_f32_16x16x32_bf16 v[26:29], v[166:169], v[210:213], v[26:29]
	v_mfma_f32_16x16x32_bf16 v[18:21], v[158:161], v[218:221], v[18:21]
	v_mfma_f32_16x16x32_bf16 v[10:13], v[166:169], v[218:221], v[10:13]
	s_setprio 0
	s_setprio 1
	v_mfma_f32_16x16x32_bf16 v[54:57], v[170:173], v[190:193], v[54:57]
	v_mfma_f32_16x16x32_bf16 v[46:49], v[182:185], v[190:193], v[46:49]
	v_mfma_f32_16x16x32_bf16 v[38:41], v[170:173], v[198:201], v[38:41]
	v_mfma_f32_16x16x32_bf16 v[30:33], v[182:185], v[198:201], v[30:33]
	v_mfma_f32_16x16x32_bf16 v[22:25], v[170:173], v[206:209], v[22:25]
	v_mfma_f32_16x16x32_bf16 v[14:17], v[182:185], v[206:209], v[14:17]
	v_mfma_f32_16x16x32_bf16 v[6:9], v[170:173], v[214:217], v[6:9]
	v_mfma_f32_16x16x32_bf16 v[2:5], v[182:185], v[214:217], v[2:5]
	v_mfma_f32_16x16x32_bf16 v[54:57], v[178:181], v[194:197], v[54:57]
	v_mfma_f32_16x16x32_bf16 v[46:49], v[186:189], v[194:197], v[46:49]
	v_mfma_f32_16x16x32_bf16 v[38:41], v[178:181], v[202:205], v[38:41]
	v_mfma_f32_16x16x32_bf16 v[30:33], v[186:189], v[202:205], v[30:33]
	v_mfma_f32_16x16x32_bf16 v[22:25], v[178:181], v[210:213], v[22:25]
	v_mfma_f32_16x16x32_bf16 v[14:17], v[186:189], v[210:213], v[14:17]
	v_mfma_f32_16x16x32_bf16 v[6:9], v[178:181], v[218:221], v[6:9]
	v_mfma_f32_16x16x32_bf16 v[2:5], v[186:189], v[218:221], v[2:5]
	s_setprio 0
	s_barrier
	s_add_i32 s52, s52, 2
	s_add_u32 s26, s26, 0x100
	s_addc_u32 s27, s27, 0
	s_add_u32 s50, s50, 0x100
	s_addc_u32 s51, s51, 0
	s_cmp_gt_u32 s52, 13
	s_cbranch_scc0 .LBB0_555

.LBB0_646:
	ds_read_b128 v[152:155], v146
	ds_read_b128 v[156:159], v146 offset:1024
	ds_read_b128 v[160:163], v146 offset:2048
	ds_read_b128 v[164:167], v146 offset:3072
	ds_read_b128 v[168:171], v147
	ds_read_b128 v[172:175], v147 offset:1024
	ds_read_b128 v[178:181], v147 offset:2048
	ds_read_b128 v[182:185], v147 offset:3072
	s_add_u32 s2, s10, s12
	s_addc_u32 s3, s11, s13
	s_add_u32 s2, s2, 0x3400100
	s_addc_u32 s3, s3, 0
	s_add_u32 s14, s24, s12
	s_addc_u32 s15, s25, s13
	s_cmpk_eq_i32 s12, 0x700
	s_cselect_b32 s3, s7, s3
	s_cselect_b32 s2, s6, s2
	s_cselect_b32 s15, s5, s15
	s_cselect_b32 s14, s4, s14
	s_mov_b32 m0, s27
	v_lshl_add_u64 v[218:219], v[138:139], 0, s[12:13]
	ds_read_b128 v[186:189], v148
	ds_read_b128 v[190:193], v148 offset:1024
	ds_read_b128 v[194:197], v148 offset:2048
	ds_read_b128 v[198:201], v148 offset:3072
	ds_read_b128 v[202:205], v148 offset:4096
	ds_read_b128 v[206:209], v148 offset:5120
	ds_read_b128 v[210:213], v148 offset:6144
	ds_read_b128 v[214:217], v148 offset:7168
	global_load_lds_dwordx4 v[218:219], off
	v_lshl_add_u64 v[218:219], v[140:141], 0, s[12:13]
	s_mov_b32 m0, s28
	s_nop 0
	global_load_lds_dwordx4 v[218:219], off
	s_waitcnt vmcnt(8)
	s_waitcnt lgkmcnt(0)
	s_setprio 1
	s_barrier
	s_waitcnt lgkmcnt(0)
	v_mfma_f32_16x16x32_bf16 v[126:129], v[152:155], v[186:189], v[126:129]
	v_mfma_f32_16x16x32_bf16 v[122:125], v[160:163], v[186:189], v[122:125]
	v_mfma_f32_16x16x32_bf16 v[114:117], v[152:155], v[194:197], v[114:117]
	v_mfma_f32_16x16x32_bf16 v[106:109], v[160:163], v[194:197], v[106:109]
	v_mfma_f32_16x16x32_bf16 v[98:101], v[152:155], v[202:205], v[98:101]
	v_mfma_f32_16x16x32_bf16 v[90:93], v[160:163], v[202:205], v[90:93]
	v_mfma_f32_16x16x32_bf16 v[82:85], v[152:155], v[210:213], v[82:85]
	v_mfma_f32_16x16x32_bf16 v[74:77], v[160:163], v[210:213], v[74:77]
	v_mfma_f32_16x16x32_bf16 v[126:129], v[156:159], v[190:193], v[126:129]
	v_mfma_f32_16x16x32_bf16 v[122:125], v[164:167], v[190:193], v[122:125]
	v_mfma_f32_16x16x32_bf16 v[114:117], v[156:159], v[198:201], v[114:117]
	v_mfma_f32_16x16x32_bf16 v[106:109], v[164:167], v[198:201], v[106:109]
	v_mfma_f32_16x16x32_bf16 v[98:101], v[156:159], v[206:209], v[98:101]
	v_mfma_f32_16x16x32_bf16 v[90:93], v[164:167], v[206:209], v[90:93]
	v_mfma_f32_16x16x32_bf16 v[82:85], v[156:159], v[214:217], v[82:85]
	v_mfma_f32_16x16x32_bf16 v[74:77], v[164:167], v[214:217], v[74:77]
	s_setprio 0
	s_setprio 1
	v_mfma_f32_16x16x32_bf16 v[118:121], v[168:171], v[186:189], v[118:121]
	v_mfma_f32_16x16x32_bf16 v[110:113], v[178:181], v[186:189], v[110:113]
	v_mfma_f32_16x16x32_bf16 v[102:105], v[168:171], v[194:197], v[102:105]
	v_mfma_f32_16x16x32_bf16 v[94:97], v[178:181], v[194:197], v[94:97]
	v_mfma_f32_16x16x32_bf16 v[86:89], v[168:171], v[202:205], v[86:89]
	v_mfma_f32_16x16x32_bf16 v[78:81], v[178:181], v[202:205], v[78:81]
	v_mfma_f32_16x16x32_bf16 v[70:73], v[168:171], v[210:213], v[70:73]
	v_mfma_f32_16x16x32_bf16 v[66:69], v[178:181], v[210:213], v[66:69]
	v_mfma_f32_16x16x32_bf16 v[118:121], v[172:175], v[190:193], v[118:121]
	v_mfma_f32_16x16x32_bf16 v[110:113], v[182:185], v[190:193], v[110:113]
	v_mfma_f32_16x16x32_bf16 v[102:105], v[172:175], v[198:201], v[102:105]
	v_mfma_f32_16x16x32_bf16 v[94:97], v[182:185], v[198:201], v[94:97]
	v_mfma_f32_16x16x32_bf16 v[86:89], v[172:175], v[206:209], v[86:89]
	v_mfma_f32_16x16x32_bf16 v[78:81], v[182:185], v[206:209], v[78:81]
	v_mfma_f32_16x16x32_bf16 v[70:73], v[172:175], v[214:217], v[70:73]
	v_mfma_f32_16x16x32_bf16 v[66:69], v[182:185], v[214:217], v[66:69]
	s_setprio 0
	s_barrier
	s_mov_b32 m0, s29
	v_lshl_add_u64 v[218:219], s[14:15], 0, v[134:135]
	s_add_u32 s40, s14, 0x40000
	ds_read_b128 v[186:189], v148 offset:16384
	ds_read_b128 v[190:193], v148 offset:17408
	ds_read_b128 v[194:197], v148 offset:18432
	ds_read_b128 v[198:201], v148 offset:19456
	ds_read_b128 v[202:205], v148 offset:20480
	ds_read_b128 v[206:209], v148 offset:21504
	ds_read_b128 v[210:213], v148 offset:22528
	ds_read_b128 v[214:217], v148 offset:23552
	global_load_lds_dwordx4 v[218:219], off
	v_lshl_add_u64 v[220:221], s[14:15], 0, v[130:131]
	s_mov_b32 m0, s30
	s_addc_u32 s41, s15, 0
	global_load_lds_dwordx4 v[220:221], off
	v_lshl_add_u64 v[222:223], s[40:41], 0, v[134:135]
	s_mov_b32 m0, s31
	v_lshl_add_u64 v[224:225], s[2:3], 0, v[132:133]
	global_load_lds_dwordx4 v[222:223], off
	v_lshl_add_u64 v[222:223], s[40:41], 0, v[130:131]
	s_mov_b32 m0, s34
	s_nop 0
	global_load_lds_dwordx4 v[222:223], off
	v_lshl_add_u64 v[222:223], s[2:3], 0, v[136:137]
	s_mov_b32 m0, s18
	s_nop 0
	global_load_lds_dwordx4 v[222:223], off
	s_mov_b32 m0, s1
	s_nop 0
	global_load_lds_dwordx4 v[224:225], off
	s_waitcnt vmcnt(8)
	s_waitcnt lgkmcnt(0)
	s_setprio 1
	s_barrier
	s_waitcnt lgkmcnt(0)
	v_mfma_f32_16x16x32_bf16 v[62:65], v[152:155], v[186:189], v[62:65]
	v_mfma_f32_16x16x32_bf16 v[58:61], v[160:163], v[186:189], v[58:61]
	v_mfma_f32_16x16x32_bf16 v[50:53], v[152:155], v[194:197], v[50:53]
	v_mfma_f32_16x16x32_bf16 v[42:45], v[160:163], v[194:197], v[42:45]
	v_mfma_f32_16x16x32_bf16 v[34:37], v[152:155], v[202:205], v[34:37]
	v_mfma_f32_16x16x32_bf16 v[26:29], v[160:163], v[202:205], v[26:29]
	v_mfma_f32_16x16x32_bf16 v[18:21], v[152:155], v[210:213], v[18:21]
	v_mfma_f32_16x16x32_bf16 v[10:13], v[160:163], v[210:213], v[10:13]
	v_mfma_f32_16x16x32_bf16 v[62:65], v[156:159], v[190:193], v[62:65]
	v_mfma_f32_16x16x32_bf16 v[58:61], v[164:167], v[190:193], v[58:61]
	v_mfma_f32_16x16x32_bf16 v[50:53], v[156:159], v[198:201], v[50:53]
	v_mfma_f32_16x16x32_bf16 v[42:45], v[164:167], v[198:201], v[42:45]
	v_mfma_f32_16x16x32_bf16 v[34:37], v[156:159], v[206:209], v[34:37]
	v_mfma_f32_16x16x32_bf16 v[26:29], v[164:167], v[206:209], v[26:29]
	v_mfma_f32_16x16x32_bf16 v[18:21], v[156:159], v[214:217], v[18:21]
	v_mfma_f32_16x16x32_bf16 v[10:13], v[164:167], v[214:217], v[10:13]
	s_setprio 0
	s_setprio 1
	v_mfma_f32_16x16x32_bf16 v[54:57], v[168:171], v[186:189], v[54:57]
	v_mfma_f32_16x16x32_bf16 v[46:49], v[178:181], v[186:189], v[46:49]
	v_mfma_f32_16x16x32_bf16 v[38:41], v[168:171], v[194:197], v[38:41]
	v_mfma_f32_16x16x32_bf16 v[30:33], v[178:181], v[194:197], v[30:33]
	v_mfma_f32_16x16x32_bf16 v[22:25], v[168:171], v[202:205], v[22:25]
	v_mfma_f32_16x16x32_bf16 v[14:17], v[178:181], v[202:205], v[14:17]
	v_mfma_f32_16x16x32_bf16 v[6:9], v[168:171], v[210:213], v[6:9]
	v_mfma_f32_16x16x32_bf16 v[2:5], v[178:181], v[210:213], v[2:5]
	v_mfma_f32_16x16x32_bf16 v[54:57], v[172:175], v[190:193], v[54:57]
	v_mfma_f32_16x16x32_bf16 v[46:49], v[182:185], v[190:193], v[46:49]
	v_mfma_f32_16x16x32_bf16 v[38:41], v[172:175], v[198:201], v[38:41]
	v_mfma_f32_16x16x32_bf16 v[30:33], v[182:185], v[198:201], v[30:33]
	v_mfma_f32_16x16x32_bf16 v[22:25], v[172:175], v[206:209], v[22:25]
	v_mfma_f32_16x16x32_bf16 v[14:17], v[182:185], v[206:209], v[14:17]
	v_mfma_f32_16x16x32_bf16 v[6:9], v[172:175], v[214:217], v[6:9]
	v_mfma_f32_16x16x32_bf16 v[2:5], v[182:185], v[214:217], v[2:5]
	s_setprio 0
	s_barrier
	ds_read_b128 v[152:155], v149
	ds_read_b128 v[156:159], v149 offset:1024
	ds_read_b128 v[160:163], v149 offset:2048
	ds_read_b128 v[164:167], v149 offset:3072
	ds_read_b128 v[168:171], v150
	ds_read_b128 v[172:175], v150 offset:1024
	ds_read_b128 v[178:181], v150 offset:2048
	ds_read_b128 v[182:185], v150 offset:3072
	s_add_u32 s2, s2, 0x40000
	s_addc_u32 s3, s3, 0
	s_mov_b32 m0, s19
	v_lshl_add_u64 v[226:227], s[2:3], 0, v[136:137]
	ds_read_b128 v[186:189], v148 offset:32768
	ds_read_b128 v[190:193], v148 offset:33792
	ds_read_b128 v[194:197], v148 offset:34816
	ds_read_b128 v[198:201], v148 offset:35840
	ds_read_b128 v[202:205], v148 offset:36864
	ds_read_b128 v[206:209], v148 offset:37888
	ds_read_b128 v[210:213], v148 offset:38912
	ds_read_b128 v[214:217], v148 offset:39936
	global_load_lds_dwordx4 v[226:227], off
	v_lshl_add_u64 v[226:227], s[2:3], 0, v[132:133]
	s_mov_b32 m0, s20
	s_nop 0
	global_load_lds_dwordx4 v[226:227], off
	s_waitcnt vmcnt(8)
	s_waitcnt lgkmcnt(0)
	s_setprio 1
	s_barrier
	s_waitcnt lgkmcnt(0)
	v_mfma_f32_16x16x32_bf16 v[126:129], v[152:155], v[186:189], v[126:129]
	v_mfma_f32_16x16x32_bf16 v[122:125], v[160:163], v[186:189], v[122:125]
	v_mfma_f32_16x16x32_bf16 v[114:117], v[152:155], v[194:197], v[114:117]
	v_mfma_f32_16x16x32_bf16 v[106:109], v[160:163], v[194:197], v[106:109]
	v_mfma_f32_16x16x32_bf16 v[98:101], v[152:155], v[202:205], v[98:101]
	v_mfma_f32_16x16x32_bf16 v[90:93], v[160:163], v[202:205], v[90:93]
	v_mfma_f32_16x16x32_bf16 v[82:85], v[152:155], v[210:213], v[82:85]
	v_mfma_f32_16x16x32_bf16 v[74:77], v[160:163], v[210:213], v[74:77]
	v_mfma_f32_16x16x32_bf16 v[126:129], v[156:159], v[190:193], v[126:129]
	v_mfma_f32_16x16x32_bf16 v[122:125], v[164:167], v[190:193], v[122:125]
	v_mfma_f32_16x16x32_bf16 v[114:117], v[156:159], v[198:201], v[114:117]
	v_mfma_f32_16x16x32_bf16 v[106:109], v[164:167], v[198:201], v[106:109]
	v_mfma_f32_16x16x32_bf16 v[98:101], v[156:159], v[206:209], v[98:101]
	v_mfma_f32_16x16x32_bf16 v[90:93], v[164:167], v[206:209], v[90:93]
	v_mfma_f32_16x16x32_bf16 v[82:85], v[156:159], v[214:217], v[82:85]
	v_mfma_f32_16x16x32_bf16 v[74:77], v[164:167], v[214:217], v[74:77]
	s_setprio 0
	s_setprio 1
	v_mfma_f32_16x16x32_bf16 v[118:121], v[168:171], v[186:189], v[118:121]
	v_mfma_f32_16x16x32_bf16 v[110:113], v[178:181], v[186:189], v[110:113]
	v_mfma_f32_16x16x32_bf16 v[102:105], v[168:171], v[194:197], v[102:105]
	v_mfma_f32_16x16x32_bf16 v[94:97], v[178:181], v[194:197], v[94:97]
	v_mfma_f32_16x16x32_bf16 v[86:89], v[168:171], v[202:205], v[86:89]
	v_mfma_f32_16x16x32_bf16 v[78:81], v[178:181], v[202:205], v[78:81]
	v_mfma_f32_16x16x32_bf16 v[70:73], v[168:171], v[210:213], v[70:73]
	v_mfma_f32_16x16x32_bf16 v[66:69], v[178:181], v[210:213], v[66:69]
	v_mfma_f32_16x16x32_bf16 v[118:121], v[172:175], v[190:193], v[118:121]
	v_mfma_f32_16x16x32_bf16 v[110:113], v[182:185], v[190:193], v[110:113]
	v_mfma_f32_16x16x32_bf16 v[102:105], v[172:175], v[198:201], v[102:105]
	v_mfma_f32_16x16x32_bf16 v[94:97], v[182:185], v[198:201], v[94:97]
	v_mfma_f32_16x16x32_bf16 v[86:89], v[172:175], v[206:209], v[86:89]
	v_mfma_f32_16x16x32_bf16 v[78:81], v[182:185], v[206:209], v[78:81]
	v_mfma_f32_16x16x32_bf16 v[70:73], v[172:175], v[214:217], v[70:73]
	v_mfma_f32_16x16x32_bf16 v[66:69], v[182:185], v[214:217], v[66:69]
	s_setprio 0
	s_barrier
	s_mov_b32 m0, s35
	v_lshl_add_u64 v[218:219], v[218:219], 0, s[8:9]
	s_add_u32 s2, s14, 0x40080
	ds_read_b128 v[186:189], v148 offset:49152
	ds_read_b128 v[190:193], v148 offset:50176
	ds_read_b128 v[194:197], v148 offset:51200
	ds_read_b128 v[198:201], v148 offset:52224
	ds_read_b128 v[202:205], v148 offset:53248
	ds_read_b128 v[206:209], v148 offset:54272
	ds_read_b128 v[210:213], v148 offset:55296
	ds_read_b128 v[214:217], v148 offset:56320
	global_load_lds_dwordx4 v[218:219], off
	v_lshl_add_u64 v[218:219], v[220:221], 0, s[8:9]
	s_mov_b32 m0, s36
	s_addc_u32 s3, s15, 0
	global_load_lds_dwordx4 v[218:219], off
	v_lshl_add_u64 v[218:219], s[2:3], 0, v[134:135]
	s_mov_b32 m0, s37
	s_nop 0
	global_load_lds_dwordx4 v[218:219], off
	v_lshl_add_u64 v[218:219], s[2:3], 0, v[130:131]
	s_mov_b32 m0, s38
	s_nop 0
	global_load_lds_dwordx4 v[218:219], off
	v_lshl_add_u64 v[218:219], v[222:223], 0, s[8:9]
	s_mov_b32 m0, s22
	s_nop 0
	global_load_lds_dwordx4 v[218:219], off
	v_lshl_add_u64 v[218:219], v[224:225], 0, s[8:9]
	s_mov_b32 m0, s23
	s_nop 0
	global_load_lds_dwordx4 v[218:219], off
	s_waitcnt vmcnt(8)
	s_waitcnt lgkmcnt(0)
	s_setprio 1
	s_barrier
	s_waitcnt lgkmcnt(0)
	v_mfma_f32_16x16x32_bf16 v[62:65], v[152:155], v[186:189], v[62:65]
	v_mfma_f32_16x16x32_bf16 v[58:61], v[160:163], v[186:189], v[58:61]
	v_mfma_f32_16x16x32_bf16 v[50:53], v[152:155], v[194:197], v[50:53]
	v_mfma_f32_16x16x32_bf16 v[42:45], v[160:163], v[194:197], v[42:45]
	v_mfma_f32_16x16x32_bf16 v[34:37], v[152:155], v[202:205], v[34:37]
	v_mfma_f32_16x16x32_bf16 v[26:29], v[160:163], v[202:205], v[26:29]
	v_mfma_f32_16x16x32_bf16 v[18:21], v[152:155], v[210:213], v[18:21]
	v_mfma_f32_16x16x32_bf16 v[10:13], v[160:163], v[210:213], v[10:13]
	v_mfma_f32_16x16x32_bf16 v[62:65], v[156:159], v[190:193], v[62:65]
	v_mfma_f32_16x16x32_bf16 v[58:61], v[164:167], v[190:193], v[58:61]
	v_mfma_f32_16x16x32_bf16 v[50:53], v[156:159], v[198:201], v[50:53]
	v_mfma_f32_16x16x32_bf16 v[42:45], v[164:167], v[198:201], v[42:45]
	v_mfma_f32_16x16x32_bf16 v[34:37], v[156:159], v[206:209], v[34:37]
	v_mfma_f32_16x16x32_bf16 v[26:29], v[164:167], v[206:209], v[26:29]
	v_mfma_f32_16x16x32_bf16 v[18:21], v[156:159], v[214:217], v[18:21]
	v_mfma_f32_16x16x32_bf16 v[10:13], v[164:167], v[214:217], v[10:13]
	s_setprio 0
	s_setprio 1
	v_mfma_f32_16x16x32_bf16 v[54:57], v[168:171], v[186:189], v[54:57]
	v_mfma_f32_16x16x32_bf16 v[46:49], v[178:181], v[186:189], v[46:49]
	v_mfma_f32_16x16x32_bf16 v[38:41], v[168:171], v[194:197], v[38:41]
	v_mfma_f32_16x16x32_bf16 v[30:33], v[178:181], v[194:197], v[30:33]
	v_mfma_f32_16x16x32_bf16 v[22:25], v[168:171], v[202:205], v[22:25]
	v_mfma_f32_16x16x32_bf16 v[14:17], v[178:181], v[202:205], v[14:17]
	v_mfma_f32_16x16x32_bf16 v[6:9], v[168:171], v[210:213], v[6:9]
	v_mfma_f32_16x16x32_bf16 v[2:5], v[178:181], v[210:213], v[2:5]
	v_mfma_f32_16x16x32_bf16 v[54:57], v[172:175], v[190:193], v[54:57]
	v_mfma_f32_16x16x32_bf16 v[46:49], v[182:185], v[190:193], v[46:49]
	v_mfma_f32_16x16x32_bf16 v[38:41], v[172:175], v[198:201], v[38:41]
	v_mfma_f32_16x16x32_bf16 v[30:33], v[182:185], v[198:201], v[30:33]
	v_mfma_f32_16x16x32_bf16 v[22:25], v[172:175], v[206:209], v[22:25]
	v_mfma_f32_16x16x32_bf16 v[14:17], v[182:185], v[206:209], v[14:17]
	v_mfma_f32_16x16x32_bf16 v[6:9], v[172:175], v[214:217], v[6:9]
	v_mfma_f32_16x16x32_bf16 v[2:5], v[182:185], v[214:217], v[2:5]
	s_setprio 0
	s_barrier
	s_add_i32 s26, s26, 2
	s_add_u32 s12, s12, 0x100
	s_addc_u32 s13, s13, 0
	s_cmp_gt_u32 s26, 13
	s_cbranch_scc0 .LBB0_646
	s_cmpk_lt_u32 s16, 0x100
	s_mov_b32 s28, s33
	v_readlane_b32 s30, v253, 58
	s_cbranch_scc0 .LBB0_649
	s_barrier

.Lpk1098_peel:
	ds_read_b128 v[152:155], v148
	ds_read_b128 v[156:159], v148 offset:1024
	ds_read_b128 v[160:163], v148 offset:2048
	ds_read_b128 v[164:167], v148 offset:3072
	ds_read_b128 v[168:171], v149
	ds_read_b128 v[172:175], v149 offset:1024
	ds_read_b128 v[178:181], v149 offset:2048
	ds_read_b128 v[182:185], v149 offset:3072
	s_add_u32 s2, s30, 0xfffc0080
	s_addc_u32 s3, s31, -1
	s_cmp_eq_u32 s56, 12
	s_cselect_b32 s3, s15, s3
	s_cselect_b32 s2, s17, s2
	s_cselect_b32 s35, s52, s55
	s_cselect_b32 s34, s53, s54
	v_lshl_add_u64 v[144:145], s[30:31], 0, v[138:139]
	s_add_i32 m0, s40, 0xc000
	ds_read_b128 v[186:189], v150
	ds_read_b128 v[190:193], v150 offset:1024
	ds_read_b128 v[194:197], v150 offset:2048
	ds_read_b128 v[198:201], v150 offset:3072
	ds_read_b128 v[202:205], v150 offset:4096
	ds_read_b128 v[206:209], v150 offset:5120
	ds_read_b128 v[210:213], v150 offset:6144
	ds_read_b128 v[214:217], v150 offset:7168
	global_load_lds_dwordx4 v[144:145], off
	v_lshl_add_u64 v[144:145], s[30:31], 0, v[140:141]
	s_add_i32 m0, s40, 0xe000
	s_nop 0
	global_load_lds_dwordx4 v[144:145], off
	s_waitcnt vmcnt(8)
	s_waitcnt lgkmcnt(0)
	s_setprio 1
	s_barrier
	s_waitcnt lgkmcnt(0)
	v_mfma_f32_16x16x32_bf16 v[126:129], v[152:155], v[186:189], 0
	v_mfma_f32_16x16x32_bf16 v[122:125], v[160:163], v[186:189], 0
	v_mfma_f32_16x16x32_bf16 v[114:117], v[152:155], v[194:197], 0
	v_mfma_f32_16x16x32_bf16 v[106:109], v[160:163], v[194:197], 0
	v_mfma_f32_16x16x32_bf16 v[98:101], v[152:155], v[202:205], 0
	v_mfma_f32_16x16x32_bf16 v[90:93], v[160:163], v[202:205], 0
	v_mfma_f32_16x16x32_bf16 v[82:85], v[152:155], v[210:213], 0
	v_mfma_f32_16x16x32_bf16 v[74:77], v[160:163], v[210:213], 0
	v_mfma_f32_16x16x32_bf16 v[126:129], v[156:159], v[190:193], v[126:129]
	v_mfma_f32_16x16x32_bf16 v[122:125], v[164:167], v[190:193], v[122:125]
	v_mfma_f32_16x16x32_bf16 v[114:117], v[156:159], v[198:201], v[114:117]
	v_mfma_f32_16x16x32_bf16 v[106:109], v[164:167], v[198:201], v[106:109]
	v_mfma_f32_16x16x32_bf16 v[98:101], v[156:159], v[206:209], v[98:101]
	v_mfma_f32_16x16x32_bf16 v[90:93], v[164:167], v[206:209], v[90:93]
	v_mfma_f32_16x16x32_bf16 v[82:85], v[156:159], v[214:217], v[82:85]
	v_mfma_f32_16x16x32_bf16 v[74:77], v[164:167], v[214:217], v[74:77]
	s_setprio 0
	s_setprio 1
	v_mfma_f32_16x16x32_bf16 v[118:121], v[168:171], v[186:189], 0
	v_mfma_f32_16x16x32_bf16 v[110:113], v[178:181], v[186:189], 0
	v_mfma_f32_16x16x32_bf16 v[102:105], v[168:171], v[194:197], 0
	v_mfma_f32_16x16x32_bf16 v[94:97], v[178:181], v[194:197], 0
	v_mfma_f32_16x16x32_bf16 v[86:89], v[168:171], v[202:205], 0
	v_mfma_f32_16x16x32_bf16 v[78:81], v[178:181], v[202:205], 0
	v_mfma_f32_16x16x32_bf16 v[70:73], v[168:171], v[210:213], 0
	v_mfma_f32_16x16x32_bf16 v[66:69], v[178:181], v[210:213], 0
	v_mfma_f32_16x16x32_bf16 v[118:121], v[172:175], v[190:193], v[118:121]
	v_mfma_f32_16x16x32_bf16 v[110:113], v[182:185], v[190:193], v[110:113]
	v_mfma_f32_16x16x32_bf16 v[102:105], v[172:175], v[198:201], v[102:105]
	v_mfma_f32_16x16x32_bf16 v[94:97], v[182:185], v[198:201], v[94:97]
	v_mfma_f32_16x16x32_bf16 v[86:89], v[172:175], v[206:209], v[86:89]
	v_mfma_f32_16x16x32_bf16 v[78:81], v[182:185], v[206:209], v[78:81]
	v_mfma_f32_16x16x32_bf16 v[70:73], v[172:175], v[214:217], v[70:73]
	v_mfma_f32_16x16x32_bf16 v[66:69], v[182:185], v[214:217], v[66:69]
	s_setprio 0
	s_barrier
	s_add_i32 s57, s47, s39
	v_lshl_add_u64 v[144:145], s[34:35], 0, v[132:133]
	s_mov_b32 m0, s57
	ds_read_b128 v[186:189], v150 offset:16384
	ds_read_b128 v[190:193], v150 offset:17408
	ds_read_b128 v[194:197], v150 offset:18432
	ds_read_b128 v[198:201], v150 offset:19456
	ds_read_b128 v[202:205], v150 offset:20480
	ds_read_b128 v[206:209], v150 offset:21504
	ds_read_b128 v[210:213], v150 offset:22528
	ds_read_b128 v[214:217], v150 offset:23552
	global_load_lds_dwordx4 v[144:145], off
	s_add_i32 m0, s57, 0x2000
	s_add_u32 s58, s34, 0x40000
	v_lshl_add_u64 v[218:219], s[34:35], 0, v[136:137]
	s_addc_u32 s59, s35, 0
	s_add_i32 s57, s48, s39
	global_load_lds_dwordx4 v[218:219], off
	v_lshl_add_u64 v[220:221], s[58:59], 0, v[132:133]
	s_mov_b32 m0, s57
	v_lshl_add_u64 v[222:223], s[2:3], 0, v[134:135]
	global_load_lds_dwordx4 v[220:221], off
	v_lshl_add_u64 v[220:221], s[58:59], 0, v[136:137]
	s_add_i32 m0, s57, 0x2000
	s_nop 0
	global_load_lds_dwordx4 v[220:221], off
	v_lshl_add_u64 v[220:221], s[2:3], 0, v[130:131]
	s_mov_b32 m0, s40
	s_nop 0
	global_load_lds_dwordx4 v[220:221], off
	s_mov_b32 m0, s29
	s_nop 0
	global_load_lds_dwordx4 v[222:223], off
	s_waitcnt vmcnt(8)
	s_waitcnt lgkmcnt(0)
	s_setprio 1
	s_barrier
	s_waitcnt lgkmcnt(0)
	v_mfma_f32_16x16x32_bf16 v[62:65], v[152:155], v[186:189], 0
	v_mfma_f32_16x16x32_bf16 v[58:61], v[160:163], v[186:189], 0
	v_mfma_f32_16x16x32_bf16 v[50:53], v[152:155], v[194:197], 0
	v_mfma_f32_16x16x32_bf16 v[42:45], v[160:163], v[194:197], 0
	v_mfma_f32_16x16x32_bf16 v[34:37], v[152:155], v[202:205], 0
	v_mfma_f32_16x16x32_bf16 v[26:29], v[160:163], v[202:205], 0
	v_mfma_f32_16x16x32_bf16 v[18:21], v[152:155], v[210:213], 0
	v_mfma_f32_16x16x32_bf16 v[10:13], v[160:163], v[210:213], 0
	v_mfma_f32_16x16x32_bf16 v[62:65], v[156:159], v[190:193], v[62:65]
	v_mfma_f32_16x16x32_bf16 v[58:61], v[164:167], v[190:193], v[58:61]
	v_mfma_f32_16x16x32_bf16 v[50:53], v[156:159], v[198:201], v[50:53]
	v_mfma_f32_16x16x32_bf16 v[42:45], v[164:167], v[198:201], v[42:45]
	v_mfma_f32_16x16x32_bf16 v[34:37], v[156:159], v[206:209], v[34:37]
	v_mfma_f32_16x16x32_bf16 v[26:29], v[164:167], v[206:209], v[26:29]
	v_mfma_f32_16x16x32_bf16 v[18:21], v[156:159], v[214:217], v[18:21]
	v_mfma_f32_16x16x32_bf16 v[10:13], v[164:167], v[214:217], v[10:13]
	s_setprio 0
	s_setprio 1
	v_mfma_f32_16x16x32_bf16 v[54:57], v[168:171], v[186:189], 0
	v_mfma_f32_16x16x32_bf16 v[46:49], v[178:181], v[186:189], 0
	v_mfma_f32_16x16x32_bf16 v[38:41], v[168:171], v[194:197], 0
	v_mfma_f32_16x16x32_bf16 v[30:33], v[178:181], v[194:197], 0
	v_mfma_f32_16x16x32_bf16 v[22:25], v[168:171], v[202:205], 0
	v_mfma_f32_16x16x32_bf16 v[14:17], v[178:181], v[202:205], 0
	v_mfma_f32_16x16x32_bf16 v[6:9], v[168:171], v[210:213], 0
	v_mfma_f32_16x16x32_bf16 v[2:5], v[178:181], v[210:213], 0
	v_mfma_f32_16x16x32_bf16 v[54:57], v[172:175], v[190:193], v[54:57]
	v_mfma_f32_16x16x32_bf16 v[46:49], v[182:185], v[190:193], v[46:49]
	v_mfma_f32_16x16x32_bf16 v[38:41], v[172:175], v[198:201], v[38:41]
	v_mfma_f32_16x16x32_bf16 v[30:33], v[182:185], v[198:201], v[30:33]
	v_mfma_f32_16x16x32_bf16 v[22:25], v[172:175], v[206:209], v[22:25]
	v_mfma_f32_16x16x32_bf16 v[14:17], v[182:185], v[206:209], v[14:17]
	v_mfma_f32_16x16x32_bf16 v[6:9], v[172:175], v[214:217], v[6:9]
	v_mfma_f32_16x16x32_bf16 v[2:5], v[182:185], v[214:217], v[2:5]
	s_setprio 0
	s_barrier
	s_add_i32 s57, 0, 0x18000
	v_add_u32_e32 v151, s57, v146
	s_add_i32 s58, 0, 0x1c000
	ds_read_b128 v[152:155], v151
	ds_read_b128 v[156:159], v151 offset:1024
	ds_read_b128 v[160:163], v151 offset:2048
	ds_read_b128 v[164:167], v151 offset:3072
	v_add_u32_e32 v151, s58, v146
	ds_read_b128 v[168:171], v151
	ds_read_b128 v[172:175], v151 offset:1024
	ds_read_b128 v[178:181], v151 offset:2048
	ds_read_b128 v[182:185], v151 offset:3072
	s_add_u32 s2, s2, 0x40000
	s_addc_u32 s3, s3, 0
	s_mov_b32 m0, s41
	v_lshl_add_u64 v[224:225], s[2:3], 0, v[130:131]
	ds_read_b128 v[186:189], v150 offset:32768
	ds_read_b128 v[190:193], v150 offset:33792
	ds_read_b128 v[194:197], v150 offset:34816
	ds_read_b128 v[198:201], v150 offset:35840
	ds_read_b128 v[202:205], v150 offset:36864
	ds_read_b128 v[206:209], v150 offset:37888
	ds_read_b128 v[210:213], v150 offset:38912
	ds_read_b128 v[214:217], v150 offset:39936
	global_load_lds_dwordx4 v[224:225], off
	v_lshl_add_u64 v[224:225], s[2:3], 0, v[134:135]
	s_mov_b32 m0, s42
	s_nop 0
	global_load_lds_dwordx4 v[224:225], off
	s_waitcnt vmcnt(8)
	s_waitcnt lgkmcnt(0)
	s_setprio 1
	s_barrier
	s_waitcnt lgkmcnt(0)
	v_mfma_f32_16x16x32_bf16 v[126:129], v[152:155], v[186:189], v[126:129]
	v_mfma_f32_16x16x32_bf16 v[122:125], v[160:163], v[186:189], v[122:125]
	v_mfma_f32_16x16x32_bf16 v[114:117], v[152:155], v[194:197], v[114:117]
	v_mfma_f32_16x16x32_bf16 v[106:109], v[160:163], v[194:197], v[106:109]
	v_mfma_f32_16x16x32_bf16 v[98:101], v[152:155], v[202:205], v[98:101]
	v_mfma_f32_16x16x32_bf16 v[90:93], v[160:163], v[202:205], v[90:93]
	v_mfma_f32_16x16x32_bf16 v[82:85], v[152:155], v[210:213], v[82:85]
	v_mfma_f32_16x16x32_bf16 v[74:77], v[160:163], v[210:213], v[74:77]
	v_mfma_f32_16x16x32_bf16 v[126:129], v[156:159], v[190:193], v[126:129]
	v_mfma_f32_16x16x32_bf16 v[122:125], v[164:167], v[190:193], v[122:125]
	v_mfma_f32_16x16x32_bf16 v[114:117], v[156:159], v[198:201], v[114:117]
	v_mfma_f32_16x16x32_bf16 v[106:109], v[164:167], v[198:201], v[106:109]
	v_mfma_f32_16x16x32_bf16 v[98:101], v[156:159], v[206:209], v[98:101]
	v_mfma_f32_16x16x32_bf16 v[90:93], v[164:167], v[206:209], v[90:93]
	v_mfma_f32_16x16x32_bf16 v[82:85], v[156:159], v[214:217], v[82:85]
	v_mfma_f32_16x16x32_bf16 v[74:77], v[164:167], v[214:217], v[74:77]
	s_setprio 0
	s_setprio 1
	v_mfma_f32_16x16x32_bf16 v[118:121], v[168:171], v[186:189], v[118:121]
	v_mfma_f32_16x16x32_bf16 v[110:113], v[178:181], v[186:189], v[110:113]
	v_mfma_f32_16x16x32_bf16 v[102:105], v[168:171], v[194:197], v[102:105]
	v_mfma_f32_16x16x32_bf16 v[94:97], v[178:181], v[194:197], v[94:97]
	v_mfma_f32_16x16x32_bf16 v[86:89], v[168:171], v[202:205], v[86:89]
	v_mfma_f32_16x16x32_bf16 v[78:81], v[178:181], v[202:205], v[78:81]
	v_mfma_f32_16x16x32_bf16 v[70:73], v[168:171], v[210:213], v[70:73]
	v_mfma_f32_16x16x32_bf16 v[66:69], v[178:181], v[210:213], v[66:69]
	v_mfma_f32_16x16x32_bf16 v[118:121], v[172:175], v[190:193], v[118:121]
	v_mfma_f32_16x16x32_bf16 v[110:113], v[182:185], v[190:193], v[110:113]
	v_mfma_f32_16x16x32_bf16 v[102:105], v[172:175], v[198:201], v[102:105]
	v_mfma_f32_16x16x32_bf16 v[94:97], v[182:185], v[198:201], v[94:97]
	v_mfma_f32_16x16x32_bf16 v[86:89], v[172:175], v[206:209], v[86:89]
	v_mfma_f32_16x16x32_bf16 v[78:81], v[182:185], v[206:209], v[78:81]
	v_mfma_f32_16x16x32_bf16 v[70:73], v[172:175], v[214:217], v[70:73]
	v_mfma_f32_16x16x32_bf16 v[66:69], v[182:185], v[214:217], v[66:69]
	s_setprio 0
	s_barrier
	s_add_i32 s2, s57, s39
	v_lshl_add_u64 v[144:145], v[144:145], 0, s[6:7]
	s_mov_b32 m0, s2
	ds_read_b128 v[186:189], v150 offset:49152
	ds_read_b128 v[190:193], v150 offset:50176
	ds_read_b128 v[194:197], v150 offset:51200
	ds_read_b128 v[198:201], v150 offset:52224
	ds_read_b128 v[202:205], v150 offset:53248
	ds_read_b128 v[206:209], v150 offset:54272
	ds_read_b128 v[210:213], v150 offset:55296
	ds_read_b128 v[214:217], v150 offset:56320
	global_load_lds_dwordx4 v[144:145], off
	s_add_i32 m0, s2, 0x2000
	s_add_u32 s2, s34, 0x40080
	v_lshl_add_u64 v[144:145], v[218:219], 0, s[6:7]
	s_addc_u32 s3, s35, 0
	s_add_i32 s34, s58, s39
	global_load_lds_dwordx4 v[144:145], off
	v_lshl_add_u64 v[144:145], s[2:3], 0, v[132:133]
	s_mov_b32 m0, s34
	s_nop 0
	global_load_lds_dwordx4 v[144:145], off
	v_lshl_add_u64 v[144:145], s[2:3], 0, v[136:137]
	s_add_i32 m0, s34, 0x2000
	s_nop 0
	global_load_lds_dwordx4 v[144:145], off
	v_lshl_add_u64 v[144:145], v[220:221], 0, s[6:7]
	s_mov_b32 m0, s44
	s_nop 0
	global_load_lds_dwordx4 v[144:145], off
	v_lshl_add_u64 v[144:145], v[222:223], 0, s[6:7]
	s_mov_b32 m0, s45
	s_nop 0
	global_load_lds_dwordx4 v[144:145], off
	s_waitcnt vmcnt(8)
	s_waitcnt lgkmcnt(0)
	s_setprio 1
	s_barrier
	s_waitcnt lgkmcnt(0)
	v_mfma_f32_16x16x32_bf16 v[62:65], v[152:155], v[186:189], v[62:65]
	v_mfma_f32_16x16x32_bf16 v[58:61], v[160:163], v[186:189], v[58:61]
	v_mfma_f32_16x16x32_bf16 v[50:53], v[152:155], v[194:197], v[50:53]
	v_mfma_f32_16x16x32_bf16 v[42:45], v[160:163], v[194:197], v[42:45]
	v_mfma_f32_16x16x32_bf16 v[34:37], v[152:155], v[202:205], v[34:37]
	v_mfma_f32_16x16x32_bf16 v[26:29], v[160:163], v[202:205], v[26:29]
	v_mfma_f32_16x16x32_bf16 v[18:21], v[152:155], v[210:213], v[18:21]
	v_mfma_f32_16x16x32_bf16 v[10:13], v[160:163], v[210:213], v[10:13]
	v_mfma_f32_16x16x32_bf16 v[62:65], v[156:159], v[190:193], v[62:65]
	v_mfma_f32_16x16x32_bf16 v[58:61], v[164:167], v[190:193], v[58:61]
	v_mfma_f32_16x16x32_bf16 v[50:53], v[156:159], v[198:201], v[50:53]
	v_mfma_f32_16x16x32_bf16 v[42:45], v[164:167], v[198:201], v[42:45]
	v_mfma_f32_16x16x32_bf16 v[34:37], v[156:159], v[206:209], v[34:37]
	v_mfma_f32_16x16x32_bf16 v[26:29], v[164:167], v[206:209], v[26:29]
	v_mfma_f32_16x16x32_bf16 v[18:21], v[156:159], v[214:217], v[18:21]
	v_mfma_f32_16x16x32_bf16 v[10:13], v[164:167], v[214:217], v[10:13]
	s_setprio 0
	s_setprio 1
	v_mfma_f32_16x16x32_bf16 v[54:57], v[168:171], v[186:189], v[54:57]
	v_mfma_f32_16x16x32_bf16 v[46:49], v[178:181], v[186:189], v[46:49]
	v_mfma_f32_16x16x32_bf16 v[38:41], v[168:171], v[194:197], v[38:41]
	v_mfma_f32_16x16x32_bf16 v[30:33], v[178:181], v[194:197], v[30:33]
	v_mfma_f32_16x16x32_bf16 v[22:25], v[168:171], v[202:205], v[22:25]
	v_mfma_f32_16x16x32_bf16 v[14:17], v[178:181], v[202:205], v[14:17]
	v_mfma_f32_16x16x32_bf16 v[6:9], v[168:171], v[210:213], v[6:9]
	v_mfma_f32_16x16x32_bf16 v[2:5], v[178:181], v[210:213], v[2:5]
	v_mfma_f32_16x16x32_bf16 v[54:57], v[172:175], v[190:193], v[54:57]
	v_mfma_f32_16x16x32_bf16 v[46:49], v[182:185], v[190:193], v[46:49]
	v_mfma_f32_16x16x32_bf16 v[38:41], v[172:175], v[198:201], v[38:41]
	v_mfma_f32_16x16x32_bf16 v[30:33], v[182:185], v[198:201], v[30:33]
	v_mfma_f32_16x16x32_bf16 v[22:25], v[172:175], v[206:209], v[22:25]
	v_mfma_f32_16x16x32_bf16 v[14:17], v[182:185], v[206:209], v[14:17]
	v_mfma_f32_16x16x32_bf16 v[6:9], v[172:175], v[214:217], v[6:9]
	v_mfma_f32_16x16x32_bf16 v[2:5], v[182:185], v[214:217], v[2:5]
	s_setprio 0
	s_barrier
	s_add_i32 s56, s56, 2
	s_add_u32 s30, s30, 0x100
	s_addc_u32 s31, s31, 0
	s_add_u32 s54, s54, 0x100
	s_addc_u32 s55, s55, 0
	s_cmp_gt_u32 s56, 13
	s_cbranch_scc0 .LBB0_1098
	s_branch .Lpk1098_exit
.LBB0_1098:
	ds_read_b128 v[152:155], v148
	ds_read_b128 v[156:159], v148 offset:1024
	ds_read_b128 v[160:163], v148 offset:2048
	ds_read_b128 v[164:167], v148 offset:3072
	ds_read_b128 v[168:171], v149
	ds_read_b128 v[172:175], v149 offset:1024
	ds_read_b128 v[178:181], v149 offset:2048
	ds_read_b128 v[182:185], v149 offset:3072
	s_add_u32 s2, s30, 0xfffc0080
	s_addc_u32 s3, s31, -1
	s_cmp_eq_u32 s56, 12
	s_cselect_b32 s3, s15, s3
	s_cselect_b32 s2, s17, s2
	s_cselect_b32 s35, s52, s55
	s_cselect_b32 s34, s53, s54
	v_lshl_add_u64 v[144:145], s[30:31], 0, v[138:139]
	s_add_i32 m0, s40, 0xc000
	ds_read_b128 v[186:189], v150
	ds_read_b128 v[190:193], v150 offset:1024
	ds_read_b128 v[194:197], v150 offset:2048
	ds_read_b128 v[198:201], v150 offset:3072
	ds_read_b128 v[202:205], v150 offset:4096
	ds_read_b128 v[206:209], v150 offset:5120
	ds_read_b128 v[210:213], v150 offset:6144
	ds_read_b128 v[214:217], v150 offset:7168
	global_load_lds_dwordx4 v[144:145], off
	v_lshl_add_u64 v[144:145], s[30:31], 0, v[140:141]
	s_add_i32 m0, s40, 0xe000
	s_nop 0
	global_load_lds_dwordx4 v[144:145], off
	s_waitcnt vmcnt(8)
	s_waitcnt lgkmcnt(0)
	s_setprio 1
	s_barrier
	s_waitcnt lgkmcnt(0)
	v_mfma_f32_16x16x32_bf16 v[126:129], v[152:155], v[186:189], v[126:129]
	v_mfma_f32_16x16x32_bf16 v[122:125], v[160:163], v[186:189], v[122:125]
	v_mfma_f32_16x16x32_bf16 v[114:117], v[152:155], v[194:197], v[114:117]
	v_mfma_f32_16x16x32_bf16 v[106:109], v[160:163], v[194:197], v[106:109]
	v_mfma_f32_16x16x32_bf16 v[98:101], v[152:155], v[202:205], v[98:101]
	v_mfma_f32_16x16x32_bf16 v[90:93], v[160:163], v[202:205], v[90:93]
	v_mfma_f32_16x16x32_bf16 v[82:85], v[152:155], v[210:213], v[82:85]
	v_mfma_f32_16x16x32_bf16 v[74:77], v[160:163], v[210:213], v[74:77]
	v_mfma_f32_16x16x32_bf16 v[126:129], v[156:159], v[190:193], v[126:129]
	v_mfma_f32_16x16x32_bf16 v[122:125], v[164:167], v[190:193], v[122:125]
	v_mfma_f32_16x16x32_bf16 v[114:117], v[156:159], v[198:201], v[114:117]
	v_mfma_f32_16x16x32_bf16 v[106:109], v[164:167], v[198:201], v[106:109]
	v_mfma_f32_16x16x32_bf16 v[98:101], v[156:159], v[206:209], v[98:101]
	v_mfma_f32_16x16x32_bf16 v[90:93], v[164:167], v[206:209], v[90:93]
	v_mfma_f32_16x16x32_bf16 v[82:85], v[156:159], v[214:217], v[82:85]
	v_mfma_f32_16x16x32_bf16 v[74:77], v[164:167], v[214:217], v[74:77]
	s_setprio 0
	s_setprio 1
	v_mfma_f32_16x16x32_bf16 v[118:121], v[168:171], v[186:189], v[118:121]
	v_mfma_f32_16x16x32_bf16 v[110:113], v[178:181], v[186:189], v[110:113]
	v_mfma_f32_16x16x32_bf16 v[102:105], v[168:171], v[194:197], v[102:105]
	v_mfma_f32_16x16x32_bf16 v[94:97], v[178:181], v[194:197], v[94:97]
	v_mfma_f32_16x16x32_bf16 v[86:89], v[168:171], v[202:205], v[86:89]
	v_mfma_f32_16x16x32_bf16 v[78:81], v[178:181], v[202:205], v[78:81]
	v_mfma_f32_16x16x32_bf16 v[70:73], v[168:171], v[210:213], v[70:73]
	v_mfma_f32_16x16x32_bf16 v[66:69], v[178:181], v[210:213], v[66:69]
	v_mfma_f32_16x16x32_bf16 v[118:121], v[172:175], v[190:193], v[118:121]
	v_mfma_f32_16x16x32_bf16 v[110:113], v[182:185], v[190:193], v[110:113]
	v_mfma_f32_16x16x32_bf16 v[102:105], v[172:175], v[198:201], v[102:105]
	v_mfma_f32_16x16x32_bf16 v[94:97], v[182:185], v[198:201], v[94:97]
	v_mfma_f32_16x16x32_bf16 v[86:89], v[172:175], v[206:209], v[86:89]
	v_mfma_f32_16x16x32_bf16 v[78:81], v[182:185], v[206:209], v[78:81]
	v_mfma_f32_16x16x32_bf16 v[70:73], v[172:175], v[214:217], v[70:73]
	v_mfma_f32_16x16x32_bf16 v[66:69], v[182:185], v[214:217], v[66:69]
	s_setprio 0
	s_barrier
	s_add_i32 s57, s47, s39
	v_lshl_add_u64 v[144:145], s[34:35], 0, v[132:133]
	s_mov_b32 m0, s57
	ds_read_b128 v[186:189], v150 offset:16384
	ds_read_b128 v[190:193], v150 offset:17408
	ds_read_b128 v[194:197], v150 offset:18432
	ds_read_b128 v[198:201], v150 offset:19456
	ds_read_b128 v[202:205], v150 offset:20480
	ds_read_b128 v[206:209], v150 offset:21504
	ds_read_b128 v[210:213], v150 offset:22528
	ds_read_b128 v[214:217], v150 offset:23552
	global_load_lds_dwordx4 v[144:145], off
	s_add_i32 m0, s57, 0x2000
	s_add_u32 s58, s34, 0x40000
	v_lshl_add_u64 v[218:219], s[34:35], 0, v[136:137]
	s_addc_u32 s59, s35, 0
	s_add_i32 s57, s48, s39
	global_load_lds_dwordx4 v[218:219], off
	v_lshl_add_u64 v[220:221], s[58:59], 0, v[132:133]
	s_mov_b32 m0, s57
	v_lshl_add_u64 v[222:223], s[2:3], 0, v[134:135]
	global_load_lds_dwordx4 v[220:221], off
	v_lshl_add_u64 v[220:221], s[58:59], 0, v[136:137]
	s_add_i32 m0, s57, 0x2000
	s_nop 0
	global_load_lds_dwordx4 v[220:221], off
	v_lshl_add_u64 v[220:221], s[2:3], 0, v[130:131]
	s_mov_b32 m0, s40
	s_nop 0
	global_load_lds_dwordx4 v[220:221], off
	s_mov_b32 m0, s29
	s_nop 0
	global_load_lds_dwordx4 v[222:223], off
	s_waitcnt vmcnt(8)
	s_waitcnt lgkmcnt(0)
	s_setprio 1
	s_barrier
	s_waitcnt lgkmcnt(0)
	v_mfma_f32_16x16x32_bf16 v[62:65], v[152:155], v[186:189], v[62:65]
	v_mfma_f32_16x16x32_bf16 v[58:61], v[160:163], v[186:189], v[58:61]
	v_mfma_f32_16x16x32_bf16 v[50:53], v[152:155], v[194:197], v[50:53]
	v_mfma_f32_16x16x32_bf16 v[42:45], v[160:163], v[194:197], v[42:45]
	v_mfma_f32_16x16x32_bf16 v[34:37], v[152:155], v[202:205], v[34:37]
	v_mfma_f32_16x16x32_bf16 v[26:29], v[160:163], v[202:205], v[26:29]
	v_mfma_f32_16x16x32_bf16 v[18:21], v[152:155], v[210:213], v[18:21]
	v_mfma_f32_16x16x32_bf16 v[10:13], v[160:163], v[210:213], v[10:13]
	v_mfma_f32_16x16x32_bf16 v[62:65], v[156:159], v[190:193], v[62:65]
	v_mfma_f32_16x16x32_bf16 v[58:61], v[164:167], v[190:193], v[58:61]
	v_mfma_f32_16x16x32_bf16 v[50:53], v[156:159], v[198:201], v[50:53]
	v_mfma_f32_16x16x32_bf16 v[42:45], v[164:167], v[198:201], v[42:45]
	v_mfma_f32_16x16x32_bf16 v[34:37], v[156:159], v[206:209], v[34:37]
	v_mfma_f32_16x16x32_bf16 v[26:29], v[164:167], v[206:209], v[26:29]
	v_mfma_f32_16x16x32_bf16 v[18:21], v[156:159], v[214:217], v[18:21]
	v_mfma_f32_16x16x32_bf16 v[10:13], v[164:167], v[214:217], v[10:13]
	s_setprio 0
	s_setprio 1
	v_mfma_f32_16x16x32_bf16 v[54:57], v[168:171], v[186:189], v[54:57]
	v_mfma_f32_16x16x32_bf16 v[46:49], v[178:181], v[186:189], v[46:49]
	v_mfma_f32_16x16x32_bf16 v[38:41], v[168:171], v[194:197], v[38:41]
	v_mfma_f32_16x16x32_bf16 v[30:33], v[178:181], v[194:197], v[30:33]
	v_mfma_f32_16x16x32_bf16 v[22:25], v[168:171], v[202:205], v[22:25]
	v_mfma_f32_16x16x32_bf16 v[14:17], v[178:181], v[202:205], v[14:17]
	v_mfma_f32_16x16x32_bf16 v[6:9], v[168:171], v[210:213], v[6:9]
	v_mfma_f32_16x16x32_bf16 v[2:5], v[178:181], v[210:213], v[2:5]
	v_mfma_f32_16x16x32_bf16 v[54:57], v[172:175], v[190:193], v[54:57]
	v_mfma_f32_16x16x32_bf16 v[46:49], v[182:185], v[190:193], v[46:49]
	v_mfma_f32_16x16x32_bf16 v[38:41], v[172:175], v[198:201], v[38:41]
	v_mfma_f32_16x16x32_bf16 v[30:33], v[182:185], v[198:201], v[30:33]
	v_mfma_f32_16x16x32_bf16 v[22:25], v[172:175], v[206:209], v[22:25]
	v_mfma_f32_16x16x32_bf16 v[14:17], v[182:185], v[206:209], v[14:17]
	v_mfma_f32_16x16x32_bf16 v[6:9], v[172:175], v[214:217], v[6:9]
	v_mfma_f32_16x16x32_bf16 v[2:5], v[182:185], v[214:217], v[2:5]
	s_setprio 0
	s_barrier
	s_add_i32 s57, 0, 0x18000
	v_add_u32_e32 v151, s57, v146
	s_add_i32 s58, 0, 0x1c000
	ds_read_b128 v[152:155], v151
	ds_read_b128 v[156:159], v151 offset:1024
	ds_read_b128 v[160:163], v151 offset:2048
	ds_read_b128 v[164:167], v151 offset:3072
	v_add_u32_e32 v151, s58, v146
	ds_read_b128 v[168:171], v151
	ds_read_b128 v[172:175], v151 offset:1024
	ds_read_b128 v[178:181], v151 offset:2048
	ds_read_b128 v[182:185], v151 offset:3072
	s_add_u32 s2, s2, 0x40000
	s_addc_u32 s3, s3, 0
	s_mov_b32 m0, s41
	v_lshl_add_u64 v[224:225], s[2:3], 0, v[130:131]
	ds_read_b128 v[186:189], v150 offset:32768
	ds_read_b128 v[190:193], v150 offset:33792
	ds_read_b128 v[194:197], v150 offset:34816
	ds_read_b128 v[198:201], v150 offset:35840
	ds_read_b128 v[202:205], v150 offset:36864
	ds_read_b128 v[206:209], v150 offset:37888
	ds_read_b128 v[210:213], v150 offset:38912
	ds_read_b128 v[214:217], v150 offset:39936
	global_load_lds_dwordx4 v[224:225], off
	v_lshl_add_u64 v[224:225], s[2:3], 0, v[134:135]
	s_mov_b32 m0, s42
	s_nop 0
	global_load_lds_dwordx4 v[224:225], off
	s_waitcnt vmcnt(8)
	s_waitcnt lgkmcnt(0)
	s_setprio 1
	s_barrier
	s_waitcnt lgkmcnt(0)
	v_mfma_f32_16x16x32_bf16 v[126:129], v[152:155], v[186:189], v[126:129]
	v_mfma_f32_16x16x32_bf16 v[122:125], v[160:163], v[186:189], v[122:125]
	v_mfma_f32_16x16x32_bf16 v[114:117], v[152:155], v[194:197], v[114:117]
	v_mfma_f32_16x16x32_bf16 v[106:109], v[160:163], v[194:197], v[106:109]
	v_mfma_f32_16x16x32_bf16 v[98:101], v[152:155], v[202:205], v[98:101]
	v_mfma_f32_16x16x32_bf16 v[90:93], v[160:163], v[202:205], v[90:93]
	v_mfma_f32_16x16x32_bf16 v[82:85], v[152:155], v[210:213], v[82:85]
	v_mfma_f32_16x16x32_bf16 v[74:77], v[160:163], v[210:213], v[74:77]
	v_mfma_f32_16x16x32_bf16 v[126:129], v[156:159], v[190:193], v[126:129]
	v_mfma_f32_16x16x32_bf16 v[122:125], v[164:167], v[190:193], v[122:125]
	v_mfma_f32_16x16x32_bf16 v[114:117], v[156:159], v[198:201], v[114:117]
	v_mfma_f32_16x16x32_bf16 v[106:109], v[164:167], v[198:201], v[106:109]
	v_mfma_f32_16x16x32_bf16 v[98:101], v[156:159], v[206:209], v[98:101]
	v_mfma_f32_16x16x32_bf16 v[90:93], v[164:167], v[206:209], v[90:93]
	v_mfma_f32_16x16x32_bf16 v[82:85], v[156:159], v[214:217], v[82:85]
	v_mfma_f32_16x16x32_bf16 v[74:77], v[164:167], v[214:217], v[74:77]
	s_setprio 0
	s_setprio 1
	v_mfma_f32_16x16x32_bf16 v[118:121], v[168:171], v[186:189], v[118:121]
	v_mfma_f32_16x16x32_bf16 v[110:113], v[178:181], v[186:189], v[110:113]
	v_mfma_f32_16x16x32_bf16 v[102:105], v[168:171], v[194:197], v[102:105]
	v_mfma_f32_16x16x32_bf16 v[94:97], v[178:181], v[194:197], v[94:97]
	v_mfma_f32_16x16x32_bf16 v[86:89], v[168:171], v[202:205], v[86:89]
	v_mfma_f32_16x16x32_bf16 v[78:81], v[178:181], v[202:205], v[78:81]
	v_mfma_f32_16x16x32_bf16 v[70:73], v[168:171], v[210:213], v[70:73]
	v_mfma_f32_16x16x32_bf16 v[66:69], v[178:181], v[210:213], v[66:69]
	v_mfma_f32_16x16x32_bf16 v[118:121], v[172:175], v[190:193], v[118:121]
	v_mfma_f32_16x16x32_bf16 v[110:113], v[182:185], v[190:193], v[110:113]
	v_mfma_f32_16x16x32_bf16 v[102:105], v[172:175], v[198:201], v[102:105]
	v_mfma_f32_16x16x32_bf16 v[94:97], v[182:185], v[198:201], v[94:97]
	v_mfma_f32_16x16x32_bf16 v[86:89], v[172:175], v[206:209], v[86:89]
	v_mfma_f32_16x16x32_bf16 v[78:81], v[182:185], v[206:209], v[78:81]
	v_mfma_f32_16x16x32_bf16 v[70:73], v[172:175], v[214:217], v[70:73]
	v_mfma_f32_16x16x32_bf16 v[66:69], v[182:185], v[214:217], v[66:69]
	s_setprio 0
	s_barrier
	s_add_i32 s2, s57, s39
	v_lshl_add_u64 v[144:145], v[144:145], 0, s[6:7]
	s_mov_b32 m0, s2
	ds_read_b128 v[186:189], v150 offset:49152
	ds_read_b128 v[190:193], v150 offset:50176
	ds_read_b128 v[194:197], v150 offset:51200
	ds_read_b128 v[198:201], v150 offset:52224
	ds_read_b128 v[202:205], v150 offset:53248
	ds_read_b128 v[206:209], v150 offset:54272
	ds_read_b128 v[210:213], v150 offset:55296
	ds_read_b128 v[214:217], v150 offset:56320
	global_load_lds_dwordx4 v[144:145], off
	s_add_i32 m0, s2, 0x2000
	s_add_u32 s2, s34, 0x40080
	v_lshl_add_u64 v[144:145], v[218:219], 0, s[6:7]
	s_addc_u32 s3, s35, 0
	s_add_i32 s34, s58, s39
	global_load_lds_dwordx4 v[144:145], off
	v_lshl_add_u64 v[144:145], s[2:3], 0, v[132:133]
	s_mov_b32 m0, s34
	s_nop 0
	global_load_lds_dwordx4 v[144:145], off
	v_lshl_add_u64 v[144:145], s[2:3], 0, v[136:137]
	s_add_i32 m0, s34, 0x2000
	s_nop 0
	global_load_lds_dwordx4 v[144:145], off
	v_lshl_add_u64 v[144:145], v[220:221], 0, s[6:7]
	s_mov_b32 m0, s44
	s_nop 0
	global_load_lds_dwordx4 v[144:145], off
	v_lshl_add_u64 v[144:145], v[222:223], 0, s[6:7]
	s_mov_b32 m0, s45
	s_nop 0
	global_load_lds_dwordx4 v[144:145], off
	s_waitcnt vmcnt(8)
	s_waitcnt lgkmcnt(0)
	s_setprio 1
	s_barrier
	s_waitcnt lgkmcnt(0)
	v_mfma_f32_16x16x32_bf16 v[62:65], v[152:155], v[186:189], v[62:65]
	v_mfma_f32_16x16x32_bf16 v[58:61], v[160:163], v[186:189], v[58:61]
	v_mfma_f32_16x16x32_bf16 v[50:53], v[152:155], v[194:197], v[50:53]
	v_mfma_f32_16x16x32_bf16 v[42:45], v[160:163], v[194:197], v[42:45]
	v_mfma_f32_16x16x32_bf16 v[34:37], v[152:155], v[202:205], v[34:37]
	v_mfma_f32_16x16x32_bf16 v[26:29], v[160:163], v[202:205], v[26:29]
	v_mfma_f32_16x16x32_bf16 v[18:21], v[152:155], v[210:213], v[18:21]
	v_mfma_f32_16x16x32_bf16 v[10:13], v[160:163], v[210:213], v[10:13]
	v_mfma_f32_16x16x32_bf16 v[62:65], v[156:159], v[190:193], v[62:65]
	v_mfma_f32_16x16x32_bf16 v[58:61], v[164:167], v[190:193], v[58:61]
	v_mfma_f32_16x16x32_bf16 v[50:53], v[156:159], v[198:201], v[50:53]
	v_mfma_f32_16x16x32_bf16 v[42:45], v[164:167], v[198:201], v[42:45]
	v_mfma_f32_16x16x32_bf16 v[34:37], v[156:159], v[206:209], v[34:37]
	v_mfma_f32_16x16x32_bf16 v[26:29], v[164:167], v[206:209], v[26:29]
	v_mfma_f32_16x16x32_bf16 v[18:21], v[156:159], v[214:217], v[18:21]
	v_mfma_f32_16x16x32_bf16 v[10:13], v[164:167], v[214:217], v[10:13]
	s_setprio 0
	s_setprio 1
	v_mfma_f32_16x16x32_bf16 v[54:57], v[168:171], v[186:189], v[54:57]
	v_mfma_f32_16x16x32_bf16 v[46:49], v[178:181], v[186:189], v[46:49]
	v_mfma_f32_16x16x32_bf16 v[38:41], v[168:171], v[194:197], v[38:41]
	v_mfma_f32_16x16x32_bf16 v[30:33], v[178:181], v[194:197], v[30:33]
	v_mfma_f32_16x16x32_bf16 v[22:25], v[168:171], v[202:205], v[22:25]
	v_mfma_f32_16x16x32_bf16 v[14:17], v[178:181], v[202:205], v[14:17]
	v_mfma_f32_16x16x32_bf16 v[6:9], v[168:171], v[210:213], v[6:9]
	v_mfma_f32_16x16x32_bf16 v[2:5], v[178:181], v[210:213], v[2:5]
	v_mfma_f32_16x16x32_bf16 v[54:57], v[172:175], v[190:193], v[54:57]
	v_mfma_f32_16x16x32_bf16 v[46:49], v[182:185], v[190:193], v[46:49]
	v_mfma_f32_16x16x32_bf16 v[38:41], v[172:175], v[198:201], v[38:41]
	v_mfma_f32_16x16x32_bf16 v[30:33], v[182:185], v[198:201], v[30:33]
	v_mfma_f32_16x16x32_bf16 v[22:25], v[172:175], v[206:209], v[22:25]
	v_mfma_f32_16x16x32_bf16 v[14:17], v[182:185], v[206:209], v[14:17]
	v_mfma_f32_16x16x32_bf16 v[6:9], v[172:175], v[214:217], v[6:9]
	v_mfma_f32_16x16x32_bf16 v[2:5], v[182:185], v[214:217], v[2:5]
	s_setprio 0
	s_barrier
	s_add_i32 s56, s56, 2
	s_add_u32 s30, s30, 0x100
	s_addc_u32 s31, s31, 0
	s_add_u32 s54, s54, 0x100
	s_addc_u32 s55, s55, 0
	s_cmp_gt_u32 s56, 13
	s_cbranch_scc0 .LBB0_1098

.LBB0_1137:
	s_add_i32 s26, 0, 0x18000
	s_add_i32 s3, s26, s18
	s_mov_b64 s[24:25], 0x80
	v_lshl_add_u64 v[4:5], v[26:27], 0, s[24:25]
	s_mov_b32 m0, s3
	s_add_i32 s5, s3, 0x2000
	s_waitcnt vmcnt(2)
	s_barrier
	global_load_lds_dwordx4 v[4:5], off
	v_lshl_add_u64 v[6:7], v[28:29], 0, s[24:25]
	s_mov_b32 m0, s5
	s_add_i32 s4, s15, 0x8000
	global_load_lds_dwordx4 v[6:7], off
	v_lshl_add_u64 v[2:3], v[20:21], 0, s[24:25]
	s_mov_b32 m0, s4
	s_add_i32 s9, s15, 0xa000
	s_add_i32 s27, 0, 0x1c000
	global_load_lds_dwordx4 v[2:3], off
	v_lshl_add_u64 v[8:9], v[22:23], 0, s[24:25]
	s_mov_b32 m0, s9
	s_add_i32 s13, s27, s18
	global_load_lds_dwordx4 v[8:9], off
	v_lshl_add_u64 v[10:11], v[24:25], 0, s[24:25]
	s_mov_b32 m0, s13
	s_add_i32 s14, s13, 0x2000
	global_load_lds_dwordx4 v[10:11], off
	v_lshl_add_u64 v[12:13], v[18:19], 0, s[24:25]
	s_mov_b32 m0, s14
	v_and_b32_e32 v30, 15, v0
	global_load_lds_dwordx4 v[12:13], off
	v_lshlrev_b32_e32 v31, 1, v1
	v_lshlrev_b32_e32 v32, 2, v0
	v_lshl_or_b32 v130, s17, 6, v30
	v_lshl_or_b32 v30, v30, 6, v31
	s_lshl_b32 s2, s17, 13
	v_and_b32_e32 v32, 32, v32
	v_bitop3_b32 v62, v30, s2, v32 bitop3:0xde
	s_lshl_b32 s2, s19, 5
	s_and_b32 s2, s2, 0x60
	v_lshlrev_b32_e32 v30, 6, v0
	s_movk_i32 s17, 0x3c0
	v_and_or_b32 v30, v30, s17, v31
	s_lshl_b32 s17, s2, 7
	v_bitop3_b32 v63, s17, v30, v32 bitop3:0xf6
	s_add_i32 s29, 0, 0x10000
	s_add_i32 s28, 0, 0x14000
	v_add_u32_e32 v176, s29, v63
	s_waitcnt vmcnt(6)
	s_barrier
	v_add_u32_e32 v131, s28, v63
	ds_read_b128 v[30:33], v176
	ds_read_b128 v[34:37], v176 offset:1024
	ds_read_b128 v[38:41], v176 offset:2048
	ds_read_b128 v[42:45], v176 offset:3072
	ds_read_b128 v[46:49], v131
	ds_read_b128 v[50:53], v131 offset:1024
	ds_read_b128 v[54:57], v131 offset:2048
	ds_read_b128 v[58:61], v131 offset:3072
	s_add_i32 s20, s29, s18
	s_add_i32 s18, s28, s18
	s_add_i32 s22, s15, 0xc000
	s_add_i32 s21, s15, 0xe000
	s_add_i32 s19, s20, 0x2000
	s_add_i32 s17, s18, 0x2000
	s_cmpk_gt_u32 s23, 0xff
	v_add_u32_e32 v242, 0, v62
	v_add_u32_e32 v238, s27, v63
	v_add_u32_e32 v239, s26, v63
	s_mov_b32 m0, s22
	v_lshl_add_u64 v[94:95], v[14:15], 0, s[24:25]
	ds_read_b128 v[62:65], v242
	ds_read_b128 v[66:69], v242 offset:1024
	ds_read_b128 v[70:73], v242 offset:2048
	ds_read_b128 v[74:77], v242 offset:3072
	ds_read_b128 v[78:81], v242 offset:4096
	ds_read_b128 v[82:85], v242 offset:5120
	ds_read_b128 v[86:89], v242 offset:6144
	ds_read_b128 v[90:93], v242 offset:7168
	global_load_lds_dwordx4 v[94:95], off
	v_lshl_add_u64 v[94:95], v[16:17], 0, s[24:25]
	s_mov_b32 m0, s21
	s_nop 0
	global_load_lds_dwordx4 v[94:95], off
	s_waitcnt vmcnt(8)
	s_waitcnt lgkmcnt(0)
	s_setprio 1
	s_barrier
	s_waitcnt lgkmcnt(0)
	v_mfma_f32_16x16x32_bf16 v[94:97], v[30:33], v[62:65], 0
	v_mfma_f32_16x16x32_bf16 v[98:101], v[38:41], v[62:65], 0
	v_mfma_f32_16x16x32_bf16 v[102:105], v[30:33], v[70:73], 0
	v_mfma_f32_16x16x32_bf16 v[106:109], v[38:41], v[70:73], 0
	v_mfma_f32_16x16x32_bf16 v[110:113], v[30:33], v[78:81], 0
	v_mfma_f32_16x16x32_bf16 v[114:117], v[38:41], v[78:81], 0
	v_mfma_f32_16x16x32_bf16 v[118:121], v[30:33], v[86:89], 0
	v_mfma_f32_16x16x32_bf16 v[122:125], v[38:41], v[86:89], 0
	v_mfma_f32_16x16x32_bf16 v[94:97], v[34:37], v[66:69], v[94:97]
	v_mfma_f32_16x16x32_bf16 v[98:101], v[42:45], v[66:69], v[98:101]
	v_mfma_f32_16x16x32_bf16 v[102:105], v[34:37], v[74:77], v[102:105]
	v_mfma_f32_16x16x32_bf16 v[106:109], v[42:45], v[74:77], v[106:109]
	v_mfma_f32_16x16x32_bf16 v[110:113], v[34:37], v[82:85], v[110:113]
	v_mfma_f32_16x16x32_bf16 v[114:117], v[42:45], v[82:85], v[114:117]
	v_mfma_f32_16x16x32_bf16 v[118:121], v[34:37], v[90:93], v[118:121]
	v_mfma_f32_16x16x32_bf16 v[122:125], v[42:45], v[90:93], v[122:125]
	s_setprio 0
	s_setprio 1
	v_mfma_f32_16x16x32_bf16 v[126:129], v[46:49], v[62:65], 0
	v_mfma_f32_16x16x32_bf16 v[62:65], v[54:57], v[62:65], 0
	v_mfma_f32_16x16x32_bf16 v[126:129], v[50:53], v[66:69], v[126:129]
	v_mfma_f32_16x16x32_bf16 v[62:65], v[58:61], v[66:69], v[62:65]
	v_mfma_f32_16x16x32_bf16 v[66:69], v[46:49], v[70:73], 0
	v_mfma_f32_16x16x32_bf16 v[70:73], v[54:57], v[70:73], 0
	v_mfma_f32_16x16x32_bf16 v[66:69], v[50:53], v[74:77], v[66:69]
	v_mfma_f32_16x16x32_bf16 v[70:73], v[58:61], v[74:77], v[70:73]
	v_mfma_f32_16x16x32_bf16 v[74:77], v[46:49], v[78:81], 0
	v_mfma_f32_16x16x32_bf16 v[78:81], v[54:57], v[78:81], 0
	v_mfma_f32_16x16x32_bf16 v[74:77], v[50:53], v[82:85], v[74:77]
	v_mfma_f32_16x16x32_bf16 v[78:81], v[58:61], v[82:85], v[78:81]
	v_mfma_f32_16x16x32_bf16 v[82:85], v[46:49], v[86:89], 0
	v_mfma_f32_16x16x32_bf16 v[86:89], v[54:57], v[86:89], 0
	v_mfma_f32_16x16x32_bf16 v[82:85], v[50:53], v[90:93], v[82:85]
	v_mfma_f32_16x16x32_bf16 v[86:89], v[58:61], v[90:93], v[86:89]
	s_setprio 0
	s_barrier
	s_mov_b64 s[24:25], 0x100
	s_mov_b32 m0, s20
	v_lshl_add_u64 v[160:161], v[26:27], 0, s[24:25]
	ds_read_b128 v[90:93], v242 offset:16384
	ds_read_b128 v[132:135], v242 offset:17408
	ds_read_b128 v[136:139], v242 offset:18432
	ds_read_b128 v[140:143], v242 offset:19456
	ds_read_b128 v[144:147], v242 offset:20480
	ds_read_b128 v[148:151], v242 offset:21504
	ds_read_b128 v[152:155], v242 offset:22528
	ds_read_b128 v[156:159], v242 offset:23552
	global_load_lds_dwordx4 v[160:161], off
	v_lshl_add_u64 v[160:161], v[28:29], 0, s[24:25]
	s_mov_b32 m0, s19
	s_nop 0
	global_load_lds_dwordx4 v[160:161], off
	v_lshl_add_u64 v[160:161], v[24:25], 0, s[24:25]
	s_mov_b32 m0, s18
	s_nop 0
	global_load_lds_dwordx4 v[160:161], off
	v_lshl_add_u64 v[160:161], v[18:19], 0, s[24:25]
	s_mov_b32 m0, s17
	s_nop 0
	global_load_lds_dwordx4 v[160:161], off
	v_lshl_add_u64 v[160:161], v[20:21], 0, s[24:25]
	s_mov_b32 m0, s15
	s_nop 0
	global_load_lds_dwordx4 v[160:161], off
	v_lshl_add_u64 v[160:161], v[22:23], 0, s[24:25]
	s_mov_b32 m0, s16
	s_nop 0
	global_load_lds_dwordx4 v[160:161], off
	s_waitcnt vmcnt(8)
	s_waitcnt lgkmcnt(0)
	s_setprio 1
	s_barrier
	s_waitcnt lgkmcnt(0)
	v_mfma_f32_16x16x32_bf16 v[160:163], v[30:33], v[90:93], 0
	v_mfma_f32_16x16x32_bf16 v[168:171], v[30:33], v[136:139], 0
	v_mfma_f32_16x16x32_bf16 v[178:181], v[30:33], v[144:147], 0
	v_mfma_f32_16x16x32_bf16 v[30:33], v[30:33], v[152:155], 0
	v_mfma_f32_16x16x32_bf16 v[160:163], v[34:37], v[132:135], v[160:163]
	v_mfma_f32_16x16x32_bf16 v[168:171], v[34:37], v[140:143], v[168:171]
	v_mfma_f32_16x16x32_bf16 v[178:181], v[34:37], v[148:151], v[178:181]
	v_mfma_f32_16x16x32_bf16 v[30:33], v[34:37], v[156:159], v[30:33]
	v_mfma_f32_16x16x32_bf16 v[34:37], v[38:41], v[152:155], 0
	v_mfma_f32_16x16x32_bf16 v[164:167], v[38:41], v[90:93], 0
	v_mfma_f32_16x16x32_bf16 v[172:175], v[38:41], v[136:139], 0
	v_mfma_f32_16x16x32_bf16 v[182:185], v[38:41], v[144:147], 0
	v_mfma_f32_16x16x32_bf16 v[34:37], v[42:45], v[156:159], v[34:37]
	v_mfma_f32_16x16x32_bf16 v[164:167], v[42:45], v[132:135], v[164:167]
	v_mfma_f32_16x16x32_bf16 v[172:175], v[42:45], v[140:143], v[172:175]
	v_mfma_f32_16x16x32_bf16 v[182:185], v[42:45], v[148:151], v[182:185]
	s_setprio 0
	s_setprio 1
	v_mfma_f32_16x16x32_bf16 v[38:41], v[46:49], v[90:93], 0
	v_mfma_f32_16x16x32_bf16 v[42:45], v[54:57], v[90:93], 0
	v_mfma_f32_16x16x32_bf16 v[38:41], v[50:53], v[132:135], v[38:41]
	v_mfma_f32_16x16x32_bf16 v[42:45], v[58:61], v[132:135], v[42:45]
	v_mfma_f32_16x16x32_bf16 v[90:93], v[46:49], v[136:139], 0
	v_mfma_f32_16x16x32_bf16 v[132:135], v[54:57], v[136:139], 0
	v_mfma_f32_16x16x32_bf16 v[136:139], v[46:49], v[144:147], 0
	v_mfma_f32_16x16x32_bf16 v[46:49], v[46:49], v[152:155], 0
	v_mfma_f32_16x16x32_bf16 v[90:93], v[50:53], v[140:143], v[90:93]
	v_mfma_f32_16x16x32_bf16 v[136:139], v[50:53], v[148:151], v[136:139]
	v_mfma_f32_16x16x32_bf16 v[46:49], v[50:53], v[156:159], v[46:49]
	v_mfma_f32_16x16x32_bf16 v[50:53], v[54:57], v[152:155], 0
	v_mfma_f32_16x16x32_bf16 v[132:135], v[58:61], v[140:143], v[132:135]
	v_mfma_f32_16x16x32_bf16 v[140:143], v[54:57], v[144:147], 0
	v_mfma_f32_16x16x32_bf16 v[50:53], v[58:61], v[156:159], v[50:53]
	v_mfma_f32_16x16x32_bf16 v[140:143], v[58:61], v[148:151], v[140:143]
	s_setprio 0
	s_barrier
	ds_read_b128 v[54:57], v239
	ds_read_b128 v[58:61], v239 offset:1024
	ds_read_b128 v[144:147], v239 offset:2048
	ds_read_b128 v[148:151], v239 offset:3072
	ds_read_b128 v[152:155], v238
	ds_read_b128 v[156:159], v238 offset:1024
	ds_read_b128 v[186:189], v238 offset:2048
	ds_read_b128 v[190:193], v238 offset:3072
	s_mov_b32 m0, s11
	v_lshl_add_u64 v[226:227], v[14:15], 0, s[24:25]
	ds_read_b128 v[194:197], v242 offset:32768
	ds_read_b128 v[198:201], v242 offset:33792
	ds_read_b128 v[202:205], v242 offset:34816
	ds_read_b128 v[206:209], v242 offset:35840
	ds_read_b128 v[210:213], v242 offset:36864
	ds_read_b128 v[214:217], v242 offset:37888
	ds_read_b128 v[218:221], v242 offset:38912
	ds_read_b128 v[222:225], v242 offset:39936
	global_load_lds_dwordx4 v[226:227], off
	v_lshl_add_u64 v[226:227], v[16:17], 0, s[24:25]
	s_mov_b32 m0, s12
	s_nop 0
	global_load_lds_dwordx4 v[226:227], off
	s_waitcnt vmcnt(8)
	s_waitcnt lgkmcnt(0)
	s_setprio 1
	s_barrier
	s_waitcnt lgkmcnt(0)
	v_mfma_f32_16x16x32_bf16 v[94:97], v[54:57], v[194:197], v[94:97]
	v_mfma_f32_16x16x32_bf16 v[98:101], v[144:147], v[194:197], v[98:101]
	v_mfma_f32_16x16x32_bf16 v[102:105], v[54:57], v[202:205], v[102:105]
	v_mfma_f32_16x16x32_bf16 v[106:109], v[144:147], v[202:205], v[106:109]
	v_mfma_f32_16x16x32_bf16 v[110:113], v[54:57], v[210:213], v[110:113]
	v_mfma_f32_16x16x32_bf16 v[114:117], v[144:147], v[210:213], v[114:117]
	v_mfma_f32_16x16x32_bf16 v[118:121], v[54:57], v[218:221], v[118:121]
	v_mfma_f32_16x16x32_bf16 v[122:125], v[144:147], v[218:221], v[122:125]
	v_mfma_f32_16x16x32_bf16 v[94:97], v[58:61], v[198:201], v[94:97]
	v_mfma_f32_16x16x32_bf16 v[98:101], v[148:151], v[198:201], v[98:101]
	v_mfma_f32_16x16x32_bf16 v[102:105], v[58:61], v[206:209], v[102:105]
	v_mfma_f32_16x16x32_bf16 v[106:109], v[148:151], v[206:209], v[106:109]
	v_mfma_f32_16x16x32_bf16 v[110:113], v[58:61], v[214:217], v[110:113]
	v_mfma_f32_16x16x32_bf16 v[114:117], v[148:151], v[214:217], v[114:117]
	v_mfma_f32_16x16x32_bf16 v[118:121], v[58:61], v[222:225], v[118:121]
	v_mfma_f32_16x16x32_bf16 v[122:125], v[148:151], v[222:225], v[122:125]
	s_setprio 0
	s_setprio 1
	v_mfma_f32_16x16x32_bf16 v[126:129], v[152:155], v[194:197], v[126:129]
	v_mfma_f32_16x16x32_bf16 v[62:65], v[186:189], v[194:197], v[62:65]
	v_mfma_f32_16x16x32_bf16 v[66:69], v[152:155], v[202:205], v[66:69]
	v_mfma_f32_16x16x32_bf16 v[70:73], v[186:189], v[202:205], v[70:73]
	v_mfma_f32_16x16x32_bf16 v[74:77], v[152:155], v[210:213], v[74:77]
	v_mfma_f32_16x16x32_bf16 v[78:81], v[186:189], v[210:213], v[78:81]
	v_mfma_f32_16x16x32_bf16 v[82:85], v[152:155], v[218:221], v[82:85]
	v_mfma_f32_16x16x32_bf16 v[86:89], v[186:189], v[218:221], v[86:89]
	v_mfma_f32_16x16x32_bf16 v[126:129], v[156:159], v[198:201], v[126:129]
	v_mfma_f32_16x16x32_bf16 v[62:65], v[190:193], v[198:201], v[62:65]
	v_mfma_f32_16x16x32_bf16 v[66:69], v[156:159], v[206:209], v[66:69]
	v_mfma_f32_16x16x32_bf16 v[70:73], v[190:193], v[206:209], v[70:73]
	v_mfma_f32_16x16x32_bf16 v[74:77], v[156:159], v[214:217], v[74:77]
	v_mfma_f32_16x16x32_bf16 v[78:81], v[190:193], v[214:217], v[78:81]
	v_mfma_f32_16x16x32_bf16 v[82:85], v[156:159], v[222:225], v[82:85]
	v_mfma_f32_16x16x32_bf16 v[86:89], v[190:193], v[222:225], v[86:89]
	s_setprio 0
	s_barrier
	s_mov_b64 s[24:25], 0x180
	s_mov_b32 m0, s3
	v_lshl_add_u64 v[226:227], v[26:27], 0, s[24:25]
	ds_read_b128 v[194:197], v242 offset:49152
	ds_read_b128 v[198:201], v242 offset:50176
	ds_read_b128 v[202:205], v242 offset:51200
	ds_read_b128 v[206:209], v242 offset:52224
	ds_read_b128 v[210:213], v242 offset:53248
	ds_read_b128 v[214:217], v242 offset:54272
	ds_read_b128 v[218:221], v242 offset:55296
	ds_read_b128 v[222:225], v242 offset:56320
	global_load_lds_dwordx4 v[226:227], off
	v_lshl_add_u64 v[226:227], v[28:29], 0, s[24:25]
	s_mov_b32 m0, s5
	s_nop 0
	global_load_lds_dwordx4 v[226:227], off
	v_lshl_add_u64 v[226:227], v[24:25], 0, s[24:25]
	s_mov_b32 m0, s13
	s_nop 0
	global_load_lds_dwordx4 v[226:227], off
	v_lshl_add_u64 v[226:227], v[18:19], 0, s[24:25]
	s_mov_b32 m0, s14
	s_nop 0
	global_load_lds_dwordx4 v[226:227], off
	v_lshl_add_u64 v[226:227], v[20:21], 0, s[24:25]
	s_mov_b32 m0, s4
	s_nop 0
	global_load_lds_dwordx4 v[226:227], off
	v_lshl_add_u64 v[226:227], v[22:23], 0, s[24:25]
	s_mov_b32 m0, s9
	s_nop 0
	global_load_lds_dwordx4 v[226:227], off
	s_waitcnt vmcnt(8)
	s_waitcnt lgkmcnt(0)
	s_setprio 1
	s_barrier
	s_waitcnt lgkmcnt(0)
	v_mfma_f32_16x16x32_bf16 v[30:33], v[54:57], v[218:221], v[30:33]
	v_mfma_f32_16x16x32_bf16 v[34:37], v[144:147], v[218:221], v[34:37]
	v_mfma_f32_16x16x32_bf16 v[160:163], v[54:57], v[194:197], v[160:163]
	v_mfma_f32_16x16x32_bf16 v[164:167], v[144:147], v[194:197], v[164:167]
	v_mfma_f32_16x16x32_bf16 v[168:171], v[54:57], v[202:205], v[168:171]
	v_mfma_f32_16x16x32_bf16 v[172:175], v[144:147], v[202:205], v[172:175]
	v_mfma_f32_16x16x32_bf16 v[178:181], v[54:57], v[210:213], v[178:181]
	v_mfma_f32_16x16x32_bf16 v[182:185], v[144:147], v[210:213], v[182:185]
	v_mfma_f32_16x16x32_bf16 v[30:33], v[58:61], v[222:225], v[30:33]
	v_mfma_f32_16x16x32_bf16 v[34:37], v[148:151], v[222:225], v[34:37]
	v_mfma_f32_16x16x32_bf16 v[160:163], v[58:61], v[198:201], v[160:163]
	v_mfma_f32_16x16x32_bf16 v[164:167], v[148:151], v[198:201], v[164:167]
	v_mfma_f32_16x16x32_bf16 v[168:171], v[58:61], v[206:209], v[168:171]
	v_mfma_f32_16x16x32_bf16 v[172:175], v[148:151], v[206:209], v[172:175]
	v_mfma_f32_16x16x32_bf16 v[178:181], v[58:61], v[214:217], v[178:181]
	v_mfma_f32_16x16x32_bf16 v[182:185], v[148:151], v[214:217], v[182:185]
	s_setprio 0
	s_setprio 1
	v_mfma_f32_16x16x32_bf16 v[38:41], v[152:155], v[194:197], v[38:41]
	v_mfma_f32_16x16x32_bf16 v[42:45], v[186:189], v[194:197], v[42:45]
	v_mfma_f32_16x16x32_bf16 v[54:57], v[152:155], v[202:205], v[90:93]
	v_mfma_f32_16x16x32_bf16 v[58:61], v[186:189], v[202:205], v[132:135]
	v_mfma_f32_16x16x32_bf16 v[90:93], v[152:155], v[210:213], v[136:139]
	v_mfma_f32_16x16x32_bf16 v[46:49], v[152:155], v[218:221], v[46:49]
	v_mfma_f32_16x16x32_bf16 v[50:53], v[186:189], v[218:221], v[50:53]
	v_mfma_f32_16x16x32_bf16 v[38:41], v[156:159], v[198:201], v[38:41]
	v_mfma_f32_16x16x32_bf16 v[42:45], v[190:193], v[198:201], v[42:45]
	v_mfma_f32_16x16x32_bf16 v[54:57], v[156:159], v[206:209], v[54:57]
	v_mfma_f32_16x16x32_bf16 v[58:61], v[190:193], v[206:209], v[58:61]
	v_mfma_f32_16x16x32_bf16 v[90:93], v[156:159], v[214:217], v[90:93]
	v_mfma_f32_16x16x32_bf16 v[132:135], v[186:189], v[210:213], v[140:143]
	v_mfma_f32_16x16x32_bf16 v[46:49], v[156:159], v[222:225], v[46:49]
	v_mfma_f32_16x16x32_bf16 v[50:53], v[190:193], v[222:225], v[50:53]
	v_mfma_f32_16x16x32_bf16 v[132:135], v[190:193], v[214:217], v[132:135]
	s_setprio 0
	s_barrier
	ds_read_b128 v[136:139], v176
	ds_read_b128 v[140:143], v176 offset:1024
	ds_read_b128 v[144:147], v176 offset:2048
	ds_read_b128 v[148:151], v176 offset:3072
	ds_read_b128 v[152:155], v131
	ds_read_b128 v[156:159], v131 offset:1024
	ds_read_b128 v[186:189], v131 offset:2048
	ds_read_b128 v[190:193], v131 offset:3072
	s_mov_b32 m0, s22
	v_lshl_add_u64 v[226:227], v[14:15], 0, s[24:25]
	ds_read_b128 v[194:197], v242
	ds_read_b128 v[198:201], v242 offset:1024
	ds_read_b128 v[202:205], v242 offset:2048
	ds_read_b128 v[206:209], v242 offset:3072
	ds_read_b128 v[210:213], v242 offset:4096
	ds_read_b128 v[214:217], v242 offset:5120
	ds_read_b128 v[218:221], v242 offset:6144
	ds_read_b128 v[222:225], v242 offset:7168
	global_load_lds_dwordx4 v[226:227], off
	v_lshl_add_u64 v[226:227], v[16:17], 0, s[24:25]
	s_mov_b32 m0, s21
	s_nop 0
	global_load_lds_dwordx4 v[226:227], off
	s_waitcnt vmcnt(8)
	s_waitcnt lgkmcnt(0)
	s_setprio 1
	s_barrier
	s_waitcnt lgkmcnt(0)
	v_mfma_f32_16x16x32_bf16 v[110:113], v[136:139], v[210:213], v[110:113]
	v_mfma_f32_16x16x32_bf16 v[226:229], v[140:143], v[214:217], v[110:113]
	v_mfma_f32_16x16x32_bf16 v[110:113], v[144:147], v[210:213], v[114:117]
	v_mfma_f32_16x16x32_bf16 v[94:97], v[136:139], v[194:197], v[94:97]
	v_mfma_f32_16x16x32_bf16 v[98:101], v[144:147], v[194:197], v[98:101]
	v_mfma_f32_16x16x32_bf16 v[102:105], v[136:139], v[202:205], v[102:105]
	v_mfma_f32_16x16x32_bf16 v[106:109], v[144:147], v[202:205], v[106:109]
	v_mfma_f32_16x16x32_bf16 v[114:117], v[148:151], v[214:217], v[110:113]
	v_mfma_f32_16x16x32_bf16 v[110:113], v[136:139], v[218:221], v[118:121]
	v_mfma_f32_16x16x32_bf16 v[94:97], v[140:143], v[198:201], v[94:97]
	v_mfma_f32_16x16x32_bf16 v[98:101], v[148:151], v[198:201], v[98:101]
	v_mfma_f32_16x16x32_bf16 v[102:105], v[140:143], v[206:209], v[102:105]
	v_mfma_f32_16x16x32_bf16 v[106:109], v[148:151], v[206:209], v[106:109]
	v_mfma_f32_16x16x32_bf16 v[118:121], v[140:143], v[222:225], v[110:113]
	v_mfma_f32_16x16x32_bf16 v[110:113], v[144:147], v[218:221], v[122:125]
	v_mfma_f32_16x16x32_bf16 v[230:233], v[148:151], v[222:225], v[110:113]
	s_setprio 0
	s_setprio 1
	v_mfma_f32_16x16x32_bf16 v[74:77], v[152:155], v[210:213], v[74:77]
	v_mfma_f32_16x16x32_bf16 v[110:113], v[152:155], v[194:197], v[126:129]
	v_mfma_f32_16x16x32_bf16 v[62:65], v[186:189], v[194:197], v[62:65]
	v_mfma_f32_16x16x32_bf16 v[194:197], v[156:159], v[214:217], v[74:77]
	v_mfma_f32_16x16x32_bf16 v[74:77], v[186:189], v[210:213], v[78:81]
	v_mfma_f32_16x16x32_bf16 v[234:237], v[156:159], v[198:201], v[110:113]
	v_mfma_f32_16x16x32_bf16 v[62:65], v[190:193], v[198:201], v[62:65]
	v_mfma_f32_16x16x32_bf16 v[66:69], v[152:155], v[202:205], v[66:69]
	v_mfma_f32_16x16x32_bf16 v[70:73], v[186:189], v[202:205], v[70:73]
	v_mfma_f32_16x16x32_bf16 v[198:201], v[190:193], v[214:217], v[74:77]
	v_mfma_f32_16x16x32_bf16 v[74:77], v[152:155], v[218:221], v[82:85]
	v_mfma_f32_16x16x32_bf16 v[66:69], v[156:159], v[206:209], v[66:69]
	v_mfma_f32_16x16x32_bf16 v[70:73], v[190:193], v[206:209], v[70:73]
	v_mfma_f32_16x16x32_bf16 v[202:205], v[156:159], v[222:225], v[74:77]
	v_mfma_f32_16x16x32_bf16 v[74:77], v[186:189], v[218:221], v[86:89]
	v_mfma_f32_16x16x32_bf16 v[206:209], v[190:193], v[222:225], v[74:77]
	s_setprio 0
	s_barrier
	s_mov_b32 m0, s20
	s_nop 3
	ds_read_b128 v[74:77], v242 offset:16384
	ds_read_b128 v[78:81], v242 offset:17408
	ds_read_b128 v[82:85], v242 offset:18432
	ds_read_b128 v[86:89], v242 offset:19456
	ds_read_b128 v[110:113], v242 offset:20480
	ds_read_b128 v[122:125], v242 offset:21504
	ds_read_b128 v[126:129], v242 offset:22528
	ds_read_b128 v[210:213], v242 offset:23552
	global_load_lds_dwordx4 v[26:27], off
	s_mov_b32 m0, s19
	s_nop 0
	global_load_lds_dwordx4 v[28:29], off
	s_mov_b32 m0, s18
	s_nop 0
	global_load_lds_dwordx4 v[24:25], off
	s_mov_b32 m0, s17
	s_nop 0
	global_load_lds_dwordx4 v[18:19], off
	s_mov_b32 m0, s15
	s_nop 0
	global_load_lds_dwordx4 v[20:21], off
	s_mov_b32 m0, s16
	s_nop 0
	global_load_lds_dwordx4 v[22:23], off
	s_waitcnt vmcnt(8)
	s_waitcnt lgkmcnt(0)
	s_setprio 1
	s_barrier
	s_waitcnt lgkmcnt(0)
	v_mfma_f32_16x16x32_bf16 v[30:33], v[136:139], v[126:129], v[30:33]
	v_mfma_f32_16x16x32_bf16 v[18:21], v[136:139], v[74:77], v[160:163]
	v_mfma_f32_16x16x32_bf16 v[22:25], v[144:147], v[74:77], v[164:167]
	v_mfma_f32_16x16x32_bf16 v[26:29], v[136:139], v[82:85], v[168:171]
	v_mfma_f32_16x16x32_bf16 v[164:167], v[136:139], v[110:113], v[178:181]
	v_mfma_f32_16x16x32_bf16 v[136:139], v[140:143], v[210:213], v[30:33]
	v_mfma_f32_16x16x32_bf16 v[30:33], v[144:147], v[126:129], v[34:37]
	v_mfma_f32_16x16x32_bf16 v[18:21], v[140:143], v[78:81], v[18:21]
	v_mfma_f32_16x16x32_bf16 v[22:25], v[148:151], v[78:81], v[22:25]
	v_mfma_f32_16x16x32_bf16 v[26:29], v[140:143], v[86:89], v[26:29]
	v_mfma_f32_16x16x32_bf16 v[160:163], v[144:147], v[82:85], v[172:175]
	v_mfma_f32_16x16x32_bf16 v[168:171], v[144:147], v[110:113], v[182:185]
	v_mfma_f32_16x16x32_bf16 v[34:37], v[148:151], v[210:213], v[30:33]
	v_mfma_f32_16x16x32_bf16 v[160:163], v[148:151], v[86:89], v[160:163]
	v_mfma_f32_16x16x32_bf16 v[164:167], v[140:143], v[122:125], v[164:167]
	v_mfma_f32_16x16x32_bf16 v[168:171], v[148:151], v[122:125], v[168:171]
	s_setprio 0
	s_setprio 1
	v_mfma_f32_16x16x32_bf16 v[30:33], v[152:155], v[74:77], v[38:41]
	v_mfma_f32_16x16x32_bf16 v[38:41], v[156:159], v[78:81], v[30:33]
	v_mfma_f32_16x16x32_bf16 v[30:33], v[186:189], v[74:77], v[42:45]
	v_mfma_f32_16x16x32_bf16 v[140:143], v[190:193], v[78:81], v[30:33]
	v_mfma_f32_16x16x32_bf16 v[30:33], v[152:155], v[82:85], v[54:57]
	v_mfma_f32_16x16x32_bf16 v[144:147], v[156:159], v[86:89], v[30:33]
	v_mfma_f32_16x16x32_bf16 v[30:33], v[186:189], v[82:85], v[58:61]
	v_mfma_f32_16x16x32_bf16 v[148:151], v[190:193], v[86:89], v[30:33]
	v_mfma_f32_16x16x32_bf16 v[30:33], v[152:155], v[110:113], v[90:93]
	v_mfma_f32_16x16x32_bf16 v[172:175], v[156:159], v[122:125], v[30:33]
	v_mfma_f32_16x16x32_bf16 v[30:33], v[186:189], v[110:113], v[132:135]
	v_mfma_f32_16x16x32_bf16 v[132:135], v[190:193], v[122:125], v[30:33]
	v_mfma_f32_16x16x32_bf16 v[30:33], v[152:155], v[126:129], v[46:49]
	v_mfma_f32_16x16x32_bf16 v[152:155], v[156:159], v[210:213], v[30:33]
	v_mfma_f32_16x16x32_bf16 v[30:33], v[186:189], v[126:129], v[50:53]
	v_mfma_f32_16x16x32_bf16 v[156:159], v[190:193], v[210:213], v[30:33]
	s_setprio 0
	s_barrier
	ds_read_b128 v[50:53], v239
	ds_read_b128 v[54:57], v239 offset:1024
	ds_read_b128 v[178:181], v239 offset:2048
	ds_read_b128 v[182:185], v239 offset:3072
	ds_read_b128 v[186:189], v238
	ds_read_b128 v[190:193], v238 offset:1024
	ds_read_b128 v[210:213], v238 offset:2048
	ds_read_b128 v[214:217], v238 offset:3072
	s_mov_b32 m0, s11
	ds_read_b128 v[30:33], v242 offset:32768
	ds_read_b128 v[42:45], v242 offset:33792
	ds_read_b128 v[46:49], v242 offset:34816
	ds_read_b128 v[58:61], v242 offset:35840
	ds_read_b128 v[82:85], v242 offset:36864
	ds_read_b128 v[218:221], v242 offset:37888
	ds_read_b128 v[222:225], v242 offset:38912
	ds_read_b128 v[238:241], v242 offset:39936
	global_load_lds_dwordx4 v[14:15], off
	s_mov_b32 m0, s12
	s_nop 0
	global_load_lds_dwordx4 v[16:17], off
	s_waitcnt vmcnt(8)
	s_waitcnt lgkmcnt(0)
	s_setprio 1
	s_barrier
	s_waitcnt lgkmcnt(0)
	v_mfma_f32_16x16x32_bf16 v[14:17], v[50:53], v[30:33], v[94:97]
	v_mfma_f32_16x16x32_bf16 v[126:129], v[54:57], v[42:45], v[14:17]
	v_mfma_f32_16x16x32_bf16 v[14:17], v[178:181], v[30:33], v[98:101]
	v_mfma_f32_16x16x32_bf16 v[122:125], v[182:185], v[42:45], v[14:17]
	v_mfma_f32_16x16x32_bf16 v[14:17], v[50:53], v[46:49], v[102:105]
	v_mfma_f32_16x16x32_bf16 v[110:113], v[54:57], v[58:61], v[14:17]
	v_mfma_f32_16x16x32_bf16 v[14:17], v[178:181], v[46:49], v[106:109]
	v_mfma_f32_16x16x32_bf16 v[106:109], v[182:185], v[58:61], v[14:17]
	v_mfma_f32_16x16x32_bf16 v[14:17], v[50:53], v[82:85], v[226:229]
	v_mfma_f32_16x16x32_bf16 v[94:97], v[54:57], v[218:221], v[14:17]
	v_mfma_f32_16x16x32_bf16 v[14:17], v[178:181], v[82:85], v[114:117]
	v_mfma_f32_16x16x32_bf16 v[90:93], v[182:185], v[218:221], v[14:17]
	v_mfma_f32_16x16x32_bf16 v[14:17], v[50:53], v[222:225], v[118:121]
	v_mfma_f32_16x16x32_bf16 v[78:81], v[54:57], v[238:241], v[14:17]
	v_mfma_f32_16x16x32_bf16 v[14:17], v[178:181], v[222:225], v[230:233]
	v_mfma_f32_16x16x32_bf16 v[74:77], v[182:185], v[238:241], v[14:17]
	s_setprio 0
	s_setprio 1
	v_mfma_f32_16x16x32_bf16 v[14:17], v[186:189], v[30:33], v[234:237]
	v_mfma_f32_16x16x32_bf16 v[118:121], v[190:193], v[42:45], v[14:17]
	v_mfma_f32_16x16x32_bf16 v[14:17], v[210:213], v[30:33], v[62:65]
	v_mfma_f32_16x16x32_bf16 v[114:117], v[214:217], v[42:45], v[14:17]
	v_mfma_f32_16x16x32_bf16 v[14:17], v[186:189], v[46:49], v[66:69]
	v_mfma_f32_16x16x32_bf16 v[102:105], v[190:193], v[58:61], v[14:17]
	v_mfma_f32_16x16x32_bf16 v[14:17], v[210:213], v[46:49], v[70:73]
	v_mfma_f32_16x16x32_bf16 v[98:101], v[214:217], v[58:61], v[14:17]
	v_mfma_f32_16x16x32_bf16 v[14:17], v[186:189], v[82:85], v[194:197]
	v_mfma_f32_16x16x32_bf16 v[86:89], v[190:193], v[218:221], v[14:17]
	v_mfma_f32_16x16x32_bf16 v[14:17], v[210:213], v[82:85], v[198:201]
	v_mfma_f32_16x16x32_bf16 v[82:85], v[214:217], v[218:221], v[14:17]
	v_mfma_f32_16x16x32_bf16 v[14:17], v[186:189], v[222:225], v[202:205]
	v_mfma_f32_16x16x32_bf16 v[66:69], v[190:193], v[238:241], v[14:17]
	v_mfma_f32_16x16x32_bf16 v[14:17], v[210:213], v[222:225], v[206:209]
	v_mfma_f32_16x16x32_bf16 v[58:61], v[214:217], v[238:241], v[14:17]
	s_setprio 0
	s_barrier
	s_mov_b32 m0, s3
	ds_read_b128 v[194:197], v242 offset:49152
	ds_read_b128 v[198:201], v242 offset:50176
	ds_read_b128 v[202:205], v242 offset:51200
	ds_read_b128 v[206:209], v242 offset:52224
	ds_read_b128 v[218:221], v242 offset:53248
	ds_read_b128 v[222:225], v242 offset:54272
	ds_read_b128 v[226:229], v242 offset:55296
	ds_read_b128 v[230:233], v242 offset:56320
	global_load_lds_dwordx4 v[4:5], off
	s_mov_b32 m0, s5
	s_nop 0
	global_load_lds_dwordx4 v[6:7], off
	s_mov_b32 m0, s13
	s_nop 0
	global_load_lds_dwordx4 v[10:11], off
	s_mov_b32 m0, s14
	s_nop 0
	global_load_lds_dwordx4 v[12:13], off
	s_mov_b32 m0, s4
	s_nop 0
	global_load_lds_dwordx4 v[2:3], off
	s_mov_b32 m0, s9
	s_nop 0
	global_load_lds_dwordx4 v[8:9], off
	s_waitcnt vmcnt(8)
	s_waitcnt lgkmcnt(0)
	s_setprio 1
	s_barrier
	s_waitcnt lgkmcnt(0)
	v_mfma_f32_16x16x32_bf16 v[2:5], v[50:53], v[194:197], v[18:21]
	v_mfma_f32_16x16x32_bf16 v[70:73], v[54:57], v[198:201], v[2:5]
	v_mfma_f32_16x16x32_bf16 v[2:5], v[178:181], v[194:197], v[22:25]
	v_mfma_f32_16x16x32_bf16 v[62:65], v[182:185], v[198:201], v[2:5]
	v_mfma_f32_16x16x32_bf16 v[2:5], v[50:53], v[202:205], v[26:29]
	v_mfma_f32_16x16x32_bf16 v[46:49], v[54:57], v[206:209], v[2:5]
	v_mfma_f32_16x16x32_bf16 v[2:5], v[178:181], v[202:205], v[160:163]
	v_mfma_f32_16x16x32_bf16 v[42:45], v[182:185], v[206:209], v[2:5]
	v_mfma_f32_16x16x32_bf16 v[2:5], v[50:53], v[218:221], v[164:167]
	v_mfma_f32_16x16x32_bf16 v[30:33], v[54:57], v[222:225], v[2:5]
	v_mfma_f32_16x16x32_bf16 v[2:5], v[178:181], v[218:221], v[168:171]
	v_mfma_f32_16x16x32_bf16 v[26:29], v[182:185], v[222:225], v[2:5]
	v_mfma_f32_16x16x32_bf16 v[2:5], v[50:53], v[226:229], v[136:139]
	v_mfma_f32_16x16x32_bf16 v[14:17], v[54:57], v[230:233], v[2:5]
	v_mfma_f32_16x16x32_bf16 v[2:5], v[178:181], v[226:229], v[34:37]
	v_mfma_f32_16x16x32_bf16 v[10:13], v[182:185], v[230:233], v[2:5]
	s_setprio 0
	s_setprio 1
	v_mfma_f32_16x16x32_bf16 v[2:5], v[186:189], v[194:197], v[38:41]
	v_mfma_f32_16x16x32_bf16 v[54:57], v[190:193], v[198:201], v[2:5]
	v_mfma_f32_16x16x32_bf16 v[2:5], v[210:213], v[194:197], v[140:143]
	v_mfma_f32_16x16x32_bf16 v[50:53], v[214:217], v[198:201], v[2:5]
	v_mfma_f32_16x16x32_bf16 v[2:5], v[186:189], v[202:205], v[144:147]
	v_mfma_f32_16x16x32_bf16 v[38:41], v[190:193], v[206:209], v[2:5]
	v_mfma_f32_16x16x32_bf16 v[2:5], v[210:213], v[202:205], v[148:151]
	v_mfma_f32_16x16x32_bf16 v[34:37], v[214:217], v[206:209], v[2:5]
	v_mfma_f32_16x16x32_bf16 v[2:5], v[186:189], v[218:221], v[172:175]
	v_mfma_f32_16x16x32_bf16 v[22:25], v[190:193], v[222:225], v[2:5]
	v_mfma_f32_16x16x32_bf16 v[2:5], v[210:213], v[218:221], v[132:135]
	v_mfma_f32_16x16x32_bf16 v[18:21], v[214:217], v[222:225], v[2:5]
	v_mfma_f32_16x16x32_bf16 v[2:5], v[186:189], v[226:229], v[152:155]
	v_mfma_f32_16x16x32_bf16 v[6:9], v[190:193], v[230:233], v[2:5]
	v_mfma_f32_16x16x32_bf16 v[2:5], v[210:213], v[226:229], v[156:159]
	v_mfma_f32_16x16x32_bf16 v[2:5], v[214:217], v[230:233], v[2:5]
	s_setprio 0
	s_barrier
	s_cbranch_scc1 .LBB0_1139
	s_barrier

.Lpk1179_peel:
	ds_read_b128 v[144:147], v158
	ds_read_b128 v[164:167], v158 offset:1024
	ds_read_b128 v[168:171], v158 offset:2048
	ds_read_b128 v[172:175], v158 offset:3072
	ds_read_b128 v[178:181], v159
	ds_read_b128 v[182:185], v159 offset:1024
	ds_read_b128 v[186:189], v159 offset:2048
	ds_read_b128 v[190:193], v159 offset:3072
	s_add_u32 s2, s36, 0xfffc0080
	s_addc_u32 s3, s37, -1
	s_cmp_eq_u32 s61, 12
	s_cselect_b32 s3, s19, s3
	s_cselect_b32 s2, s21, s2
	s_cselect_b32 s39, s57, s60
	s_cselect_b32 s38, s58, s59
	v_lshl_add_u64 v[226:227], s[36:37], 0, v[138:139]
	s_add_i32 m0, s42, 0xc000
	ds_read_b128 v[194:197], v160
	ds_read_b128 v[198:201], v160 offset:1024
	ds_read_b128 v[202:205], v160 offset:2048
	ds_read_b128 v[206:209], v160 offset:3072
	ds_read_b128 v[210:213], v160 offset:4096
	ds_read_b128 v[214:217], v160 offset:5120
	ds_read_b128 v[218:221], v160 offset:6144
	ds_read_b128 v[222:225], v160 offset:7168
	global_load_lds_dwordx4 v[226:227], off
	v_lshl_add_u64 v[226:227], s[36:37], 0, v[140:141]
	s_add_i32 m0, s42, 0xe000
	s_nop 0
	global_load_lds_dwordx4 v[226:227], off
	s_waitcnt vmcnt(8)
	s_waitcnt lgkmcnt(0)
	s_setprio 1
	s_barrier
	s_waitcnt lgkmcnt(0)
	v_mfma_f32_16x16x32_bf16 v[126:129], v[144:147], v[194:197], 0
	v_mfma_f32_16x16x32_bf16 v[122:125], v[168:171], v[194:197], 0
	v_mfma_f32_16x16x32_bf16 v[114:117], v[144:147], v[202:205], 0
	v_mfma_f32_16x16x32_bf16 v[106:109], v[168:171], v[202:205], 0
	v_mfma_f32_16x16x32_bf16 v[98:101], v[144:147], v[210:213], 0
	v_mfma_f32_16x16x32_bf16 v[90:93], v[168:171], v[210:213], 0
	v_mfma_f32_16x16x32_bf16 v[82:85], v[144:147], v[218:221], 0
	v_mfma_f32_16x16x32_bf16 v[74:77], v[168:171], v[218:221], 0
	v_mfma_f32_16x16x32_bf16 v[126:129], v[164:167], v[198:201], v[126:129]
	v_mfma_f32_16x16x32_bf16 v[122:125], v[172:175], v[198:201], v[122:125]
	v_mfma_f32_16x16x32_bf16 v[114:117], v[164:167], v[206:209], v[114:117]
	v_mfma_f32_16x16x32_bf16 v[106:109], v[172:175], v[206:209], v[106:109]
	v_mfma_f32_16x16x32_bf16 v[98:101], v[164:167], v[214:217], v[98:101]
	v_mfma_f32_16x16x32_bf16 v[90:93], v[172:175], v[214:217], v[90:93]
	v_mfma_f32_16x16x32_bf16 v[82:85], v[164:167], v[222:225], v[82:85]
	v_mfma_f32_16x16x32_bf16 v[74:77], v[172:175], v[222:225], v[74:77]
	s_setprio 0
	s_setprio 1
	v_mfma_f32_16x16x32_bf16 v[118:121], v[178:181], v[194:197], 0
	v_mfma_f32_16x16x32_bf16 v[110:113], v[186:189], v[194:197], 0
	v_mfma_f32_16x16x32_bf16 v[102:105], v[178:181], v[202:205], 0
	v_mfma_f32_16x16x32_bf16 v[94:97], v[186:189], v[202:205], 0
	v_mfma_f32_16x16x32_bf16 v[86:89], v[178:181], v[210:213], 0
	v_mfma_f32_16x16x32_bf16 v[78:81], v[186:189], v[210:213], 0
	v_mfma_f32_16x16x32_bf16 v[70:73], v[178:181], v[218:221], 0
	v_mfma_f32_16x16x32_bf16 v[66:69], v[186:189], v[218:221], 0
	v_mfma_f32_16x16x32_bf16 v[118:121], v[182:185], v[198:201], v[118:121]
	v_mfma_f32_16x16x32_bf16 v[110:113], v[190:193], v[198:201], v[110:113]
	v_mfma_f32_16x16x32_bf16 v[102:105], v[182:185], v[206:209], v[102:105]
	v_mfma_f32_16x16x32_bf16 v[94:97], v[190:193], v[206:209], v[94:97]
	v_mfma_f32_16x16x32_bf16 v[86:89], v[182:185], v[214:217], v[86:89]
	v_mfma_f32_16x16x32_bf16 v[78:81], v[190:193], v[214:217], v[78:81]
	v_mfma_f32_16x16x32_bf16 v[70:73], v[182:185], v[222:225], v[70:73]
	v_mfma_f32_16x16x32_bf16 v[66:69], v[190:193], v[222:225], v[66:69]
	s_setprio 0
	s_barrier
	s_add_i32 s62, s51, s41
	v_lshl_add_u64 v[226:227], s[38:39], 0, v[132:133]
	s_mov_b32 m0, s62
	ds_read_b128 v[194:197], v160 offset:16384
	ds_read_b128 v[198:201], v160 offset:17408
	ds_read_b128 v[202:205], v160 offset:18432
	ds_read_b128 v[206:209], v160 offset:19456
	ds_read_b128 v[210:213], v160 offset:20480
	ds_read_b128 v[214:217], v160 offset:21504
	ds_read_b128 v[218:221], v160 offset:22528
	ds_read_b128 v[222:225], v160 offset:23552
	global_load_lds_dwordx4 v[226:227], off
	s_add_i32 m0, s62, 0x2000
	s_add_u32 s62, s38, 0x40000
	v_lshl_add_u64 v[228:229], s[38:39], 0, v[136:137]
	s_addc_u32 s63, s39, 0
	s_add_i32 s64, s52, s41
	global_load_lds_dwordx4 v[228:229], off
	v_lshl_add_u64 v[230:231], s[62:63], 0, v[132:133]
	s_mov_b32 m0, s64
	v_lshl_add_u64 v[232:233], s[2:3], 0, v[134:135]
	global_load_lds_dwordx4 v[230:231], off
	v_lshl_add_u64 v[230:231], s[62:63], 0, v[136:137]
	s_add_i32 m0, s64, 0x2000
	s_nop 0
	global_load_lds_dwordx4 v[230:231], off
	v_lshl_add_u64 v[230:231], s[2:3], 0, v[130:131]
	s_mov_b32 m0, s42
	s_nop 0
	global_load_lds_dwordx4 v[230:231], off
	s_mov_b32 m0, s43
	s_nop 0
	global_load_lds_dwordx4 v[232:233], off
	s_waitcnt vmcnt(8)
	s_waitcnt lgkmcnt(0)
	s_setprio 1
	s_barrier
	s_waitcnt lgkmcnt(0)
	v_mfma_f32_16x16x32_bf16 v[62:65], v[144:147], v[194:197], 0
	v_mfma_f32_16x16x32_bf16 v[58:61], v[168:171], v[194:197], 0
	v_mfma_f32_16x16x32_bf16 v[50:53], v[144:147], v[202:205], 0
	v_mfma_f32_16x16x32_bf16 v[42:45], v[168:171], v[202:205], 0
	v_mfma_f32_16x16x32_bf16 v[34:37], v[144:147], v[210:213], 0
	v_mfma_f32_16x16x32_bf16 v[26:29], v[168:171], v[210:213], 0
	v_mfma_f32_16x16x32_bf16 v[18:21], v[144:147], v[218:221], 0
	v_mfma_f32_16x16x32_bf16 v[10:13], v[168:171], v[218:221], 0
	v_mfma_f32_16x16x32_bf16 v[62:65], v[164:167], v[198:201], v[62:65]
	v_mfma_f32_16x16x32_bf16 v[58:61], v[172:175], v[198:201], v[58:61]
	v_mfma_f32_16x16x32_bf16 v[50:53], v[164:167], v[206:209], v[50:53]
	v_mfma_f32_16x16x32_bf16 v[42:45], v[172:175], v[206:209], v[42:45]
	v_mfma_f32_16x16x32_bf16 v[34:37], v[164:167], v[214:217], v[34:37]
	v_mfma_f32_16x16x32_bf16 v[26:29], v[172:175], v[214:217], v[26:29]
	v_mfma_f32_16x16x32_bf16 v[18:21], v[164:167], v[222:225], v[18:21]
	v_mfma_f32_16x16x32_bf16 v[10:13], v[172:175], v[222:225], v[10:13]
	s_setprio 0
	s_setprio 1
	v_mfma_f32_16x16x32_bf16 v[54:57], v[178:181], v[194:197], 0
	v_mfma_f32_16x16x32_bf16 v[46:49], v[186:189], v[194:197], 0
	v_mfma_f32_16x16x32_bf16 v[38:41], v[178:181], v[202:205], 0
	v_mfma_f32_16x16x32_bf16 v[30:33], v[186:189], v[202:205], 0
	v_mfma_f32_16x16x32_bf16 v[22:25], v[178:181], v[210:213], 0
	v_mfma_f32_16x16x32_bf16 v[14:17], v[186:189], v[210:213], 0
	v_mfma_f32_16x16x32_bf16 v[6:9], v[178:181], v[218:221], 0
	v_mfma_f32_16x16x32_bf16 v[2:5], v[186:189], v[218:221], 0
	v_mfma_f32_16x16x32_bf16 v[54:57], v[182:185], v[198:201], v[54:57]
	v_mfma_f32_16x16x32_bf16 v[46:49], v[190:193], v[198:201], v[46:49]
	v_mfma_f32_16x16x32_bf16 v[38:41], v[182:185], v[206:209], v[38:41]
	v_mfma_f32_16x16x32_bf16 v[30:33], v[190:193], v[206:209], v[30:33]
	v_mfma_f32_16x16x32_bf16 v[22:25], v[182:185], v[214:217], v[22:25]
	v_mfma_f32_16x16x32_bf16 v[14:17], v[190:193], v[214:217], v[14:17]
	v_mfma_f32_16x16x32_bf16 v[6:9], v[182:185], v[222:225], v[6:9]
	v_mfma_f32_16x16x32_bf16 v[2:5], v[190:193], v[222:225], v[2:5]
	s_setprio 0
	s_barrier
	s_add_i32 s62, 0, 0x18000
	v_add_u32_e32 v163, s62, v148
	s_add_i32 s63, 0, 0x1c000
	ds_read_b128 v[144:147], v163
	ds_read_b128 v[164:167], v163 offset:1024
	ds_read_b128 v[168:171], v163 offset:2048
	ds_read_b128 v[172:175], v163 offset:3072
	v_add_u32_e32 v163, s63, v148
	ds_read_b128 v[178:181], v163
	ds_read_b128 v[182:185], v163 offset:1024
	ds_read_b128 v[186:189], v163 offset:2048
	ds_read_b128 v[190:193], v163 offset:3072
	s_add_u32 s2, s2, 0x40000
	s_addc_u32 s3, s3, 0
	s_mov_b32 m0, s44
	v_lshl_add_u64 v[234:235], s[2:3], 0, v[130:131]
	ds_read_b128 v[194:197], v160 offset:32768
	ds_read_b128 v[198:201], v160 offset:33792
	ds_read_b128 v[202:205], v160 offset:34816
	ds_read_b128 v[206:209], v160 offset:35840
	ds_read_b128 v[210:213], v160 offset:36864
	ds_read_b128 v[214:217], v160 offset:37888
	ds_read_b128 v[218:221], v160 offset:38912
	ds_read_b128 v[222:225], v160 offset:39936
	global_load_lds_dwordx4 v[234:235], off
	v_lshl_add_u64 v[234:235], s[2:3], 0, v[134:135]
	s_mov_b32 m0, s45
	s_nop 0
	global_load_lds_dwordx4 v[234:235], off
	s_waitcnt vmcnt(8)
	s_waitcnt lgkmcnt(0)
	s_setprio 1
	s_barrier
	s_waitcnt lgkmcnt(0)
	v_mfma_f32_16x16x32_bf16 v[126:129], v[144:147], v[194:197], v[126:129]
	v_mfma_f32_16x16x32_bf16 v[122:125], v[168:171], v[194:197], v[122:125]
	v_mfma_f32_16x16x32_bf16 v[114:117], v[144:147], v[202:205], v[114:117]
	v_mfma_f32_16x16x32_bf16 v[106:109], v[168:171], v[202:205], v[106:109]
	v_mfma_f32_16x16x32_bf16 v[98:101], v[144:147], v[210:213], v[98:101]
	v_mfma_f32_16x16x32_bf16 v[90:93], v[168:171], v[210:213], v[90:93]
	v_mfma_f32_16x16x32_bf16 v[82:85], v[144:147], v[218:221], v[82:85]
	v_mfma_f32_16x16x32_bf16 v[74:77], v[168:171], v[218:221], v[74:77]
	v_mfma_f32_16x16x32_bf16 v[126:129], v[164:167], v[198:201], v[126:129]
	v_mfma_f32_16x16x32_bf16 v[122:125], v[172:175], v[198:201], v[122:125]
	v_mfma_f32_16x16x32_bf16 v[114:117], v[164:167], v[206:209], v[114:117]
	v_mfma_f32_16x16x32_bf16 v[106:109], v[172:175], v[206:209], v[106:109]
	v_mfma_f32_16x16x32_bf16 v[98:101], v[164:167], v[214:217], v[98:101]
	v_mfma_f32_16x16x32_bf16 v[90:93], v[172:175], v[214:217], v[90:93]
	v_mfma_f32_16x16x32_bf16 v[82:85], v[164:167], v[222:225], v[82:85]
	v_mfma_f32_16x16x32_bf16 v[74:77], v[172:175], v[222:225], v[74:77]
	s_setprio 0
	s_setprio 1
	v_mfma_f32_16x16x32_bf16 v[118:121], v[178:181], v[194:197], v[118:121]
	v_mfma_f32_16x16x32_bf16 v[110:113], v[186:189], v[194:197], v[110:113]
	v_mfma_f32_16x16x32_bf16 v[102:105], v[178:181], v[202:205], v[102:105]
	v_mfma_f32_16x16x32_bf16 v[94:97], v[186:189], v[202:205], v[94:97]
	v_mfma_f32_16x16x32_bf16 v[86:89], v[178:181], v[210:213], v[86:89]
	v_mfma_f32_16x16x32_bf16 v[78:81], v[186:189], v[210:213], v[78:81]
	v_mfma_f32_16x16x32_bf16 v[70:73], v[178:181], v[218:221], v[70:73]
	v_mfma_f32_16x16x32_bf16 v[66:69], v[186:189], v[218:221], v[66:69]
	v_mfma_f32_16x16x32_bf16 v[118:121], v[182:185], v[198:201], v[118:121]
	v_mfma_f32_16x16x32_bf16 v[110:113], v[190:193], v[198:201], v[110:113]
	v_mfma_f32_16x16x32_bf16 v[102:105], v[182:185], v[206:209], v[102:105]
	v_mfma_f32_16x16x32_bf16 v[94:97], v[190:193], v[206:209], v[94:97]
	v_mfma_f32_16x16x32_bf16 v[86:89], v[182:185], v[214:217], v[86:89]
	v_mfma_f32_16x16x32_bf16 v[78:81], v[190:193], v[214:217], v[78:81]
	v_mfma_f32_16x16x32_bf16 v[70:73], v[182:185], v[222:225], v[70:73]
	v_mfma_f32_16x16x32_bf16 v[66:69], v[190:193], v[222:225], v[66:69]
	s_setprio 0
	s_barrier
	s_add_i32 s2, s62, s41
	v_lshl_add_u64 v[226:227], v[226:227], 0, s[10:11]
	s_mov_b32 m0, s2
	ds_read_b128 v[194:197], v160 offset:49152
	ds_read_b128 v[198:201], v160 offset:50176
	ds_read_b128 v[202:205], v160 offset:51200
	ds_read_b128 v[206:209], v160 offset:52224
	ds_read_b128 v[210:213], v160 offset:53248
	ds_read_b128 v[214:217], v160 offset:54272
	ds_read_b128 v[218:221], v160 offset:55296
	ds_read_b128 v[222:225], v160 offset:56320
	global_load_lds_dwordx4 v[226:227], off
	s_add_i32 m0, s2, 0x2000
	s_add_u32 s2, s38, 0x40080
	v_lshl_add_u64 v[226:227], v[228:229], 0, s[10:11]
	s_addc_u32 s3, s39, 0
	s_add_i32 s38, s63, s41
	global_load_lds_dwordx4 v[226:227], off
	v_lshl_add_u64 v[226:227], s[2:3], 0, v[132:133]
	s_mov_b32 m0, s38
	s_nop 0
	global_load_lds_dwordx4 v[226:227], off
	v_lshl_add_u64 v[226:227], s[2:3], 0, v[136:137]
	s_add_i32 m0, s38, 0x2000
	s_nop 0
	global_load_lds_dwordx4 v[226:227], off
	v_lshl_add_u64 v[226:227], v[230:231], 0, s[10:11]
	s_mov_b32 m0, s47
	s_nop 0
	global_load_lds_dwordx4 v[226:227], off
	v_lshl_add_u64 v[226:227], v[232:233], 0, s[10:11]
	s_mov_b32 m0, s48
	s_nop 0
	global_load_lds_dwordx4 v[226:227], off
	s_waitcnt vmcnt(8)
	s_waitcnt lgkmcnt(0)
	s_setprio 1
	s_barrier
	s_waitcnt lgkmcnt(0)
	v_mfma_f32_16x16x32_bf16 v[62:65], v[144:147], v[194:197], v[62:65]
	v_mfma_f32_16x16x32_bf16 v[58:61], v[168:171], v[194:197], v[58:61]
	v_mfma_f32_16x16x32_bf16 v[50:53], v[144:147], v[202:205], v[50:53]
	v_mfma_f32_16x16x32_bf16 v[42:45], v[168:171], v[202:205], v[42:45]
	v_mfma_f32_16x16x32_bf16 v[34:37], v[144:147], v[210:213], v[34:37]
	v_mfma_f32_16x16x32_bf16 v[26:29], v[168:171], v[210:213], v[26:29]
	v_mfma_f32_16x16x32_bf16 v[18:21], v[144:147], v[218:221], v[18:21]
	v_mfma_f32_16x16x32_bf16 v[10:13], v[168:171], v[218:221], v[10:13]
	v_mfma_f32_16x16x32_bf16 v[62:65], v[164:167], v[198:201], v[62:65]
	v_mfma_f32_16x16x32_bf16 v[58:61], v[172:175], v[198:201], v[58:61]
	v_mfma_f32_16x16x32_bf16 v[50:53], v[164:167], v[206:209], v[50:53]
	v_mfma_f32_16x16x32_bf16 v[42:45], v[172:175], v[206:209], v[42:45]
	v_mfma_f32_16x16x32_bf16 v[34:37], v[164:167], v[214:217], v[34:37]
	v_mfma_f32_16x16x32_bf16 v[26:29], v[172:175], v[214:217], v[26:29]
	v_mfma_f32_16x16x32_bf16 v[18:21], v[164:167], v[222:225], v[18:21]
	v_mfma_f32_16x16x32_bf16 v[10:13], v[172:175], v[222:225], v[10:13]
	s_setprio 0
	s_setprio 1
	v_mfma_f32_16x16x32_bf16 v[54:57], v[178:181], v[194:197], v[54:57]
	v_mfma_f32_16x16x32_bf16 v[46:49], v[186:189], v[194:197], v[46:49]
	v_mfma_f32_16x16x32_bf16 v[38:41], v[178:181], v[202:205], v[38:41]
	v_mfma_f32_16x16x32_bf16 v[30:33], v[186:189], v[202:205], v[30:33]
	v_mfma_f32_16x16x32_bf16 v[22:25], v[178:181], v[210:213], v[22:25]
	v_mfma_f32_16x16x32_bf16 v[14:17], v[186:189], v[210:213], v[14:17]
	v_mfma_f32_16x16x32_bf16 v[6:9], v[178:181], v[218:221], v[6:9]
	v_mfma_f32_16x16x32_bf16 v[2:5], v[186:189], v[218:221], v[2:5]
	v_mfma_f32_16x16x32_bf16 v[54:57], v[182:185], v[198:201], v[54:57]
	v_mfma_f32_16x16x32_bf16 v[46:49], v[190:193], v[198:201], v[46:49]
	v_mfma_f32_16x16x32_bf16 v[38:41], v[182:185], v[206:209], v[38:41]
	v_mfma_f32_16x16x32_bf16 v[30:33], v[190:193], v[206:209], v[30:33]
	v_mfma_f32_16x16x32_bf16 v[22:25], v[182:185], v[214:217], v[22:25]
	v_mfma_f32_16x16x32_bf16 v[14:17], v[190:193], v[214:217], v[14:17]
	v_mfma_f32_16x16x32_bf16 v[6:9], v[182:185], v[222:225], v[6:9]
	v_mfma_f32_16x16x32_bf16 v[2:5], v[190:193], v[222:225], v[2:5]
	s_setprio 0
	s_barrier
	s_add_i32 s61, s61, 2
	s_add_u32 s36, s36, 0x100
	s_addc_u32 s37, s37, 0
	s_add_u32 s59, s59, 0x100
	s_addc_u32 s60, s60, 0
	s_cmp_gt_u32 s61, 13
	s_cbranch_scc0 .LBB0_1179
	s_branch .Lpk1179_exit
.LBB0_1179:
	ds_read_b128 v[144:147], v158
	ds_read_b128 v[164:167], v158 offset:1024
	ds_read_b128 v[168:171], v158 offset:2048
	ds_read_b128 v[172:175], v158 offset:3072
	ds_read_b128 v[178:181], v159
	ds_read_b128 v[182:185], v159 offset:1024
	ds_read_b128 v[186:189], v159 offset:2048
	ds_read_b128 v[190:193], v159 offset:3072
	s_add_u32 s2, s36, 0xfffc0080
	s_addc_u32 s3, s37, -1
	s_cmp_eq_u32 s61, 12
	s_cselect_b32 s3, s19, s3
	s_cselect_b32 s2, s21, s2
	s_cselect_b32 s39, s57, s60
	s_cselect_b32 s38, s58, s59
	v_lshl_add_u64 v[226:227], s[36:37], 0, v[138:139]
	s_add_i32 m0, s42, 0xc000
	ds_read_b128 v[194:197], v160
	ds_read_b128 v[198:201], v160 offset:1024
	ds_read_b128 v[202:205], v160 offset:2048
	ds_read_b128 v[206:209], v160 offset:3072
	ds_read_b128 v[210:213], v160 offset:4096
	ds_read_b128 v[214:217], v160 offset:5120
	ds_read_b128 v[218:221], v160 offset:6144
	ds_read_b128 v[222:225], v160 offset:7168
	global_load_lds_dwordx4 v[226:227], off
	v_lshl_add_u64 v[226:227], s[36:37], 0, v[140:141]
	s_add_i32 m0, s42, 0xe000
	s_nop 0
	global_load_lds_dwordx4 v[226:227], off
	s_waitcnt vmcnt(8)
	s_waitcnt lgkmcnt(0)
	s_setprio 1
	s_barrier
	s_waitcnt lgkmcnt(0)
	v_mfma_f32_16x16x32_bf16 v[126:129], v[144:147], v[194:197], v[126:129]
	v_mfma_f32_16x16x32_bf16 v[122:125], v[168:171], v[194:197], v[122:125]
	v_mfma_f32_16x16x32_bf16 v[114:117], v[144:147], v[202:205], v[114:117]
	v_mfma_f32_16x16x32_bf16 v[106:109], v[168:171], v[202:205], v[106:109]
	v_mfma_f32_16x16x32_bf16 v[98:101], v[144:147], v[210:213], v[98:101]
	v_mfma_f32_16x16x32_bf16 v[90:93], v[168:171], v[210:213], v[90:93]
	v_mfma_f32_16x16x32_bf16 v[82:85], v[144:147], v[218:221], v[82:85]
	v_mfma_f32_16x16x32_bf16 v[74:77], v[168:171], v[218:221], v[74:77]
	v_mfma_f32_16x16x32_bf16 v[126:129], v[164:167], v[198:201], v[126:129]
	v_mfma_f32_16x16x32_bf16 v[122:125], v[172:175], v[198:201], v[122:125]
	v_mfma_f32_16x16x32_bf16 v[114:117], v[164:167], v[206:209], v[114:117]
	v_mfma_f32_16x16x32_bf16 v[106:109], v[172:175], v[206:209], v[106:109]
	v_mfma_f32_16x16x32_bf16 v[98:101], v[164:167], v[214:217], v[98:101]
	v_mfma_f32_16x16x32_bf16 v[90:93], v[172:175], v[214:217], v[90:93]
	v_mfma_f32_16x16x32_bf16 v[82:85], v[164:167], v[222:225], v[82:85]
	v_mfma_f32_16x16x32_bf16 v[74:77], v[172:175], v[222:225], v[74:77]
	s_setprio 0
	s_setprio 1
	v_mfma_f32_16x16x32_bf16 v[118:121], v[178:181], v[194:197], v[118:121]
	v_mfma_f32_16x16x32_bf16 v[110:113], v[186:189], v[194:197], v[110:113]
	v_mfma_f32_16x16x32_bf16 v[102:105], v[178:181], v[202:205], v[102:105]
	v_mfma_f32_16x16x32_bf16 v[94:97], v[186:189], v[202:205], v[94:97]
	v_mfma_f32_16x16x32_bf16 v[86:89], v[178:181], v[210:213], v[86:89]
	v_mfma_f32_16x16x32_bf16 v[78:81], v[186:189], v[210:213], v[78:81]
	v_mfma_f32_16x16x32_bf16 v[70:73], v[178:181], v[218:221], v[70:73]
	v_mfma_f32_16x16x32_bf16 v[66:69], v[186:189], v[218:221], v[66:69]
	v_mfma_f32_16x16x32_bf16 v[118:121], v[182:185], v[198:201], v[118:121]
	v_mfma_f32_16x16x32_bf16 v[110:113], v[190:193], v[198:201], v[110:113]
	v_mfma_f32_16x16x32_bf16 v[102:105], v[182:185], v[206:209], v[102:105]
	v_mfma_f32_16x16x32_bf16 v[94:97], v[190:193], v[206:209], v[94:97]
	v_mfma_f32_16x16x32_bf16 v[86:89], v[182:185], v[214:217], v[86:89]
	v_mfma_f32_16x16x32_bf16 v[78:81], v[190:193], v[214:217], v[78:81]
	v_mfma_f32_16x16x32_bf16 v[70:73], v[182:185], v[222:225], v[70:73]
	v_mfma_f32_16x16x32_bf16 v[66:69], v[190:193], v[222:225], v[66:69]
	s_setprio 0
	s_barrier
	s_add_i32 s62, s51, s41
	v_lshl_add_u64 v[226:227], s[38:39], 0, v[132:133]
	s_mov_b32 m0, s62
	ds_read_b128 v[194:197], v160 offset:16384
	ds_read_b128 v[198:201], v160 offset:17408
	ds_read_b128 v[202:205], v160 offset:18432
	ds_read_b128 v[206:209], v160 offset:19456
	ds_read_b128 v[210:213], v160 offset:20480
	ds_read_b128 v[214:217], v160 offset:21504
	ds_read_b128 v[218:221], v160 offset:22528
	ds_read_b128 v[222:225], v160 offset:23552
	global_load_lds_dwordx4 v[226:227], off
	s_add_i32 m0, s62, 0x2000
	s_add_u32 s62, s38, 0x40000
	v_lshl_add_u64 v[228:229], s[38:39], 0, v[136:137]
	s_addc_u32 s63, s39, 0
	s_add_i32 s64, s52, s41
	global_load_lds_dwordx4 v[228:229], off
	v_lshl_add_u64 v[230:231], s[62:63], 0, v[132:133]
	s_mov_b32 m0, s64
	v_lshl_add_u64 v[232:233], s[2:3], 0, v[134:135]
	global_load_lds_dwordx4 v[230:231], off
	v_lshl_add_u64 v[230:231], s[62:63], 0, v[136:137]
	s_add_i32 m0, s64, 0x2000
	s_nop 0
	global_load_lds_dwordx4 v[230:231], off
	v_lshl_add_u64 v[230:231], s[2:3], 0, v[130:131]
	s_mov_b32 m0, s42
	s_nop 0
	global_load_lds_dwordx4 v[230:231], off
	s_mov_b32 m0, s43
	s_nop 0
	global_load_lds_dwordx4 v[232:233], off
	s_waitcnt vmcnt(8)
	s_waitcnt lgkmcnt(0)
	s_setprio 1
	s_barrier
	s_waitcnt lgkmcnt(0)
	v_mfma_f32_16x16x32_bf16 v[62:65], v[144:147], v[194:197], v[62:65]
	v_mfma_f32_16x16x32_bf16 v[58:61], v[168:171], v[194:197], v[58:61]
	v_mfma_f32_16x16x32_bf16 v[50:53], v[144:147], v[202:205], v[50:53]
	v_mfma_f32_16x16x32_bf16 v[42:45], v[168:171], v[202:205], v[42:45]
	v_mfma_f32_16x16x32_bf16 v[34:37], v[144:147], v[210:213], v[34:37]
	v_mfma_f32_16x16x32_bf16 v[26:29], v[168:171], v[210:213], v[26:29]
	v_mfma_f32_16x16x32_bf16 v[18:21], v[144:147], v[218:221], v[18:21]
	v_mfma_f32_16x16x32_bf16 v[10:13], v[168:171], v[218:221], v[10:13]
	v_mfma_f32_16x16x32_bf16 v[62:65], v[164:167], v[198:201], v[62:65]
	v_mfma_f32_16x16x32_bf16 v[58:61], v[172:175], v[198:201], v[58:61]
	v_mfma_f32_16x16x32_bf16 v[50:53], v[164:167], v[206:209], v[50:53]
	v_mfma_f32_16x16x32_bf16 v[42:45], v[172:175], v[206:209], v[42:45]
	v_mfma_f32_16x16x32_bf16 v[34:37], v[164:167], v[214:217], v[34:37]
	v_mfma_f32_16x16x32_bf16 v[26:29], v[172:175], v[214:217], v[26:29]
	v_mfma_f32_16x16x32_bf16 v[18:21], v[164:167], v[222:225], v[18:21]
	v_mfma_f32_16x16x32_bf16 v[10:13], v[172:175], v[222:225], v[10:13]
	s_setprio 0
	s_setprio 1
	v_mfma_f32_16x16x32_bf16 v[54:57], v[178:181], v[194:197], v[54:57]
	v_mfma_f32_16x16x32_bf16 v[46:49], v[186:189], v[194:197], v[46:49]
	v_mfma_f32_16x16x32_bf16 v[38:41], v[178:181], v[202:205], v[38:41]
	v_mfma_f32_16x16x32_bf16 v[30:33], v[186:189], v[202:205], v[30:33]
	v_mfma_f32_16x16x32_bf16 v[22:25], v[178:181], v[210:213], v[22:25]
	v_mfma_f32_16x16x32_bf16 v[14:17], v[186:189], v[210:213], v[14:17]
	v_mfma_f32_16x16x32_bf16 v[6:9], v[178:181], v[218:221], v[6:9]
	v_mfma_f32_16x16x32_bf16 v[2:5], v[186:189], v[218:221], v[2:5]
	v_mfma_f32_16x16x32_bf16 v[54:57], v[182:185], v[198:201], v[54:57]
	v_mfma_f32_16x16x32_bf16 v[46:49], v[190:193], v[198:201], v[46:49]
	v_mfma_f32_16x16x32_bf16 v[38:41], v[182:185], v[206:209], v[38:41]
	v_mfma_f32_16x16x32_bf16 v[30:33], v[190:193], v[206:209], v[30:33]
	v_mfma_f32_16x16x32_bf16 v[22:25], v[182:185], v[214:217], v[22:25]
	v_mfma_f32_16x16x32_bf16 v[14:17], v[190:193], v[214:217], v[14:17]
	v_mfma_f32_16x16x32_bf16 v[6:9], v[182:185], v[222:225], v[6:9]
	v_mfma_f32_16x16x32_bf16 v[2:5], v[190:193], v[222:225], v[2:5]
	s_setprio 0
	s_barrier
	s_add_i32 s62, 0, 0x18000
	v_add_u32_e32 v163, s62, v148
	s_add_i32 s63, 0, 0x1c000
	ds_read_b128 v[144:147], v163
	ds_read_b128 v[164:167], v163 offset:1024
	ds_read_b128 v[168:171], v163 offset:2048
	ds_read_b128 v[172:175], v163 offset:3072
	v_add_u32_e32 v163, s63, v148
	ds_read_b128 v[178:181], v163
	ds_read_b128 v[182:185], v163 offset:1024
	ds_read_b128 v[186:189], v163 offset:2048
	ds_read_b128 v[190:193], v163 offset:3072
	s_add_u32 s2, s2, 0x40000
	s_addc_u32 s3, s3, 0
	s_mov_b32 m0, s44
	v_lshl_add_u64 v[234:235], s[2:3], 0, v[130:131]
	ds_read_b128 v[194:197], v160 offset:32768
	ds_read_b128 v[198:201], v160 offset:33792
	ds_read_b128 v[202:205], v160 offset:34816
	ds_read_b128 v[206:209], v160 offset:35840
	ds_read_b128 v[210:213], v160 offset:36864
	ds_read_b128 v[214:217], v160 offset:37888
	ds_read_b128 v[218:221], v160 offset:38912
	ds_read_b128 v[222:225], v160 offset:39936
	global_load_lds_dwordx4 v[234:235], off
	v_lshl_add_u64 v[234:235], s[2:3], 0, v[134:135]
	s_mov_b32 m0, s45
	s_nop 0
	global_load_lds_dwordx4 v[234:235], off
	s_waitcnt vmcnt(8)
	s_waitcnt lgkmcnt(0)
	s_setprio 1
	s_barrier
	s_waitcnt lgkmcnt(0)
	v_mfma_f32_16x16x32_bf16 v[126:129], v[144:147], v[194:197], v[126:129]
	v_mfma_f32_16x16x32_bf16 v[122:125], v[168:171], v[194:197], v[122:125]
	v_mfma_f32_16x16x32_bf16 v[114:117], v[144:147], v[202:205], v[114:117]
	v_mfma_f32_16x16x32_bf16 v[106:109], v[168:171], v[202:205], v[106:109]
	v_mfma_f32_16x16x32_bf16 v[98:101], v[144:147], v[210:213], v[98:101]
	v_mfma_f32_16x16x32_bf16 v[90:93], v[168:171], v[210:213], v[90:93]
	v_mfma_f32_16x16x32_bf16 v[82:85], v[144:147], v[218:221], v[82:85]
	v_mfma_f32_16x16x32_bf16 v[74:77], v[168:171], v[218:221], v[74:77]
	v_mfma_f32_16x16x32_bf16 v[126:129], v[164:167], v[198:201], v[126:129]
	v_mfma_f32_16x16x32_bf16 v[122:125], v[172:175], v[198:201], v[122:125]
	v_mfma_f32_16x16x32_bf16 v[114:117], v[164:167], v[206:209], v[114:117]
	v_mfma_f32_16x16x32_bf16 v[106:109], v[172:175], v[206:209], v[106:109]
	v_mfma_f32_16x16x32_bf16 v[98:101], v[164:167], v[214:217], v[98:101]
	v_mfma_f32_16x16x32_bf16 v[90:93], v[172:175], v[214:217], v[90:93]
	v_mfma_f32_16x16x32_bf16 v[82:85], v[164:167], v[222:225], v[82:85]
	v_mfma_f32_16x16x32_bf16 v[74:77], v[172:175], v[222:225], v[74:77]
	s_setprio 0
	s_setprio 1
	v_mfma_f32_16x16x32_bf16 v[118:121], v[178:181], v[194:197], v[118:121]
	v_mfma_f32_16x16x32_bf16 v[110:113], v[186:189], v[194:197], v[110:113]
	v_mfma_f32_16x16x32_bf16 v[102:105], v[178:181], v[202:205], v[102:105]
	v_mfma_f32_16x16x32_bf16 v[94:97], v[186:189], v[202:205], v[94:97]
	v_mfma_f32_16x16x32_bf16 v[86:89], v[178:181], v[210:213], v[86:89]
	v_mfma_f32_16x16x32_bf16 v[78:81], v[186:189], v[210:213], v[78:81]
	v_mfma_f32_16x16x32_bf16 v[70:73], v[178:181], v[218:221], v[70:73]
	v_mfma_f32_16x16x32_bf16 v[66:69], v[186:189], v[218:221], v[66:69]
	v_mfma_f32_16x16x32_bf16 v[118:121], v[182:185], v[198:201], v[118:121]
	v_mfma_f32_16x16x32_bf16 v[110:113], v[190:193], v[198:201], v[110:113]
	v_mfma_f32_16x16x32_bf16 v[102:105], v[182:185], v[206:209], v[102:105]
	v_mfma_f32_16x16x32_bf16 v[94:97], v[190:193], v[206:209], v[94:97]
	v_mfma_f32_16x16x32_bf16 v[86:89], v[182:185], v[214:217], v[86:89]
	v_mfma_f32_16x16x32_bf16 v[78:81], v[190:193], v[214:217], v[78:81]
	v_mfma_f32_16x16x32_bf16 v[70:73], v[182:185], v[222:225], v[70:73]
	v_mfma_f32_16x16x32_bf16 v[66:69], v[190:193], v[222:225], v[66:69]
	s_setprio 0
	s_barrier
	s_add_i32 s2, s62, s41
	v_lshl_add_u64 v[226:227], v[226:227], 0, s[10:11]
	s_mov_b32 m0, s2
	ds_read_b128 v[194:197], v160 offset:49152
	ds_read_b128 v[198:201], v160 offset:50176
	ds_read_b128 v[202:205], v160 offset:51200
	ds_read_b128 v[206:209], v160 offset:52224
	ds_read_b128 v[210:213], v160 offset:53248
	ds_read_b128 v[214:217], v160 offset:54272
	ds_read_b128 v[218:221], v160 offset:55296
	ds_read_b128 v[222:225], v160 offset:56320
	global_load_lds_dwordx4 v[226:227], off
	s_add_i32 m0, s2, 0x2000
	s_add_u32 s2, s38, 0x40080
	v_lshl_add_u64 v[226:227], v[228:229], 0, s[10:11]
	s_addc_u32 s3, s39, 0
	s_add_i32 s38, s63, s41
	global_load_lds_dwordx4 v[226:227], off
	v_lshl_add_u64 v[226:227], s[2:3], 0, v[132:133]
	s_mov_b32 m0, s38
	s_nop 0
	global_load_lds_dwordx4 v[226:227], off
	v_lshl_add_u64 v[226:227], s[2:3], 0, v[136:137]
	s_add_i32 m0, s38, 0x2000
	s_nop 0
	global_load_lds_dwordx4 v[226:227], off
	v_lshl_add_u64 v[226:227], v[230:231], 0, s[10:11]
	s_mov_b32 m0, s47
	s_nop 0
	global_load_lds_dwordx4 v[226:227], off
	v_lshl_add_u64 v[226:227], v[232:233], 0, s[10:11]
	s_mov_b32 m0, s48
	s_nop 0
	global_load_lds_dwordx4 v[226:227], off
	s_waitcnt vmcnt(8)
	s_waitcnt lgkmcnt(0)
	s_setprio 1
	s_barrier
	s_waitcnt lgkmcnt(0)
	v_mfma_f32_16x16x32_bf16 v[62:65], v[144:147], v[194:197], v[62:65]
	v_mfma_f32_16x16x32_bf16 v[58:61], v[168:171], v[194:197], v[58:61]
	v_mfma_f32_16x16x32_bf16 v[50:53], v[144:147], v[202:205], v[50:53]
	v_mfma_f32_16x16x32_bf16 v[42:45], v[168:171], v[202:205], v[42:45]
	v_mfma_f32_16x16x32_bf16 v[34:37], v[144:147], v[210:213], v[34:37]
	v_mfma_f32_16x16x32_bf16 v[26:29], v[168:171], v[210:213], v[26:29]
	v_mfma_f32_16x16x32_bf16 v[18:21], v[144:147], v[218:221], v[18:21]
	v_mfma_f32_16x16x32_bf16 v[10:13], v[168:171], v[218:221], v[10:13]
	v_mfma_f32_16x16x32_bf16 v[62:65], v[164:167], v[198:201], v[62:65]
	v_mfma_f32_16x16x32_bf16 v[58:61], v[172:175], v[198:201], v[58:61]
	v_mfma_f32_16x16x32_bf16 v[50:53], v[164:167], v[206:209], v[50:53]
	v_mfma_f32_16x16x32_bf16 v[42:45], v[172:175], v[206:209], v[42:45]
	v_mfma_f32_16x16x32_bf16 v[34:37], v[164:167], v[214:217], v[34:37]
	v_mfma_f32_16x16x32_bf16 v[26:29], v[172:175], v[214:217], v[26:29]
	v_mfma_f32_16x16x32_bf16 v[18:21], v[164:167], v[222:225], v[18:21]
	v_mfma_f32_16x16x32_bf16 v[10:13], v[172:175], v[222:225], v[10:13]
	s_setprio 0
	s_setprio 1
	v_mfma_f32_16x16x32_bf16 v[54:57], v[178:181], v[194:197], v[54:57]
	v_mfma_f32_16x16x32_bf16 v[46:49], v[186:189], v[194:197], v[46:49]
	v_mfma_f32_16x16x32_bf16 v[38:41], v[178:181], v[202:205], v[38:41]
	v_mfma_f32_16x16x32_bf16 v[30:33], v[186:189], v[202:205], v[30:33]
	v_mfma_f32_16x16x32_bf16 v[22:25], v[178:181], v[210:213], v[22:25]
	v_mfma_f32_16x16x32_bf16 v[14:17], v[186:189], v[210:213], v[14:17]
	v_mfma_f32_16x16x32_bf16 v[6:9], v[178:181], v[218:221], v[6:9]
	v_mfma_f32_16x16x32_bf16 v[2:5], v[186:189], v[218:221], v[2:5]
	v_mfma_f32_16x16x32_bf16 v[54:57], v[182:185], v[198:201], v[54:57]
	v_mfma_f32_16x16x32_bf16 v[46:49], v[190:193], v[198:201], v[46:49]
	v_mfma_f32_16x16x32_bf16 v[38:41], v[182:185], v[206:209], v[38:41]
	v_mfma_f32_16x16x32_bf16 v[30:33], v[190:193], v[206:209], v[30:33]
	v_mfma_f32_16x16x32_bf16 v[22:25], v[182:185], v[214:217], v[22:25]
	v_mfma_f32_16x16x32_bf16 v[14:17], v[190:193], v[214:217], v[14:17]
	v_mfma_f32_16x16x32_bf16 v[6:9], v[182:185], v[222:225], v[6:9]
	v_mfma_f32_16x16x32_bf16 v[2:5], v[190:193], v[222:225], v[2:5]
	s_setprio 0
	s_barrier
	s_add_i32 s61, s61, 2
	s_add_u32 s36, s36, 0x100
	s_addc_u32 s37, s37, 0
	s_add_u32 s59, s59, 0x100
	s_addc_u32 s60, s60, 0
	s_cmp_gt_u32 s61, 13
	s_cbranch_scc0 .LBB0_1179

.Lpk1239_peel:
	ds_read_b128 v[152:155], v148
	ds_read_b128 v[156:159], v148 offset:1024
	ds_read_b128 v[160:163], v148 offset:2048
	ds_read_b128 v[164:167], v148 offset:3072
	ds_read_b128 v[168:171], v149
	ds_read_b128 v[172:175], v149 offset:1024
	ds_read_b128 v[178:181], v149 offset:2048
	ds_read_b128 v[182:185], v149 offset:3072
	s_add_u32 s2, s36, 0xfffc0080
	s_addc_u32 s3, s37, -1
	s_cmp_eq_u32 s62, 12
	s_cselect_b32 s3, s19, s3
	s_cselect_b32 s2, s21, s2
	s_cselect_b32 s39, s58, s61
	s_cselect_b32 s38, s59, s60
	v_lshl_add_u64 v[144:145], s[36:37], 0, v[138:139]
	s_add_i32 m0, s44, 0xc000
	ds_read_b128 v[186:189], v150
	ds_read_b128 v[190:193], v150 offset:1024
	ds_read_b128 v[194:197], v150 offset:2048
	ds_read_b128 v[198:201], v150 offset:3072
	ds_read_b128 v[202:205], v150 offset:4096
	ds_read_b128 v[206:209], v150 offset:5120
	ds_read_b128 v[210:213], v150 offset:6144
	ds_read_b128 v[214:217], v150 offset:7168
	global_load_lds_dwordx4 v[144:145], off
	v_lshl_add_u64 v[144:145], s[36:37], 0, v[140:141]
	s_add_i32 m0, s44, 0xe000
	s_nop 0
	global_load_lds_dwordx4 v[144:145], off
	s_waitcnt vmcnt(8)
	s_waitcnt lgkmcnt(0)
	s_setprio 1
	s_barrier
	s_waitcnt lgkmcnt(0)
	v_mfma_f32_16x16x32_bf16 v[126:129], v[152:155], v[186:189], 0
	v_mfma_f32_16x16x32_bf16 v[122:125], v[160:163], v[186:189], 0
	v_mfma_f32_16x16x32_bf16 v[114:117], v[152:155], v[194:197], 0
	v_mfma_f32_16x16x32_bf16 v[106:109], v[160:163], v[194:197], 0
	v_mfma_f32_16x16x32_bf16 v[98:101], v[152:155], v[202:205], 0
	v_mfma_f32_16x16x32_bf16 v[90:93], v[160:163], v[202:205], 0
	v_mfma_f32_16x16x32_bf16 v[82:85], v[152:155], v[210:213], 0
	v_mfma_f32_16x16x32_bf16 v[74:77], v[160:163], v[210:213], 0
	v_mfma_f32_16x16x32_bf16 v[126:129], v[156:159], v[190:193], v[126:129]
	v_mfma_f32_16x16x32_bf16 v[122:125], v[164:167], v[190:193], v[122:125]
	v_mfma_f32_16x16x32_bf16 v[114:117], v[156:159], v[198:201], v[114:117]
	v_mfma_f32_16x16x32_bf16 v[106:109], v[164:167], v[198:201], v[106:109]
	v_mfma_f32_16x16x32_bf16 v[98:101], v[156:159], v[206:209], v[98:101]
	v_mfma_f32_16x16x32_bf16 v[90:93], v[164:167], v[206:209], v[90:93]
	v_mfma_f32_16x16x32_bf16 v[82:85], v[156:159], v[214:217], v[82:85]
	v_mfma_f32_16x16x32_bf16 v[74:77], v[164:167], v[214:217], v[74:77]
	s_setprio 0
	s_setprio 1
	v_mfma_f32_16x16x32_bf16 v[118:121], v[168:171], v[186:189], 0
	v_mfma_f32_16x16x32_bf16 v[110:113], v[178:181], v[186:189], 0
	v_mfma_f32_16x16x32_bf16 v[102:105], v[168:171], v[194:197], 0
	v_mfma_f32_16x16x32_bf16 v[94:97], v[178:181], v[194:197], 0
	v_mfma_f32_16x16x32_bf16 v[86:89], v[168:171], v[202:205], 0
	v_mfma_f32_16x16x32_bf16 v[78:81], v[178:181], v[202:205], 0
	v_mfma_f32_16x16x32_bf16 v[70:73], v[168:171], v[210:213], 0
	v_mfma_f32_16x16x32_bf16 v[66:69], v[178:181], v[210:213], 0
	v_mfma_f32_16x16x32_bf16 v[118:121], v[172:175], v[190:193], v[118:121]
	v_mfma_f32_16x16x32_bf16 v[110:113], v[182:185], v[190:193], v[110:113]
	v_mfma_f32_16x16x32_bf16 v[102:105], v[172:175], v[198:201], v[102:105]
	v_mfma_f32_16x16x32_bf16 v[94:97], v[182:185], v[198:201], v[94:97]
	v_mfma_f32_16x16x32_bf16 v[86:89], v[172:175], v[206:209], v[86:89]
	v_mfma_f32_16x16x32_bf16 v[78:81], v[182:185], v[206:209], v[78:81]
	v_mfma_f32_16x16x32_bf16 v[70:73], v[172:175], v[214:217], v[70:73]
	v_mfma_f32_16x16x32_bf16 v[66:69], v[182:185], v[214:217], v[66:69]
	s_setprio 0
	s_barrier
	s_add_i32 s63, s51, s43
	v_lshl_add_u64 v[144:145], s[38:39], 0, v[132:133]
	s_mov_b32 m0, s63
	ds_read_b128 v[186:189], v150 offset:16384
	ds_read_b128 v[190:193], v150 offset:17408
	ds_read_b128 v[194:197], v150 offset:18432
	ds_read_b128 v[198:201], v150 offset:19456
	ds_read_b128 v[202:205], v150 offset:20480
	ds_read_b128 v[206:209], v150 offset:21504
	ds_read_b128 v[210:213], v150 offset:22528
	ds_read_b128 v[214:217], v150 offset:23552
	global_load_lds_dwordx4 v[144:145], off
	s_add_i32 m0, s63, 0x2000
	s_add_u32 s64, s38, 0x40000
	v_lshl_add_u64 v[218:219], s[38:39], 0, v[136:137]
	s_addc_u32 s65, s39, 0
	s_add_i32 s63, s52, s43
	global_load_lds_dwordx4 v[218:219], off
	v_lshl_add_u64 v[220:221], s[64:65], 0, v[132:133]
	s_mov_b32 m0, s63
	v_lshl_add_u64 v[222:223], s[2:3], 0, v[134:135]
	global_load_lds_dwordx4 v[220:221], off
	v_lshl_add_u64 v[220:221], s[64:65], 0, v[136:137]
	s_add_i32 m0, s63, 0x2000
	s_nop 0
	global_load_lds_dwordx4 v[220:221], off
	v_lshl_add_u64 v[220:221], s[2:3], 0, v[130:131]
	s_mov_b32 m0, s44
	s_nop 0
	global_load_lds_dwordx4 v[220:221], off
	s_mov_b32 m0, s35
	s_nop 0
	global_load_lds_dwordx4 v[222:223], off
	s_waitcnt vmcnt(8)
	s_waitcnt lgkmcnt(0)
	s_setprio 1
	s_barrier
	s_waitcnt lgkmcnt(0)
	v_mfma_f32_16x16x32_bf16 v[62:65], v[152:155], v[186:189], 0
	v_mfma_f32_16x16x32_bf16 v[58:61], v[160:163], v[186:189], 0
	v_mfma_f32_16x16x32_bf16 v[50:53], v[152:155], v[194:197], 0
	v_mfma_f32_16x16x32_bf16 v[42:45], v[160:163], v[194:197], 0
	v_mfma_f32_16x16x32_bf16 v[34:37], v[152:155], v[202:205], 0
	v_mfma_f32_16x16x32_bf16 v[26:29], v[160:163], v[202:205], 0
	v_mfma_f32_16x16x32_bf16 v[18:21], v[152:155], v[210:213], 0
	v_mfma_f32_16x16x32_bf16 v[10:13], v[160:163], v[210:213], 0
	v_mfma_f32_16x16x32_bf16 v[62:65], v[156:159], v[190:193], v[62:65]
	v_mfma_f32_16x16x32_bf16 v[58:61], v[164:167], v[190:193], v[58:61]
	v_mfma_f32_16x16x32_bf16 v[50:53], v[156:159], v[198:201], v[50:53]
	v_mfma_f32_16x16x32_bf16 v[42:45], v[164:167], v[198:201], v[42:45]
	v_mfma_f32_16x16x32_bf16 v[34:37], v[156:159], v[206:209], v[34:37]
	v_mfma_f32_16x16x32_bf16 v[26:29], v[164:167], v[206:209], v[26:29]
	v_mfma_f32_16x16x32_bf16 v[18:21], v[156:159], v[214:217], v[18:21]
	v_mfma_f32_16x16x32_bf16 v[10:13], v[164:167], v[214:217], v[10:13]
	s_setprio 0
	s_setprio 1
	v_mfma_f32_16x16x32_bf16 v[54:57], v[168:171], v[186:189], 0
	v_mfma_f32_16x16x32_bf16 v[46:49], v[178:181], v[186:189], 0
	v_mfma_f32_16x16x32_bf16 v[38:41], v[168:171], v[194:197], 0
	v_mfma_f32_16x16x32_bf16 v[30:33], v[178:181], v[194:197], 0
	v_mfma_f32_16x16x32_bf16 v[22:25], v[168:171], v[202:205], 0
	v_mfma_f32_16x16x32_bf16 v[14:17], v[178:181], v[202:205], 0
	v_mfma_f32_16x16x32_bf16 v[6:9], v[168:171], v[210:213], 0
	v_mfma_f32_16x16x32_bf16 v[2:5], v[178:181], v[210:213], 0
	v_mfma_f32_16x16x32_bf16 v[54:57], v[172:175], v[190:193], v[54:57]
	v_mfma_f32_16x16x32_bf16 v[46:49], v[182:185], v[190:193], v[46:49]
	v_mfma_f32_16x16x32_bf16 v[38:41], v[172:175], v[198:201], v[38:41]
	v_mfma_f32_16x16x32_bf16 v[30:33], v[182:185], v[198:201], v[30:33]
	v_mfma_f32_16x16x32_bf16 v[22:25], v[172:175], v[206:209], v[22:25]
	v_mfma_f32_16x16x32_bf16 v[14:17], v[182:185], v[206:209], v[14:17]
	v_mfma_f32_16x16x32_bf16 v[6:9], v[172:175], v[214:217], v[6:9]
	v_mfma_f32_16x16x32_bf16 v[2:5], v[182:185], v[214:217], v[2:5]
	s_setprio 0
	s_barrier
	s_add_i32 s63, 0, 0x18000
	v_add_u32_e32 v151, s63, v146
	s_add_i32 s64, 0, 0x1c000
	ds_read_b128 v[152:155], v151
	ds_read_b128 v[156:159], v151 offset:1024
	ds_read_b128 v[160:163], v151 offset:2048
	ds_read_b128 v[164:167], v151 offset:3072
	v_add_u32_e32 v151, s64, v146
	ds_read_b128 v[168:171], v151
	ds_read_b128 v[172:175], v151 offset:1024
	ds_read_b128 v[178:181], v151 offset:2048
	ds_read_b128 v[182:185], v151 offset:3072
	s_add_u32 s2, s2, 0x40000
	s_addc_u32 s3, s3, 0
	s_mov_b32 m0, s45
	v_lshl_add_u64 v[224:225], s[2:3], 0, v[130:131]
	ds_read_b128 v[186:189], v150 offset:32768
	ds_read_b128 v[190:193], v150 offset:33792
	ds_read_b128 v[194:197], v150 offset:34816
	ds_read_b128 v[198:201], v150 offset:35840
	ds_read_b128 v[202:205], v150 offset:36864
	ds_read_b128 v[206:209], v150 offset:37888
	ds_read_b128 v[210:213], v150 offset:38912
	ds_read_b128 v[214:217], v150 offset:39936
	global_load_lds_dwordx4 v[224:225], off
	v_lshl_add_u64 v[224:225], s[2:3], 0, v[134:135]
	s_mov_b32 m0, s46
	s_nop 0
	global_load_lds_dwordx4 v[224:225], off
	s_waitcnt vmcnt(8)
	s_waitcnt lgkmcnt(0)
	s_setprio 1
	s_barrier
	s_waitcnt lgkmcnt(0)
	v_mfma_f32_16x16x32_bf16 v[126:129], v[152:155], v[186:189], v[126:129]
	v_mfma_f32_16x16x32_bf16 v[122:125], v[160:163], v[186:189], v[122:125]
	v_mfma_f32_16x16x32_bf16 v[114:117], v[152:155], v[194:197], v[114:117]
	v_mfma_f32_16x16x32_bf16 v[106:109], v[160:163], v[194:197], v[106:109]
	v_mfma_f32_16x16x32_bf16 v[98:101], v[152:155], v[202:205], v[98:101]
	v_mfma_f32_16x16x32_bf16 v[90:93], v[160:163], v[202:205], v[90:93]
	v_mfma_f32_16x16x32_bf16 v[82:85], v[152:155], v[210:213], v[82:85]
	v_mfma_f32_16x16x32_bf16 v[74:77], v[160:163], v[210:213], v[74:77]
	v_mfma_f32_16x16x32_bf16 v[126:129], v[156:159], v[190:193], v[126:129]
	v_mfma_f32_16x16x32_bf16 v[122:125], v[164:167], v[190:193], v[122:125]
	v_mfma_f32_16x16x32_bf16 v[114:117], v[156:159], v[198:201], v[114:117]
	v_mfma_f32_16x16x32_bf16 v[106:109], v[164:167], v[198:201], v[106:109]
	v_mfma_f32_16x16x32_bf16 v[98:101], v[156:159], v[206:209], v[98:101]
	v_mfma_f32_16x16x32_bf16 v[90:93], v[164:167], v[206:209], v[90:93]
	v_mfma_f32_16x16x32_bf16 v[82:85], v[156:159], v[214:217], v[82:85]
	v_mfma_f32_16x16x32_bf16 v[74:77], v[164:167], v[214:217], v[74:77]
	s_setprio 0
	s_setprio 1
	v_mfma_f32_16x16x32_bf16 v[118:121], v[168:171], v[186:189], v[118:121]
	v_mfma_f32_16x16x32_bf16 v[110:113], v[178:181], v[186:189], v[110:113]
	v_mfma_f32_16x16x32_bf16 v[102:105], v[168:171], v[194:197], v[102:105]
	v_mfma_f32_16x16x32_bf16 v[94:97], v[178:181], v[194:197], v[94:97]
	v_mfma_f32_16x16x32_bf16 v[86:89], v[168:171], v[202:205], v[86:89]
	v_mfma_f32_16x16x32_bf16 v[78:81], v[178:181], v[202:205], v[78:81]
	v_mfma_f32_16x16x32_bf16 v[70:73], v[168:171], v[210:213], v[70:73]
	v_mfma_f32_16x16x32_bf16 v[66:69], v[178:181], v[210:213], v[66:69]
	v_mfma_f32_16x16x32_bf16 v[118:121], v[172:175], v[190:193], v[118:121]
	v_mfma_f32_16x16x32_bf16 v[110:113], v[182:185], v[190:193], v[110:113]
	v_mfma_f32_16x16x32_bf16 v[102:105], v[172:175], v[198:201], v[102:105]
	v_mfma_f32_16x16x32_bf16 v[94:97], v[182:185], v[198:201], v[94:97]
	v_mfma_f32_16x16x32_bf16 v[86:89], v[172:175], v[206:209], v[86:89]
	v_mfma_f32_16x16x32_bf16 v[78:81], v[182:185], v[206:209], v[78:81]
	v_mfma_f32_16x16x32_bf16 v[70:73], v[172:175], v[214:217], v[70:73]
	v_mfma_f32_16x16x32_bf16 v[66:69], v[182:185], v[214:217], v[66:69]
	s_setprio 0
	s_barrier
	s_add_i32 s2, s63, s43
	v_lshl_add_u64 v[144:145], v[144:145], 0, s[8:9]
	s_mov_b32 m0, s2
	ds_read_b128 v[186:189], v150 offset:49152
	ds_read_b128 v[190:193], v150 offset:50176
	ds_read_b128 v[194:197], v150 offset:51200
	ds_read_b128 v[198:201], v150 offset:52224
	ds_read_b128 v[202:205], v150 offset:53248
	ds_read_b128 v[206:209], v150 offset:54272
	ds_read_b128 v[210:213], v150 offset:55296
	ds_read_b128 v[214:217], v150 offset:56320
	global_load_lds_dwordx4 v[144:145], off
	s_add_i32 m0, s2, 0x2000
	s_add_u32 s2, s38, 0x40080
	v_lshl_add_u64 v[144:145], v[218:219], 0, s[8:9]
	s_addc_u32 s3, s39, 0
	s_add_i32 s38, s64, s43
	global_load_lds_dwordx4 v[144:145], off
	v_lshl_add_u64 v[144:145], s[2:3], 0, v[132:133]
	s_mov_b32 m0, s38
	s_nop 0
	global_load_lds_dwordx4 v[144:145], off
	v_lshl_add_u64 v[144:145], s[2:3], 0, v[136:137]
	s_add_i32 m0, s38, 0x2000
	s_nop 0
	global_load_lds_dwordx4 v[144:145], off
	v_lshl_add_u64 v[144:145], v[220:221], 0, s[8:9]
	s_mov_b32 m0, s48
	s_nop 0
	global_load_lds_dwordx4 v[144:145], off
	v_lshl_add_u64 v[144:145], v[222:223], 0, s[8:9]
	s_mov_b32 m0, s49
	s_nop 0
	global_load_lds_dwordx4 v[144:145], off
	s_waitcnt vmcnt(8)
	s_waitcnt lgkmcnt(0)
	s_setprio 1
	s_barrier
	s_waitcnt lgkmcnt(0)
	v_mfma_f32_16x16x32_bf16 v[62:65], v[152:155], v[186:189], v[62:65]
	v_mfma_f32_16x16x32_bf16 v[58:61], v[160:163], v[186:189], v[58:61]
	v_mfma_f32_16x16x32_bf16 v[50:53], v[152:155], v[194:197], v[50:53]
	v_mfma_f32_16x16x32_bf16 v[42:45], v[160:163], v[194:197], v[42:45]
	v_mfma_f32_16x16x32_bf16 v[34:37], v[152:155], v[202:205], v[34:37]
	v_mfma_f32_16x16x32_bf16 v[26:29], v[160:163], v[202:205], v[26:29]
	v_mfma_f32_16x16x32_bf16 v[18:21], v[152:155], v[210:213], v[18:21]
	v_mfma_f32_16x16x32_bf16 v[10:13], v[160:163], v[210:213], v[10:13]
	v_mfma_f32_16x16x32_bf16 v[62:65], v[156:159], v[190:193], v[62:65]
	v_mfma_f32_16x16x32_bf16 v[58:61], v[164:167], v[190:193], v[58:61]
	v_mfma_f32_16x16x32_bf16 v[50:53], v[156:159], v[198:201], v[50:53]
	v_mfma_f32_16x16x32_bf16 v[42:45], v[164:167], v[198:201], v[42:45]
	v_mfma_f32_16x16x32_bf16 v[34:37], v[156:159], v[206:209], v[34:37]
	v_mfma_f32_16x16x32_bf16 v[26:29], v[164:167], v[206:209], v[26:29]
	v_mfma_f32_16x16x32_bf16 v[18:21], v[156:159], v[214:217], v[18:21]
	v_mfma_f32_16x16x32_bf16 v[10:13], v[164:167], v[214:217], v[10:13]
	s_setprio 0
	s_setprio 1
	v_mfma_f32_16x16x32_bf16 v[54:57], v[168:171], v[186:189], v[54:57]
	v_mfma_f32_16x16x32_bf16 v[46:49], v[178:181], v[186:189], v[46:49]
	v_mfma_f32_16x16x32_bf16 v[38:41], v[168:171], v[194:197], v[38:41]
	v_mfma_f32_16x16x32_bf16 v[30:33], v[178:181], v[194:197], v[30:33]
	v_mfma_f32_16x16x32_bf16 v[22:25], v[168:171], v[202:205], v[22:25]
	v_mfma_f32_16x16x32_bf16 v[14:17], v[178:181], v[202:205], v[14:17]
	v_mfma_f32_16x16x32_bf16 v[6:9], v[168:171], v[210:213], v[6:9]
	v_mfma_f32_16x16x32_bf16 v[2:5], v[178:181], v[210:213], v[2:5]
	v_mfma_f32_16x16x32_bf16 v[54:57], v[172:175], v[190:193], v[54:57]
	v_mfma_f32_16x16x32_bf16 v[46:49], v[182:185], v[190:193], v[46:49]
	v_mfma_f32_16x16x32_bf16 v[38:41], v[172:175], v[198:201], v[38:41]
	v_mfma_f32_16x16x32_bf16 v[30:33], v[182:185], v[198:201], v[30:33]
	v_mfma_f32_16x16x32_bf16 v[22:25], v[172:175], v[206:209], v[22:25]
	v_mfma_f32_16x16x32_bf16 v[14:17], v[182:185], v[206:209], v[14:17]
	v_mfma_f32_16x16x32_bf16 v[6:9], v[172:175], v[214:217], v[6:9]
	v_mfma_f32_16x16x32_bf16 v[2:5], v[182:185], v[214:217], v[2:5]
	s_setprio 0
	s_barrier
	s_add_i32 s62, s62, 2
	s_add_u32 s36, s36, 0x100
	s_addc_u32 s37, s37, 0
	s_add_u32 s60, s60, 0x100
	s_addc_u32 s61, s61, 0
	s_cmp_gt_u32 s62, 13
	s_cbranch_scc0 .LBB0_1239
	s_branch .Lpk1239_exit
.LBB0_1239:
	ds_read_b128 v[152:155], v148
	ds_read_b128 v[156:159], v148 offset:1024
	ds_read_b128 v[160:163], v148 offset:2048
	ds_read_b128 v[164:167], v148 offset:3072
	ds_read_b128 v[168:171], v149
	ds_read_b128 v[172:175], v149 offset:1024
	ds_read_b128 v[178:181], v149 offset:2048
	ds_read_b128 v[182:185], v149 offset:3072
	s_add_u32 s2, s36, 0xfffc0080
	s_addc_u32 s3, s37, -1
	s_cmp_eq_u32 s62, 12
	s_cselect_b32 s3, s19, s3
	s_cselect_b32 s2, s21, s2
	s_cselect_b32 s39, s58, s61
	s_cselect_b32 s38, s59, s60
	v_lshl_add_u64 v[144:145], s[36:37], 0, v[138:139]
	s_add_i32 m0, s44, 0xc000
	ds_read_b128 v[186:189], v150
	ds_read_b128 v[190:193], v150 offset:1024
	ds_read_b128 v[194:197], v150 offset:2048
	ds_read_b128 v[198:201], v150 offset:3072
	ds_read_b128 v[202:205], v150 offset:4096
	ds_read_b128 v[206:209], v150 offset:5120
	ds_read_b128 v[210:213], v150 offset:6144
	ds_read_b128 v[214:217], v150 offset:7168
	global_load_lds_dwordx4 v[144:145], off
	v_lshl_add_u64 v[144:145], s[36:37], 0, v[140:141]
	s_add_i32 m0, s44, 0xe000
	s_nop 0
	global_load_lds_dwordx4 v[144:145], off
	s_waitcnt vmcnt(8)
	s_waitcnt lgkmcnt(0)
	s_setprio 1
	s_barrier
	s_waitcnt lgkmcnt(0)
	v_mfma_f32_16x16x32_bf16 v[126:129], v[152:155], v[186:189], v[126:129]
	v_mfma_f32_16x16x32_bf16 v[122:125], v[160:163], v[186:189], v[122:125]
	v_mfma_f32_16x16x32_bf16 v[114:117], v[152:155], v[194:197], v[114:117]
	v_mfma_f32_16x16x32_bf16 v[106:109], v[160:163], v[194:197], v[106:109]
	v_mfma_f32_16x16x32_bf16 v[98:101], v[152:155], v[202:205], v[98:101]
	v_mfma_f32_16x16x32_bf16 v[90:93], v[160:163], v[202:205], v[90:93]
	v_mfma_f32_16x16x32_bf16 v[82:85], v[152:155], v[210:213], v[82:85]
	v_mfma_f32_16x16x32_bf16 v[74:77], v[160:163], v[210:213], v[74:77]
	v_mfma_f32_16x16x32_bf16 v[126:129], v[156:159], v[190:193], v[126:129]
	v_mfma_f32_16x16x32_bf16 v[122:125], v[164:167], v[190:193], v[122:125]
	v_mfma_f32_16x16x32_bf16 v[114:117], v[156:159], v[198:201], v[114:117]
	v_mfma_f32_16x16x32_bf16 v[106:109], v[164:167], v[198:201], v[106:109]
	v_mfma_f32_16x16x32_bf16 v[98:101], v[156:159], v[206:209], v[98:101]
	v_mfma_f32_16x16x32_bf16 v[90:93], v[164:167], v[206:209], v[90:93]
	v_mfma_f32_16x16x32_bf16 v[82:85], v[156:159], v[214:217], v[82:85]
	v_mfma_f32_16x16x32_bf16 v[74:77], v[164:167], v[214:217], v[74:77]
	s_setprio 0
	s_setprio 1
	v_mfma_f32_16x16x32_bf16 v[118:121], v[168:171], v[186:189], v[118:121]
	v_mfma_f32_16x16x32_bf16 v[110:113], v[178:181], v[186:189], v[110:113]
	v_mfma_f32_16x16x32_bf16 v[102:105], v[168:171], v[194:197], v[102:105]
	v_mfma_f32_16x16x32_bf16 v[94:97], v[178:181], v[194:197], v[94:97]
	v_mfma_f32_16x16x32_bf16 v[86:89], v[168:171], v[202:205], v[86:89]
	v_mfma_f32_16x16x32_bf16 v[78:81], v[178:181], v[202:205], v[78:81]
	v_mfma_f32_16x16x32_bf16 v[70:73], v[168:171], v[210:213], v[70:73]
	v_mfma_f32_16x16x32_bf16 v[66:69], v[178:181], v[210:213], v[66:69]
	v_mfma_f32_16x16x32_bf16 v[118:121], v[172:175], v[190:193], v[118:121]
	v_mfma_f32_16x16x32_bf16 v[110:113], v[182:185], v[190:193], v[110:113]
	v_mfma_f32_16x16x32_bf16 v[102:105], v[172:175], v[198:201], v[102:105]
	v_mfma_f32_16x16x32_bf16 v[94:97], v[182:185], v[198:201], v[94:97]
	v_mfma_f32_16x16x32_bf16 v[86:89], v[172:175], v[206:209], v[86:89]
	v_mfma_f32_16x16x32_bf16 v[78:81], v[182:185], v[206:209], v[78:81]
	v_mfma_f32_16x16x32_bf16 v[70:73], v[172:175], v[214:217], v[70:73]
	v_mfma_f32_16x16x32_bf16 v[66:69], v[182:185], v[214:217], v[66:69]
	s_setprio 0
	s_barrier
	s_add_i32 s63, s51, s43
	v_lshl_add_u64 v[144:145], s[38:39], 0, v[132:133]
	s_mov_b32 m0, s63
	ds_read_b128 v[186:189], v150 offset:16384
	ds_read_b128 v[190:193], v150 offset:17408
	ds_read_b128 v[194:197], v150 offset:18432
	ds_read_b128 v[198:201], v150 offset:19456
	ds_read_b128 v[202:205], v150 offset:20480
	ds_read_b128 v[206:209], v150 offset:21504
	ds_read_b128 v[210:213], v150 offset:22528
	ds_read_b128 v[214:217], v150 offset:23552
	global_load_lds_dwordx4 v[144:145], off
	s_add_i32 m0, s63, 0x2000
	s_add_u32 s64, s38, 0x40000
	v_lshl_add_u64 v[218:219], s[38:39], 0, v[136:137]
	s_addc_u32 s65, s39, 0
	s_add_i32 s63, s52, s43
	global_load_lds_dwordx4 v[218:219], off
	v_lshl_add_u64 v[220:221], s[64:65], 0, v[132:133]
	s_mov_b32 m0, s63
	v_lshl_add_u64 v[222:223], s[2:3], 0, v[134:135]
	global_load_lds_dwordx4 v[220:221], off
	v_lshl_add_u64 v[220:221], s[64:65], 0, v[136:137]
	s_add_i32 m0, s63, 0x2000
	s_nop 0
	global_load_lds_dwordx4 v[220:221], off
	v_lshl_add_u64 v[220:221], s[2:3], 0, v[130:131]
	s_mov_b32 m0, s44
	s_nop 0
	global_load_lds_dwordx4 v[220:221], off
	s_mov_b32 m0, s35
	s_nop 0
	global_load_lds_dwordx4 v[222:223], off
	s_waitcnt vmcnt(8)
	s_waitcnt lgkmcnt(0)
	s_setprio 1
	s_barrier
	s_waitcnt lgkmcnt(0)
	v_mfma_f32_16x16x32_bf16 v[62:65], v[152:155], v[186:189], v[62:65]
	v_mfma_f32_16x16x32_bf16 v[58:61], v[160:163], v[186:189], v[58:61]
	v_mfma_f32_16x16x32_bf16 v[50:53], v[152:155], v[194:197], v[50:53]
	v_mfma_f32_16x16x32_bf16 v[42:45], v[160:163], v[194:197], v[42:45]
	v_mfma_f32_16x16x32_bf16 v[34:37], v[152:155], v[202:205], v[34:37]
	v_mfma_f32_16x16x32_bf16 v[26:29], v[160:163], v[202:205], v[26:29]
	v_mfma_f32_16x16x32_bf16 v[18:21], v[152:155], v[210:213], v[18:21]
	v_mfma_f32_16x16x32_bf16 v[10:13], v[160:163], v[210:213], v[10:13]
	v_mfma_f32_16x16x32_bf16 v[62:65], v[156:159], v[190:193], v[62:65]
	v_mfma_f32_16x16x32_bf16 v[58:61], v[164:167], v[190:193], v[58:61]
	v_mfma_f32_16x16x32_bf16 v[50:53], v[156:159], v[198:201], v[50:53]
	v_mfma_f32_16x16x32_bf16 v[42:45], v[164:167], v[198:201], v[42:45]
	v_mfma_f32_16x16x32_bf16 v[34:37], v[156:159], v[206:209], v[34:37]
	v_mfma_f32_16x16x32_bf16 v[26:29], v[164:167], v[206:209], v[26:29]
	v_mfma_f32_16x16x32_bf16 v[18:21], v[156:159], v[214:217], v[18:21]
	v_mfma_f32_16x16x32_bf16 v[10:13], v[164:167], v[214:217], v[10:13]
	s_setprio 0
	s_setprio 1
	v_mfma_f32_16x16x32_bf16 v[54:57], v[168:171], v[186:189], v[54:57]
	v_mfma_f32_16x16x32_bf16 v[46:49], v[178:181], v[186:189], v[46:49]
	v_mfma_f32_16x16x32_bf16 v[38:41], v[168:171], v[194:197], v[38:41]
	v_mfma_f32_16x16x32_bf16 v[30:33], v[178:181], v[194:197], v[30:33]
	v_mfma_f32_16x16x32_bf16 v[22:25], v[168:171], v[202:205], v[22:25]
	v_mfma_f32_16x16x32_bf16 v[14:17], v[178:181], v[202:205], v[14:17]
	v_mfma_f32_16x16x32_bf16 v[6:9], v[168:171], v[210:213], v[6:9]
	v_mfma_f32_16x16x32_bf16 v[2:5], v[178:181], v[210:213], v[2:5]
	v_mfma_f32_16x16x32_bf16 v[54:57], v[172:175], v[190:193], v[54:57]
	v_mfma_f32_16x16x32_bf16 v[46:49], v[182:185], v[190:193], v[46:49]
	v_mfma_f32_16x16x32_bf16 v[38:41], v[172:175], v[198:201], v[38:41]
	v_mfma_f32_16x16x32_bf16 v[30:33], v[182:185], v[198:201], v[30:33]
	v_mfma_f32_16x16x32_bf16 v[22:25], v[172:175], v[206:209], v[22:25]
	v_mfma_f32_16x16x32_bf16 v[14:17], v[182:185], v[206:209], v[14:17]
	v_mfma_f32_16x16x32_bf16 v[6:9], v[172:175], v[214:217], v[6:9]
	v_mfma_f32_16x16x32_bf16 v[2:5], v[182:185], v[214:217], v[2:5]
	s_setprio 0
	s_barrier
	s_add_i32 s63, 0, 0x18000
	v_add_u32_e32 v151, s63, v146
	s_add_i32 s64, 0, 0x1c000
	ds_read_b128 v[152:155], v151
	ds_read_b128 v[156:159], v151 offset:1024
	ds_read_b128 v[160:163], v151 offset:2048
	ds_read_b128 v[164:167], v151 offset:3072
	v_add_u32_e32 v151, s64, v146
	ds_read_b128 v[168:171], v151
	ds_read_b128 v[172:175], v151 offset:1024
	ds_read_b128 v[178:181], v151 offset:2048
	ds_read_b128 v[182:185], v151 offset:3072
	s_add_u32 s2, s2, 0x40000
	s_addc_u32 s3, s3, 0
	s_mov_b32 m0, s45
	v_lshl_add_u64 v[224:225], s[2:3], 0, v[130:131]
	ds_read_b128 v[186:189], v150 offset:32768
	ds_read_b128 v[190:193], v150 offset:33792
	ds_read_b128 v[194:197], v150 offset:34816
	ds_read_b128 v[198:201], v150 offset:35840
	ds_read_b128 v[202:205], v150 offset:36864
	ds_read_b128 v[206:209], v150 offset:37888
	ds_read_b128 v[210:213], v150 offset:38912
	ds_read_b128 v[214:217], v150 offset:39936
	global_load_lds_dwordx4 v[224:225], off
	v_lshl_add_u64 v[224:225], s[2:3], 0, v[134:135]
	s_mov_b32 m0, s46
	s_nop 0
	global_load_lds_dwordx4 v[224:225], off
	s_waitcnt vmcnt(8)
	s_waitcnt lgkmcnt(0)
	s_setprio 1
	s_barrier
	s_waitcnt lgkmcnt(0)
	v_mfma_f32_16x16x32_bf16 v[126:129], v[152:155], v[186:189], v[126:129]
	v_mfma_f32_16x16x32_bf16 v[122:125], v[160:163], v[186:189], v[122:125]
	v_mfma_f32_16x16x32_bf16 v[114:117], v[152:155], v[194:197], v[114:117]
	v_mfma_f32_16x16x32_bf16 v[106:109], v[160:163], v[194:197], v[106:109]
	v_mfma_f32_16x16x32_bf16 v[98:101], v[152:155], v[202:205], v[98:101]
	v_mfma_f32_16x16x32_bf16 v[90:93], v[160:163], v[202:205], v[90:93]
	v_mfma_f32_16x16x32_bf16 v[82:85], v[152:155], v[210:213], v[82:85]
	v_mfma_f32_16x16x32_bf16 v[74:77], v[160:163], v[210:213], v[74:77]
	v_mfma_f32_16x16x32_bf16 v[126:129], v[156:159], v[190:193], v[126:129]
	v_mfma_f32_16x16x32_bf16 v[122:125], v[164:167], v[190:193], v[122:125]
	v_mfma_f32_16x16x32_bf16 v[114:117], v[156:159], v[198:201], v[114:117]
	v_mfma_f32_16x16x32_bf16 v[106:109], v[164:167], v[198:201], v[106:109]
	v_mfma_f32_16x16x32_bf16 v[98:101], v[156:159], v[206:209], v[98:101]
	v_mfma_f32_16x16x32_bf16 v[90:93], v[164:167], v[206:209], v[90:93]
	v_mfma_f32_16x16x32_bf16 v[82:85], v[156:159], v[214:217], v[82:85]
	v_mfma_f32_16x16x32_bf16 v[74:77], v[164:167], v[214:217], v[74:77]
	s_setprio 0
	s_setprio 1
	v_mfma_f32_16x16x32_bf16 v[118:121], v[168:171], v[186:189], v[118:121]
	v_mfma_f32_16x16x32_bf16 v[110:113], v[178:181], v[186:189], v[110:113]
	v_mfma_f32_16x16x32_bf16 v[102:105], v[168:171], v[194:197], v[102:105]
	v_mfma_f32_16x16x32_bf16 v[94:97], v[178:181], v[194:197], v[94:97]
	v_mfma_f32_16x16x32_bf16 v[86:89], v[168:171], v[202:205], v[86:89]
	v_mfma_f32_16x16x32_bf16 v[78:81], v[178:181], v[202:205], v[78:81]
	v_mfma_f32_16x16x32_bf16 v[70:73], v[168:171], v[210:213], v[70:73]
	v_mfma_f32_16x16x32_bf16 v[66:69], v[178:181], v[210:213], v[66:69]
	v_mfma_f32_16x16x32_bf16 v[118:121], v[172:175], v[190:193], v[118:121]
	v_mfma_f32_16x16x32_bf16 v[110:113], v[182:185], v[190:193], v[110:113]
	v_mfma_f32_16x16x32_bf16 v[102:105], v[172:175], v[198:201], v[102:105]
	v_mfma_f32_16x16x32_bf16 v[94:97], v[182:185], v[198:201], v[94:97]
	v_mfma_f32_16x16x32_bf16 v[86:89], v[172:175], v[206:209], v[86:89]
	v_mfma_f32_16x16x32_bf16 v[78:81], v[182:185], v[206:209], v[78:81]
	v_mfma_f32_16x16x32_bf16 v[70:73], v[172:175], v[214:217], v[70:73]
	v_mfma_f32_16x16x32_bf16 v[66:69], v[182:185], v[214:217], v[66:69]
	s_setprio 0
	s_barrier
	s_add_i32 s2, s63, s43
	v_lshl_add_u64 v[144:145], v[144:145], 0, s[8:9]
	s_mov_b32 m0, s2
	ds_read_b128 v[186:189], v150 offset:49152
	ds_read_b128 v[190:193], v150 offset:50176
	ds_read_b128 v[194:197], v150 offset:51200
	ds_read_b128 v[198:201], v150 offset:52224
	ds_read_b128 v[202:205], v150 offset:53248
	ds_read_b128 v[206:209], v150 offset:54272
	ds_read_b128 v[210:213], v150 offset:55296
	ds_read_b128 v[214:217], v150 offset:56320
	global_load_lds_dwordx4 v[144:145], off
	s_add_i32 m0, s2, 0x2000
	s_add_u32 s2, s38, 0x40080
	v_lshl_add_u64 v[144:145], v[218:219], 0, s[8:9]
	s_addc_u32 s3, s39, 0
	s_add_i32 s38, s64, s43
	global_load_lds_dwordx4 v[144:145], off
	v_lshl_add_u64 v[144:145], s[2:3], 0, v[132:133]
	s_mov_b32 m0, s38
	s_nop 0
	global_load_lds_dwordx4 v[144:145], off
	v_lshl_add_u64 v[144:145], s[2:3], 0, v[136:137]
	s_add_i32 m0, s38, 0x2000
	s_nop 0
	global_load_lds_dwordx4 v[144:145], off
	v_lshl_add_u64 v[144:145], v[220:221], 0, s[8:9]
	s_mov_b32 m0, s48
	s_nop 0
	global_load_lds_dwordx4 v[144:145], off
	v_lshl_add_u64 v[144:145], v[222:223], 0, s[8:9]
	s_mov_b32 m0, s49
	s_nop 0
	global_load_lds_dwordx4 v[144:145], off
	s_waitcnt vmcnt(8)
	s_waitcnt lgkmcnt(0)
	s_setprio 1
	s_barrier
	s_waitcnt lgkmcnt(0)
	v_mfma_f32_16x16x32_bf16 v[62:65], v[152:155], v[186:189], v[62:65]
	v_mfma_f32_16x16x32_bf16 v[58:61], v[160:163], v[186:189], v[58:61]
	v_mfma_f32_16x16x32_bf16 v[50:53], v[152:155], v[194:197], v[50:53]
	v_mfma_f32_16x16x32_bf16 v[42:45], v[160:163], v[194:197], v[42:45]
	v_mfma_f32_16x16x32_bf16 v[34:37], v[152:155], v[202:205], v[34:37]
	v_mfma_f32_16x16x32_bf16 v[26:29], v[160:163], v[202:205], v[26:29]
	v_mfma_f32_16x16x32_bf16 v[18:21], v[152:155], v[210:213], v[18:21]
	v_mfma_f32_16x16x32_bf16 v[10:13], v[160:163], v[210:213], v[10:13]
	v_mfma_f32_16x16x32_bf16 v[62:65], v[156:159], v[190:193], v[62:65]
	v_mfma_f32_16x16x32_bf16 v[58:61], v[164:167], v[190:193], v[58:61]
	v_mfma_f32_16x16x32_bf16 v[50:53], v[156:159], v[198:201], v[50:53]
	v_mfma_f32_16x16x32_bf16 v[42:45], v[164:167], v[198:201], v[42:45]
	v_mfma_f32_16x16x32_bf16 v[34:37], v[156:159], v[206:209], v[34:37]
	v_mfma_f32_16x16x32_bf16 v[26:29], v[164:167], v[206:209], v[26:29]
	v_mfma_f32_16x16x32_bf16 v[18:21], v[156:159], v[214:217], v[18:21]
	v_mfma_f32_16x16x32_bf16 v[10:13], v[164:167], v[214:217], v[10:13]
	s_setprio 0
	s_setprio 1
	v_mfma_f32_16x16x32_bf16 v[54:57], v[168:171], v[186:189], v[54:57]
	v_mfma_f32_16x16x32_bf16 v[46:49], v[178:181], v[186:189], v[46:49]
	v_mfma_f32_16x16x32_bf16 v[38:41], v[168:171], v[194:197], v[38:41]
	v_mfma_f32_16x16x32_bf16 v[30:33], v[178:181], v[194:197], v[30:33]
	v_mfma_f32_16x16x32_bf16 v[22:25], v[168:171], v[202:205], v[22:25]
	v_mfma_f32_16x16x32_bf16 v[14:17], v[178:181], v[202:205], v[14:17]
	v_mfma_f32_16x16x32_bf16 v[6:9], v[168:171], v[210:213], v[6:9]
	v_mfma_f32_16x16x32_bf16 v[2:5], v[178:181], v[210:213], v[2:5]
	v_mfma_f32_16x16x32_bf16 v[54:57], v[172:175], v[190:193], v[54:57]
	v_mfma_f32_16x16x32_bf16 v[46:49], v[182:185], v[190:193], v[46:49]
	v_mfma_f32_16x16x32_bf16 v[38:41], v[172:175], v[198:201], v[38:41]
	v_mfma_f32_16x16x32_bf16 v[30:33], v[182:185], v[198:201], v[30:33]
	v_mfma_f32_16x16x32_bf16 v[22:25], v[172:175], v[206:209], v[22:25]
	v_mfma_f32_16x16x32_bf16 v[14:17], v[182:185], v[206:209], v[14:17]
	v_mfma_f32_16x16x32_bf16 v[6:9], v[172:175], v[214:217], v[6:9]
	v_mfma_f32_16x16x32_bf16 v[2:5], v[182:185], v[214:217], v[2:5]
	s_setprio 0
	s_barrier
	s_add_i32 s62, s62, 2
	s_add_u32 s36, s36, 0x100
	s_addc_u32 s37, s37, 0
	s_add_u32 s60, s60, 0x100
	s_addc_u32 s61, s61, 0
	s_cmp_gt_u32 s62, 13
	s_cbranch_scc0 .LBB0_1239

.Lpk1303_peel:
	ds_read_b128 v[166:169], v139
	ds_read_b128 v[170:173], v139 offset:1024
	ds_read_b128 v[178:181], v139 offset:2048
	ds_read_b128 v[182:185], v139 offset:3072
	ds_read_b128 v[186:189], v163
	ds_read_b128 v[190:193], v163 offset:1024
	ds_read_b128 v[194:197], v163 offset:2048
	ds_read_b128 v[198:201], v163 offset:3072
	s_add_u32 s2, s26, 0xfffc0080
	s_addc_u32 s3, s27, -1
	s_cmp_eq_u32 s55, 12
	s_cselect_b32 s3, s11, s3
	s_cselect_b32 s2, s13, s2
	s_cselect_b32 s29, s47, s54
	s_cselect_b32 s28, s52, s53
	v_lshl_add_u64 v[148:149], s[26:27], 0, v[142:143]
	s_add_i32 m0, s34, 0xc000
	ds_read_b128 v[202:205], v164
	ds_read_b128 v[206:209], v164 offset:1024
	ds_read_b128 v[210:213], v164 offset:2048
	ds_read_b128 v[214:217], v164 offset:3072
	ds_read_b128 v[218:221], v164 offset:4096
	ds_read_b128 v[222:225], v164 offset:5120
	ds_read_b128 v[226:229], v164 offset:6144
	ds_read_b128 v[230:233], v164 offset:7168
	global_load_lds_dwordx4 v[148:149], off
	v_lshl_add_u64 v[148:149], s[26:27], 0, v[144:145]
	s_add_i32 m0, s34, 0xe000
	s_nop 0
	global_load_lds_dwordx4 v[148:149], off
	s_waitcnt vmcnt(8)
	s_waitcnt lgkmcnt(0)
	s_setprio 1
	s_barrier
	s_waitcnt lgkmcnt(0)
	v_mfma_f32_16x16x32_bf16 v[126:129], v[166:169], v[202:205], 0
	v_mfma_f32_16x16x32_bf16 v[122:125], v[178:181], v[202:205], 0
	v_mfma_f32_16x16x32_bf16 v[110:113], v[166:169], v[210:213], 0
	v_mfma_f32_16x16x32_bf16 v[106:109], v[178:181], v[210:213], 0
	v_mfma_f32_16x16x32_bf16 v[94:97], v[166:169], v[218:221], 0
	v_mfma_f32_16x16x32_bf16 v[90:93], v[178:181], v[218:221], 0
	v_mfma_f32_16x16x32_bf16 v[78:81], v[166:169], v[226:229], 0
	v_mfma_f32_16x16x32_bf16 v[74:77], v[178:181], v[226:229], 0
	v_mfma_f32_16x16x32_bf16 v[126:129], v[170:173], v[206:209], v[126:129]
	v_mfma_f32_16x16x32_bf16 v[122:125], v[182:185], v[206:209], v[122:125]
	v_mfma_f32_16x16x32_bf16 v[110:113], v[170:173], v[214:217], v[110:113]
	v_mfma_f32_16x16x32_bf16 v[106:109], v[182:185], v[214:217], v[106:109]
	v_mfma_f32_16x16x32_bf16 v[94:97], v[170:173], v[222:225], v[94:97]
	v_mfma_f32_16x16x32_bf16 v[90:93], v[182:185], v[222:225], v[90:93]
	v_mfma_f32_16x16x32_bf16 v[78:81], v[170:173], v[230:233], v[78:81]
	v_mfma_f32_16x16x32_bf16 v[74:77], v[182:185], v[230:233], v[74:77]
	s_setprio 0
	s_setprio 1
	v_mfma_f32_16x16x32_bf16 v[118:121], v[186:189], v[202:205], 0
	v_mfma_f32_16x16x32_bf16 v[114:117], v[194:197], v[202:205], 0
	v_mfma_f32_16x16x32_bf16 v[102:105], v[186:189], v[210:213], 0
	v_mfma_f32_16x16x32_bf16 v[98:101], v[194:197], v[210:213], 0
	v_mfma_f32_16x16x32_bf16 v[86:89], v[186:189], v[218:221], 0
	v_mfma_f32_16x16x32_bf16 v[82:85], v[194:197], v[218:221], 0
	v_mfma_f32_16x16x32_bf16 v[70:73], v[186:189], v[226:229], 0
	v_mfma_f32_16x16x32_bf16 v[66:69], v[194:197], v[226:229], 0
	v_mfma_f32_16x16x32_bf16 v[118:121], v[190:193], v[206:209], v[118:121]
	v_mfma_f32_16x16x32_bf16 v[114:117], v[198:201], v[206:209], v[114:117]
	v_mfma_f32_16x16x32_bf16 v[102:105], v[190:193], v[214:217], v[102:105]
	v_mfma_f32_16x16x32_bf16 v[98:101], v[198:201], v[214:217], v[98:101]
	v_mfma_f32_16x16x32_bf16 v[86:89], v[190:193], v[222:225], v[86:89]
	v_mfma_f32_16x16x32_bf16 v[82:85], v[198:201], v[222:225], v[82:85]
	v_mfma_f32_16x16x32_bf16 v[70:73], v[190:193], v[230:233], v[70:73]
	v_mfma_f32_16x16x32_bf16 v[66:69], v[198:201], v[230:233], v[66:69]
	s_setprio 0
	s_barrier
	s_add_i32 s56, s42, s30
	v_lshl_add_u64 v[148:149], s[28:29], 0, v[132:133]
	s_mov_b32 m0, s56
	ds_read_b128 v[202:205], v164 offset:16384
	ds_read_b128 v[206:209], v164 offset:17408
	ds_read_b128 v[210:213], v164 offset:18432
	ds_read_b128 v[214:217], v164 offset:19456
	ds_read_b128 v[218:221], v164 offset:20480
	ds_read_b128 v[222:225], v164 offset:21504
	ds_read_b128 v[226:229], v164 offset:22528
	ds_read_b128 v[230:233], v164 offset:23552
	global_load_lds_dwordx4 v[148:149], off
	s_add_i32 m0, s56, 0x2000
	s_add_u32 s56, s28, 0x40000
	v_lshl_add_u64 v[174:175], s[28:29], 0, v[136:137]
	s_addc_u32 s57, s29, 0
	s_add_i32 s58, s43, s30
	global_load_lds_dwordx4 v[174:175], off
	v_lshl_add_u64 v[234:235], s[56:57], 0, v[132:133]
	s_mov_b32 m0, s58
	v_lshl_add_u64 v[236:237], s[2:3], 0, v[134:135]
	global_load_lds_dwordx4 v[234:235], off
	v_lshl_add_u64 v[234:235], s[56:57], 0, v[136:137]
	s_add_i32 m0, s58, 0x2000
	s_nop 0
	global_load_lds_dwordx4 v[234:235], off
	v_lshl_add_u64 v[234:235], s[2:3], 0, v[130:131]
	s_mov_b32 m0, s34
	s_nop 0
	global_load_lds_dwordx4 v[234:235], off
	s_mov_b32 m0, s25
	s_nop 0
	global_load_lds_dwordx4 v[236:237], off
	s_waitcnt vmcnt(8)
	s_waitcnt lgkmcnt(0)
	s_setprio 1
	s_barrier
	s_waitcnt lgkmcnt(0)
	v_mfma_f32_16x16x32_bf16 v[62:65], v[166:169], v[202:205], 0
	v_mfma_f32_16x16x32_bf16 v[58:61], v[178:181], v[202:205], 0
	v_mfma_f32_16x16x32_bf16 v[46:49], v[166:169], v[210:213], 0
	v_mfma_f32_16x16x32_bf16 v[42:45], v[178:181], v[210:213], 0
	v_mfma_f32_16x16x32_bf16 v[30:33], v[166:169], v[218:221], 0
	v_mfma_f32_16x16x32_bf16 v[26:29], v[178:181], v[218:221], 0
	v_mfma_f32_16x16x32_bf16 v[14:17], v[166:169], v[226:229], 0
	v_mfma_f32_16x16x32_bf16 v[10:13], v[178:181], v[226:229], 0
	v_mfma_f32_16x16x32_bf16 v[62:65], v[170:173], v[206:209], v[62:65]
	v_mfma_f32_16x16x32_bf16 v[58:61], v[182:185], v[206:209], v[58:61]
	v_mfma_f32_16x16x32_bf16 v[46:49], v[170:173], v[214:217], v[46:49]
	v_mfma_f32_16x16x32_bf16 v[42:45], v[182:185], v[214:217], v[42:45]
	v_mfma_f32_16x16x32_bf16 v[30:33], v[170:173], v[222:225], v[30:33]
	v_mfma_f32_16x16x32_bf16 v[26:29], v[182:185], v[222:225], v[26:29]
	v_mfma_f32_16x16x32_bf16 v[14:17], v[170:173], v[230:233], v[14:17]
	v_mfma_f32_16x16x32_bf16 v[10:13], v[182:185], v[230:233], v[10:13]
	s_setprio 0
	s_setprio 1
	v_mfma_f32_16x16x32_bf16 v[54:57], v[186:189], v[202:205], 0
	v_mfma_f32_16x16x32_bf16 v[50:53], v[194:197], v[202:205], 0
	v_mfma_f32_16x16x32_bf16 v[38:41], v[186:189], v[210:213], 0
	v_mfma_f32_16x16x32_bf16 v[34:37], v[194:197], v[210:213], 0
	v_mfma_f32_16x16x32_bf16 v[22:25], v[186:189], v[218:221], 0
	v_mfma_f32_16x16x32_bf16 v[18:21], v[194:197], v[218:221], 0
	v_mfma_f32_16x16x32_bf16 v[6:9], v[186:189], v[226:229], 0
	v_mfma_f32_16x16x32_bf16 v[2:5], v[194:197], v[226:229], 0
	v_mfma_f32_16x16x32_bf16 v[54:57], v[190:193], v[206:209], v[54:57]
	v_mfma_f32_16x16x32_bf16 v[50:53], v[198:201], v[206:209], v[50:53]
	v_mfma_f32_16x16x32_bf16 v[38:41], v[190:193], v[214:217], v[38:41]
	v_mfma_f32_16x16x32_bf16 v[34:37], v[198:201], v[214:217], v[34:37]
	v_mfma_f32_16x16x32_bf16 v[22:25], v[190:193], v[222:225], v[22:25]
	v_mfma_f32_16x16x32_bf16 v[18:21], v[198:201], v[222:225], v[18:21]
	v_mfma_f32_16x16x32_bf16 v[6:9], v[190:193], v[230:233], v[6:9]
	v_mfma_f32_16x16x32_bf16 v[2:5], v[198:201], v[230:233], v[2:5]
	s_setprio 0
	s_barrier
	s_add_i32 s56, 0, 0x18000
	v_add_u32_e32 v165, s56, v162
	s_add_i32 s57, 0, 0x1c000
	ds_read_b128 v[166:169], v165
	ds_read_b128 v[170:173], v165 offset:1024
	ds_read_b128 v[178:181], v165 offset:2048
	ds_read_b128 v[182:185], v165 offset:3072
	v_add_u32_e32 v165, s57, v162
	ds_read_b128 v[186:189], v165
	ds_read_b128 v[190:193], v165 offset:1024
	ds_read_b128 v[194:197], v165 offset:2048
	ds_read_b128 v[198:201], v165 offset:3072
	s_add_u32 s2, s2, 0x40000
	s_addc_u32 s3, s3, 0
	s_mov_b32 m0, s35
	v_lshl_add_u64 v[238:239], s[2:3], 0, v[130:131]
	ds_read_b128 v[202:205], v164 offset:32768
	ds_read_b128 v[206:209], v164 offset:33792
	ds_read_b128 v[210:213], v164 offset:34816
	ds_read_b128 v[214:217], v164 offset:35840
	ds_read_b128 v[218:221], v164 offset:36864
	ds_read_b128 v[222:225], v164 offset:37888
	ds_read_b128 v[226:229], v164 offset:38912
	ds_read_b128 v[230:233], v164 offset:39936
	global_load_lds_dwordx4 v[238:239], off
	v_lshl_add_u64 v[238:239], s[2:3], 0, v[134:135]
	s_mov_b32 m0, s36
	s_nop 0
	global_load_lds_dwordx4 v[238:239], off
	s_waitcnt vmcnt(8)
	s_waitcnt lgkmcnt(0)
	s_setprio 1
	s_barrier
	s_waitcnt lgkmcnt(0)
	v_mfma_f32_16x16x32_bf16 v[126:129], v[166:169], v[202:205], v[126:129]
	v_mfma_f32_16x16x32_bf16 v[122:125], v[178:181], v[202:205], v[122:125]
	v_mfma_f32_16x16x32_bf16 v[110:113], v[166:169], v[210:213], v[110:113]
	v_mfma_f32_16x16x32_bf16 v[106:109], v[178:181], v[210:213], v[106:109]
	v_mfma_f32_16x16x32_bf16 v[94:97], v[166:169], v[218:221], v[94:97]
	v_mfma_f32_16x16x32_bf16 v[90:93], v[178:181], v[218:221], v[90:93]
	v_mfma_f32_16x16x32_bf16 v[78:81], v[166:169], v[226:229], v[78:81]
	v_mfma_f32_16x16x32_bf16 v[74:77], v[178:181], v[226:229], v[74:77]
	v_mfma_f32_16x16x32_bf16 v[126:129], v[170:173], v[206:209], v[126:129]
	v_mfma_f32_16x16x32_bf16 v[122:125], v[182:185], v[206:209], v[122:125]
	v_mfma_f32_16x16x32_bf16 v[110:113], v[170:173], v[214:217], v[110:113]
	v_mfma_f32_16x16x32_bf16 v[106:109], v[182:185], v[214:217], v[106:109]
	v_mfma_f32_16x16x32_bf16 v[94:97], v[170:173], v[222:225], v[94:97]
	v_mfma_f32_16x16x32_bf16 v[90:93], v[182:185], v[222:225], v[90:93]
	v_mfma_f32_16x16x32_bf16 v[78:81], v[170:173], v[230:233], v[78:81]
	v_mfma_f32_16x16x32_bf16 v[74:77], v[182:185], v[230:233], v[74:77]
	s_setprio 0
	s_setprio 1
	v_mfma_f32_16x16x32_bf16 v[118:121], v[186:189], v[202:205], v[118:121]
	v_mfma_f32_16x16x32_bf16 v[114:117], v[194:197], v[202:205], v[114:117]
	v_mfma_f32_16x16x32_bf16 v[102:105], v[186:189], v[210:213], v[102:105]
	v_mfma_f32_16x16x32_bf16 v[98:101], v[194:197], v[210:213], v[98:101]
	v_mfma_f32_16x16x32_bf16 v[86:89], v[186:189], v[218:221], v[86:89]
	v_mfma_f32_16x16x32_bf16 v[82:85], v[194:197], v[218:221], v[82:85]
	v_mfma_f32_16x16x32_bf16 v[70:73], v[186:189], v[226:229], v[70:73]
	v_mfma_f32_16x16x32_bf16 v[66:69], v[194:197], v[226:229], v[66:69]
	v_mfma_f32_16x16x32_bf16 v[118:121], v[190:193], v[206:209], v[118:121]
	v_mfma_f32_16x16x32_bf16 v[114:117], v[198:201], v[206:209], v[114:117]
	v_mfma_f32_16x16x32_bf16 v[102:105], v[190:193], v[214:217], v[102:105]
	v_mfma_f32_16x16x32_bf16 v[98:101], v[198:201], v[214:217], v[98:101]
	v_mfma_f32_16x16x32_bf16 v[86:89], v[190:193], v[222:225], v[86:89]
	v_mfma_f32_16x16x32_bf16 v[82:85], v[198:201], v[222:225], v[82:85]
	v_mfma_f32_16x16x32_bf16 v[70:73], v[190:193], v[230:233], v[70:73]
	v_mfma_f32_16x16x32_bf16 v[66:69], v[198:201], v[230:233], v[66:69]
	s_setprio 0
	s_barrier
	s_add_i32 s2, s56, s30
	v_lshl_add_u64 v[148:149], v[148:149], 0, s[6:7]
	s_mov_b32 m0, s2
	ds_read_b128 v[202:205], v164 offset:49152
	ds_read_b128 v[206:209], v164 offset:50176
	ds_read_b128 v[210:213], v164 offset:51200
	ds_read_b128 v[214:217], v164 offset:52224
	ds_read_b128 v[218:221], v164 offset:53248
	ds_read_b128 v[222:225], v164 offset:54272
	ds_read_b128 v[226:229], v164 offset:55296
	ds_read_b128 v[230:233], v164 offset:56320
	global_load_lds_dwordx4 v[148:149], off
	s_add_i32 m0, s2, 0x2000
	s_add_u32 s2, s28, 0x40080
	v_lshl_add_u64 v[148:149], v[174:175], 0, s[6:7]
	s_addc_u32 s3, s29, 0
	s_add_i32 s28, s57, s30
	global_load_lds_dwordx4 v[148:149], off
	v_lshl_add_u64 v[148:149], s[2:3], 0, v[132:133]
	s_mov_b32 m0, s28
	s_nop 0
	global_load_lds_dwordx4 v[148:149], off
	v_lshl_add_u64 v[148:149], s[2:3], 0, v[136:137]
	s_add_i32 m0, s28, 0x2000
	s_nop 0
	global_load_lds_dwordx4 v[148:149], off
	v_lshl_add_u64 v[148:149], v[234:235], 0, s[6:7]
	s_mov_b32 m0, s39
	s_nop 0
	global_load_lds_dwordx4 v[148:149], off
	v_lshl_add_u64 v[148:149], v[236:237], 0, s[6:7]
	s_mov_b32 m0, s40
	s_nop 0
	global_load_lds_dwordx4 v[148:149], off
	s_waitcnt vmcnt(8)
	s_waitcnt lgkmcnt(0)
	s_setprio 1
	s_barrier
	s_waitcnt lgkmcnt(0)
	v_mfma_f32_16x16x32_bf16 v[62:65], v[166:169], v[202:205], v[62:65]
	v_mfma_f32_16x16x32_bf16 v[58:61], v[178:181], v[202:205], v[58:61]
	v_mfma_f32_16x16x32_bf16 v[46:49], v[166:169], v[210:213], v[46:49]
	v_mfma_f32_16x16x32_bf16 v[42:45], v[178:181], v[210:213], v[42:45]
	v_mfma_f32_16x16x32_bf16 v[30:33], v[166:169], v[218:221], v[30:33]
	v_mfma_f32_16x16x32_bf16 v[26:29], v[178:181], v[218:221], v[26:29]
	v_mfma_f32_16x16x32_bf16 v[14:17], v[166:169], v[226:229], v[14:17]
	v_mfma_f32_16x16x32_bf16 v[10:13], v[178:181], v[226:229], v[10:13]
	v_mfma_f32_16x16x32_bf16 v[62:65], v[170:173], v[206:209], v[62:65]
	v_mfma_f32_16x16x32_bf16 v[58:61], v[182:185], v[206:209], v[58:61]
	v_mfma_f32_16x16x32_bf16 v[46:49], v[170:173], v[214:217], v[46:49]
	v_mfma_f32_16x16x32_bf16 v[42:45], v[182:185], v[214:217], v[42:45]
	v_mfma_f32_16x16x32_bf16 v[30:33], v[170:173], v[222:225], v[30:33]
	v_mfma_f32_16x16x32_bf16 v[26:29], v[182:185], v[222:225], v[26:29]
	v_mfma_f32_16x16x32_bf16 v[14:17], v[170:173], v[230:233], v[14:17]
	v_mfma_f32_16x16x32_bf16 v[10:13], v[182:185], v[230:233], v[10:13]
	s_setprio 0
	s_setprio 1
	v_mfma_f32_16x16x32_bf16 v[54:57], v[186:189], v[202:205], v[54:57]
	v_mfma_f32_16x16x32_bf16 v[50:53], v[194:197], v[202:205], v[50:53]
	v_mfma_f32_16x16x32_bf16 v[38:41], v[186:189], v[210:213], v[38:41]
	v_mfma_f32_16x16x32_bf16 v[34:37], v[194:197], v[210:213], v[34:37]
	v_mfma_f32_16x16x32_bf16 v[22:25], v[186:189], v[218:221], v[22:25]
	v_mfma_f32_16x16x32_bf16 v[18:21], v[194:197], v[218:221], v[18:21]
	v_mfma_f32_16x16x32_bf16 v[6:9], v[186:189], v[226:229], v[6:9]
	v_mfma_f32_16x16x32_bf16 v[2:5], v[194:197], v[226:229], v[2:5]
	v_mfma_f32_16x16x32_bf16 v[54:57], v[190:193], v[206:209], v[54:57]
	v_mfma_f32_16x16x32_bf16 v[50:53], v[198:201], v[206:209], v[50:53]
	v_mfma_f32_16x16x32_bf16 v[38:41], v[190:193], v[214:217], v[38:41]
	v_mfma_f32_16x16x32_bf16 v[34:37], v[198:201], v[214:217], v[34:37]
	v_mfma_f32_16x16x32_bf16 v[22:25], v[190:193], v[222:225], v[22:25]
	v_mfma_f32_16x16x32_bf16 v[18:21], v[198:201], v[222:225], v[18:21]
	v_mfma_f32_16x16x32_bf16 v[6:9], v[190:193], v[230:233], v[6:9]
	v_mfma_f32_16x16x32_bf16 v[2:5], v[198:201], v[230:233], v[2:5]
	s_setprio 0
	s_barrier
	s_add_i32 s55, s55, 2
	s_add_u32 s26, s26, 0x100
	s_addc_u32 s27, s27, 0
	s_add_u32 s53, s53, 0x100
	s_addc_u32 s54, s54, 0
	s_cmp_gt_u32 s55, 13
	s_cbranch_scc0 .LBB0_1303
	s_branch .Lpk1303_exit
.LBB0_1303:
	ds_read_b128 v[166:169], v139
	ds_read_b128 v[170:173], v139 offset:1024
	ds_read_b128 v[178:181], v139 offset:2048
	ds_read_b128 v[182:185], v139 offset:3072
	ds_read_b128 v[186:189], v163
	ds_read_b128 v[190:193], v163 offset:1024
	ds_read_b128 v[194:197], v163 offset:2048
	ds_read_b128 v[198:201], v163 offset:3072
	s_add_u32 s2, s26, 0xfffc0080
	s_addc_u32 s3, s27, -1
	s_cmp_eq_u32 s55, 12
	s_cselect_b32 s3, s11, s3
	s_cselect_b32 s2, s13, s2
	s_cselect_b32 s29, s47, s54
	s_cselect_b32 s28, s52, s53
	v_lshl_add_u64 v[148:149], s[26:27], 0, v[142:143]
	s_add_i32 m0, s34, 0xc000
	ds_read_b128 v[202:205], v164
	ds_read_b128 v[206:209], v164 offset:1024
	ds_read_b128 v[210:213], v164 offset:2048
	ds_read_b128 v[214:217], v164 offset:3072
	ds_read_b128 v[218:221], v164 offset:4096
	ds_read_b128 v[222:225], v164 offset:5120
	ds_read_b128 v[226:229], v164 offset:6144
	ds_read_b128 v[230:233], v164 offset:7168
	global_load_lds_dwordx4 v[148:149], off
	v_lshl_add_u64 v[148:149], s[26:27], 0, v[144:145]
	s_add_i32 m0, s34, 0xe000
	s_nop 0
	global_load_lds_dwordx4 v[148:149], off
	s_waitcnt vmcnt(8)
	s_waitcnt lgkmcnt(0)
	s_setprio 1
	s_barrier
	s_waitcnt lgkmcnt(0)
	v_mfma_f32_16x16x32_bf16 v[126:129], v[166:169], v[202:205], v[126:129]
	v_mfma_f32_16x16x32_bf16 v[122:125], v[178:181], v[202:205], v[122:125]
	v_mfma_f32_16x16x32_bf16 v[110:113], v[166:169], v[210:213], v[110:113]
	v_mfma_f32_16x16x32_bf16 v[106:109], v[178:181], v[210:213], v[106:109]
	v_mfma_f32_16x16x32_bf16 v[94:97], v[166:169], v[218:221], v[94:97]
	v_mfma_f32_16x16x32_bf16 v[90:93], v[178:181], v[218:221], v[90:93]
	v_mfma_f32_16x16x32_bf16 v[78:81], v[166:169], v[226:229], v[78:81]
	v_mfma_f32_16x16x32_bf16 v[74:77], v[178:181], v[226:229], v[74:77]
	v_mfma_f32_16x16x32_bf16 v[126:129], v[170:173], v[206:209], v[126:129]
	v_mfma_f32_16x16x32_bf16 v[122:125], v[182:185], v[206:209], v[122:125]
	v_mfma_f32_16x16x32_bf16 v[110:113], v[170:173], v[214:217], v[110:113]
	v_mfma_f32_16x16x32_bf16 v[106:109], v[182:185], v[214:217], v[106:109]
	v_mfma_f32_16x16x32_bf16 v[94:97], v[170:173], v[222:225], v[94:97]
	v_mfma_f32_16x16x32_bf16 v[90:93], v[182:185], v[222:225], v[90:93]
	v_mfma_f32_16x16x32_bf16 v[78:81], v[170:173], v[230:233], v[78:81]
	v_mfma_f32_16x16x32_bf16 v[74:77], v[182:185], v[230:233], v[74:77]
	s_setprio 0
	s_setprio 1
	v_mfma_f32_16x16x32_bf16 v[118:121], v[186:189], v[202:205], v[118:121]
	v_mfma_f32_16x16x32_bf16 v[114:117], v[194:197], v[202:205], v[114:117]
	v_mfma_f32_16x16x32_bf16 v[102:105], v[186:189], v[210:213], v[102:105]
	v_mfma_f32_16x16x32_bf16 v[98:101], v[194:197], v[210:213], v[98:101]
	v_mfma_f32_16x16x32_bf16 v[86:89], v[186:189], v[218:221], v[86:89]
	v_mfma_f32_16x16x32_bf16 v[82:85], v[194:197], v[218:221], v[82:85]
	v_mfma_f32_16x16x32_bf16 v[70:73], v[186:189], v[226:229], v[70:73]
	v_mfma_f32_16x16x32_bf16 v[66:69], v[194:197], v[226:229], v[66:69]
	v_mfma_f32_16x16x32_bf16 v[118:121], v[190:193], v[206:209], v[118:121]
	v_mfma_f32_16x16x32_bf16 v[114:117], v[198:201], v[206:209], v[114:117]
	v_mfma_f32_16x16x32_bf16 v[102:105], v[190:193], v[214:217], v[102:105]
	v_mfma_f32_16x16x32_bf16 v[98:101], v[198:201], v[214:217], v[98:101]
	v_mfma_f32_16x16x32_bf16 v[86:89], v[190:193], v[222:225], v[86:89]
	v_mfma_f32_16x16x32_bf16 v[82:85], v[198:201], v[222:225], v[82:85]
	v_mfma_f32_16x16x32_bf16 v[70:73], v[190:193], v[230:233], v[70:73]
	v_mfma_f32_16x16x32_bf16 v[66:69], v[198:201], v[230:233], v[66:69]
	s_setprio 0
	s_barrier
	s_add_i32 s56, s42, s30
	v_lshl_add_u64 v[148:149], s[28:29], 0, v[132:133]
	s_mov_b32 m0, s56
	ds_read_b128 v[202:205], v164 offset:16384
	ds_read_b128 v[206:209], v164 offset:17408
	ds_read_b128 v[210:213], v164 offset:18432
	ds_read_b128 v[214:217], v164 offset:19456
	ds_read_b128 v[218:221], v164 offset:20480
	ds_read_b128 v[222:225], v164 offset:21504
	ds_read_b128 v[226:229], v164 offset:22528
	ds_read_b128 v[230:233], v164 offset:23552
	global_load_lds_dwordx4 v[148:149], off
	s_add_i32 m0, s56, 0x2000
	s_add_u32 s56, s28, 0x40000
	v_lshl_add_u64 v[174:175], s[28:29], 0, v[136:137]
	s_addc_u32 s57, s29, 0
	s_add_i32 s58, s43, s30
	global_load_lds_dwordx4 v[174:175], off
	v_lshl_add_u64 v[234:235], s[56:57], 0, v[132:133]
	s_mov_b32 m0, s58
	v_lshl_add_u64 v[236:237], s[2:3], 0, v[134:135]
	global_load_lds_dwordx4 v[234:235], off
	v_lshl_add_u64 v[234:235], s[56:57], 0, v[136:137]
	s_add_i32 m0, s58, 0x2000
	s_nop 0
	global_load_lds_dwordx4 v[234:235], off
	v_lshl_add_u64 v[234:235], s[2:3], 0, v[130:131]
	s_mov_b32 m0, s34
	s_nop 0
	global_load_lds_dwordx4 v[234:235], off
	s_mov_b32 m0, s25
	s_nop 0
	global_load_lds_dwordx4 v[236:237], off
	s_waitcnt vmcnt(8)
	s_waitcnt lgkmcnt(0)
	s_setprio 1
	s_barrier
	s_waitcnt lgkmcnt(0)
	v_mfma_f32_16x16x32_bf16 v[62:65], v[166:169], v[202:205], v[62:65]
	v_mfma_f32_16x16x32_bf16 v[58:61], v[178:181], v[202:205], v[58:61]
	v_mfma_f32_16x16x32_bf16 v[46:49], v[166:169], v[210:213], v[46:49]
	v_mfma_f32_16x16x32_bf16 v[42:45], v[178:181], v[210:213], v[42:45]
	v_mfma_f32_16x16x32_bf16 v[30:33], v[166:169], v[218:221], v[30:33]
	v_mfma_f32_16x16x32_bf16 v[26:29], v[178:181], v[218:221], v[26:29]
	v_mfma_f32_16x16x32_bf16 v[14:17], v[166:169], v[226:229], v[14:17]
	v_mfma_f32_16x16x32_bf16 v[10:13], v[178:181], v[226:229], v[10:13]
	v_mfma_f32_16x16x32_bf16 v[62:65], v[170:173], v[206:209], v[62:65]
	v_mfma_f32_16x16x32_bf16 v[58:61], v[182:185], v[206:209], v[58:61]
	v_mfma_f32_16x16x32_bf16 v[46:49], v[170:173], v[214:217], v[46:49]
	v_mfma_f32_16x16x32_bf16 v[42:45], v[182:185], v[214:217], v[42:45]
	v_mfma_f32_16x16x32_bf16 v[30:33], v[170:173], v[222:225], v[30:33]
	v_mfma_f32_16x16x32_bf16 v[26:29], v[182:185], v[222:225], v[26:29]
	v_mfma_f32_16x16x32_bf16 v[14:17], v[170:173], v[230:233], v[14:17]
	v_mfma_f32_16x16x32_bf16 v[10:13], v[182:185], v[230:233], v[10:13]
	s_setprio 0
	s_setprio 1
	v_mfma_f32_16x16x32_bf16 v[54:57], v[186:189], v[202:205], v[54:57]
	v_mfma_f32_16x16x32_bf16 v[50:53], v[194:197], v[202:205], v[50:53]
	v_mfma_f32_16x16x32_bf16 v[38:41], v[186:189], v[210:213], v[38:41]
	v_mfma_f32_16x16x32_bf16 v[34:37], v[194:197], v[210:213], v[34:37]
	v_mfma_f32_16x16x32_bf16 v[22:25], v[186:189], v[218:221], v[22:25]
	v_mfma_f32_16x16x32_bf16 v[18:21], v[194:197], v[218:221], v[18:21]
	v_mfma_f32_16x16x32_bf16 v[6:9], v[186:189], v[226:229], v[6:9]
	v_mfma_f32_16x16x32_bf16 v[2:5], v[194:197], v[226:229], v[2:5]
	v_mfma_f32_16x16x32_bf16 v[54:57], v[190:193], v[206:209], v[54:57]
	v_mfma_f32_16x16x32_bf16 v[50:53], v[198:201], v[206:209], v[50:53]
	v_mfma_f32_16x16x32_bf16 v[38:41], v[190:193], v[214:217], v[38:41]
	v_mfma_f32_16x16x32_bf16 v[34:37], v[198:201], v[214:217], v[34:37]
	v_mfma_f32_16x16x32_bf16 v[22:25], v[190:193], v[222:225], v[22:25]
	v_mfma_f32_16x16x32_bf16 v[18:21], v[198:201], v[222:225], v[18:21]
	v_mfma_f32_16x16x32_bf16 v[6:9], v[190:193], v[230:233], v[6:9]
	v_mfma_f32_16x16x32_bf16 v[2:5], v[198:201], v[230:233], v[2:5]
	s_setprio 0
	s_barrier
	s_add_i32 s56, 0, 0x18000
	v_add_u32_e32 v165, s56, v162
	s_add_i32 s57, 0, 0x1c000
	ds_read_b128 v[166:169], v165
	ds_read_b128 v[170:173], v165 offset:1024
	ds_read_b128 v[178:181], v165 offset:2048
	ds_read_b128 v[182:185], v165 offset:3072
	v_add_u32_e32 v165, s57, v162
	ds_read_b128 v[186:189], v165
	ds_read_b128 v[190:193], v165 offset:1024
	ds_read_b128 v[194:197], v165 offset:2048
	ds_read_b128 v[198:201], v165 offset:3072
	s_add_u32 s2, s2, 0x40000
	s_addc_u32 s3, s3, 0
	s_mov_b32 m0, s35
	v_lshl_add_u64 v[238:239], s[2:3], 0, v[130:131]
	ds_read_b128 v[202:205], v164 offset:32768
	ds_read_b128 v[206:209], v164 offset:33792
	ds_read_b128 v[210:213], v164 offset:34816
	ds_read_b128 v[214:217], v164 offset:35840
	ds_read_b128 v[218:221], v164 offset:36864
	ds_read_b128 v[222:225], v164 offset:37888
	ds_read_b128 v[226:229], v164 offset:38912
	ds_read_b128 v[230:233], v164 offset:39936
	global_load_lds_dwordx4 v[238:239], off
	v_lshl_add_u64 v[238:239], s[2:3], 0, v[134:135]
	s_mov_b32 m0, s36
	s_nop 0
	global_load_lds_dwordx4 v[238:239], off
	s_waitcnt vmcnt(8)
	s_waitcnt lgkmcnt(0)
	s_setprio 1
	s_barrier
	s_waitcnt lgkmcnt(0)
	v_mfma_f32_16x16x32_bf16 v[126:129], v[166:169], v[202:205], v[126:129]
	v_mfma_f32_16x16x32_bf16 v[122:125], v[178:181], v[202:205], v[122:125]
	v_mfma_f32_16x16x32_bf16 v[110:113], v[166:169], v[210:213], v[110:113]
	v_mfma_f32_16x16x32_bf16 v[106:109], v[178:181], v[210:213], v[106:109]
	v_mfma_f32_16x16x32_bf16 v[94:97], v[166:169], v[218:221], v[94:97]
	v_mfma_f32_16x16x32_bf16 v[90:93], v[178:181], v[218:221], v[90:93]
	v_mfma_f32_16x16x32_bf16 v[78:81], v[166:169], v[226:229], v[78:81]
	v_mfma_f32_16x16x32_bf16 v[74:77], v[178:181], v[226:229], v[74:77]
	v_mfma_f32_16x16x32_bf16 v[126:129], v[170:173], v[206:209], v[126:129]
	v_mfma_f32_16x16x32_bf16 v[122:125], v[182:185], v[206:209], v[122:125]
	v_mfma_f32_16x16x32_bf16 v[110:113], v[170:173], v[214:217], v[110:113]
	v_mfma_f32_16x16x32_bf16 v[106:109], v[182:185], v[214:217], v[106:109]
	v_mfma_f32_16x16x32_bf16 v[94:97], v[170:173], v[222:225], v[94:97]
	v_mfma_f32_16x16x32_bf16 v[90:93], v[182:185], v[222:225], v[90:93]
	v_mfma_f32_16x16x32_bf16 v[78:81], v[170:173], v[230:233], v[78:81]
	v_mfma_f32_16x16x32_bf16 v[74:77], v[182:185], v[230:233], v[74:77]
	s_setprio 0
	s_setprio 1
	v_mfma_f32_16x16x32_bf16 v[118:121], v[186:189], v[202:205], v[118:121]
	v_mfma_f32_16x16x32_bf16 v[114:117], v[194:197], v[202:205], v[114:117]
	v_mfma_f32_16x16x32_bf16 v[102:105], v[186:189], v[210:213], v[102:105]
	v_mfma_f32_16x16x32_bf16 v[98:101], v[194:197], v[210:213], v[98:101]
	v_mfma_f32_16x16x32_bf16 v[86:89], v[186:189], v[218:221], v[86:89]
	v_mfma_f32_16x16x32_bf16 v[82:85], v[194:197], v[218:221], v[82:85]
	v_mfma_f32_16x16x32_bf16 v[70:73], v[186:189], v[226:229], v[70:73]
	v_mfma_f32_16x16x32_bf16 v[66:69], v[194:197], v[226:229], v[66:69]
	v_mfma_f32_16x16x32_bf16 v[118:121], v[190:193], v[206:209], v[118:121]
	v_mfma_f32_16x16x32_bf16 v[114:117], v[198:201], v[206:209], v[114:117]
	v_mfma_f32_16x16x32_bf16 v[102:105], v[190:193], v[214:217], v[102:105]
	v_mfma_f32_16x16x32_bf16 v[98:101], v[198:201], v[214:217], v[98:101]
	v_mfma_f32_16x16x32_bf16 v[86:89], v[190:193], v[222:225], v[86:89]
	v_mfma_f32_16x16x32_bf16 v[82:85], v[198:201], v[222:225], v[82:85]
	v_mfma_f32_16x16x32_bf16 v[70:73], v[190:193], v[230:233], v[70:73]
	v_mfma_f32_16x16x32_bf16 v[66:69], v[198:201], v[230:233], v[66:69]
	s_setprio 0
	s_barrier
	s_add_i32 s2, s56, s30
	v_lshl_add_u64 v[148:149], v[148:149], 0, s[6:7]
	s_mov_b32 m0, s2
	ds_read_b128 v[202:205], v164 offset:49152
	ds_read_b128 v[206:209], v164 offset:50176
	ds_read_b128 v[210:213], v164 offset:51200
	ds_read_b128 v[214:217], v164 offset:52224
	ds_read_b128 v[218:221], v164 offset:53248
	ds_read_b128 v[222:225], v164 offset:54272
	ds_read_b128 v[226:229], v164 offset:55296
	ds_read_b128 v[230:233], v164 offset:56320
	global_load_lds_dwordx4 v[148:149], off
	s_add_i32 m0, s2, 0x2000
	s_add_u32 s2, s28, 0x40080
	v_lshl_add_u64 v[148:149], v[174:175], 0, s[6:7]
	s_addc_u32 s3, s29, 0
	s_add_i32 s28, s57, s30
	global_load_lds_dwordx4 v[148:149], off
	v_lshl_add_u64 v[148:149], s[2:3], 0, v[132:133]
	s_mov_b32 m0, s28
	s_nop 0
	global_load_lds_dwordx4 v[148:149], off
	v_lshl_add_u64 v[148:149], s[2:3], 0, v[136:137]
	s_add_i32 m0, s28, 0x2000
	s_nop 0
	global_load_lds_dwordx4 v[148:149], off
	v_lshl_add_u64 v[148:149], v[234:235], 0, s[6:7]
	s_mov_b32 m0, s39
	s_nop 0
	global_load_lds_dwordx4 v[148:149], off
	v_lshl_add_u64 v[148:149], v[236:237], 0, s[6:7]
	s_mov_b32 m0, s40
	s_nop 0
	global_load_lds_dwordx4 v[148:149], off
	s_waitcnt vmcnt(8)
	s_waitcnt lgkmcnt(0)
	s_setprio 1
	s_barrier
	s_waitcnt lgkmcnt(0)
	v_mfma_f32_16x16x32_bf16 v[62:65], v[166:169], v[202:205], v[62:65]
	v_mfma_f32_16x16x32_bf16 v[58:61], v[178:181], v[202:205], v[58:61]
	v_mfma_f32_16x16x32_bf16 v[46:49], v[166:169], v[210:213], v[46:49]
	v_mfma_f32_16x16x32_bf16 v[42:45], v[178:181], v[210:213], v[42:45]
	v_mfma_f32_16x16x32_bf16 v[30:33], v[166:169], v[218:221], v[30:33]
	v_mfma_f32_16x16x32_bf16 v[26:29], v[178:181], v[218:221], v[26:29]
	v_mfma_f32_16x16x32_bf16 v[14:17], v[166:169], v[226:229], v[14:17]
	v_mfma_f32_16x16x32_bf16 v[10:13], v[178:181], v[226:229], v[10:13]
	v_mfma_f32_16x16x32_bf16 v[62:65], v[170:173], v[206:209], v[62:65]
	v_mfma_f32_16x16x32_bf16 v[58:61], v[182:185], v[206:209], v[58:61]
	v_mfma_f32_16x16x32_bf16 v[46:49], v[170:173], v[214:217], v[46:49]
	v_mfma_f32_16x16x32_bf16 v[42:45], v[182:185], v[214:217], v[42:45]
	v_mfma_f32_16x16x32_bf16 v[30:33], v[170:173], v[222:225], v[30:33]
	v_mfma_f32_16x16x32_bf16 v[26:29], v[182:185], v[222:225], v[26:29]
	v_mfma_f32_16x16x32_bf16 v[14:17], v[170:173], v[230:233], v[14:17]
	v_mfma_f32_16x16x32_bf16 v[10:13], v[182:185], v[230:233], v[10:13]
	s_setprio 0
	s_setprio 1
	v_mfma_f32_16x16x32_bf16 v[54:57], v[186:189], v[202:205], v[54:57]
	v_mfma_f32_16x16x32_bf16 v[50:53], v[194:197], v[202:205], v[50:53]
	v_mfma_f32_16x16x32_bf16 v[38:41], v[186:189], v[210:213], v[38:41]
	v_mfma_f32_16x16x32_bf16 v[34:37], v[194:197], v[210:213], v[34:37]
	v_mfma_f32_16x16x32_bf16 v[22:25], v[186:189], v[218:221], v[22:25]
	v_mfma_f32_16x16x32_bf16 v[18:21], v[194:197], v[218:221], v[18:21]
	v_mfma_f32_16x16x32_bf16 v[6:9], v[186:189], v[226:229], v[6:9]
	v_mfma_f32_16x16x32_bf16 v[2:5], v[194:197], v[226:229], v[2:5]
	v_mfma_f32_16x16x32_bf16 v[54:57], v[190:193], v[206:209], v[54:57]
	v_mfma_f32_16x16x32_bf16 v[50:53], v[198:201], v[206:209], v[50:53]
	v_mfma_f32_16x16x32_bf16 v[38:41], v[190:193], v[214:217], v[38:41]
	v_mfma_f32_16x16x32_bf16 v[34:37], v[198:201], v[214:217], v[34:37]
	v_mfma_f32_16x16x32_bf16 v[22:25], v[190:193], v[222:225], v[22:25]
	v_mfma_f32_16x16x32_bf16 v[18:21], v[198:201], v[222:225], v[18:21]
	v_mfma_f32_16x16x32_bf16 v[6:9], v[190:193], v[230:233], v[6:9]
	v_mfma_f32_16x16x32_bf16 v[2:5], v[198:201], v[230:233], v[2:5]
	s_setprio 0
	s_barrier
	s_add_i32 s55, s55, 2
	s_add_u32 s26, s26, 0x100
	s_addc_u32 s27, s27, 0
	s_add_u32 s53, s53, 0x100
	s_addc_u32 s54, s54, 0
	s_cmp_gt_u32 s55, 13
	s_cbranch_scc0 .LBB0_1303

.LBB0_1386:
	ds_read_b128 v[160:163], v133
	ds_read_b128 v[164:167], v133 offset:1024
	ds_read_b128 v[168:171], v133 offset:2048
	ds_read_b128 v[172:175], v133 offset:3072
	ds_read_b128 v[178:181], v135
	ds_read_b128 v[182:185], v135 offset:1024
	ds_read_b128 v[186:189], v135 offset:2048
	ds_read_b128 v[190:193], v135 offset:3072
	s_cmp_lg_u32 s8, 0x160000
	s_cselect_b32 s13, s8, 0
	s_cselect_b32 s12, s9, 0
	s_add_u32 s2, s6, s13
	s_addc_u32 s3, s7, s12
	s_add_u32 s14, s0, s13
	s_addc_u32 s15, s1, s12
	s_add_u32 s12, s2, 0x8000
	s_addc_u32 s13, s3, 0
	v_lshl_add_u64 v[226:227], v[148:149], 0, s[8:9]
	s_mov_b32 m0, s27
	v_lshl_add_u64 v[226:227], v[226:227], 0, s[10:11]
	ds_read_b128 v[194:197], v137
	ds_read_b128 v[198:201], v137 offset:1024
	ds_read_b128 v[202:205], v137 offset:2048
	ds_read_b128 v[206:209], v137 offset:3072
	ds_read_b128 v[210:213], v137 offset:4096
	ds_read_b128 v[214:217], v137 offset:5120
	ds_read_b128 v[218:221], v137 offset:6144
	ds_read_b128 v[222:225], v137 offset:7168
	global_load_lds_dwordx4 v[226:227], off
	v_lshl_add_u64 v[226:227], v[150:151], 0, s[8:9]
	v_lshl_add_u64 v[226:227], v[226:227], 0, s[10:11]
	s_mov_b32 m0, s28
	s_nop 0
	global_load_lds_dwordx4 v[226:227], off
	s_waitcnt vmcnt(8)
	s_waitcnt lgkmcnt(0)
	s_setprio 1
	s_barrier
	s_waitcnt lgkmcnt(0)
	v_mfma_f32_16x16x32_bf16 v[126:129], v[160:163], v[194:197], v[126:129]
	v_mfma_f32_16x16x32_bf16 v[122:125], v[168:171], v[194:197], v[122:125]
	v_mfma_f32_16x16x32_bf16 v[114:117], v[160:163], v[202:205], v[114:117]
	v_mfma_f32_16x16x32_bf16 v[106:109], v[168:171], v[202:205], v[106:109]
	v_mfma_f32_16x16x32_bf16 v[98:101], v[160:163], v[210:213], v[98:101]
	v_mfma_f32_16x16x32_bf16 v[90:93], v[168:171], v[210:213], v[90:93]
	v_mfma_f32_16x16x32_bf16 v[82:85], v[160:163], v[218:221], v[82:85]
	v_mfma_f32_16x16x32_bf16 v[74:77], v[168:171], v[218:221], v[74:77]
	v_mfma_f32_16x16x32_bf16 v[126:129], v[164:167], v[198:201], v[126:129]
	v_mfma_f32_16x16x32_bf16 v[122:125], v[172:175], v[198:201], v[122:125]
	v_mfma_f32_16x16x32_bf16 v[114:117], v[164:167], v[206:209], v[114:117]
	v_mfma_f32_16x16x32_bf16 v[106:109], v[172:175], v[206:209], v[106:109]
	v_mfma_f32_16x16x32_bf16 v[98:101], v[164:167], v[214:217], v[98:101]
	v_mfma_f32_16x16x32_bf16 v[90:93], v[172:175], v[214:217], v[90:93]
	v_mfma_f32_16x16x32_bf16 v[82:85], v[164:167], v[222:225], v[82:85]
	v_mfma_f32_16x16x32_bf16 v[74:77], v[172:175], v[222:225], v[74:77]
	s_setprio 0
	s_setprio 1
	v_mfma_f32_16x16x32_bf16 v[118:121], v[178:181], v[194:197], v[118:121]
	v_mfma_f32_16x16x32_bf16 v[110:113], v[186:189], v[194:197], v[110:113]
	v_mfma_f32_16x16x32_bf16 v[102:105], v[178:181], v[202:205], v[102:105]
	v_mfma_f32_16x16x32_bf16 v[94:97], v[186:189], v[202:205], v[94:97]
	v_mfma_f32_16x16x32_bf16 v[86:89], v[178:181], v[210:213], v[86:89]
	v_mfma_f32_16x16x32_bf16 v[78:81], v[186:189], v[210:213], v[78:81]
	v_mfma_f32_16x16x32_bf16 v[70:73], v[178:181], v[218:221], v[70:73]
	v_mfma_f32_16x16x32_bf16 v[66:69], v[186:189], v[218:221], v[66:69]
	v_mfma_f32_16x16x32_bf16 v[118:121], v[182:185], v[198:201], v[118:121]
	v_mfma_f32_16x16x32_bf16 v[110:113], v[190:193], v[198:201], v[110:113]
	v_mfma_f32_16x16x32_bf16 v[102:105], v[182:185], v[206:209], v[102:105]
	v_mfma_f32_16x16x32_bf16 v[94:97], v[190:193], v[206:209], v[94:97]
	v_mfma_f32_16x16x32_bf16 v[86:89], v[182:185], v[214:217], v[86:89]
	v_mfma_f32_16x16x32_bf16 v[78:81], v[190:193], v[214:217], v[78:81]
	v_mfma_f32_16x16x32_bf16 v[70:73], v[182:185], v[222:225], v[70:73]
	v_mfma_f32_16x16x32_bf16 v[66:69], v[190:193], v[222:225], v[66:69]
	s_setprio 0
	s_barrier
	s_mov_b32 m0, s29
	v_lshl_add_u64 v[226:227], s[14:15], 0, v[142:143]
	s_add_u32 s40, s14, 0x4000
	ds_read_b128 v[194:197], v137 offset:16384
	ds_read_b128 v[198:201], v137 offset:17408
	ds_read_b128 v[202:205], v137 offset:18432
	ds_read_b128 v[206:209], v137 offset:19456
	ds_read_b128 v[210:213], v137 offset:20480
	ds_read_b128 v[214:217], v137 offset:21504
	ds_read_b128 v[218:221], v137 offset:22528
	ds_read_b128 v[222:225], v137 offset:23552
	global_load_lds_dwordx4 v[226:227], off
	v_lshl_add_u64 v[226:227], s[14:15], 0, v[146:147]
	s_mov_b32 m0, s30
	s_addc_u32 s41, s15, 0
	global_load_lds_dwordx4 v[226:227], off
	v_lshl_add_u64 v[226:227], s[40:41], 0, v[142:143]
	s_mov_b32 m0, s31
	s_nop 0
	global_load_lds_dwordx4 v[226:227], off
	v_lshl_add_u64 v[226:227], s[40:41], 0, v[146:147]
	s_mov_b32 m0, s34
	s_nop 0
	global_load_lds_dwordx4 v[226:227], off
	v_lshl_add_u64 v[226:227], s[2:3], 0, v[140:141]
	s_mov_b32 m0, s19
	s_nop 0
	global_load_lds_dwordx4 v[226:227], off
	v_lshl_add_u64 v[226:227], s[2:3], 0, v[144:145]
	s_mov_b32 m0, s20
	s_nop 0
	global_load_lds_dwordx4 v[226:227], off
	s_waitcnt vmcnt(8)
	s_waitcnt lgkmcnt(0)
	s_setprio 1
	s_barrier
	s_waitcnt lgkmcnt(0)
	v_mfma_f32_16x16x32_bf16 v[62:65], v[160:163], v[194:197], v[62:65]
	v_mfma_f32_16x16x32_bf16 v[58:61], v[168:171], v[194:197], v[58:61]
	v_mfma_f32_16x16x32_bf16 v[50:53], v[160:163], v[202:205], v[50:53]
	v_mfma_f32_16x16x32_bf16 v[42:45], v[168:171], v[202:205], v[42:45]
	v_mfma_f32_16x16x32_bf16 v[34:37], v[160:163], v[210:213], v[34:37]
	v_mfma_f32_16x16x32_bf16 v[26:29], v[168:171], v[210:213], v[26:29]
	v_mfma_f32_16x16x32_bf16 v[18:21], v[160:163], v[218:221], v[18:21]
	v_mfma_f32_16x16x32_bf16 v[10:13], v[168:171], v[218:221], v[10:13]
	v_mfma_f32_16x16x32_bf16 v[62:65], v[164:167], v[198:201], v[62:65]
	v_mfma_f32_16x16x32_bf16 v[58:61], v[172:175], v[198:201], v[58:61]
	v_mfma_f32_16x16x32_bf16 v[50:53], v[164:167], v[206:209], v[50:53]
	v_mfma_f32_16x16x32_bf16 v[42:45], v[172:175], v[206:209], v[42:45]
	v_mfma_f32_16x16x32_bf16 v[34:37], v[164:167], v[214:217], v[34:37]
	v_mfma_f32_16x16x32_bf16 v[26:29], v[172:175], v[214:217], v[26:29]
	v_mfma_f32_16x16x32_bf16 v[18:21], v[164:167], v[222:225], v[18:21]
	v_mfma_f32_16x16x32_bf16 v[10:13], v[172:175], v[222:225], v[10:13]
	s_setprio 0
	s_setprio 1
	v_mfma_f32_16x16x32_bf16 v[54:57], v[178:181], v[194:197], v[54:57]
	v_mfma_f32_16x16x32_bf16 v[46:49], v[186:189], v[194:197], v[46:49]
	v_mfma_f32_16x16x32_bf16 v[38:41], v[178:181], v[202:205], v[38:41]
	v_mfma_f32_16x16x32_bf16 v[30:33], v[186:189], v[202:205], v[30:33]
	v_mfma_f32_16x16x32_bf16 v[22:25], v[178:181], v[210:213], v[22:25]
	v_mfma_f32_16x16x32_bf16 v[14:17], v[186:189], v[210:213], v[14:17]
	v_mfma_f32_16x16x32_bf16 v[6:9], v[178:181], v[218:221], v[6:9]
	v_mfma_f32_16x16x32_bf16 v[2:5], v[186:189], v[218:221], v[2:5]
	v_mfma_f32_16x16x32_bf16 v[54:57], v[182:185], v[198:201], v[54:57]
	v_mfma_f32_16x16x32_bf16 v[46:49], v[190:193], v[198:201], v[46:49]
	v_mfma_f32_16x16x32_bf16 v[38:41], v[182:185], v[206:209], v[38:41]
	v_mfma_f32_16x16x32_bf16 v[30:33], v[190:193], v[206:209], v[30:33]
	v_mfma_f32_16x16x32_bf16 v[22:25], v[182:185], v[214:217], v[22:25]
	v_mfma_f32_16x16x32_bf16 v[14:17], v[190:193], v[214:217], v[14:17]
	v_mfma_f32_16x16x32_bf16 v[6:9], v[182:185], v[222:225], v[6:9]
	v_mfma_f32_16x16x32_bf16 v[2:5], v[190:193], v[222:225], v[2:5]
	s_setprio 0
	s_barrier
	ds_read_b128 v[160:163], v139
	ds_read_b128 v[164:167], v139 offset:1024
	ds_read_b128 v[168:171], v139 offset:2048
	ds_read_b128 v[172:175], v139 offset:3072
	ds_read_b128 v[178:181], v158
	ds_read_b128 v[182:185], v158 offset:1024
	ds_read_b128 v[186:189], v158 offset:2048
	ds_read_b128 v[190:193], v158 offset:3072
	s_add_u32 s2, s2, 0x4000
	s_addc_u32 s3, s3, 0
	s_mov_b32 m0, s21
	v_lshl_add_u64 v[226:227], s[2:3], 0, v[140:141]
	ds_read_b128 v[194:197], v137 offset:32768
	ds_read_b128 v[198:201], v137 offset:33792
	ds_read_b128 v[202:205], v137 offset:34816
	ds_read_b128 v[206:209], v137 offset:35840
	ds_read_b128 v[210:213], v137 offset:36864
	ds_read_b128 v[214:217], v137 offset:37888
	ds_read_b128 v[218:221], v137 offset:38912
	ds_read_b128 v[222:225], v137 offset:39936
	global_load_lds_dwordx4 v[226:227], off
	v_lshl_add_u64 v[226:227], s[2:3], 0, v[144:145]
	s_mov_b32 m0, s22
	s_nop 0
	global_load_lds_dwordx4 v[226:227], off
	s_waitcnt vmcnt(8)
	s_waitcnt lgkmcnt(0)
	s_setprio 1
	s_barrier
	s_waitcnt lgkmcnt(0)
	v_mfma_f32_16x16x32_bf16 v[126:129], v[160:163], v[194:197], v[126:129]
	v_mfma_f32_16x16x32_bf16 v[122:125], v[168:171], v[194:197], v[122:125]
	v_mfma_f32_16x16x32_bf16 v[114:117], v[160:163], v[202:205], v[114:117]
	v_mfma_f32_16x16x32_bf16 v[106:109], v[168:171], v[202:205], v[106:109]
	v_mfma_f32_16x16x32_bf16 v[98:101], v[160:163], v[210:213], v[98:101]
	v_mfma_f32_16x16x32_bf16 v[90:93], v[168:171], v[210:213], v[90:93]
	v_mfma_f32_16x16x32_bf16 v[82:85], v[160:163], v[218:221], v[82:85]
	v_mfma_f32_16x16x32_bf16 v[74:77], v[168:171], v[218:221], v[74:77]
	v_mfma_f32_16x16x32_bf16 v[126:129], v[164:167], v[198:201], v[126:129]
	v_mfma_f32_16x16x32_bf16 v[122:125], v[172:175], v[198:201], v[122:125]
	v_mfma_f32_16x16x32_bf16 v[114:117], v[164:167], v[206:209], v[114:117]
	v_mfma_f32_16x16x32_bf16 v[106:109], v[172:175], v[206:209], v[106:109]
	v_mfma_f32_16x16x32_bf16 v[98:101], v[164:167], v[214:217], v[98:101]
	v_mfma_f32_16x16x32_bf16 v[90:93], v[172:175], v[214:217], v[90:93]
	v_mfma_f32_16x16x32_bf16 v[82:85], v[164:167], v[222:225], v[82:85]
	v_mfma_f32_16x16x32_bf16 v[74:77], v[172:175], v[222:225], v[74:77]
	s_setprio 0
	s_setprio 1
	v_mfma_f32_16x16x32_bf16 v[118:121], v[178:181], v[194:197], v[118:121]
	v_mfma_f32_16x16x32_bf16 v[110:113], v[186:189], v[194:197], v[110:113]
	v_mfma_f32_16x16x32_bf16 v[102:105], v[178:181], v[202:205], v[102:105]
	v_mfma_f32_16x16x32_bf16 v[94:97], v[186:189], v[202:205], v[94:97]
	v_mfma_f32_16x16x32_bf16 v[86:89], v[178:181], v[210:213], v[86:89]
	v_mfma_f32_16x16x32_bf16 v[78:81], v[186:189], v[210:213], v[78:81]
	v_mfma_f32_16x16x32_bf16 v[70:73], v[178:181], v[218:221], v[70:73]
	v_mfma_f32_16x16x32_bf16 v[66:69], v[186:189], v[218:221], v[66:69]
	v_mfma_f32_16x16x32_bf16 v[118:121], v[182:185], v[198:201], v[118:121]
	v_mfma_f32_16x16x32_bf16 v[110:113], v[190:193], v[198:201], v[110:113]
	v_mfma_f32_16x16x32_bf16 v[102:105], v[182:185], v[206:209], v[102:105]
	v_mfma_f32_16x16x32_bf16 v[94:97], v[190:193], v[206:209], v[94:97]
	v_mfma_f32_16x16x32_bf16 v[86:89], v[182:185], v[214:217], v[86:89]
	v_mfma_f32_16x16x32_bf16 v[78:81], v[190:193], v[214:217], v[78:81]
	v_mfma_f32_16x16x32_bf16 v[70:73], v[182:185], v[222:225], v[70:73]
	v_mfma_f32_16x16x32_bf16 v[66:69], v[190:193], v[222:225], v[66:69]
	s_setprio 0
	s_barrier
	s_add_u32 s2, s14, 0x8000
	s_addc_u32 s3, s15, 0
	s_mov_b32 m0, s35
	v_lshl_add_u64 v[226:227], s[2:3], 0, v[142:143]
	ds_read_b128 v[194:197], v137 offset:49152
	ds_read_b128 v[198:201], v137 offset:50176
	ds_read_b128 v[202:205], v137 offset:51200
	ds_read_b128 v[206:209], v137 offset:52224
	ds_read_b128 v[210:213], v137 offset:53248
	ds_read_b128 v[214:217], v137 offset:54272
	ds_read_b128 v[218:221], v137 offset:55296
	ds_read_b128 v[222:225], v137 offset:56320
	global_load_lds_dwordx4 v[226:227], off
	v_lshl_add_u64 v[226:227], s[2:3], 0, v[146:147]
	s_add_u32 s2, s14, 0xc000
	s_mov_b32 m0, s36
	s_addc_u32 s3, s15, 0
	global_load_lds_dwordx4 v[226:227], off
	v_lshl_add_u64 v[226:227], s[2:3], 0, v[142:143]
	s_mov_b32 m0, s37
	s_nop 0
	global_load_lds_dwordx4 v[226:227], off
	v_lshl_add_u64 v[226:227], s[2:3], 0, v[146:147]
	s_mov_b32 m0, s38
	s_nop 0
	global_load_lds_dwordx4 v[226:227], off
	v_lshl_add_u64 v[226:227], s[12:13], 0, v[140:141]
	s_mov_b32 m0, s24
	s_nop 0
	global_load_lds_dwordx4 v[226:227], off
	v_lshl_add_u64 v[226:227], s[12:13], 0, v[144:145]
	s_mov_b32 m0, s25
	s_nop 0
	global_load_lds_dwordx4 v[226:227], off
	s_waitcnt vmcnt(8)
	s_waitcnt lgkmcnt(0)
	s_setprio 1
	s_barrier
	s_waitcnt lgkmcnt(0)
	v_mfma_f32_16x16x32_bf16 v[62:65], v[160:163], v[194:197], v[62:65]
	v_mfma_f32_16x16x32_bf16 v[58:61], v[168:171], v[194:197], v[58:61]
	v_mfma_f32_16x16x32_bf16 v[50:53], v[160:163], v[202:205], v[50:53]
	v_mfma_f32_16x16x32_bf16 v[42:45], v[168:171], v[202:205], v[42:45]
	v_mfma_f32_16x16x32_bf16 v[34:37], v[160:163], v[210:213], v[34:37]
	v_mfma_f32_16x16x32_bf16 v[26:29], v[168:171], v[210:213], v[26:29]
	v_mfma_f32_16x16x32_bf16 v[18:21], v[160:163], v[218:221], v[18:21]
	v_mfma_f32_16x16x32_bf16 v[10:13], v[168:171], v[218:221], v[10:13]
	v_mfma_f32_16x16x32_bf16 v[62:65], v[164:167], v[198:201], v[62:65]
	v_mfma_f32_16x16x32_bf16 v[58:61], v[172:175], v[198:201], v[58:61]
	v_mfma_f32_16x16x32_bf16 v[50:53], v[164:167], v[206:209], v[50:53]
	v_mfma_f32_16x16x32_bf16 v[42:45], v[172:175], v[206:209], v[42:45]
	v_mfma_f32_16x16x32_bf16 v[34:37], v[164:167], v[214:217], v[34:37]
	v_mfma_f32_16x16x32_bf16 v[26:29], v[172:175], v[214:217], v[26:29]
	v_mfma_f32_16x16x32_bf16 v[18:21], v[164:167], v[222:225], v[18:21]
	v_mfma_f32_16x16x32_bf16 v[10:13], v[172:175], v[222:225], v[10:13]
	s_setprio 0
	s_setprio 1
	v_mfma_f32_16x16x32_bf16 v[54:57], v[178:181], v[194:197], v[54:57]
	v_mfma_f32_16x16x32_bf16 v[46:49], v[186:189], v[194:197], v[46:49]
	v_mfma_f32_16x16x32_bf16 v[38:41], v[178:181], v[202:205], v[38:41]
	v_mfma_f32_16x16x32_bf16 v[30:33], v[186:189], v[202:205], v[30:33]
	v_mfma_f32_16x16x32_bf16 v[22:25], v[178:181], v[210:213], v[22:25]
	v_mfma_f32_16x16x32_bf16 v[14:17], v[186:189], v[210:213], v[14:17]
	v_mfma_f32_16x16x32_bf16 v[6:9], v[178:181], v[218:221], v[6:9]
	v_mfma_f32_16x16x32_bf16 v[2:5], v[186:189], v[218:221], v[2:5]
	v_mfma_f32_16x16x32_bf16 v[54:57], v[182:185], v[198:201], v[54:57]
	v_mfma_f32_16x16x32_bf16 v[46:49], v[190:193], v[198:201], v[46:49]
	v_mfma_f32_16x16x32_bf16 v[38:41], v[182:185], v[206:209], v[38:41]
	v_mfma_f32_16x16x32_bf16 v[30:33], v[190:193], v[206:209], v[30:33]
	v_mfma_f32_16x16x32_bf16 v[22:25], v[182:185], v[214:217], v[22:25]
	v_mfma_f32_16x16x32_bf16 v[14:17], v[190:193], v[214:217], v[14:17]
	v_mfma_f32_16x16x32_bf16 v[6:9], v[182:185], v[222:225], v[6:9]
	v_mfma_f32_16x16x32_bf16 v[2:5], v[190:193], v[222:225], v[2:5]
	s_setprio 0
	s_barrier
	s_add_i32 s26, s26, 2
	s_add_u32 s8, s8, 0x10000
	s_addc_u32 s9, s9, 0
	s_cmp_gt_u32 s26, 41
	s_cbranch_scc0 .LBB0_1386
	s_cmpk_lt_u32 s16, 0x100
	s_cbranch_scc0 .LBB0_1389
	s_barrier

.Lpk1400_peel:
	ds_read_b128 v[152:155], v1
	ds_read_b128 v[156:159], v1 offset:1024
	ds_read_b128 v[160:163], v1 offset:2048
	ds_read_b128 v[164:167], v1 offset:3072
	ds_read_b128 v[168:171], v149
	ds_read_b128 v[172:175], v149 offset:1024
	ds_read_b128 v[178:181], v149 offset:2048
	ds_read_b128 v[182:185], v149 offset:3072
	s_add_u32 s2, s28, 0xfffc0080
	s_addc_u32 s3, s29, -1
	s_cmp_eq_u32 s55, 12
	s_cselect_b32 s3, s11, s3
	s_cselect_b32 s2, s13, s2
	s_cselect_b32 s31, s47, s54
	s_cselect_b32 s30, s52, s53
	v_lshl_add_u64 v[146:147], s[28:29], 0, v[140:141]
	s_add_i32 m0, s25, 0xc000
	ds_read_b128 v[186:189], v150
	ds_read_b128 v[190:193], v150 offset:1024
	ds_read_b128 v[194:197], v150 offset:2048
	ds_read_b128 v[198:201], v150 offset:3072
	ds_read_b128 v[202:205], v150 offset:4096
	ds_read_b128 v[206:209], v150 offset:5120
	ds_read_b128 v[210:213], v150 offset:6144
	ds_read_b128 v[214:217], v150 offset:7168
	global_load_lds_dwordx4 v[146:147], off
	v_lshl_add_u64 v[146:147], s[28:29], 0, v[142:143]
	s_add_i32 m0, s25, 0xe000
	s_nop 0
	global_load_lds_dwordx4 v[146:147], off
	s_waitcnt vmcnt(8)
	s_waitcnt lgkmcnt(0)
	s_setprio 1
	s_barrier
	s_waitcnt lgkmcnt(0)
	v_mfma_f32_16x16x32_bf16 v[126:129], v[152:155], v[186:189], 0
	v_mfma_f32_16x16x32_bf16 v[122:125], v[160:163], v[186:189], 0
	v_mfma_f32_16x16x32_bf16 v[110:113], v[152:155], v[194:197], 0
	v_mfma_f32_16x16x32_bf16 v[106:109], v[160:163], v[194:197], 0
	v_mfma_f32_16x16x32_bf16 v[94:97], v[152:155], v[202:205], 0
	v_mfma_f32_16x16x32_bf16 v[90:93], v[160:163], v[202:205], 0
	v_mfma_f32_16x16x32_bf16 v[78:81], v[152:155], v[210:213], 0
	v_mfma_f32_16x16x32_bf16 v[74:77], v[160:163], v[210:213], 0
	v_mfma_f32_16x16x32_bf16 v[126:129], v[156:159], v[190:193], v[126:129]
	v_mfma_f32_16x16x32_bf16 v[122:125], v[164:167], v[190:193], v[122:125]
	v_mfma_f32_16x16x32_bf16 v[110:113], v[156:159], v[198:201], v[110:113]
	v_mfma_f32_16x16x32_bf16 v[106:109], v[164:167], v[198:201], v[106:109]
	v_mfma_f32_16x16x32_bf16 v[94:97], v[156:159], v[206:209], v[94:97]
	v_mfma_f32_16x16x32_bf16 v[90:93], v[164:167], v[206:209], v[90:93]
	v_mfma_f32_16x16x32_bf16 v[78:81], v[156:159], v[214:217], v[78:81]
	v_mfma_f32_16x16x32_bf16 v[74:77], v[164:167], v[214:217], v[74:77]
	s_setprio 0
	s_setprio 1
	v_mfma_f32_16x16x32_bf16 v[118:121], v[168:171], v[186:189], 0
	v_mfma_f32_16x16x32_bf16 v[114:117], v[178:181], v[186:189], 0
	v_mfma_f32_16x16x32_bf16 v[102:105], v[168:171], v[194:197], 0
	v_mfma_f32_16x16x32_bf16 v[98:101], v[178:181], v[194:197], 0
	v_mfma_f32_16x16x32_bf16 v[86:89], v[168:171], v[202:205], 0
	v_mfma_f32_16x16x32_bf16 v[82:85], v[178:181], v[202:205], 0
	v_mfma_f32_16x16x32_bf16 v[70:73], v[168:171], v[210:213], 0
	v_mfma_f32_16x16x32_bf16 v[66:69], v[178:181], v[210:213], 0
	v_mfma_f32_16x16x32_bf16 v[118:121], v[172:175], v[190:193], v[118:121]
	v_mfma_f32_16x16x32_bf16 v[114:117], v[182:185], v[190:193], v[114:117]
	v_mfma_f32_16x16x32_bf16 v[102:105], v[172:175], v[198:201], v[102:105]
	v_mfma_f32_16x16x32_bf16 v[98:101], v[182:185], v[198:201], v[98:101]
	v_mfma_f32_16x16x32_bf16 v[86:89], v[172:175], v[206:209], v[86:89]
	v_mfma_f32_16x16x32_bf16 v[82:85], v[182:185], v[206:209], v[82:85]
	v_mfma_f32_16x16x32_bf16 v[70:73], v[172:175], v[214:217], v[70:73]
	v_mfma_f32_16x16x32_bf16 v[66:69], v[182:185], v[214:217], v[66:69]
	s_setprio 0
	s_barrier
	s_add_i32 s56, s43, s34
	v_lshl_add_u64 v[146:147], s[30:31], 0, v[132:133]
	s_mov_b32 m0, s56
	ds_read_b128 v[186:189], v150 offset:16384
	ds_read_b128 v[190:193], v150 offset:17408
	ds_read_b128 v[194:197], v150 offset:18432
	ds_read_b128 v[198:201], v150 offset:19456
	ds_read_b128 v[202:205], v150 offset:20480
	ds_read_b128 v[206:209], v150 offset:21504
	ds_read_b128 v[210:213], v150 offset:22528
	ds_read_b128 v[214:217], v150 offset:23552
	global_load_lds_dwordx4 v[146:147], off
	s_add_i32 m0, s56, 0x2000
	s_add_u32 s56, s30, 0x40000
	v_lshl_add_u64 v[218:219], s[30:31], 0, v[136:137]
	s_addc_u32 s57, s31, 0
	s_add_i32 s58, s44, s34
	global_load_lds_dwordx4 v[218:219], off
	v_lshl_add_u64 v[220:221], s[56:57], 0, v[132:133]
	s_mov_b32 m0, s58
	v_lshl_add_u64 v[222:223], s[2:3], 0, v[134:135]
	global_load_lds_dwordx4 v[220:221], off
	v_lshl_add_u64 v[220:221], s[56:57], 0, v[136:137]
	s_add_i32 m0, s58, 0x2000
	s_nop 0
	global_load_lds_dwordx4 v[220:221], off
	v_lshl_add_u64 v[220:221], s[2:3], 0, v[130:131]
	s_mov_b32 m0, s25
	s_nop 0
	global_load_lds_dwordx4 v[220:221], off
	s_mov_b32 m0, s27
	s_nop 0
	global_load_lds_dwordx4 v[222:223], off
	s_waitcnt vmcnt(8)
	s_waitcnt lgkmcnt(0)
	s_setprio 1
	s_barrier
	s_waitcnt lgkmcnt(0)
	v_mfma_f32_16x16x32_bf16 v[62:65], v[152:155], v[186:189], 0
	v_mfma_f32_16x16x32_bf16 v[58:61], v[160:163], v[186:189], 0
	v_mfma_f32_16x16x32_bf16 v[46:49], v[152:155], v[194:197], 0
	v_mfma_f32_16x16x32_bf16 v[42:45], v[160:163], v[194:197], 0
	v_mfma_f32_16x16x32_bf16 v[30:33], v[152:155], v[202:205], 0
	v_mfma_f32_16x16x32_bf16 v[26:29], v[160:163], v[202:205], 0
	v_mfma_f32_16x16x32_bf16 v[14:17], v[152:155], v[210:213], 0
	v_mfma_f32_16x16x32_bf16 v[10:13], v[160:163], v[210:213], 0
	v_mfma_f32_16x16x32_bf16 v[62:65], v[156:159], v[190:193], v[62:65]
	v_mfma_f32_16x16x32_bf16 v[58:61], v[164:167], v[190:193], v[58:61]
	v_mfma_f32_16x16x32_bf16 v[46:49], v[156:159], v[198:201], v[46:49]
	v_mfma_f32_16x16x32_bf16 v[42:45], v[164:167], v[198:201], v[42:45]
	v_mfma_f32_16x16x32_bf16 v[30:33], v[156:159], v[206:209], v[30:33]
	v_mfma_f32_16x16x32_bf16 v[26:29], v[164:167], v[206:209], v[26:29]
	v_mfma_f32_16x16x32_bf16 v[14:17], v[156:159], v[214:217], v[14:17]
	v_mfma_f32_16x16x32_bf16 v[10:13], v[164:167], v[214:217], v[10:13]
	s_setprio 0
	s_setprio 1
	v_mfma_f32_16x16x32_bf16 v[54:57], v[168:171], v[186:189], 0
	v_mfma_f32_16x16x32_bf16 v[50:53], v[178:181], v[186:189], 0
	v_mfma_f32_16x16x32_bf16 v[38:41], v[168:171], v[194:197], 0
	v_mfma_f32_16x16x32_bf16 v[34:37], v[178:181], v[194:197], 0
	v_mfma_f32_16x16x32_bf16 v[22:25], v[168:171], v[202:205], 0
	v_mfma_f32_16x16x32_bf16 v[18:21], v[178:181], v[202:205], 0
	v_mfma_f32_16x16x32_bf16 v[6:9], v[168:171], v[210:213], 0
	v_mfma_f32_16x16x32_bf16 v[2:5], v[178:181], v[210:213], 0
	v_mfma_f32_16x16x32_bf16 v[54:57], v[172:175], v[190:193], v[54:57]
	v_mfma_f32_16x16x32_bf16 v[50:53], v[182:185], v[190:193], v[50:53]
	v_mfma_f32_16x16x32_bf16 v[38:41], v[172:175], v[198:201], v[38:41]
	v_mfma_f32_16x16x32_bf16 v[34:37], v[182:185], v[198:201], v[34:37]
	v_mfma_f32_16x16x32_bf16 v[22:25], v[172:175], v[206:209], v[22:25]
	v_mfma_f32_16x16x32_bf16 v[18:21], v[182:185], v[206:209], v[18:21]
	v_mfma_f32_16x16x32_bf16 v[6:9], v[172:175], v[214:217], v[6:9]
	v_mfma_f32_16x16x32_bf16 v[2:5], v[182:185], v[214:217], v[2:5]
	s_setprio 0
	s_barrier
	s_add_i32 s56, 0, 0x18000
	v_add_u32_e32 v151, s56, v148
	s_add_i32 s57, 0, 0x1c000
	ds_read_b128 v[152:155], v151
	ds_read_b128 v[156:159], v151 offset:1024
	ds_read_b128 v[160:163], v151 offset:2048
	ds_read_b128 v[164:167], v151 offset:3072
	v_add_u32_e32 v151, s57, v148
	ds_read_b128 v[168:171], v151
	ds_read_b128 v[172:175], v151 offset:1024
	ds_read_b128 v[178:181], v151 offset:2048
	ds_read_b128 v[182:185], v151 offset:3072
	s_add_u32 s2, s2, 0x40000
	s_addc_u32 s3, s3, 0
	s_mov_b32 m0, s36
	v_lshl_add_u64 v[224:225], s[2:3], 0, v[130:131]
	ds_read_b128 v[186:189], v150 offset:32768
	ds_read_b128 v[190:193], v150 offset:33792
	ds_read_b128 v[194:197], v150 offset:34816
	ds_read_b128 v[198:201], v150 offset:35840
	ds_read_b128 v[202:205], v150 offset:36864
	ds_read_b128 v[206:209], v150 offset:37888
	ds_read_b128 v[210:213], v150 offset:38912
	ds_read_b128 v[214:217], v150 offset:39936
	global_load_lds_dwordx4 v[224:225], off
	v_lshl_add_u64 v[224:225], s[2:3], 0, v[134:135]
	s_mov_b32 m0, s37
	s_nop 0
	global_load_lds_dwordx4 v[224:225], off
	s_waitcnt vmcnt(8)
	s_waitcnt lgkmcnt(0)
	s_setprio 1
	s_barrier
	s_waitcnt lgkmcnt(0)
	v_mfma_f32_16x16x32_bf16 v[126:129], v[152:155], v[186:189], v[126:129]
	v_mfma_f32_16x16x32_bf16 v[122:125], v[160:163], v[186:189], v[122:125]
	v_mfma_f32_16x16x32_bf16 v[110:113], v[152:155], v[194:197], v[110:113]
	v_mfma_f32_16x16x32_bf16 v[106:109], v[160:163], v[194:197], v[106:109]
	v_mfma_f32_16x16x32_bf16 v[94:97], v[152:155], v[202:205], v[94:97]
	v_mfma_f32_16x16x32_bf16 v[90:93], v[160:163], v[202:205], v[90:93]
	v_mfma_f32_16x16x32_bf16 v[78:81], v[152:155], v[210:213], v[78:81]
	v_mfma_f32_16x16x32_bf16 v[74:77], v[160:163], v[210:213], v[74:77]
	v_mfma_f32_16x16x32_bf16 v[126:129], v[156:159], v[190:193], v[126:129]
	v_mfma_f32_16x16x32_bf16 v[122:125], v[164:167], v[190:193], v[122:125]
	v_mfma_f32_16x16x32_bf16 v[110:113], v[156:159], v[198:201], v[110:113]
	v_mfma_f32_16x16x32_bf16 v[106:109], v[164:167], v[198:201], v[106:109]
	v_mfma_f32_16x16x32_bf16 v[94:97], v[156:159], v[206:209], v[94:97]
	v_mfma_f32_16x16x32_bf16 v[90:93], v[164:167], v[206:209], v[90:93]
	v_mfma_f32_16x16x32_bf16 v[78:81], v[156:159], v[214:217], v[78:81]
	v_mfma_f32_16x16x32_bf16 v[74:77], v[164:167], v[214:217], v[74:77]
	s_setprio 0
	s_setprio 1
	v_mfma_f32_16x16x32_bf16 v[118:121], v[168:171], v[186:189], v[118:121]
	v_mfma_f32_16x16x32_bf16 v[114:117], v[178:181], v[186:189], v[114:117]
	v_mfma_f32_16x16x32_bf16 v[102:105], v[168:171], v[194:197], v[102:105]
	v_mfma_f32_16x16x32_bf16 v[98:101], v[178:181], v[194:197], v[98:101]
	v_mfma_f32_16x16x32_bf16 v[86:89], v[168:171], v[202:205], v[86:89]
	v_mfma_f32_16x16x32_bf16 v[82:85], v[178:181], v[202:205], v[82:85]
	v_mfma_f32_16x16x32_bf16 v[70:73], v[168:171], v[210:213], v[70:73]
	v_mfma_f32_16x16x32_bf16 v[66:69], v[178:181], v[210:213], v[66:69]
	v_mfma_f32_16x16x32_bf16 v[118:121], v[172:175], v[190:193], v[118:121]
	v_mfma_f32_16x16x32_bf16 v[114:117], v[182:185], v[190:193], v[114:117]
	v_mfma_f32_16x16x32_bf16 v[102:105], v[172:175], v[198:201], v[102:105]
	v_mfma_f32_16x16x32_bf16 v[98:101], v[182:185], v[198:201], v[98:101]
	v_mfma_f32_16x16x32_bf16 v[86:89], v[172:175], v[206:209], v[86:89]
	v_mfma_f32_16x16x32_bf16 v[82:85], v[182:185], v[206:209], v[82:85]
	v_mfma_f32_16x16x32_bf16 v[70:73], v[172:175], v[214:217], v[70:73]
	v_mfma_f32_16x16x32_bf16 v[66:69], v[182:185], v[214:217], v[66:69]
	s_setprio 0
	s_barrier
	s_add_i32 s2, s56, s34
	v_lshl_add_u64 v[146:147], v[146:147], 0, s[6:7]
	s_mov_b32 m0, s2
	ds_read_b128 v[186:189], v150 offset:49152
	ds_read_b128 v[190:193], v150 offset:50176
	ds_read_b128 v[194:197], v150 offset:51200
	ds_read_b128 v[198:201], v150 offset:52224
	ds_read_b128 v[202:205], v150 offset:53248
	ds_read_b128 v[206:209], v150 offset:54272
	ds_read_b128 v[210:213], v150 offset:55296
	ds_read_b128 v[214:217], v150 offset:56320
	global_load_lds_dwordx4 v[146:147], off
	s_add_i32 m0, s2, 0x2000
	s_add_u32 s2, s30, 0x40080
	v_lshl_add_u64 v[146:147], v[218:219], 0, s[6:7]
	s_addc_u32 s3, s31, 0
	s_add_i32 s30, s57, s34
	global_load_lds_dwordx4 v[146:147], off
	v_lshl_add_u64 v[146:147], s[2:3], 0, v[132:133]
	s_mov_b32 m0, s30
	s_nop 0
	global_load_lds_dwordx4 v[146:147], off
	v_lshl_add_u64 v[146:147], s[2:3], 0, v[136:137]
	s_add_i32 m0, s30, 0x2000
	s_nop 0
	global_load_lds_dwordx4 v[146:147], off
	v_lshl_add_u64 v[146:147], v[220:221], 0, s[6:7]
	s_mov_b32 m0, s40
	s_nop 0
	global_load_lds_dwordx4 v[146:147], off
	v_lshl_add_u64 v[146:147], v[222:223], 0, s[6:7]
	s_mov_b32 m0, s41
	s_nop 0
	global_load_lds_dwordx4 v[146:147], off
	s_waitcnt vmcnt(8)
	s_waitcnt lgkmcnt(0)
	s_setprio 1
	s_barrier
	s_waitcnt lgkmcnt(0)
	v_mfma_f32_16x16x32_bf16 v[62:65], v[152:155], v[186:189], v[62:65]
	v_mfma_f32_16x16x32_bf16 v[58:61], v[160:163], v[186:189], v[58:61]
	v_mfma_f32_16x16x32_bf16 v[46:49], v[152:155], v[194:197], v[46:49]
	v_mfma_f32_16x16x32_bf16 v[42:45], v[160:163], v[194:197], v[42:45]
	v_mfma_f32_16x16x32_bf16 v[30:33], v[152:155], v[202:205], v[30:33]
	v_mfma_f32_16x16x32_bf16 v[26:29], v[160:163], v[202:205], v[26:29]
	v_mfma_f32_16x16x32_bf16 v[14:17], v[152:155], v[210:213], v[14:17]
	v_mfma_f32_16x16x32_bf16 v[10:13], v[160:163], v[210:213], v[10:13]
	v_mfma_f32_16x16x32_bf16 v[62:65], v[156:159], v[190:193], v[62:65]
	v_mfma_f32_16x16x32_bf16 v[58:61], v[164:167], v[190:193], v[58:61]
	v_mfma_f32_16x16x32_bf16 v[46:49], v[156:159], v[198:201], v[46:49]
	v_mfma_f32_16x16x32_bf16 v[42:45], v[164:167], v[198:201], v[42:45]
	v_mfma_f32_16x16x32_bf16 v[30:33], v[156:159], v[206:209], v[30:33]
	v_mfma_f32_16x16x32_bf16 v[26:29], v[164:167], v[206:209], v[26:29]
	v_mfma_f32_16x16x32_bf16 v[14:17], v[156:159], v[214:217], v[14:17]
	v_mfma_f32_16x16x32_bf16 v[10:13], v[164:167], v[214:217], v[10:13]
	s_setprio 0
	s_setprio 1
	v_mfma_f32_16x16x32_bf16 v[54:57], v[168:171], v[186:189], v[54:57]
	v_mfma_f32_16x16x32_bf16 v[50:53], v[178:181], v[186:189], v[50:53]
	v_mfma_f32_16x16x32_bf16 v[38:41], v[168:171], v[194:197], v[38:41]
	v_mfma_f32_16x16x32_bf16 v[34:37], v[178:181], v[194:197], v[34:37]
	v_mfma_f32_16x16x32_bf16 v[22:25], v[168:171], v[202:205], v[22:25]
	v_mfma_f32_16x16x32_bf16 v[18:21], v[178:181], v[202:205], v[18:21]
	v_mfma_f32_16x16x32_bf16 v[6:9], v[168:171], v[210:213], v[6:9]
	v_mfma_f32_16x16x32_bf16 v[2:5], v[178:181], v[210:213], v[2:5]
	v_mfma_f32_16x16x32_bf16 v[54:57], v[172:175], v[190:193], v[54:57]
	v_mfma_f32_16x16x32_bf16 v[50:53], v[182:185], v[190:193], v[50:53]
	v_mfma_f32_16x16x32_bf16 v[38:41], v[172:175], v[198:201], v[38:41]
	v_mfma_f32_16x16x32_bf16 v[34:37], v[182:185], v[198:201], v[34:37]
	v_mfma_f32_16x16x32_bf16 v[22:25], v[172:175], v[206:209], v[22:25]
	v_mfma_f32_16x16x32_bf16 v[18:21], v[182:185], v[206:209], v[18:21]
	v_mfma_f32_16x16x32_bf16 v[6:9], v[172:175], v[214:217], v[6:9]
	v_mfma_f32_16x16x32_bf16 v[2:5], v[182:185], v[214:217], v[2:5]
	s_setprio 0
	s_barrier
	s_add_i32 s55, s55, 2
	s_add_u32 s28, s28, 0x100
	s_addc_u32 s29, s29, 0
	s_add_u32 s53, s53, 0x100
	s_addc_u32 s54, s54, 0
	s_cmp_gt_u32 s55, 13
	s_cbranch_scc0 .LBB0_1400
	s_branch .Lpk1400_exit
.LBB0_1400:
	ds_read_b128 v[152:155], v1
	ds_read_b128 v[156:159], v1 offset:1024
	ds_read_b128 v[160:163], v1 offset:2048
	ds_read_b128 v[164:167], v1 offset:3072
	ds_read_b128 v[168:171], v149
	ds_read_b128 v[172:175], v149 offset:1024
	ds_read_b128 v[178:181], v149 offset:2048
	ds_read_b128 v[182:185], v149 offset:3072
	s_add_u32 s2, s28, 0xfffc0080
	s_addc_u32 s3, s29, -1
	s_cmp_eq_u32 s55, 12
	s_cselect_b32 s3, s11, s3
	s_cselect_b32 s2, s13, s2
	s_cselect_b32 s31, s47, s54
	s_cselect_b32 s30, s52, s53
	v_lshl_add_u64 v[146:147], s[28:29], 0, v[140:141]
	s_add_i32 m0, s25, 0xc000
	ds_read_b128 v[186:189], v150
	ds_read_b128 v[190:193], v150 offset:1024
	ds_read_b128 v[194:197], v150 offset:2048
	ds_read_b128 v[198:201], v150 offset:3072
	ds_read_b128 v[202:205], v150 offset:4096
	ds_read_b128 v[206:209], v150 offset:5120
	ds_read_b128 v[210:213], v150 offset:6144
	ds_read_b128 v[214:217], v150 offset:7168
	global_load_lds_dwordx4 v[146:147], off
	v_lshl_add_u64 v[146:147], s[28:29], 0, v[142:143]
	s_add_i32 m0, s25, 0xe000
	s_nop 0
	global_load_lds_dwordx4 v[146:147], off
	s_waitcnt vmcnt(8)
	s_waitcnt lgkmcnt(0)
	s_setprio 1
	s_barrier
	s_waitcnt lgkmcnt(0)
	v_mfma_f32_16x16x32_bf16 v[126:129], v[152:155], v[186:189], v[126:129]
	v_mfma_f32_16x16x32_bf16 v[122:125], v[160:163], v[186:189], v[122:125]
	v_mfma_f32_16x16x32_bf16 v[110:113], v[152:155], v[194:197], v[110:113]
	v_mfma_f32_16x16x32_bf16 v[106:109], v[160:163], v[194:197], v[106:109]
	v_mfma_f32_16x16x32_bf16 v[94:97], v[152:155], v[202:205], v[94:97]
	v_mfma_f32_16x16x32_bf16 v[90:93], v[160:163], v[202:205], v[90:93]
	v_mfma_f32_16x16x32_bf16 v[78:81], v[152:155], v[210:213], v[78:81]
	v_mfma_f32_16x16x32_bf16 v[74:77], v[160:163], v[210:213], v[74:77]
	v_mfma_f32_16x16x32_bf16 v[126:129], v[156:159], v[190:193], v[126:129]
	v_mfma_f32_16x16x32_bf16 v[122:125], v[164:167], v[190:193], v[122:125]
	v_mfma_f32_16x16x32_bf16 v[110:113], v[156:159], v[198:201], v[110:113]
	v_mfma_f32_16x16x32_bf16 v[106:109], v[164:167], v[198:201], v[106:109]
	v_mfma_f32_16x16x32_bf16 v[94:97], v[156:159], v[206:209], v[94:97]
	v_mfma_f32_16x16x32_bf16 v[90:93], v[164:167], v[206:209], v[90:93]
	v_mfma_f32_16x16x32_bf16 v[78:81], v[156:159], v[214:217], v[78:81]
	v_mfma_f32_16x16x32_bf16 v[74:77], v[164:167], v[214:217], v[74:77]
	s_setprio 0
	s_setprio 1
	v_mfma_f32_16x16x32_bf16 v[118:121], v[168:171], v[186:189], v[118:121]
	v_mfma_f32_16x16x32_bf16 v[114:117], v[178:181], v[186:189], v[114:117]
	v_mfma_f32_16x16x32_bf16 v[102:105], v[168:171], v[194:197], v[102:105]
	v_mfma_f32_16x16x32_bf16 v[98:101], v[178:181], v[194:197], v[98:101]
	v_mfma_f32_16x16x32_bf16 v[86:89], v[168:171], v[202:205], v[86:89]
	v_mfma_f32_16x16x32_bf16 v[82:85], v[178:181], v[202:205], v[82:85]
	v_mfma_f32_16x16x32_bf16 v[70:73], v[168:171], v[210:213], v[70:73]
	v_mfma_f32_16x16x32_bf16 v[66:69], v[178:181], v[210:213], v[66:69]
	v_mfma_f32_16x16x32_bf16 v[118:121], v[172:175], v[190:193], v[118:121]
	v_mfma_f32_16x16x32_bf16 v[114:117], v[182:185], v[190:193], v[114:117]
	v_mfma_f32_16x16x32_bf16 v[102:105], v[172:175], v[198:201], v[102:105]
	v_mfma_f32_16x16x32_bf16 v[98:101], v[182:185], v[198:201], v[98:101]
	v_mfma_f32_16x16x32_bf16 v[86:89], v[172:175], v[206:209], v[86:89]
	v_mfma_f32_16x16x32_bf16 v[82:85], v[182:185], v[206:209], v[82:85]
	v_mfma_f32_16x16x32_bf16 v[70:73], v[172:175], v[214:217], v[70:73]
	v_mfma_f32_16x16x32_bf16 v[66:69], v[182:185], v[214:217], v[66:69]
	s_setprio 0
	s_barrier
	s_add_i32 s56, s43, s34
	v_lshl_add_u64 v[146:147], s[30:31], 0, v[132:133]
	s_mov_b32 m0, s56
	ds_read_b128 v[186:189], v150 offset:16384
	ds_read_b128 v[190:193], v150 offset:17408
	ds_read_b128 v[194:197], v150 offset:18432
	ds_read_b128 v[198:201], v150 offset:19456
	ds_read_b128 v[202:205], v150 offset:20480
	ds_read_b128 v[206:209], v150 offset:21504
	ds_read_b128 v[210:213], v150 offset:22528
	ds_read_b128 v[214:217], v150 offset:23552
	global_load_lds_dwordx4 v[146:147], off
	s_add_i32 m0, s56, 0x2000
	s_add_u32 s56, s30, 0x40000
	v_lshl_add_u64 v[218:219], s[30:31], 0, v[136:137]
	s_addc_u32 s57, s31, 0
	s_add_i32 s58, s44, s34
	global_load_lds_dwordx4 v[218:219], off
	v_lshl_add_u64 v[220:221], s[56:57], 0, v[132:133]
	s_mov_b32 m0, s58
	v_lshl_add_u64 v[222:223], s[2:3], 0, v[134:135]
	global_load_lds_dwordx4 v[220:221], off
	v_lshl_add_u64 v[220:221], s[56:57], 0, v[136:137]
	s_add_i32 m0, s58, 0x2000
	s_nop 0
	global_load_lds_dwordx4 v[220:221], off
	v_lshl_add_u64 v[220:221], s[2:3], 0, v[130:131]
	s_mov_b32 m0, s25
	s_nop 0
	global_load_lds_dwordx4 v[220:221], off
	s_mov_b32 m0, s27
	s_nop 0
	global_load_lds_dwordx4 v[222:223], off
	s_waitcnt vmcnt(8)
	s_waitcnt lgkmcnt(0)
	s_setprio 1
	s_barrier
	s_waitcnt lgkmcnt(0)
	v_mfma_f32_16x16x32_bf16 v[62:65], v[152:155], v[186:189], v[62:65]
	v_mfma_f32_16x16x32_bf16 v[58:61], v[160:163], v[186:189], v[58:61]
	v_mfma_f32_16x16x32_bf16 v[46:49], v[152:155], v[194:197], v[46:49]
	v_mfma_f32_16x16x32_bf16 v[42:45], v[160:163], v[194:197], v[42:45]
	v_mfma_f32_16x16x32_bf16 v[30:33], v[152:155], v[202:205], v[30:33]
	v_mfma_f32_16x16x32_bf16 v[26:29], v[160:163], v[202:205], v[26:29]
	v_mfma_f32_16x16x32_bf16 v[14:17], v[152:155], v[210:213], v[14:17]
	v_mfma_f32_16x16x32_bf16 v[10:13], v[160:163], v[210:213], v[10:13]
	v_mfma_f32_16x16x32_bf16 v[62:65], v[156:159], v[190:193], v[62:65]
	v_mfma_f32_16x16x32_bf16 v[58:61], v[164:167], v[190:193], v[58:61]
	v_mfma_f32_16x16x32_bf16 v[46:49], v[156:159], v[198:201], v[46:49]
	v_mfma_f32_16x16x32_bf16 v[42:45], v[164:167], v[198:201], v[42:45]
	v_mfma_f32_16x16x32_bf16 v[30:33], v[156:159], v[206:209], v[30:33]
	v_mfma_f32_16x16x32_bf16 v[26:29], v[164:167], v[206:209], v[26:29]
	v_mfma_f32_16x16x32_bf16 v[14:17], v[156:159], v[214:217], v[14:17]
	v_mfma_f32_16x16x32_bf16 v[10:13], v[164:167], v[214:217], v[10:13]
	s_setprio 0
	s_setprio 1
	v_mfma_f32_16x16x32_bf16 v[54:57], v[168:171], v[186:189], v[54:57]
	v_mfma_f32_16x16x32_bf16 v[50:53], v[178:181], v[186:189], v[50:53]
	v_mfma_f32_16x16x32_bf16 v[38:41], v[168:171], v[194:197], v[38:41]
	v_mfma_f32_16x16x32_bf16 v[34:37], v[178:181], v[194:197], v[34:37]
	v_mfma_f32_16x16x32_bf16 v[22:25], v[168:171], v[202:205], v[22:25]
	v_mfma_f32_16x16x32_bf16 v[18:21], v[178:181], v[202:205], v[18:21]
	v_mfma_f32_16x16x32_bf16 v[6:9], v[168:171], v[210:213], v[6:9]
	v_mfma_f32_16x16x32_bf16 v[2:5], v[178:181], v[210:213], v[2:5]
	v_mfma_f32_16x16x32_bf16 v[54:57], v[172:175], v[190:193], v[54:57]
	v_mfma_f32_16x16x32_bf16 v[50:53], v[182:185], v[190:193], v[50:53]
	v_mfma_f32_16x16x32_bf16 v[38:41], v[172:175], v[198:201], v[38:41]
	v_mfma_f32_16x16x32_bf16 v[34:37], v[182:185], v[198:201], v[34:37]
	v_mfma_f32_16x16x32_bf16 v[22:25], v[172:175], v[206:209], v[22:25]
	v_mfma_f32_16x16x32_bf16 v[18:21], v[182:185], v[206:209], v[18:21]
	v_mfma_f32_16x16x32_bf16 v[6:9], v[172:175], v[214:217], v[6:9]
	v_mfma_f32_16x16x32_bf16 v[2:5], v[182:185], v[214:217], v[2:5]
	s_setprio 0
	s_barrier
	s_add_i32 s56, 0, 0x18000
	v_add_u32_e32 v151, s56, v148
	s_add_i32 s57, 0, 0x1c000
	ds_read_b128 v[152:155], v151
	ds_read_b128 v[156:159], v151 offset:1024
	ds_read_b128 v[160:163], v151 offset:2048
	ds_read_b128 v[164:167], v151 offset:3072
	v_add_u32_e32 v151, s57, v148
	ds_read_b128 v[168:171], v151
	ds_read_b128 v[172:175], v151 offset:1024
	ds_read_b128 v[178:181], v151 offset:2048
	ds_read_b128 v[182:185], v151 offset:3072
	s_add_u32 s2, s2, 0x40000
	s_addc_u32 s3, s3, 0
	s_mov_b32 m0, s36
	v_lshl_add_u64 v[224:225], s[2:3], 0, v[130:131]
	ds_read_b128 v[186:189], v150 offset:32768
	ds_read_b128 v[190:193], v150 offset:33792
	ds_read_b128 v[194:197], v150 offset:34816
	ds_read_b128 v[198:201], v150 offset:35840
	ds_read_b128 v[202:205], v150 offset:36864
	ds_read_b128 v[206:209], v150 offset:37888
	ds_read_b128 v[210:213], v150 offset:38912
	ds_read_b128 v[214:217], v150 offset:39936
	global_load_lds_dwordx4 v[224:225], off
	v_lshl_add_u64 v[224:225], s[2:3], 0, v[134:135]
	s_mov_b32 m0, s37
	s_nop 0
	global_load_lds_dwordx4 v[224:225], off
	s_waitcnt vmcnt(8)
	s_waitcnt lgkmcnt(0)
	s_setprio 1
	s_barrier
	s_waitcnt lgkmcnt(0)
	v_mfma_f32_16x16x32_bf16 v[126:129], v[152:155], v[186:189], v[126:129]
	v_mfma_f32_16x16x32_bf16 v[122:125], v[160:163], v[186:189], v[122:125]
	v_mfma_f32_16x16x32_bf16 v[110:113], v[152:155], v[194:197], v[110:113]
	v_mfma_f32_16x16x32_bf16 v[106:109], v[160:163], v[194:197], v[106:109]
	v_mfma_f32_16x16x32_bf16 v[94:97], v[152:155], v[202:205], v[94:97]
	v_mfma_f32_16x16x32_bf16 v[90:93], v[160:163], v[202:205], v[90:93]
	v_mfma_f32_16x16x32_bf16 v[78:81], v[152:155], v[210:213], v[78:81]
	v_mfma_f32_16x16x32_bf16 v[74:77], v[160:163], v[210:213], v[74:77]
	v_mfma_f32_16x16x32_bf16 v[126:129], v[156:159], v[190:193], v[126:129]
	v_mfma_f32_16x16x32_bf16 v[122:125], v[164:167], v[190:193], v[122:125]
	v_mfma_f32_16x16x32_bf16 v[110:113], v[156:159], v[198:201], v[110:113]
	v_mfma_f32_16x16x32_bf16 v[106:109], v[164:167], v[198:201], v[106:109]
	v_mfma_f32_16x16x32_bf16 v[94:97], v[156:159], v[206:209], v[94:97]
	v_mfma_f32_16x16x32_bf16 v[90:93], v[164:167], v[206:209], v[90:93]
	v_mfma_f32_16x16x32_bf16 v[78:81], v[156:159], v[214:217], v[78:81]
	v_mfma_f32_16x16x32_bf16 v[74:77], v[164:167], v[214:217], v[74:77]
	s_setprio 0
	s_setprio 1
	v_mfma_f32_16x16x32_bf16 v[118:121], v[168:171], v[186:189], v[118:121]
	v_mfma_f32_16x16x32_bf16 v[114:117], v[178:181], v[186:189], v[114:117]
	v_mfma_f32_16x16x32_bf16 v[102:105], v[168:171], v[194:197], v[102:105]
	v_mfma_f32_16x16x32_bf16 v[98:101], v[178:181], v[194:197], v[98:101]
	v_mfma_f32_16x16x32_bf16 v[86:89], v[168:171], v[202:205], v[86:89]
	v_mfma_f32_16x16x32_bf16 v[82:85], v[178:181], v[202:205], v[82:85]
	v_mfma_f32_16x16x32_bf16 v[70:73], v[168:171], v[210:213], v[70:73]
	v_mfma_f32_16x16x32_bf16 v[66:69], v[178:181], v[210:213], v[66:69]
	v_mfma_f32_16x16x32_bf16 v[118:121], v[172:175], v[190:193], v[118:121]
	v_mfma_f32_16x16x32_bf16 v[114:117], v[182:185], v[190:193], v[114:117]
	v_mfma_f32_16x16x32_bf16 v[102:105], v[172:175], v[198:201], v[102:105]
	v_mfma_f32_16x16x32_bf16 v[98:101], v[182:185], v[198:201], v[98:101]
	v_mfma_f32_16x16x32_bf16 v[86:89], v[172:175], v[206:209], v[86:89]
	v_mfma_f32_16x16x32_bf16 v[82:85], v[182:185], v[206:209], v[82:85]
	v_mfma_f32_16x16x32_bf16 v[70:73], v[172:175], v[214:217], v[70:73]
	v_mfma_f32_16x16x32_bf16 v[66:69], v[182:185], v[214:217], v[66:69]
	s_setprio 0
	s_barrier
	s_add_i32 s2, s56, s34
	v_lshl_add_u64 v[146:147], v[146:147], 0, s[6:7]
	s_mov_b32 m0, s2
	ds_read_b128 v[186:189], v150 offset:49152
	ds_read_b128 v[190:193], v150 offset:50176
	ds_read_b128 v[194:197], v150 offset:51200
	ds_read_b128 v[198:201], v150 offset:52224
	ds_read_b128 v[202:205], v150 offset:53248
	ds_read_b128 v[206:209], v150 offset:54272
	ds_read_b128 v[210:213], v150 offset:55296
	ds_read_b128 v[214:217], v150 offset:56320
	global_load_lds_dwordx4 v[146:147], off
	s_add_i32 m0, s2, 0x2000
	s_add_u32 s2, s30, 0x40080
	v_lshl_add_u64 v[146:147], v[218:219], 0, s[6:7]
	s_addc_u32 s3, s31, 0
	s_add_i32 s30, s57, s34
	global_load_lds_dwordx4 v[146:147], off
	v_lshl_add_u64 v[146:147], s[2:3], 0, v[132:133]
	s_mov_b32 m0, s30
	s_nop 0
	global_load_lds_dwordx4 v[146:147], off
	v_lshl_add_u64 v[146:147], s[2:3], 0, v[136:137]
	s_add_i32 m0, s30, 0x2000
	s_nop 0
	global_load_lds_dwordx4 v[146:147], off
	v_lshl_add_u64 v[146:147], v[220:221], 0, s[6:7]
	s_mov_b32 m0, s40
	s_nop 0
	global_load_lds_dwordx4 v[146:147], off
	v_lshl_add_u64 v[146:147], v[222:223], 0, s[6:7]
	s_mov_b32 m0, s41
	s_nop 0
	global_load_lds_dwordx4 v[146:147], off
	s_waitcnt vmcnt(8)
	s_waitcnt lgkmcnt(0)
	s_setprio 1
	s_barrier
	s_waitcnt lgkmcnt(0)
	v_mfma_f32_16x16x32_bf16 v[62:65], v[152:155], v[186:189], v[62:65]
	v_mfma_f32_16x16x32_bf16 v[58:61], v[160:163], v[186:189], v[58:61]
	v_mfma_f32_16x16x32_bf16 v[46:49], v[152:155], v[194:197], v[46:49]
	v_mfma_f32_16x16x32_bf16 v[42:45], v[160:163], v[194:197], v[42:45]
	v_mfma_f32_16x16x32_bf16 v[30:33], v[152:155], v[202:205], v[30:33]
	v_mfma_f32_16x16x32_bf16 v[26:29], v[160:163], v[202:205], v[26:29]
	v_mfma_f32_16x16x32_bf16 v[14:17], v[152:155], v[210:213], v[14:17]
	v_mfma_f32_16x16x32_bf16 v[10:13], v[160:163], v[210:213], v[10:13]
	v_mfma_f32_16x16x32_bf16 v[62:65], v[156:159], v[190:193], v[62:65]
	v_mfma_f32_16x16x32_bf16 v[58:61], v[164:167], v[190:193], v[58:61]
	v_mfma_f32_16x16x32_bf16 v[46:49], v[156:159], v[198:201], v[46:49]
	v_mfma_f32_16x16x32_bf16 v[42:45], v[164:167], v[198:201], v[42:45]
	v_mfma_f32_16x16x32_bf16 v[30:33], v[156:159], v[206:209], v[30:33]
	v_mfma_f32_16x16x32_bf16 v[26:29], v[164:167], v[206:209], v[26:29]
	v_mfma_f32_16x16x32_bf16 v[14:17], v[156:159], v[214:217], v[14:17]
	v_mfma_f32_16x16x32_bf16 v[10:13], v[164:167], v[214:217], v[10:13]
	s_setprio 0
	s_setprio 1
	v_mfma_f32_16x16x32_bf16 v[54:57], v[168:171], v[186:189], v[54:57]
	v_mfma_f32_16x16x32_bf16 v[50:53], v[178:181], v[186:189], v[50:53]
	v_mfma_f32_16x16x32_bf16 v[38:41], v[168:171], v[194:197], v[38:41]
	v_mfma_f32_16x16x32_bf16 v[34:37], v[178:181], v[194:197], v[34:37]
	v_mfma_f32_16x16x32_bf16 v[22:25], v[168:171], v[202:205], v[22:25]
	v_mfma_f32_16x16x32_bf16 v[18:21], v[178:181], v[202:205], v[18:21]
	v_mfma_f32_16x16x32_bf16 v[6:9], v[168:171], v[210:213], v[6:9]
	v_mfma_f32_16x16x32_bf16 v[2:5], v[178:181], v[210:213], v[2:5]
	v_mfma_f32_16x16x32_bf16 v[54:57], v[172:175], v[190:193], v[54:57]
	v_mfma_f32_16x16x32_bf16 v[50:53], v[182:185], v[190:193], v[50:53]
	v_mfma_f32_16x16x32_bf16 v[38:41], v[172:175], v[198:201], v[38:41]
	v_mfma_f32_16x16x32_bf16 v[34:37], v[182:185], v[198:201], v[34:37]
	v_mfma_f32_16x16x32_bf16 v[22:25], v[172:175], v[206:209], v[22:25]
	v_mfma_f32_16x16x32_bf16 v[18:21], v[182:185], v[206:209], v[18:21]
	v_mfma_f32_16x16x32_bf16 v[6:9], v[172:175], v[214:217], v[6:9]
	v_mfma_f32_16x16x32_bf16 v[2:5], v[182:185], v[214:217], v[2:5]
	s_setprio 0
	s_barrier
	s_add_i32 s55, s55, 2
	s_add_u32 s28, s28, 0x100
	s_addc_u32 s29, s29, 0
	s_add_u32 s53, s53, 0x100
	s_addc_u32 s54, s54, 0
	s_cmp_gt_u32 s55, 13
	s_cbranch_scc0 .LBB0_1400

.Lpk1444_peel:
	ds_read_b128 v[152:155], v148
	ds_read_b128 v[156:159], v148 offset:1024
	ds_read_b128 v[160:163], v148 offset:2048
	ds_read_b128 v[164:167], v148 offset:3072
	ds_read_b128 v[168:171], v149
	ds_read_b128 v[172:175], v149 offset:1024
	ds_read_b128 v[178:181], v149 offset:2048
	ds_read_b128 v[182:185], v149 offset:3072
	s_add_u32 s2, s26, 0x4000
	s_addc_u32 s3, s27, 0
	s_cmp_eq_u32 s62, 40
	s_cselect_b32 s2, s57, s2
	s_cselect_b32 s3, s56, s3
	s_cselect_b32 s31, s58, s61
	s_cselect_b32 s30, s59, s60
	s_add_u32 s28, s2, 0x8000
	s_addc_u32 s29, s3, 0
	v_lshl_add_u64 v[144:145], s[26:27], 0, v[138:139]
	s_add_i32 m0, s39, 0xc000
	ds_read_b128 v[186:189], v150
	ds_read_b128 v[190:193], v150 offset:1024
	ds_read_b128 v[194:197], v150 offset:2048
	ds_read_b128 v[198:201], v150 offset:3072
	ds_read_b128 v[202:205], v150 offset:4096
	ds_read_b128 v[206:209], v150 offset:5120
	ds_read_b128 v[210:213], v150 offset:6144
	ds_read_b128 v[214:217], v150 offset:7168
	global_load_lds_dwordx4 v[144:145], off
	v_lshl_add_u64 v[144:145], s[26:27], 0, v[140:141]
	s_add_i32 m0, s39, 0xe000
	s_nop 0
	global_load_lds_dwordx4 v[144:145], off
	s_waitcnt vmcnt(8)
	s_waitcnt lgkmcnt(0)
	s_setprio 1
	s_barrier
	s_waitcnt lgkmcnt(0)
	v_mfma_f32_16x16x32_bf16 v[126:129], v[152:155], v[186:189], 0
	v_mfma_f32_16x16x32_bf16 v[122:125], v[160:163], v[186:189], 0
	v_mfma_f32_16x16x32_bf16 v[114:117], v[152:155], v[194:197], 0
	v_mfma_f32_16x16x32_bf16 v[106:109], v[160:163], v[194:197], 0
	v_mfma_f32_16x16x32_bf16 v[98:101], v[152:155], v[202:205], 0
	v_mfma_f32_16x16x32_bf16 v[90:93], v[160:163], v[202:205], 0
	v_mfma_f32_16x16x32_bf16 v[82:85], v[152:155], v[210:213], 0
	v_mfma_f32_16x16x32_bf16 v[74:77], v[160:163], v[210:213], 0
	v_mfma_f32_16x16x32_bf16 v[126:129], v[156:159], v[190:193], v[126:129]
	v_mfma_f32_16x16x32_bf16 v[122:125], v[164:167], v[190:193], v[122:125]
	v_mfma_f32_16x16x32_bf16 v[114:117], v[156:159], v[198:201], v[114:117]
	v_mfma_f32_16x16x32_bf16 v[106:109], v[164:167], v[198:201], v[106:109]
	v_mfma_f32_16x16x32_bf16 v[98:101], v[156:159], v[206:209], v[98:101]
	v_mfma_f32_16x16x32_bf16 v[90:93], v[164:167], v[206:209], v[90:93]
	v_mfma_f32_16x16x32_bf16 v[82:85], v[156:159], v[214:217], v[82:85]
	v_mfma_f32_16x16x32_bf16 v[74:77], v[164:167], v[214:217], v[74:77]
	s_setprio 0
	s_setprio 1
	v_mfma_f32_16x16x32_bf16 v[118:121], v[168:171], v[186:189], 0
	v_mfma_f32_16x16x32_bf16 v[110:113], v[178:181], v[186:189], 0
	v_mfma_f32_16x16x32_bf16 v[102:105], v[168:171], v[194:197], 0
	v_mfma_f32_16x16x32_bf16 v[94:97], v[178:181], v[194:197], 0
	v_mfma_f32_16x16x32_bf16 v[86:89], v[168:171], v[202:205], 0
	v_mfma_f32_16x16x32_bf16 v[78:81], v[178:181], v[202:205], 0
	v_mfma_f32_16x16x32_bf16 v[70:73], v[168:171], v[210:213], 0
	v_mfma_f32_16x16x32_bf16 v[66:69], v[178:181], v[210:213], 0
	v_mfma_f32_16x16x32_bf16 v[118:121], v[172:175], v[190:193], v[118:121]
	v_mfma_f32_16x16x32_bf16 v[110:113], v[182:185], v[190:193], v[110:113]
	v_mfma_f32_16x16x32_bf16 v[102:105], v[172:175], v[198:201], v[102:105]
	v_mfma_f32_16x16x32_bf16 v[94:97], v[182:185], v[198:201], v[94:97]
	v_mfma_f32_16x16x32_bf16 v[86:89], v[172:175], v[206:209], v[86:89]
	v_mfma_f32_16x16x32_bf16 v[78:81], v[182:185], v[206:209], v[78:81]
	v_mfma_f32_16x16x32_bf16 v[70:73], v[172:175], v[214:217], v[70:73]
	v_mfma_f32_16x16x32_bf16 v[66:69], v[182:185], v[214:217], v[66:69]
	s_setprio 0
	s_barrier
	s_add_i32 s63, s46, s38
	v_lshl_add_u64 v[144:145], s[30:31], 0, v[132:133]
	s_mov_b32 m0, s63
	ds_read_b128 v[186:189], v150 offset:16384
	ds_read_b128 v[190:193], v150 offset:17408
	ds_read_b128 v[194:197], v150 offset:18432
	ds_read_b128 v[198:201], v150 offset:19456
	ds_read_b128 v[202:205], v150 offset:20480
	ds_read_b128 v[206:209], v150 offset:21504
	ds_read_b128 v[210:213], v150 offset:22528
	ds_read_b128 v[214:217], v150 offset:23552
	global_load_lds_dwordx4 v[144:145], off
	s_add_i32 m0, s63, 0x2000
	s_add_u32 s64, s30, 0x4000
	v_lshl_add_u64 v[144:145], s[30:31], 0, v[136:137]
	s_addc_u32 s65, s31, 0
	s_add_i32 s63, s47, s38
	global_load_lds_dwordx4 v[144:145], off
	v_lshl_add_u64 v[144:145], s[64:65], 0, v[132:133]
	s_mov_b32 m0, s63
	s_nop 0
	global_load_lds_dwordx4 v[144:145], off
	v_lshl_add_u64 v[144:145], s[64:65], 0, v[136:137]
	s_add_i32 m0, s63, 0x2000
	s_nop 0
	global_load_lds_dwordx4 v[144:145], off
	v_lshl_add_u64 v[144:145], s[2:3], 0, v[130:131]
	s_mov_b32 m0, s39
	s_nop 0
	global_load_lds_dwordx4 v[144:145], off
	v_lshl_add_u64 v[144:145], s[2:3], 0, v[134:135]
	s_mov_b32 m0, s40
	s_nop 0
	global_load_lds_dwordx4 v[144:145], off
	s_waitcnt vmcnt(8)
	s_waitcnt lgkmcnt(0)
	s_setprio 1
	s_barrier
	s_waitcnt lgkmcnt(0)
	v_mfma_f32_16x16x32_bf16 v[62:65], v[152:155], v[186:189], 0
	v_mfma_f32_16x16x32_bf16 v[58:61], v[160:163], v[186:189], 0
	v_mfma_f32_16x16x32_bf16 v[50:53], v[152:155], v[194:197], 0
	v_mfma_f32_16x16x32_bf16 v[42:45], v[160:163], v[194:197], 0
	v_mfma_f32_16x16x32_bf16 v[34:37], v[152:155], v[202:205], 0
	v_mfma_f32_16x16x32_bf16 v[26:29], v[160:163], v[202:205], 0
	v_mfma_f32_16x16x32_bf16 v[18:21], v[152:155], v[210:213], 0
	v_mfma_f32_16x16x32_bf16 v[10:13], v[160:163], v[210:213], 0
	v_mfma_f32_16x16x32_bf16 v[62:65], v[156:159], v[190:193], v[62:65]
	v_mfma_f32_16x16x32_bf16 v[58:61], v[164:167], v[190:193], v[58:61]
	v_mfma_f32_16x16x32_bf16 v[50:53], v[156:159], v[198:201], v[50:53]
	v_mfma_f32_16x16x32_bf16 v[42:45], v[164:167], v[198:201], v[42:45]
	v_mfma_f32_16x16x32_bf16 v[34:37], v[156:159], v[206:209], v[34:37]
	v_mfma_f32_16x16x32_bf16 v[26:29], v[164:167], v[206:209], v[26:29]
	v_mfma_f32_16x16x32_bf16 v[18:21], v[156:159], v[214:217], v[18:21]
	v_mfma_f32_16x16x32_bf16 v[10:13], v[164:167], v[214:217], v[10:13]
	s_setprio 0
	s_setprio 1
	v_mfma_f32_16x16x32_bf16 v[54:57], v[168:171], v[186:189], 0
	v_mfma_f32_16x16x32_bf16 v[46:49], v[178:181], v[186:189], 0
	v_mfma_f32_16x16x32_bf16 v[38:41], v[168:171], v[194:197], 0
	v_mfma_f32_16x16x32_bf16 v[30:33], v[178:181], v[194:197], 0
	v_mfma_f32_16x16x32_bf16 v[22:25], v[168:171], v[202:205], 0
	v_mfma_f32_16x16x32_bf16 v[14:17], v[178:181], v[202:205], 0
	v_mfma_f32_16x16x32_bf16 v[6:9], v[168:171], v[210:213], 0
	v_mfma_f32_16x16x32_bf16 v[2:5], v[178:181], v[210:213], 0
	v_mfma_f32_16x16x32_bf16 v[54:57], v[172:175], v[190:193], v[54:57]
	v_mfma_f32_16x16x32_bf16 v[46:49], v[182:185], v[190:193], v[46:49]
	v_mfma_f32_16x16x32_bf16 v[38:41], v[172:175], v[198:201], v[38:41]
	v_mfma_f32_16x16x32_bf16 v[30:33], v[182:185], v[198:201], v[30:33]
	v_mfma_f32_16x16x32_bf16 v[22:25], v[172:175], v[206:209], v[22:25]
	v_mfma_f32_16x16x32_bf16 v[14:17], v[182:185], v[206:209], v[14:17]
	v_mfma_f32_16x16x32_bf16 v[6:9], v[172:175], v[214:217], v[6:9]
	v_mfma_f32_16x16x32_bf16 v[2:5], v[182:185], v[214:217], v[2:5]
	s_setprio 0
	s_barrier
	s_add_i32 s63, 0, 0x18000
	v_add_u32_e32 v144, s63, v146
	s_add_i32 s64, 0, 0x1c000
	ds_read_b128 v[152:155], v144
	ds_read_b128 v[156:159], v144 offset:1024
	ds_read_b128 v[160:163], v144 offset:2048
	ds_read_b128 v[164:167], v144 offset:3072
	v_add_u32_e32 v144, s64, v146
	ds_read_b128 v[168:171], v144
	ds_read_b128 v[172:175], v144 offset:1024
	ds_read_b128 v[178:181], v144 offset:2048
	ds_read_b128 v[182:185], v144 offset:3072
	s_add_u32 s2, s2, 0x4000
	s_addc_u32 s3, s3, 0
	s_mov_b32 m0, s41
	v_lshl_add_u64 v[144:145], s[2:3], 0, v[130:131]
	ds_read_b128 v[186:189], v150 offset:32768
	ds_read_b128 v[190:193], v150 offset:33792
	ds_read_b128 v[194:197], v150 offset:34816
	ds_read_b128 v[198:201], v150 offset:35840
	ds_read_b128 v[202:205], v150 offset:36864
	ds_read_b128 v[206:209], v150 offset:37888
	ds_read_b128 v[210:213], v150 offset:38912
	ds_read_b128 v[214:217], v150 offset:39936
	global_load_lds_dwordx4 v[144:145], off
	v_lshl_add_u64 v[144:145], s[2:3], 0, v[134:135]
	s_mov_b32 m0, s42
	s_nop 0
	global_load_lds_dwordx4 v[144:145], off
	s_waitcnt vmcnt(8)
	s_waitcnt lgkmcnt(0)
	s_setprio 1
	s_barrier
	s_waitcnt lgkmcnt(0)
	v_mfma_f32_16x16x32_bf16 v[126:129], v[152:155], v[186:189], v[126:129]
	v_mfma_f32_16x16x32_bf16 v[122:125], v[160:163], v[186:189], v[122:125]
	v_mfma_f32_16x16x32_bf16 v[114:117], v[152:155], v[194:197], v[114:117]
	v_mfma_f32_16x16x32_bf16 v[106:109], v[160:163], v[194:197], v[106:109]
	v_mfma_f32_16x16x32_bf16 v[98:101], v[152:155], v[202:205], v[98:101]
	v_mfma_f32_16x16x32_bf16 v[90:93], v[160:163], v[202:205], v[90:93]
	v_mfma_f32_16x16x32_bf16 v[82:85], v[152:155], v[210:213], v[82:85]
	v_mfma_f32_16x16x32_bf16 v[74:77], v[160:163], v[210:213], v[74:77]
	v_mfma_f32_16x16x32_bf16 v[126:129], v[156:159], v[190:193], v[126:129]
	v_mfma_f32_16x16x32_bf16 v[122:125], v[164:167], v[190:193], v[122:125]
	v_mfma_f32_16x16x32_bf16 v[114:117], v[156:159], v[198:201], v[114:117]
	v_mfma_f32_16x16x32_bf16 v[106:109], v[164:167], v[198:201], v[106:109]
	v_mfma_f32_16x16x32_bf16 v[98:101], v[156:159], v[206:209], v[98:101]
	v_mfma_f32_16x16x32_bf16 v[90:93], v[164:167], v[206:209], v[90:93]
	v_mfma_f32_16x16x32_bf16 v[82:85], v[156:159], v[214:217], v[82:85]
	v_mfma_f32_16x16x32_bf16 v[74:77], v[164:167], v[214:217], v[74:77]
	s_setprio 0
	s_setprio 1
	v_mfma_f32_16x16x32_bf16 v[118:121], v[168:171], v[186:189], v[118:121]
	v_mfma_f32_16x16x32_bf16 v[110:113], v[178:181], v[186:189], v[110:113]
	v_mfma_f32_16x16x32_bf16 v[102:105], v[168:171], v[194:197], v[102:105]
	v_mfma_f32_16x16x32_bf16 v[94:97], v[178:181], v[194:197], v[94:97]
	v_mfma_f32_16x16x32_bf16 v[86:89], v[168:171], v[202:205], v[86:89]
	v_mfma_f32_16x16x32_bf16 v[78:81], v[178:181], v[202:205], v[78:81]
	v_mfma_f32_16x16x32_bf16 v[70:73], v[168:171], v[210:213], v[70:73]
	v_mfma_f32_16x16x32_bf16 v[66:69], v[178:181], v[210:213], v[66:69]
	v_mfma_f32_16x16x32_bf16 v[118:121], v[172:175], v[190:193], v[118:121]
	v_mfma_f32_16x16x32_bf16 v[110:113], v[182:185], v[190:193], v[110:113]
	v_mfma_f32_16x16x32_bf16 v[102:105], v[172:175], v[198:201], v[102:105]
	v_mfma_f32_16x16x32_bf16 v[94:97], v[182:185], v[198:201], v[94:97]
	v_mfma_f32_16x16x32_bf16 v[86:89], v[172:175], v[206:209], v[86:89]
	v_mfma_f32_16x16x32_bf16 v[78:81], v[182:185], v[206:209], v[78:81]
	v_mfma_f32_16x16x32_bf16 v[70:73], v[172:175], v[214:217], v[70:73]
	v_mfma_f32_16x16x32_bf16 v[66:69], v[182:185], v[214:217], v[66:69]
	s_setprio 0
	s_barrier
	s_add_u32 s2, s30, 0x8000
	s_addc_u32 s3, s31, 0
	s_add_i32 s63, s63, s38
	v_lshl_add_u64 v[144:145], s[2:3], 0, v[132:133]
	s_mov_b32 m0, s63
	ds_read_b128 v[186:189], v150 offset:49152
	ds_read_b128 v[190:193], v150 offset:50176
	ds_read_b128 v[194:197], v150 offset:51200
	ds_read_b128 v[198:201], v150 offset:52224
	ds_read_b128 v[202:205], v150 offset:53248
	ds_read_b128 v[206:209], v150 offset:54272
	ds_read_b128 v[210:213], v150 offset:55296
	ds_read_b128 v[214:217], v150 offset:56320
	global_load_lds_dwordx4 v[144:145], off
	s_add_i32 m0, s63, 0x2000
	v_lshl_add_u64 v[144:145], s[2:3], 0, v[136:137]
	s_add_u32 s2, s30, 0xc000
	s_addc_u32 s3, s31, 0
	s_add_i32 s30, s64, s38
	global_load_lds_dwordx4 v[144:145], off
	v_lshl_add_u64 v[144:145], s[2:3], 0, v[132:133]
	s_mov_b32 m0, s30
	s_nop 0
	global_load_lds_dwordx4 v[144:145], off
	v_lshl_add_u64 v[144:145], s[2:3], 0, v[136:137]
	s_add_i32 m0, s30, 0x2000
	s_nop 0
	global_load_lds_dwordx4 v[144:145], off
	v_lshl_add_u64 v[144:145], s[28:29], 0, v[130:131]
	s_mov_b32 m0, s44
	s_nop 0
	global_load_lds_dwordx4 v[144:145], off
	v_lshl_add_u64 v[144:145], s[28:29], 0, v[134:135]
	s_mov_b32 m0, s45
	s_nop 0
	global_load_lds_dwordx4 v[144:145], off
	s_waitcnt vmcnt(8)
	s_waitcnt lgkmcnt(0)
	s_setprio 1
	s_barrier
	s_waitcnt lgkmcnt(0)
	v_mfma_f32_16x16x32_bf16 v[62:65], v[152:155], v[186:189], v[62:65]
	v_mfma_f32_16x16x32_bf16 v[58:61], v[160:163], v[186:189], v[58:61]
	v_mfma_f32_16x16x32_bf16 v[50:53], v[152:155], v[194:197], v[50:53]
	v_mfma_f32_16x16x32_bf16 v[42:45], v[160:163], v[194:197], v[42:45]
	v_mfma_f32_16x16x32_bf16 v[34:37], v[152:155], v[202:205], v[34:37]
	v_mfma_f32_16x16x32_bf16 v[26:29], v[160:163], v[202:205], v[26:29]
	v_mfma_f32_16x16x32_bf16 v[18:21], v[152:155], v[210:213], v[18:21]
	v_mfma_f32_16x16x32_bf16 v[10:13], v[160:163], v[210:213], v[10:13]
	v_mfma_f32_16x16x32_bf16 v[62:65], v[156:159], v[190:193], v[62:65]
	v_mfma_f32_16x16x32_bf16 v[58:61], v[164:167], v[190:193], v[58:61]
	v_mfma_f32_16x16x32_bf16 v[50:53], v[156:159], v[198:201], v[50:53]
	v_mfma_f32_16x16x32_bf16 v[42:45], v[164:167], v[198:201], v[42:45]
	v_mfma_f32_16x16x32_bf16 v[34:37], v[156:159], v[206:209], v[34:37]
	v_mfma_f32_16x16x32_bf16 v[26:29], v[164:167], v[206:209], v[26:29]
	v_mfma_f32_16x16x32_bf16 v[18:21], v[156:159], v[214:217], v[18:21]
	v_mfma_f32_16x16x32_bf16 v[10:13], v[164:167], v[214:217], v[10:13]
	s_setprio 0
	s_setprio 1
	v_mfma_f32_16x16x32_bf16 v[54:57], v[168:171], v[186:189], v[54:57]
	v_mfma_f32_16x16x32_bf16 v[46:49], v[178:181], v[186:189], v[46:49]
	v_mfma_f32_16x16x32_bf16 v[38:41], v[168:171], v[194:197], v[38:41]
	v_mfma_f32_16x16x32_bf16 v[30:33], v[178:181], v[194:197], v[30:33]
	v_mfma_f32_16x16x32_bf16 v[22:25], v[168:171], v[202:205], v[22:25]
	v_mfma_f32_16x16x32_bf16 v[14:17], v[178:181], v[202:205], v[14:17]
	v_mfma_f32_16x16x32_bf16 v[6:9], v[168:171], v[210:213], v[6:9]
	v_mfma_f32_16x16x32_bf16 v[2:5], v[178:181], v[210:213], v[2:5]
	v_mfma_f32_16x16x32_bf16 v[54:57], v[172:175], v[190:193], v[54:57]
	v_mfma_f32_16x16x32_bf16 v[46:49], v[182:185], v[190:193], v[46:49]
	v_mfma_f32_16x16x32_bf16 v[38:41], v[172:175], v[198:201], v[38:41]
	v_mfma_f32_16x16x32_bf16 v[30:33], v[182:185], v[198:201], v[30:33]
	v_mfma_f32_16x16x32_bf16 v[22:25], v[172:175], v[206:209], v[22:25]
	v_mfma_f32_16x16x32_bf16 v[14:17], v[182:185], v[206:209], v[14:17]
	v_mfma_f32_16x16x32_bf16 v[6:9], v[172:175], v[214:217], v[6:9]
	v_mfma_f32_16x16x32_bf16 v[2:5], v[182:185], v[214:217], v[2:5]
	s_setprio 0
	s_barrier
	s_add_i32 s62, s62, 2
	s_add_u32 s26, s26, 0x10000
	s_addc_u32 s27, s27, 0
	s_add_u32 s60, s60, 0x10000
	s_addc_u32 s61, s61, 0
	s_cmp_gt_u32 s62, 41
	s_cbranch_scc0 .LBB0_1444
	s_branch .Lpk1444_exit
.LBB0_1444:
	ds_read_b128 v[152:155], v148
	ds_read_b128 v[156:159], v148 offset:1024
	ds_read_b128 v[160:163], v148 offset:2048
	ds_read_b128 v[164:167], v148 offset:3072
	ds_read_b128 v[168:171], v149
	ds_read_b128 v[172:175], v149 offset:1024
	ds_read_b128 v[178:181], v149 offset:2048
	ds_read_b128 v[182:185], v149 offset:3072
	s_add_u32 s2, s26, 0x4000
	s_addc_u32 s3, s27, 0
	s_cmp_eq_u32 s62, 40
	s_cselect_b32 s2, s57, s2
	s_cselect_b32 s3, s56, s3
	s_cselect_b32 s31, s58, s61
	s_cselect_b32 s30, s59, s60
	s_add_u32 s28, s2, 0x8000
	s_addc_u32 s29, s3, 0
	v_lshl_add_u64 v[144:145], s[26:27], 0, v[138:139]
	s_add_i32 m0, s39, 0xc000
	ds_read_b128 v[186:189], v150
	ds_read_b128 v[190:193], v150 offset:1024
	ds_read_b128 v[194:197], v150 offset:2048
	ds_read_b128 v[198:201], v150 offset:3072
	ds_read_b128 v[202:205], v150 offset:4096
	ds_read_b128 v[206:209], v150 offset:5120
	ds_read_b128 v[210:213], v150 offset:6144
	ds_read_b128 v[214:217], v150 offset:7168
	global_load_lds_dwordx4 v[144:145], off
	v_lshl_add_u64 v[144:145], s[26:27], 0, v[140:141]
	s_add_i32 m0, s39, 0xe000
	s_nop 0
	global_load_lds_dwordx4 v[144:145], off
	s_waitcnt vmcnt(8)
	s_waitcnt lgkmcnt(0)
	s_setprio 1
	s_barrier
	s_waitcnt lgkmcnt(0)
	v_mfma_f32_16x16x32_bf16 v[126:129], v[152:155], v[186:189], v[126:129]
	v_mfma_f32_16x16x32_bf16 v[122:125], v[160:163], v[186:189], v[122:125]
	v_mfma_f32_16x16x32_bf16 v[114:117], v[152:155], v[194:197], v[114:117]
	v_mfma_f32_16x16x32_bf16 v[106:109], v[160:163], v[194:197], v[106:109]
	v_mfma_f32_16x16x32_bf16 v[98:101], v[152:155], v[202:205], v[98:101]
	v_mfma_f32_16x16x32_bf16 v[90:93], v[160:163], v[202:205], v[90:93]
	v_mfma_f32_16x16x32_bf16 v[82:85], v[152:155], v[210:213], v[82:85]
	v_mfma_f32_16x16x32_bf16 v[74:77], v[160:163], v[210:213], v[74:77]
	v_mfma_f32_16x16x32_bf16 v[126:129], v[156:159], v[190:193], v[126:129]
	v_mfma_f32_16x16x32_bf16 v[122:125], v[164:167], v[190:193], v[122:125]
	v_mfma_f32_16x16x32_bf16 v[114:117], v[156:159], v[198:201], v[114:117]
	v_mfma_f32_16x16x32_bf16 v[106:109], v[164:167], v[198:201], v[106:109]
	v_mfma_f32_16x16x32_bf16 v[98:101], v[156:159], v[206:209], v[98:101]
	v_mfma_f32_16x16x32_bf16 v[90:93], v[164:167], v[206:209], v[90:93]
	v_mfma_f32_16x16x32_bf16 v[82:85], v[156:159], v[214:217], v[82:85]
	v_mfma_f32_16x16x32_bf16 v[74:77], v[164:167], v[214:217], v[74:77]
	s_setprio 0
	s_setprio 1
	v_mfma_f32_16x16x32_bf16 v[118:121], v[168:171], v[186:189], v[118:121]
	v_mfma_f32_16x16x32_bf16 v[110:113], v[178:181], v[186:189], v[110:113]
	v_mfma_f32_16x16x32_bf16 v[102:105], v[168:171], v[194:197], v[102:105]
	v_mfma_f32_16x16x32_bf16 v[94:97], v[178:181], v[194:197], v[94:97]
	v_mfma_f32_16x16x32_bf16 v[86:89], v[168:171], v[202:205], v[86:89]
	v_mfma_f32_16x16x32_bf16 v[78:81], v[178:181], v[202:205], v[78:81]
	v_mfma_f32_16x16x32_bf16 v[70:73], v[168:171], v[210:213], v[70:73]
	v_mfma_f32_16x16x32_bf16 v[66:69], v[178:181], v[210:213], v[66:69]
	v_mfma_f32_16x16x32_bf16 v[118:121], v[172:175], v[190:193], v[118:121]
	v_mfma_f32_16x16x32_bf16 v[110:113], v[182:185], v[190:193], v[110:113]
	v_mfma_f32_16x16x32_bf16 v[102:105], v[172:175], v[198:201], v[102:105]
	v_mfma_f32_16x16x32_bf16 v[94:97], v[182:185], v[198:201], v[94:97]
	v_mfma_f32_16x16x32_bf16 v[86:89], v[172:175], v[206:209], v[86:89]
	v_mfma_f32_16x16x32_bf16 v[78:81], v[182:185], v[206:209], v[78:81]
	v_mfma_f32_16x16x32_bf16 v[70:73], v[172:175], v[214:217], v[70:73]
	v_mfma_f32_16x16x32_bf16 v[66:69], v[182:185], v[214:217], v[66:69]
	s_setprio 0
	s_barrier
	s_add_i32 s63, s46, s38
	v_lshl_add_u64 v[144:145], s[30:31], 0, v[132:133]
	s_mov_b32 m0, s63
	ds_read_b128 v[186:189], v150 offset:16384
	ds_read_b128 v[190:193], v150 offset:17408
	ds_read_b128 v[194:197], v150 offset:18432
	ds_read_b128 v[198:201], v150 offset:19456
	ds_read_b128 v[202:205], v150 offset:20480
	ds_read_b128 v[206:209], v150 offset:21504
	ds_read_b128 v[210:213], v150 offset:22528
	ds_read_b128 v[214:217], v150 offset:23552
	global_load_lds_dwordx4 v[144:145], off
	s_add_i32 m0, s63, 0x2000
	s_add_u32 s64, s30, 0x4000
	v_lshl_add_u64 v[144:145], s[30:31], 0, v[136:137]
	s_addc_u32 s65, s31, 0
	s_add_i32 s63, s47, s38
	global_load_lds_dwordx4 v[144:145], off
	v_lshl_add_u64 v[144:145], s[64:65], 0, v[132:133]
	s_mov_b32 m0, s63
	s_nop 0
	global_load_lds_dwordx4 v[144:145], off
	v_lshl_add_u64 v[144:145], s[64:65], 0, v[136:137]
	s_add_i32 m0, s63, 0x2000
	s_nop 0
	global_load_lds_dwordx4 v[144:145], off
	v_lshl_add_u64 v[144:145], s[2:3], 0, v[130:131]
	s_mov_b32 m0, s39
	s_nop 0
	global_load_lds_dwordx4 v[144:145], off
	v_lshl_add_u64 v[144:145], s[2:3], 0, v[134:135]
	s_mov_b32 m0, s40
	s_nop 0
	global_load_lds_dwordx4 v[144:145], off
	s_waitcnt vmcnt(8)
	s_waitcnt lgkmcnt(0)
	s_setprio 1
	s_barrier
	s_waitcnt lgkmcnt(0)
	v_mfma_f32_16x16x32_bf16 v[62:65], v[152:155], v[186:189], v[62:65]
	v_mfma_f32_16x16x32_bf16 v[58:61], v[160:163], v[186:189], v[58:61]
	v_mfma_f32_16x16x32_bf16 v[50:53], v[152:155], v[194:197], v[50:53]
	v_mfma_f32_16x16x32_bf16 v[42:45], v[160:163], v[194:197], v[42:45]
	v_mfma_f32_16x16x32_bf16 v[34:37], v[152:155], v[202:205], v[34:37]
	v_mfma_f32_16x16x32_bf16 v[26:29], v[160:163], v[202:205], v[26:29]
	v_mfma_f32_16x16x32_bf16 v[18:21], v[152:155], v[210:213], v[18:21]
	v_mfma_f32_16x16x32_bf16 v[10:13], v[160:163], v[210:213], v[10:13]
	v_mfma_f32_16x16x32_bf16 v[62:65], v[156:159], v[190:193], v[62:65]
	v_mfma_f32_16x16x32_bf16 v[58:61], v[164:167], v[190:193], v[58:61]
	v_mfma_f32_16x16x32_bf16 v[50:53], v[156:159], v[198:201], v[50:53]
	v_mfma_f32_16x16x32_bf16 v[42:45], v[164:167], v[198:201], v[42:45]
	v_mfma_f32_16x16x32_bf16 v[34:37], v[156:159], v[206:209], v[34:37]
	v_mfma_f32_16x16x32_bf16 v[26:29], v[164:167], v[206:209], v[26:29]
	v_mfma_f32_16x16x32_bf16 v[18:21], v[156:159], v[214:217], v[18:21]
	v_mfma_f32_16x16x32_bf16 v[10:13], v[164:167], v[214:217], v[10:13]
	s_setprio 0
	s_setprio 1
	v_mfma_f32_16x16x32_bf16 v[54:57], v[168:171], v[186:189], v[54:57]
	v_mfma_f32_16x16x32_bf16 v[46:49], v[178:181], v[186:189], v[46:49]
	v_mfma_f32_16x16x32_bf16 v[38:41], v[168:171], v[194:197], v[38:41]
	v_mfma_f32_16x16x32_bf16 v[30:33], v[178:181], v[194:197], v[30:33]
	v_mfma_f32_16x16x32_bf16 v[22:25], v[168:171], v[202:205], v[22:25]
	v_mfma_f32_16x16x32_bf16 v[14:17], v[178:181], v[202:205], v[14:17]
	v_mfma_f32_16x16x32_bf16 v[6:9], v[168:171], v[210:213], v[6:9]
	v_mfma_f32_16x16x32_bf16 v[2:5], v[178:181], v[210:213], v[2:5]
	v_mfma_f32_16x16x32_bf16 v[54:57], v[172:175], v[190:193], v[54:57]
	v_mfma_f32_16x16x32_bf16 v[46:49], v[182:185], v[190:193], v[46:49]
	v_mfma_f32_16x16x32_bf16 v[38:41], v[172:175], v[198:201], v[38:41]
	v_mfma_f32_16x16x32_bf16 v[30:33], v[182:185], v[198:201], v[30:33]
	v_mfma_f32_16x16x32_bf16 v[22:25], v[172:175], v[206:209], v[22:25]
	v_mfma_f32_16x16x32_bf16 v[14:17], v[182:185], v[206:209], v[14:17]
	v_mfma_f32_16x16x32_bf16 v[6:9], v[172:175], v[214:217], v[6:9]
	v_mfma_f32_16x16x32_bf16 v[2:5], v[182:185], v[214:217], v[2:5]
	s_setprio 0
	s_barrier
	s_add_i32 s63, 0, 0x18000
	v_add_u32_e32 v144, s63, v146
	s_add_i32 s64, 0, 0x1c000
	ds_read_b128 v[152:155], v144
	ds_read_b128 v[156:159], v144 offset:1024
	ds_read_b128 v[160:163], v144 offset:2048
	ds_read_b128 v[164:167], v144 offset:3072
	v_add_u32_e32 v144, s64, v146
	ds_read_b128 v[168:171], v144
	ds_read_b128 v[172:175], v144 offset:1024
	ds_read_b128 v[178:181], v144 offset:2048
	ds_read_b128 v[182:185], v144 offset:3072
	s_add_u32 s2, s2, 0x4000
	s_addc_u32 s3, s3, 0
	s_mov_b32 m0, s41
	v_lshl_add_u64 v[144:145], s[2:3], 0, v[130:131]
	ds_read_b128 v[186:189], v150 offset:32768
	ds_read_b128 v[190:193], v150 offset:33792
	ds_read_b128 v[194:197], v150 offset:34816
	ds_read_b128 v[198:201], v150 offset:35840
	ds_read_b128 v[202:205], v150 offset:36864
	ds_read_b128 v[206:209], v150 offset:37888
	ds_read_b128 v[210:213], v150 offset:38912
	ds_read_b128 v[214:217], v150 offset:39936
	global_load_lds_dwordx4 v[144:145], off
	v_lshl_add_u64 v[144:145], s[2:3], 0, v[134:135]
	s_mov_b32 m0, s42
	s_nop 0
	global_load_lds_dwordx4 v[144:145], off
	s_waitcnt vmcnt(8)
	s_waitcnt lgkmcnt(0)
	s_setprio 1
	s_barrier
	s_waitcnt lgkmcnt(0)
	v_mfma_f32_16x16x32_bf16 v[126:129], v[152:155], v[186:189], v[126:129]
	v_mfma_f32_16x16x32_bf16 v[122:125], v[160:163], v[186:189], v[122:125]
	v_mfma_f32_16x16x32_bf16 v[114:117], v[152:155], v[194:197], v[114:117]
	v_mfma_f32_16x16x32_bf16 v[106:109], v[160:163], v[194:197], v[106:109]
	v_mfma_f32_16x16x32_bf16 v[98:101], v[152:155], v[202:205], v[98:101]
	v_mfma_f32_16x16x32_bf16 v[90:93], v[160:163], v[202:205], v[90:93]
	v_mfma_f32_16x16x32_bf16 v[82:85], v[152:155], v[210:213], v[82:85]
	v_mfma_f32_16x16x32_bf16 v[74:77], v[160:163], v[210:213], v[74:77]
	v_mfma_f32_16x16x32_bf16 v[126:129], v[156:159], v[190:193], v[126:129]
	v_mfma_f32_16x16x32_bf16 v[122:125], v[164:167], v[190:193], v[122:125]
	v_mfma_f32_16x16x32_bf16 v[114:117], v[156:159], v[198:201], v[114:117]
	v_mfma_f32_16x16x32_bf16 v[106:109], v[164:167], v[198:201], v[106:109]
	v_mfma_f32_16x16x32_bf16 v[98:101], v[156:159], v[206:209], v[98:101]
	v_mfma_f32_16x16x32_bf16 v[90:93], v[164:167], v[206:209], v[90:93]
	v_mfma_f32_16x16x32_bf16 v[82:85], v[156:159], v[214:217], v[82:85]
	v_mfma_f32_16x16x32_bf16 v[74:77], v[164:167], v[214:217], v[74:77]
	s_setprio 0
	s_setprio 1
	v_mfma_f32_16x16x32_bf16 v[118:121], v[168:171], v[186:189], v[118:121]
	v_mfma_f32_16x16x32_bf16 v[110:113], v[178:181], v[186:189], v[110:113]
	v_mfma_f32_16x16x32_bf16 v[102:105], v[168:171], v[194:197], v[102:105]
	v_mfma_f32_16x16x32_bf16 v[94:97], v[178:181], v[194:197], v[94:97]
	v_mfma_f32_16x16x32_bf16 v[86:89], v[168:171], v[202:205], v[86:89]
	v_mfma_f32_16x16x32_bf16 v[78:81], v[178:181], v[202:205], v[78:81]
	v_mfma_f32_16x16x32_bf16 v[70:73], v[168:171], v[210:213], v[70:73]
	v_mfma_f32_16x16x32_bf16 v[66:69], v[178:181], v[210:213], v[66:69]
	v_mfma_f32_16x16x32_bf16 v[118:121], v[172:175], v[190:193], v[118:121]
	v_mfma_f32_16x16x32_bf16 v[110:113], v[182:185], v[190:193], v[110:113]
	v_mfma_f32_16x16x32_bf16 v[102:105], v[172:175], v[198:201], v[102:105]
	v_mfma_f32_16x16x32_bf16 v[94:97], v[182:185], v[198:201], v[94:97]
	v_mfma_f32_16x16x32_bf16 v[86:89], v[172:175], v[206:209], v[86:89]
	v_mfma_f32_16x16x32_bf16 v[78:81], v[182:185], v[206:209], v[78:81]
	v_mfma_f32_16x16x32_bf16 v[70:73], v[172:175], v[214:217], v[70:73]
	v_mfma_f32_16x16x32_bf16 v[66:69], v[182:185], v[214:217], v[66:69]
	s_setprio 0
	s_barrier
	s_add_u32 s2, s30, 0x8000
	s_addc_u32 s3, s31, 0
	s_add_i32 s63, s63, s38
	v_lshl_add_u64 v[144:145], s[2:3], 0, v[132:133]
	s_mov_b32 m0, s63
	ds_read_b128 v[186:189], v150 offset:49152
	ds_read_b128 v[190:193], v150 offset:50176
	ds_read_b128 v[194:197], v150 offset:51200
	ds_read_b128 v[198:201], v150 offset:52224
	ds_read_b128 v[202:205], v150 offset:53248
	ds_read_b128 v[206:209], v150 offset:54272
	ds_read_b128 v[210:213], v150 offset:55296
	ds_read_b128 v[214:217], v150 offset:56320
	global_load_lds_dwordx4 v[144:145], off
	s_add_i32 m0, s63, 0x2000
	v_lshl_add_u64 v[144:145], s[2:3], 0, v[136:137]
	s_add_u32 s2, s30, 0xc000
	s_addc_u32 s3, s31, 0
	s_add_i32 s30, s64, s38
	global_load_lds_dwordx4 v[144:145], off
	v_lshl_add_u64 v[144:145], s[2:3], 0, v[132:133]
	s_mov_b32 m0, s30
	s_nop 0
	global_load_lds_dwordx4 v[144:145], off
	v_lshl_add_u64 v[144:145], s[2:3], 0, v[136:137]
	s_add_i32 m0, s30, 0x2000
	s_nop 0
	global_load_lds_dwordx4 v[144:145], off
	v_lshl_add_u64 v[144:145], s[28:29], 0, v[130:131]
	s_mov_b32 m0, s44
	s_nop 0
	global_load_lds_dwordx4 v[144:145], off
	v_lshl_add_u64 v[144:145], s[28:29], 0, v[134:135]
	s_mov_b32 m0, s45
	s_nop 0
	global_load_lds_dwordx4 v[144:145], off
	s_waitcnt vmcnt(8)
	s_waitcnt lgkmcnt(0)
	s_setprio 1
	s_barrier
	s_waitcnt lgkmcnt(0)
	v_mfma_f32_16x16x32_bf16 v[62:65], v[152:155], v[186:189], v[62:65]
	v_mfma_f32_16x16x32_bf16 v[58:61], v[160:163], v[186:189], v[58:61]
	v_mfma_f32_16x16x32_bf16 v[50:53], v[152:155], v[194:197], v[50:53]
	v_mfma_f32_16x16x32_bf16 v[42:45], v[160:163], v[194:197], v[42:45]
	v_mfma_f32_16x16x32_bf16 v[34:37], v[152:155], v[202:205], v[34:37]
	v_mfma_f32_16x16x32_bf16 v[26:29], v[160:163], v[202:205], v[26:29]
	v_mfma_f32_16x16x32_bf16 v[18:21], v[152:155], v[210:213], v[18:21]
	v_mfma_f32_16x16x32_bf16 v[10:13], v[160:163], v[210:213], v[10:13]
	v_mfma_f32_16x16x32_bf16 v[62:65], v[156:159], v[190:193], v[62:65]
	v_mfma_f32_16x16x32_bf16 v[58:61], v[164:167], v[190:193], v[58:61]
	v_mfma_f32_16x16x32_bf16 v[50:53], v[156:159], v[198:201], v[50:53]
	v_mfma_f32_16x16x32_bf16 v[42:45], v[164:167], v[198:201], v[42:45]
	v_mfma_f32_16x16x32_bf16 v[34:37], v[156:159], v[206:209], v[34:37]
	v_mfma_f32_16x16x32_bf16 v[26:29], v[164:167], v[206:209], v[26:29]
	v_mfma_f32_16x16x32_bf16 v[18:21], v[156:159], v[214:217], v[18:21]
	v_mfma_f32_16x16x32_bf16 v[10:13], v[164:167], v[214:217], v[10:13]
	s_setprio 0
	s_setprio 1
	v_mfma_f32_16x16x32_bf16 v[54:57], v[168:171], v[186:189], v[54:57]
	v_mfma_f32_16x16x32_bf16 v[46:49], v[178:181], v[186:189], v[46:49]
	v_mfma_f32_16x16x32_bf16 v[38:41], v[168:171], v[194:197], v[38:41]
	v_mfma_f32_16x16x32_bf16 v[30:33], v[178:181], v[194:197], v[30:33]
	v_mfma_f32_16x16x32_bf16 v[22:25], v[168:171], v[202:205], v[22:25]
	v_mfma_f32_16x16x32_bf16 v[14:17], v[178:181], v[202:205], v[14:17]
	v_mfma_f32_16x16x32_bf16 v[6:9], v[168:171], v[210:213], v[6:9]
	v_mfma_f32_16x16x32_bf16 v[2:5], v[178:181], v[210:213], v[2:5]
	v_mfma_f32_16x16x32_bf16 v[54:57], v[172:175], v[190:193], v[54:57]
	v_mfma_f32_16x16x32_bf16 v[46:49], v[182:185], v[190:193], v[46:49]
	v_mfma_f32_16x16x32_bf16 v[38:41], v[172:175], v[198:201], v[38:41]
	v_mfma_f32_16x16x32_bf16 v[30:33], v[182:185], v[198:201], v[30:33]
	v_mfma_f32_16x16x32_bf16 v[22:25], v[172:175], v[206:209], v[22:25]
	v_mfma_f32_16x16x32_bf16 v[14:17], v[182:185], v[206:209], v[14:17]
	v_mfma_f32_16x16x32_bf16 v[6:9], v[172:175], v[214:217], v[6:9]
	v_mfma_f32_16x16x32_bf16 v[2:5], v[182:185], v[214:217], v[2:5]
	s_setprio 0
	s_barrier
	s_add_i32 s62, s62, 2
	s_add_u32 s26, s26, 0x10000
	s_addc_u32 s27, s27, 0
	s_add_u32 s60, s60, 0x10000
	s_addc_u32 s61, s61, 0
	s_cmp_gt_u32 s62, 41
	s_cbranch_scc0 .LBB0_1444
